# v27dropdup
# speedup vs baseline: 1.0136x; 1.0002x over previous
; #define STAGE(P, BASE, LD, br, kt) do { const char* _g = (const char*)((BASE) + (size_t)(br) * (LD) + (size_t)(kt) * 64); \
;     for (int _i = 0; _i < 2; ++_i) { int _b = tidx * 16 + _i * 8192; int _r, _c; stage_rc(_b, _r, _c); \
;       __builtin_amdgcn_global_load_lds((const unsigned*)(_g + (unsigned)((_r * (LD) + _c) * 2)), (unsigned*)((char*)(P) + _b), 16, 0, 0); } } while (0)
; #define LDA(dst, b, h) for (int m = 0; m < 4; ++m) for (int k = 0; k < 2; ++k) \
;     dst[m][k] = *reinterpret_cast<const bf16x8*>((char*)SA(b, h) + lds_byte(wr * 64 + m * 16 + fr, k * 32 + fq * 8))
; #define LDB(dst, b, h) for (int n = 0; n < 2; ++n) for (int k = 0; k < 2; ++k) \
;     dst[n][k] = *reinterpret_cast<const bf16x8*>((char*)SB(b, h) + lds_byte(wc * 32 + n * 16 + fr, k * 32 + fq * 8))
; #define MMA(ai, bj, At_, Bt_) do { __builtin_amdgcn_s_setprio(1); \
;     for (int k = 0; k < 2; ++k) for (int m = 0; m < 4; ++m) for (int n = 0; n < 2; ++n) \
;       acc[ai][bj][m][n] = __builtin_amdgcn_mfma_f32_16x16x32_bf16(At_[m][k], Bt_[n][k], acc[ai][bj][m][n], 0, 0, 0); \
;     __builtin_amdgcn_s_setprio(0); } while (0)
; #define WAIT_L(n) asm volatile("s_waitcnt lgkmcnt(" #n ")" ::: "memory")
; #define BAR __builtin_amdgcn_s_barrier()
; #define SCHED __builtin_amdgcn_sched_barrier(0)
; template <int EPI, int lda, int ldb, int N, int K>
; __device__ __forceinline__ void gemm_phase(const u16* __restrict__ A, const u16* __restrict__ Bt, const GemmEpi ep, int wv) {
;     ...
;       LDB(B0, 0, 0); SCHED; LDA(At, 0, 0); STAGE(SA(1, 1), Ab, lda, brow + HALF, t + 1);
;       WAIT_L(8); BAR; WAIT_L(0); MMA(0, 0, At, B0); BAR; SCHED;
;       LDB(B1, 0, 1); STAGE(SB(0, 0), Bt, ldb, bcol, t + 2);
;       BAR; WAIT_L(0); MMA(0, 1, At, B1); BAR;
;       LDA(At, 0, 1); STAGE(SA(0, 0), Ab, lda, brow, t + 2);
;       BAR; WAIT_L(0); MMA(1, 0, At, B0); BAR; SCHED;
.LBB0_53:
	ds_read_b128 v[172:175], v161
	ds_read_b128 v[176:179], v161 offset:1024
	ds_read_b128 v[180:183], v161 offset:2048
	ds_read_b128 v[184:187], v161 offset:3072
	v_add_u32_e32 v169, 0xc000, v148
	v_lshl_add_u64 v[236:237], v[136:137], 0, s[42:43]
	v_readfirstlane_b32 s45, v169
	v_add_u32_e32 v170, 0xe000, v148
	v_lshl_add_u64 v[162:163], v[236:237], 0, s[14:15]
	s_mov_b32 m0, s45
	v_lshl_add_u64 v[238:239], v[134:135], 0, s[42:43]
	v_readfirstlane_b32 s45, v170
	ds_read_b128 v[164:167], v152
	ds_read_b128 v[188:191], v152 offset:1024
	ds_read_b128 v[192:195], v151
	ds_read_b128 v[196:199], v151 offset:1024
	ds_read_b128 v[200:203], v150
	ds_read_b128 v[204:207], v150 offset:1024
	ds_read_b128 v[208:211], v149
	ds_read_b128 v[212:215], v149 offset:1024
	global_load_lds_dwordx4 v[162:163], off
	v_lshl_add_u64 v[162:163], v[238:239], 0, s[14:15]
	s_mov_b32 m0, s45
	s_nop 0
	global_load_lds_dwordx4 v[162:163], off
	s_waitcnt lgkmcnt(8)
	s_barrier
	s_waitcnt lgkmcnt(0)
	v_mfma_f32_16x16x32_bf16 v[124:127], v[172:175], v[164:167], v[124:127]
	v_mfma_f32_16x16x32_bf16 v[120:123], v[180:183], v[164:167], v[120:123]
	v_mfma_f32_16x16x32_bf16 v[116:119], v[172:175], v[192:195], v[116:119]
	v_mfma_f32_16x16x32_bf16 v[112:115], v[180:183], v[192:195], v[112:115]
	v_mfma_f32_16x16x32_bf16 v[108:111], v[172:175], v[200:203], v[108:111]
	v_mfma_f32_16x16x32_bf16 v[104:107], v[180:183], v[200:203], v[104:107]
	v_mfma_f32_16x16x32_bf16 v[100:103], v[172:175], v[208:211], v[100:103]
	v_mfma_f32_16x16x32_bf16 v[96:99], v[180:183], v[208:211], v[96:99]
	v_mfma_f32_16x16x32_bf16 v[124:127], v[176:179], v[188:191], v[124:127]
	v_mfma_f32_16x16x32_bf16 v[120:123], v[184:187], v[188:191], v[120:123]
	v_mfma_f32_16x16x32_bf16 v[116:119], v[176:179], v[196:199], v[116:119]
	v_mfma_f32_16x16x32_bf16 v[112:115], v[184:187], v[196:199], v[112:115]
	v_mfma_f32_16x16x32_bf16 v[108:111], v[176:179], v[204:207], v[108:111]
	v_mfma_f32_16x16x32_bf16 v[104:107], v[184:187], v[204:207], v[104:107]
	v_mfma_f32_16x16x32_bf16 v[100:103], v[176:179], v[212:215], v[100:103]
	v_mfma_f32_16x16x32_bf16 v[96:99], v[184:187], v[212:215], v[96:99]
	s_barrier
	v_add_u32_e32 v162, s54, v153
	v_lshl_add_u64 v[240:241], v[140:141], 0, s[42:43]
	v_readfirstlane_b32 s45, v162
	v_add_u32_e32 v163, 0x2000, v162
	v_lshl_add_u64 v[232:233], v[240:241], 0, s[16:17]
	s_mov_b32 m0, s45
	v_lshl_add_u64 v[242:243], v[138:139], 0, s[42:43]
	v_readfirstlane_b32 s45, v163
	ds_read_b128 v[216:219], v160
	ds_read_b128 v[220:223], v160 offset:1024
	ds_read_b128 v[224:227], v160 offset:2048
	ds_read_b128 v[228:231], v160 offset:3072
	global_load_lds_dwordx4 v[232:233], off
	v_lshl_add_u64 v[232:233], v[242:243], 0, s[16:17]
	s_mov_b32 m0, s45
	s_nop 0
	global_load_lds_dwordx4 v[232:233], off
	s_barrier
	s_waitcnt lgkmcnt(0)
	v_mfma_f32_16x16x32_bf16 v[92:95], v[216:219], v[164:167], v[92:95]
	v_mfma_f32_16x16x32_bf16 v[88:91], v[224:227], v[164:167], v[88:91]
	v_mfma_f32_16x16x32_bf16 v[84:87], v[216:219], v[192:195], v[84:87]
	v_mfma_f32_16x16x32_bf16 v[80:83], v[224:227], v[192:195], v[80:83]
	v_mfma_f32_16x16x32_bf16 v[76:79], v[216:219], v[200:203], v[76:79]
	v_mfma_f32_16x16x32_bf16 v[72:75], v[224:227], v[200:203], v[72:75]
	v_mfma_f32_16x16x32_bf16 v[68:71], v[216:219], v[208:211], v[68:71]
	v_mfma_f32_16x16x32_bf16 v[64:67], v[224:227], v[208:211], v[64:67]
	v_mfma_f32_16x16x32_bf16 v[92:95], v[220:223], v[188:191], v[92:95]
	v_mfma_f32_16x16x32_bf16 v[88:91], v[228:231], v[188:191], v[88:91]
	v_mfma_f32_16x16x32_bf16 v[84:87], v[220:223], v[196:199], v[84:87]
	v_mfma_f32_16x16x32_bf16 v[80:83], v[228:231], v[196:199], v[80:83]
	v_mfma_f32_16x16x32_bf16 v[76:79], v[220:223], v[204:207], v[76:79]
	v_mfma_f32_16x16x32_bf16 v[72:75], v[228:231], v[204:207], v[72:75]
	v_mfma_f32_16x16x32_bf16 v[68:71], v[220:223], v[212:215], v[68:71]
	v_mfma_f32_16x16x32_bf16 v[64:67], v[228:231], v[212:215], v[64:67]
	s_barrier
	v_readfirstlane_b32 s45, v148
	v_lshl_add_u64 v[164:165], v[236:237], 0, s[18:19]
	s_mov_b32 m0, s45
	ds_read_b128 v[188:191], v152 offset:16384
	ds_read_b128 v[192:195], v152 offset:17408
	ds_read_b128 v[196:199], v151 offset:16384
	ds_read_b128 v[200:203], v151 offset:17408
	ds_read_b128 v[204:207], v150 offset:16384
	ds_read_b128 v[208:211], v150 offset:17408
	ds_read_b128 v[212:215], v149 offset:16384
	ds_read_b128 v[232:235], v149 offset:17408
	global_load_lds_dwordx4 v[164:165], off
	v_add_u32_e32 v164, 0x2000, v148
	v_lshl_add_u64 v[166:167], v[238:239], 0, s[18:19]
	v_readfirstlane_b32 s45, v164
	s_mov_b32 m0, s45
	s_nop 0
	global_load_lds_dwordx4 v[166:167], off
	s_barrier
	s_waitcnt lgkmcnt(0)
	v_mfma_f32_16x16x32_bf16 v[60:63], v[172:175], v[188:191], v[60:63]
	v_mfma_f32_16x16x32_bf16 v[56:59], v[180:183], v[188:191], v[56:59]
	v_mfma_f32_16x16x32_bf16 v[52:55], v[172:175], v[196:199], v[52:55]
	v_mfma_f32_16x16x32_bf16 v[48:51], v[180:183], v[196:199], v[48:51]
	v_mfma_f32_16x16x32_bf16 v[44:47], v[172:175], v[204:207], v[44:47]
	v_mfma_f32_16x16x32_bf16 v[40:43], v[180:183], v[204:207], v[40:43]
	v_mfma_f32_16x16x32_bf16 v[36:39], v[172:175], v[212:215], v[36:39]
	v_mfma_f32_16x16x32_bf16 v[32:35], v[180:183], v[212:215], v[32:35]
	v_mfma_f32_16x16x32_bf16 v[60:63], v[176:179], v[192:195], v[60:63]
	v_mfma_f32_16x16x32_bf16 v[56:59], v[184:187], v[192:195], v[56:59]
	v_mfma_f32_16x16x32_bf16 v[52:55], v[176:179], v[200:203], v[52:55]
	v_mfma_f32_16x16x32_bf16 v[48:51], v[184:187], v[200:203], v[48:51]
	v_mfma_f32_16x16x32_bf16 v[44:47], v[176:179], v[208:211], v[44:47]
	v_mfma_f32_16x16x32_bf16 v[40:43], v[184:187], v[208:211], v[40:43]
	v_mfma_f32_16x16x32_bf16 v[36:39], v[176:179], v[232:235], v[36:39]
	v_mfma_f32_16x16x32_bf16 v[32:35], v[184:187], v[232:235], v[32:35]
	s_barrier
; #define STAGE(P, BASE, LD, br, kt) do { const char* _g = (const char*)((BASE) + (size_t)(br) * (LD) + (size_t)(kt) * 64); \
;     for (int _i = 0; _i < 2; ++_i) { int _b = tidx * 16 + _i * 8192; int _r, _c; stage_rc(_b, _r, _c); \
;       __builtin_amdgcn_global_load_lds((const unsigned*)(_g + (unsigned)((_r * (LD) + _c) * 2)), (unsigned*)((char*)(P) + _b), 16, 0, 0); } } while (0)
; #define LDA(dst, b, h) for (int m = 0; m < 4; ++m) for (int k = 0; k < 2; ++k) \
;     dst[m][k] = *reinterpret_cast<const bf16x8*>((char*)SA(b, h) + lds_byte(wr * 64 + m * 16 + fr, k * 32 + fq * 8))
; #define LDB(dst, b, h) for (int n = 0; n < 2; ++n) for (int k = 0; k < 2; ++k) \
;     dst[n][k] = *reinterpret_cast<const bf16x8*>((char*)SB(b, h) + lds_byte(wc * 32 + n * 16 + fr, k * 32 + fq * 8))
; #define MMA(ai, bj, At_, Bt_) do { __builtin_amdgcn_s_setprio(1); \
;     for (int k = 0; k < 2; ++k) for (int m = 0; m < 4; ++m) for (int n = 0; n < 2; ++n) \
;       acc[ai][bj][m][n] = __builtin_amdgcn_mfma_f32_16x16x32_bf16(At_[m][k], Bt_[n][k], acc[ai][bj][m][n], 0, 0, 0); \
;     __builtin_amdgcn_s_setprio(0); } while (0)
; #define WAIT_V(n) asm volatile("s_waitcnt vmcnt(" #n ")" ::: "memory")
; #define WAIT_L(n) asm volatile("s_waitcnt lgkmcnt(" #n ")" ::: "memory")
; #define BAR __builtin_amdgcn_s_barrier()
; #define SCHED __builtin_amdgcn_sched_barrier(0)
; template <int EPI, int lda, int ldb, int N, int K>
; __device__ __forceinline__ void gemm_phase(const u16* __restrict__ A, const u16* __restrict__ Bt, const GemmEpi ep, int wv) {
;     ...
;       STAGE(SB(0, 1), Bt, ldb, bcol + HALF, t + 2);
;       WAIT_V(6); BAR; MMA(1, 1, At, B1); BAR;
;       LDB(B0, 1, 0); SCHED; LDA(At, 1, 0); STAGE(SA(0, 1), Ab, lda, brow + HALF, t + 2);
;       WAIT_L(8); BAR; WAIT_L(0); MMA(0, 0, At, B0); BAR; SCHED;
;       LDB(B1, 1, 1); STAGE(SB(1, 0), Bt, ldb, bcol, t + 3);
;       BAR; WAIT_L(0); MMA(0, 1, At, B1); BAR;
	v_add_u32_e32 v165, s55, v153
	v_lshl_add_u64 v[166:167], v[240:241], 0, s[20:21]
	v_readfirstlane_b32 s45, v165
	s_mov_b32 m0, s45
	v_lshl_add_u64 v[172:173], v[242:243], 0, s[20:21]
	global_load_lds_dwordx4 v[166:167], off
	v_add_u32_e32 v166, 0x2000, v165
	s_nop 0
	v_readfirstlane_b32 s45, v166
	s_mov_b32 m0, s45
	s_nop 0
	global_load_lds_dwordx4 v[172:173], off
	s_waitcnt vmcnt(6)
	s_barrier
	v_mfma_f32_16x16x32_bf16 v[28:31], v[216:219], v[188:191], v[28:31]
	v_mfma_f32_16x16x32_bf16 v[24:27], v[224:227], v[188:191], v[24:27]
	v_mfma_f32_16x16x32_bf16 v[20:23], v[216:219], v[196:199], v[20:23]
	v_mfma_f32_16x16x32_bf16 v[16:19], v[224:227], v[196:199], v[16:19]
	v_mfma_f32_16x16x32_bf16 v[12:15], v[216:219], v[204:207], v[12:15]
	v_mfma_f32_16x16x32_bf16 v[8:11], v[224:227], v[204:207], v[8:11]
	v_mfma_f32_16x16x32_bf16 v[4:7], v[216:219], v[212:215], v[4:7]
	v_mfma_f32_16x16x32_bf16 v[0:3], v[224:227], v[212:215], v[0:3]
	v_mfma_f32_16x16x32_bf16 v[28:31], v[220:223], v[192:195], v[28:31]
	v_mfma_f32_16x16x32_bf16 v[24:27], v[228:231], v[192:195], v[24:27]
	v_mfma_f32_16x16x32_bf16 v[20:23], v[220:223], v[200:203], v[20:23]
	v_mfma_f32_16x16x32_bf16 v[16:19], v[228:231], v[200:203], v[16:19]
	v_mfma_f32_16x16x32_bf16 v[12:15], v[220:223], v[208:211], v[12:15]
	v_mfma_f32_16x16x32_bf16 v[8:11], v[228:231], v[208:211], v[8:11]
	v_mfma_f32_16x16x32_bf16 v[4:7], v[220:223], v[232:235], v[4:7]
	v_mfma_f32_16x16x32_bf16 v[0:3], v[228:231], v[232:235], v[0:3]
	s_barrier
	ds_read_b128 v[172:175], v156
	ds_read_b128 v[176:179], v156 offset:1024
	ds_read_b128 v[180:183], v156 offset:2048
	ds_read_b128 v[184:187], v156 offset:3072
	v_add_u32_e32 v167, 0x4000, v148
	v_add_u32_e32 v168, 0x6000, v148
	v_readfirstlane_b32 s45, v167
	v_lshl_add_u64 v[220:221], v[236:237], 0, s[22:23]
	s_mov_b32 m0, s45
	v_readfirstlane_b32 s45, v168
	ds_read_b128 v[188:191], v152 offset:32768
	ds_read_b128 v[192:195], v152 offset:33792
	ds_read_b128 v[196:199], v151 offset:32768
	ds_read_b128 v[200:203], v151 offset:33792
	ds_read_b128 v[204:207], v150 offset:32768
	ds_read_b128 v[208:211], v150 offset:33792
	ds_read_b128 v[212:215], v149 offset:32768
	ds_read_b128 v[216:219], v149 offset:33792
	global_load_lds_dwordx4 v[220:221], off
	v_lshl_add_u64 v[220:221], v[238:239], 0, s[22:23]
	s_mov_b32 m0, s45
	s_nop 0
	global_load_lds_dwordx4 v[220:221], off
	s_waitcnt lgkmcnt(8)
	s_barrier
	s_waitcnt lgkmcnt(0)
	v_mfma_f32_16x16x32_bf16 v[124:127], v[172:175], v[188:191], v[124:127]
	v_mfma_f32_16x16x32_bf16 v[120:123], v[180:183], v[188:191], v[120:123]
	v_mfma_f32_16x16x32_bf16 v[116:119], v[172:175], v[196:199], v[116:119]
	v_mfma_f32_16x16x32_bf16 v[112:115], v[180:183], v[196:199], v[112:115]
	v_mfma_f32_16x16x32_bf16 v[108:111], v[172:175], v[204:207], v[108:111]
	v_mfma_f32_16x16x32_bf16 v[104:107], v[180:183], v[204:207], v[104:107]
	v_mfma_f32_16x16x32_bf16 v[100:103], v[172:175], v[212:215], v[100:103]
	v_mfma_f32_16x16x32_bf16 v[96:99], v[180:183], v[212:215], v[96:99]
	v_mfma_f32_16x16x32_bf16 v[124:127], v[176:179], v[192:195], v[124:127]
	v_mfma_f32_16x16x32_bf16 v[120:123], v[184:187], v[192:195], v[120:123]
	v_mfma_f32_16x16x32_bf16 v[116:119], v[176:179], v[200:203], v[116:119]
	v_mfma_f32_16x16x32_bf16 v[112:115], v[184:187], v[200:203], v[112:115]
	v_mfma_f32_16x16x32_bf16 v[108:111], v[176:179], v[208:211], v[108:111]
	v_mfma_f32_16x16x32_bf16 v[104:107], v[184:187], v[208:211], v[104:107]
	v_mfma_f32_16x16x32_bf16 v[100:103], v[176:179], v[216:219], v[100:103]
	v_mfma_f32_16x16x32_bf16 v[96:99], v[184:187], v[216:219], v[96:99]
	s_barrier
	v_readfirstlane_b32 s45, v155
	v_add_u32_e32 v171, 0x2000, v155
	v_lshl_add_u64 v[244:245], v[240:241], 0, s[24:25]
	s_mov_b32 m0, s45
	v_readfirstlane_b32 s45, v171
	ds_read_b128 v[220:223], v154
	ds_read_b128 v[224:227], v154 offset:1024
	ds_read_b128 v[228:231], v154 offset:2048
	ds_read_b128 v[232:235], v154 offset:3072
	global_load_lds_dwordx4 v[244:245], off
	v_lshl_add_u64 v[244:245], v[242:243], 0, s[24:25]
	s_mov_b32 m0, s45
	s_nop 0
	global_load_lds_dwordx4 v[244:245], off
	s_barrier
	s_waitcnt lgkmcnt(0)
	v_mfma_f32_16x16x32_bf16 v[92:95], v[220:223], v[188:191], v[92:95]
	v_mfma_f32_16x16x32_bf16 v[88:91], v[228:231], v[188:191], v[88:91]
	v_mfma_f32_16x16x32_bf16 v[84:87], v[220:223], v[196:199], v[84:87]
	v_mfma_f32_16x16x32_bf16 v[80:83], v[228:231], v[196:199], v[80:83]
	v_mfma_f32_16x16x32_bf16 v[76:79], v[220:223], v[204:207], v[76:79]
	v_mfma_f32_16x16x32_bf16 v[72:75], v[228:231], v[204:207], v[72:75]
	v_mfma_f32_16x16x32_bf16 v[68:71], v[220:223], v[212:215], v[68:71]
	v_mfma_f32_16x16x32_bf16 v[64:67], v[228:231], v[212:215], v[64:67]
	v_mfma_f32_16x16x32_bf16 v[92:95], v[224:227], v[192:195], v[92:95]
	v_mfma_f32_16x16x32_bf16 v[88:91], v[232:235], v[192:195], v[88:91]
	v_mfma_f32_16x16x32_bf16 v[84:87], v[224:227], v[200:203], v[84:87]
	v_mfma_f32_16x16x32_bf16 v[80:83], v[232:235], v[200:203], v[80:83]
	v_mfma_f32_16x16x32_bf16 v[76:79], v[224:227], v[208:211], v[76:79]
	v_mfma_f32_16x16x32_bf16 v[72:75], v[232:235], v[208:211], v[72:75]
	v_mfma_f32_16x16x32_bf16 v[68:71], v[224:227], v[216:219], v[68:71]
	v_mfma_f32_16x16x32_bf16 v[64:67], v[232:235], v[216:219], v[64:67]
	s_barrier
	v_readfirstlane_b32 s45, v157
	v_lshl_add_u64 v[236:237], v[236:237], 0, s[26:27]
	s_mov_b32 m0, s45
	v_readfirstlane_b32 s45, v158
	ds_read_b128 v[188:191], v152 offset:49152
	ds_read_b128 v[192:195], v152 offset:50176
	ds_read_b128 v[196:199], v151 offset:49152
	ds_read_b128 v[200:203], v151 offset:50176
	ds_read_b128 v[204:207], v150 offset:49152
	ds_read_b128 v[208:211], v150 offset:50176
	ds_read_b128 v[212:215], v149 offset:49152
	ds_read_b128 v[216:219], v149 offset:50176
	global_load_lds_dwordx4 v[236:237], off
	v_lshl_add_u64 v[236:237], v[238:239], 0, s[26:27]
	s_mov_b32 m0, s45
	s_nop 0
	global_load_lds_dwordx4 v[236:237], off
	s_barrier
; #define STAGE(P, BASE, LD, br, kt) do { const char* _g = (const char*)((BASE) + (size_t)(br) * (LD) + (size_t)(kt) * 64); \
;     for (int _i = 0; _i < 2; ++_i) { int _b = tidx * 16 + _i * 8192; int _r, _c; stage_rc(_b, _r, _c); \
;       __builtin_amdgcn_global_load_lds((const unsigned*)(_g + (unsigned)((_r * (LD) + _c) * 2)), (unsigned*)((char*)(P) + _b), 16, 0, 0); } } while (0)
; #define LDA(dst, b, h) for (int m = 0; m < 4; ++m) for (int k = 0; k < 2; ++k) \
;     dst[m][k] = *reinterpret_cast<const bf16x8*>((char*)SA(b, h) + lds_byte(wr * 64 + m * 16 + fr, k * 32 + fq * 8))
; #define LDB(dst, b, h) for (int n = 0; n < 2; ++n) for (int k = 0; k < 2; ++k) \
;     dst[n][k] = *reinterpret_cast<const bf16x8*>((char*)SB(b, h) + lds_byte(wc * 32 + n * 16 + fr, k * 32 + fq * 8))
; #define MMA(ai, bj, At_, Bt_) do { __builtin_amdgcn_s_setprio(1); \
;     for (int k = 0; k < 2; ++k) for (int m = 0; m < 4; ++m) for (int n = 0; n < 2; ++n) \
;       acc[ai][bj][m][n] = __builtin_amdgcn_mfma_f32_16x16x32_bf16(At_[m][k], Bt_[n][k], acc[ai][bj][m][n], 0, 0, 0); \
;     __builtin_amdgcn_s_setprio(0); } while (0)
; #define WAIT_V(n) asm volatile("s_waitcnt vmcnt(" #n ")" ::: "memory")
; #define WAIT_L(n) asm volatile("s_waitcnt lgkmcnt(" #n ")" ::: "memory")
; #define BAR __builtin_amdgcn_s_barrier()
; #define SCHED __builtin_amdgcn_sched_barrier(0)
; template <int EPI, int lda, int ldb, int N, int K>
; __device__ __forceinline__ void gemm_phase(const u16* __restrict__ A, const u16* __restrict__ Bt, const GemmEpi ep, int wv) {
;     ...
;       BAR; WAIT_L(0); MMA(1, 0, At, B0); BAR; SCHED;
;       STAGE(SB(1, 1), Bt, ldb, bcol + HALF, t + 3);
;       WAIT_V(6); BAR; MMA(1, 1, At, B1); BAR;
;     }
;     { LDB(B0, 0, 0); LDA(At, 0, 0); STAGE(SA(1, 1), Ab, lda, brow + HALF, nt - 1);
;       BAR; WAIT_L(0); MMA(0, 0, At, B0); BAR;
;       LDB(B1, 0, 1); BAR; WAIT_L(0); MMA(0, 1, At, B1); BAR;
	s_waitcnt lgkmcnt(0)
	v_mfma_f32_16x16x32_bf16 v[60:63], v[172:175], v[188:191], v[60:63]
	v_mfma_f32_16x16x32_bf16 v[56:59], v[180:183], v[188:191], v[56:59]
	v_mfma_f32_16x16x32_bf16 v[52:55], v[172:175], v[196:199], v[52:55]
	v_mfma_f32_16x16x32_bf16 v[48:51], v[180:183], v[196:199], v[48:51]
	v_mfma_f32_16x16x32_bf16 v[44:47], v[172:175], v[204:207], v[44:47]
	v_mfma_f32_16x16x32_bf16 v[40:43], v[180:183], v[204:207], v[40:43]
	v_mfma_f32_16x16x32_bf16 v[36:39], v[172:175], v[212:215], v[36:39]
	v_mfma_f32_16x16x32_bf16 v[32:35], v[180:183], v[212:215], v[32:35]
	v_mfma_f32_16x16x32_bf16 v[60:63], v[176:179], v[192:195], v[60:63]
	v_mfma_f32_16x16x32_bf16 v[56:59], v[184:187], v[192:195], v[56:59]
	v_mfma_f32_16x16x32_bf16 v[52:55], v[176:179], v[200:203], v[52:55]
	v_mfma_f32_16x16x32_bf16 v[48:51], v[184:187], v[200:203], v[48:51]
	v_mfma_f32_16x16x32_bf16 v[44:47], v[176:179], v[208:211], v[44:47]
	v_mfma_f32_16x16x32_bf16 v[40:43], v[184:187], v[208:211], v[40:43]
	v_mfma_f32_16x16x32_bf16 v[36:39], v[176:179], v[216:219], v[36:39]
	v_mfma_f32_16x16x32_bf16 v[32:35], v[184:187], v[216:219], v[32:35]
	s_barrier
	v_readfirstlane_b32 s45, v159
	v_add_u32_e32 v171, 0x2000, v159
	v_lshl_add_u64 v[172:173], v[240:241], 0, s[34:35]
	s_mov_b32 m0, s45
	v_readfirstlane_b32 s45, v171
	global_load_lds_dwordx4 v[172:173], off
	v_lshl_add_u64 v[172:173], v[242:243], 0, s[34:35]
	s_mov_b32 m0, s45
	s_nop 0
	global_load_lds_dwordx4 v[172:173], off
	s_add_i32 s44, s44, 2
	s_add_u32 s42, s42, 0x100
	s_addc_u32 s43, s43, 0
	s_cmp_gt_u32 s44, 27
	s_waitcnt vmcnt(6)
	s_barrier
	v_mfma_f32_16x16x32_bf16 v[28:31], v[220:223], v[188:191], v[28:31]
	v_mfma_f32_16x16x32_bf16 v[24:27], v[228:231], v[188:191], v[24:27]
	v_mfma_f32_16x16x32_bf16 v[20:23], v[220:223], v[196:199], v[20:23]
	v_mfma_f32_16x16x32_bf16 v[16:19], v[228:231], v[196:199], v[16:19]
	v_mfma_f32_16x16x32_bf16 v[12:15], v[220:223], v[204:207], v[12:15]
	v_mfma_f32_16x16x32_bf16 v[8:11], v[228:231], v[204:207], v[8:11]
	v_mfma_f32_16x16x32_bf16 v[4:7], v[220:223], v[212:215], v[4:7]
	v_mfma_f32_16x16x32_bf16 v[0:3], v[228:231], v[212:215], v[0:3]
	v_mfma_f32_16x16x32_bf16 v[28:31], v[224:227], v[192:195], v[28:31]
	v_mfma_f32_16x16x32_bf16 v[24:27], v[232:235], v[192:195], v[24:27]
	v_mfma_f32_16x16x32_bf16 v[20:23], v[224:227], v[200:203], v[20:23]
	v_mfma_f32_16x16x32_bf16 v[16:19], v[232:235], v[200:203], v[16:19]
	v_mfma_f32_16x16x32_bf16 v[12:15], v[224:227], v[208:211], v[12:15]
	v_mfma_f32_16x16x32_bf16 v[8:11], v[232:235], v[208:211], v[8:11]
	v_mfma_f32_16x16x32_bf16 v[4:7], v[224:227], v[216:219], v[4:7]
	v_mfma_f32_16x16x32_bf16 v[0:3], v[232:235], v[216:219], v[0:3]
	s_barrier
	s_cbranch_scc0 .LBB0_53
	s_add_i32 s42, s38, 0x80
	s_mul_hi_i32 s43, s42, 0x1080
	s_mulk_i32 s42, 0x1080
	s_add_u32 s42, s51, s42
	s_addc_u32 s43, s52, s43
	v_lshl_add_u64 v[158:159], s[42:43], 0, v[128:129]
	v_readfirstlane_b32 s44, v169
	v_lshl_add_u64 v[158:159], v[158:159], 0, s[36:37]
	s_mov_b32 m0, s44
	ds_read_b128 v[134:137], v161
	ds_read_b128 v[138:141], v161 offset:1024
	ds_read_b128 v[172:175], v161 offset:2048
	ds_read_b128 v[176:179], v161 offset:3072
	ds_read_b128 v[180:183], v152
	ds_read_b128 v[184:187], v152 offset:1024
	ds_read_b128 v[188:191], v151
	ds_read_b128 v[192:195], v151 offset:1024
	ds_read_b128 v[196:199], v150
	ds_read_b128 v[200:203], v150 offset:1024
	ds_read_b128 v[204:207], v149
	ds_read_b128 v[208:211], v149 offset:1024
	global_load_lds_dwordx4 v[158:159], off
	v_lshl_add_u64 v[158:159], s[42:43], 0, v[132:133]
	v_readfirstlane_b32 s42, v170
	v_lshl_add_u64 v[158:159], v[158:159], 0, s[36:37]
	s_mov_b32 m0, s42
	s_nop 0
	global_load_lds_dwordx4 v[158:159], off
	s_barrier
	s_waitcnt lgkmcnt(0)
	v_mfma_f32_16x16x32_bf16 v[124:127], v[134:137], v[180:183], v[124:127]
	v_mfma_f32_16x16x32_bf16 v[120:123], v[172:175], v[180:183], v[120:123]
	v_mfma_f32_16x16x32_bf16 v[116:119], v[134:137], v[188:191], v[116:119]
	v_mfma_f32_16x16x32_bf16 v[112:115], v[172:175], v[188:191], v[112:115]
	v_mfma_f32_16x16x32_bf16 v[108:111], v[134:137], v[196:199], v[108:111]
	v_mfma_f32_16x16x32_bf16 v[104:107], v[172:175], v[196:199], v[104:107]
	v_mfma_f32_16x16x32_bf16 v[100:103], v[134:137], v[204:207], v[100:103]
	v_mfma_f32_16x16x32_bf16 v[96:99], v[172:175], v[204:207], v[96:99]
	v_mfma_f32_16x16x32_bf16 v[124:127], v[138:141], v[184:187], v[124:127]
	v_mfma_f32_16x16x32_bf16 v[120:123], v[176:179], v[184:187], v[120:123]
	v_mfma_f32_16x16x32_bf16 v[116:119], v[138:141], v[192:195], v[116:119]
	v_mfma_f32_16x16x32_bf16 v[112:115], v[176:179], v[192:195], v[112:115]
	v_mfma_f32_16x16x32_bf16 v[108:111], v[138:141], v[200:203], v[108:111]
	v_mfma_f32_16x16x32_bf16 v[104:107], v[176:179], v[200:203], v[104:107]
	v_mfma_f32_16x16x32_bf16 v[100:103], v[138:141], v[208:211], v[100:103]
	v_mfma_f32_16x16x32_bf16 v[96:99], v[176:179], v[208:211], v[96:99]
	s_barrier
	ds_read_b128 v[212:215], v160
	ds_read_b128 v[216:219], v160 offset:1024
	ds_read_b128 v[220:223], v160 offset:2048
	ds_read_b128 v[158:161], v160 offset:3072
	s_barrier
; #define LDA(dst, b, h) for (int m = 0; m < 4; ++m) for (int k = 0; k < 2; ++k) \
;     dst[m][k] = *reinterpret_cast<const bf16x8*>((char*)SA(b, h) + lds_byte(wr * 64 + m * 16 + fr, k * 32 + fq * 8))
; #define LDB(dst, b, h) for (int n = 0; n < 2; ++n) for (int k = 0; k < 2; ++k) \
;     dst[n][k] = *reinterpret_cast<const bf16x8*>((char*)SB(b, h) + lds_byte(wc * 32 + n * 16 + fr, k * 32 + fq * 8))
; #define MMA(ai, bj, At_, Bt_) do { __builtin_amdgcn_s_setprio(1); \
;     for (int k = 0; k < 2; ++k) for (int m = 0; m < 4; ++m) for (int n = 0; n < 2; ++n) \
;       acc[ai][bj][m][n] = __builtin_amdgcn_mfma_f32_16x16x32_bf16(At_[m][k], Bt_[n][k], acc[ai][bj][m][n], 0, 0, 0); \
;     __builtin_amdgcn_s_setprio(0); } while (0)
; #define WAIT_V(n) asm volatile("s_waitcnt vmcnt(" #n ")" ::: "memory")
; #define WAIT_L(n) asm volatile("s_waitcnt lgkmcnt(" #n ")" ::: "memory")
; #define BAR __builtin_amdgcn_s_barrier()
; template <int EPI, int lda, int ldb, int N, int K>
; __device__ __forceinline__ void gemm_phase(const u16* __restrict__ A, const u16* __restrict__ Bt, const GemmEpi ep, int wv) {
;     ...
;       LDB(B1, 0, 1); BAR; WAIT_L(0); MMA(0, 1, At, B1); BAR;
;       LDA(At, 0, 1); WAIT_V(4); BAR; WAIT_L(0); MMA(1, 0, At, B0); MMA(1, 1, At, B1); BAR; }
;     { LDB(B0, 1, 0); LDA(At, 1, 0); WAIT_V(2); BAR; WAIT_L(0); MMA(0, 0, At, B0); BAR;
	s_waitcnt lgkmcnt(0)
	v_mfma_f32_16x16x32_bf16 v[92:95], v[212:215], v[180:183], v[92:95]
	v_mfma_f32_16x16x32_bf16 v[88:91], v[220:223], v[180:183], v[88:91]
	v_mfma_f32_16x16x32_bf16 v[76:79], v[212:215], v[196:199], v[76:79]
	v_mfma_f32_16x16x32_bf16 v[72:75], v[220:223], v[196:199], v[72:75]
	v_mfma_f32_16x16x32_bf16 v[84:87], v[212:215], v[188:191], v[84:87]
	v_mfma_f32_16x16x32_bf16 v[80:83], v[220:223], v[188:191], v[80:83]
	v_mfma_f32_16x16x32_bf16 v[68:71], v[212:215], v[204:207], v[68:71]
	v_mfma_f32_16x16x32_bf16 v[64:67], v[220:223], v[204:207], v[64:67]
	v_mfma_f32_16x16x32_bf16 v[92:95], v[216:219], v[184:187], v[92:95]
	v_mfma_f32_16x16x32_bf16 v[88:91], v[158:161], v[184:187], v[88:91]
	v_mfma_f32_16x16x32_bf16 v[76:79], v[216:219], v[200:203], v[76:79]
	v_mfma_f32_16x16x32_bf16 v[72:75], v[158:161], v[200:203], v[72:75]
	v_mfma_f32_16x16x32_bf16 v[180:183], v[216:219], v[192:195], v[84:87]
	v_mfma_f32_16x16x32_bf16 v[184:187], v[158:161], v[192:195], v[80:83]
	v_mfma_f32_16x16x32_bf16 v[188:191], v[216:219], v[208:211], v[68:71]
	v_mfma_f32_16x16x32_bf16 v[192:195], v[158:161], v[208:211], v[64:67]
	s_barrier
	s_nop 0
	ds_read_b128 v[64:67], v152 offset:16384
	ds_read_b128 v[68:71], v152 offset:17408
	ds_read_b128 v[80:83], v151 offset:16384
	ds_read_b128 v[84:87], v151 offset:17408
	ds_read_b128 v[196:199], v150 offset:16384
	ds_read_b128 v[200:203], v150 offset:17408
	ds_read_b128 v[204:207], v149 offset:16384
	ds_read_b128 v[208:211], v149 offset:17408
	s_waitcnt vmcnt(4)
	s_barrier
	s_waitcnt lgkmcnt(0)
	v_mfma_f32_16x16x32_bf16 v[60:63], v[134:137], v[64:67], v[60:63]
	v_mfma_f32_16x16x32_bf16 v[56:59], v[172:175], v[64:67], v[56:59]
	v_mfma_f32_16x16x32_bf16 v[52:55], v[134:137], v[80:83], v[52:55]
	v_mfma_f32_16x16x32_bf16 v[48:51], v[172:175], v[80:83], v[48:51]
	v_mfma_f32_16x16x32_bf16 v[44:47], v[134:137], v[196:199], v[44:47]
	v_mfma_f32_16x16x32_bf16 v[40:43], v[172:175], v[196:199], v[40:43]
	v_mfma_f32_16x16x32_bf16 v[36:39], v[134:137], v[204:207], v[36:39]
	v_mfma_f32_16x16x32_bf16 v[32:35], v[172:175], v[204:207], v[32:35]
	v_mfma_f32_16x16x32_bf16 v[60:63], v[138:141], v[68:71], v[60:63]
	v_mfma_f32_16x16x32_bf16 v[56:59], v[176:179], v[68:71], v[56:59]
	v_mfma_f32_16x16x32_bf16 v[52:55], v[138:141], v[84:87], v[52:55]
	v_mfma_f32_16x16x32_bf16 v[48:51], v[176:179], v[84:87], v[48:51]
	v_mfma_f32_16x16x32_bf16 v[44:47], v[138:141], v[200:203], v[44:47]
	v_mfma_f32_16x16x32_bf16 v[40:43], v[176:179], v[200:203], v[40:43]
	v_mfma_f32_16x16x32_bf16 v[36:39], v[138:141], v[208:211], v[36:39]
	v_mfma_f32_16x16x32_bf16 v[32:35], v[176:179], v[208:211], v[32:35]
	v_mfma_f32_16x16x32_bf16 v[28:31], v[212:215], v[64:67], v[28:31]
	v_mfma_f32_16x16x32_bf16 v[24:27], v[220:223], v[64:67], v[24:27]
	v_mfma_f32_16x16x32_bf16 v[12:15], v[212:215], v[196:199], v[12:15]
	v_mfma_f32_16x16x32_bf16 v[8:11], v[220:223], v[196:199], v[8:11]
	v_mfma_f32_16x16x32_bf16 v[20:23], v[212:215], v[80:83], v[20:23]
	v_mfma_f32_16x16x32_bf16 v[16:19], v[220:223], v[80:83], v[16:19]
	v_mfma_f32_16x16x32_bf16 v[4:7], v[212:215], v[204:207], v[4:7]
	v_mfma_f32_16x16x32_bf16 v[0:3], v[220:223], v[204:207], v[0:3]
	v_mfma_f32_16x16x32_bf16 v[28:31], v[216:219], v[68:71], v[28:31]
	v_mfma_f32_16x16x32_bf16 v[24:27], v[158:161], v[68:71], v[24:27]
	v_mfma_f32_16x16x32_bf16 v[12:15], v[216:219], v[200:203], v[12:15]
	v_mfma_f32_16x16x32_bf16 v[8:11], v[158:161], v[200:203], v[8:11]
	v_mfma_f32_16x16x32_bf16 v[134:137], v[216:219], v[84:87], v[20:23]
	v_mfma_f32_16x16x32_bf16 v[138:141], v[158:161], v[84:87], v[16:19]
	v_mfma_f32_16x16x32_bf16 v[170:173], v[216:219], v[208:211], v[4:7]
	v_mfma_f32_16x16x32_bf16 v[158:161], v[158:161], v[208:211], v[0:3]
	s_barrier
	s_nop 0
	ds_read_b128 v[0:3], v156
	ds_read_b128 v[4:7], v156 offset:1024
	ds_read_b128 v[16:19], v156 offset:2048
	ds_read_b128 v[174:177], v156 offset:3072
	ds_read_b128 v[20:23], v152 offset:32768
	ds_read_b128 v[196:199], v152 offset:33792
	ds_read_b128 v[200:203], v151 offset:32768
	ds_read_b128 v[204:207], v151 offset:33792
	ds_read_b128 v[208:211], v150 offset:32768
	ds_read_b128 v[212:215], v150 offset:33792
	ds_read_b128 v[216:219], v149 offset:32768
	ds_read_b128 v[220:223], v149 offset:33792
	s_waitcnt vmcnt(2)
	s_barrier
; #define LDA(dst, b, h) for (int m = 0; m < 4; ++m) for (int k = 0; k < 2; ++k) \
;     dst[m][k] = *reinterpret_cast<const bf16x8*>((char*)SA(b, h) + lds_byte(wr * 64 + m * 16 + fr, k * 32 + fq * 8))
; #define LDB(dst, b, h) for (int n = 0; n < 2; ++n) for (int k = 0; k < 2; ++k) \
;     dst[n][k] = *reinterpret_cast<const bf16x8*>((char*)SB(b, h) + lds_byte(wc * 32 + n * 16 + fr, k * 32 + fq * 8))
; #define MMA(ai, bj, At_, Bt_) do { __builtin_amdgcn_s_setprio(1); \
;     for (int k = 0; k < 2; ++k) for (int m = 0; m < 4; ++m) for (int n = 0; n < 2; ++n) \
;       acc[ai][bj][m][n] = __builtin_amdgcn_mfma_f32_16x16x32_bf16(At_[m][k], Bt_[n][k], acc[ai][bj][m][n], 0, 0, 0); \
;     __builtin_amdgcn_s_setprio(0); } while (0)
; #define WAIT_V(n) asm volatile("s_waitcnt vmcnt(" #n ")" ::: "memory")
; #define WAIT_L(n) asm volatile("s_waitcnt lgkmcnt(" #n ")" ::: "memory")
; #define BAR __builtin_amdgcn_s_barrier()
; template <int EPI, int lda, int ldb, int N, int K>
; __device__ __forceinline__ void gemm_phase(const u16* __restrict__ A, const u16* __restrict__ Bt, const GemmEpi ep, int wv) {
;     ...
;     { LDB(B0, 1, 0); LDA(At, 1, 0); WAIT_V(2); BAR; WAIT_L(0); MMA(0, 0, At, B0); BAR;
;       LDB(B1, 1, 1); WAIT_V(0); BAR; WAIT_L(0); MMA(0, 1, At, B1); BAR;
;       LDA(At, 1, 1); BAR; WAIT_L(0); MMA(1, 0, At, B0); MMA(1, 1, At, B1); BAR; }
;     if (wr == 0) BAR;
	s_waitcnt lgkmcnt(0)
	v_mfma_f32_16x16x32_bf16 v[64:67], v[0:3], v[20:23], v[124:127]
	v_mfma_f32_16x16x32_bf16 v[68:71], v[16:19], v[20:23], v[120:123]
	v_mfma_f32_16x16x32_bf16 v[80:83], v[0:3], v[200:203], v[116:119]
	v_mfma_f32_16x16x32_bf16 v[84:87], v[16:19], v[200:203], v[112:115]
	v_mfma_f32_16x16x32_bf16 v[108:111], v[0:3], v[208:211], v[108:111]
	v_mfma_f32_16x16x32_bf16 v[104:107], v[16:19], v[208:211], v[104:107]
	v_mfma_f32_16x16x32_bf16 v[120:123], v[0:3], v[216:219], v[100:103]
	v_mfma_f32_16x16x32_bf16 v[124:127], v[16:19], v[216:219], v[96:99]
	v_mfma_f32_16x16x32_bf16 v[116:119], v[4:7], v[196:199], v[64:67]
	v_mfma_f32_16x16x32_bf16 v[112:115], v[174:177], v[196:199], v[68:71]
	v_mfma_f32_16x16x32_bf16 v[100:103], v[4:7], v[204:207], v[80:83]
	v_mfma_f32_16x16x32_bf16 v[96:99], v[174:177], v[204:207], v[84:87]
	v_mfma_f32_16x16x32_bf16 v[84:87], v[4:7], v[212:215], v[108:111]
	v_mfma_f32_16x16x32_bf16 v[80:83], v[174:177], v[212:215], v[104:107]
	v_mfma_f32_16x16x32_bf16 v[68:71], v[4:7], v[220:223], v[120:123]
	v_mfma_f32_16x16x32_bf16 v[64:67], v[174:177], v[220:223], v[124:127]
	s_barrier
	ds_read_b128 v[224:227], v154
	ds_read_b128 v[228:231], v154 offset:1024
	ds_read_b128 v[232:235], v154 offset:2048
	ds_read_b128 v[154:157], v154 offset:3072
	s_waitcnt vmcnt(0)
	s_barrier
	s_waitcnt lgkmcnt(0)
	v_mfma_f32_16x16x32_bf16 v[92:95], v[224:227], v[20:23], v[92:95]
	v_mfma_f32_16x16x32_bf16 v[20:23], v[232:235], v[20:23], v[88:91]
	v_mfma_f32_16x16x32_bf16 v[88:91], v[224:227], v[200:203], v[180:183]
	v_mfma_f32_16x16x32_bf16 v[104:107], v[232:235], v[200:203], v[184:187]
	v_mfma_f32_16x16x32_bf16 v[76:79], v[224:227], v[208:211], v[76:79]
	v_mfma_f32_16x16x32_bf16 v[72:75], v[232:235], v[208:211], v[72:75]
	v_mfma_f32_16x16x32_bf16 v[178:181], v[224:227], v[216:219], v[188:191]
	v_mfma_f32_16x16x32_bf16 v[182:185], v[232:235], v[216:219], v[192:195]
	v_mfma_f32_16x16x32_bf16 v[124:127], v[228:231], v[196:199], v[92:95]
	v_mfma_f32_16x16x32_bf16 v[120:123], v[154:157], v[196:199], v[20:23]
	v_mfma_f32_16x16x32_bf16 v[108:111], v[228:231], v[204:207], v[88:91]
	v_mfma_f32_16x16x32_bf16 v[104:107], v[154:157], v[204:207], v[104:107]
	v_mfma_f32_16x16x32_bf16 v[92:95], v[228:231], v[212:215], v[76:79]
	v_mfma_f32_16x16x32_bf16 v[88:91], v[154:157], v[212:215], v[72:75]
	v_mfma_f32_16x16x32_bf16 v[76:79], v[228:231], v[220:223], v[178:181]
	v_mfma_f32_16x16x32_bf16 v[72:75], v[154:157], v[220:223], v[182:185]
	s_barrier
	ds_read_b128 v[178:181], v152 offset:49152
	ds_read_b128 v[182:185], v152 offset:50176
	ds_read_b128 v[186:189], v151 offset:49152
	ds_read_b128 v[190:193], v151 offset:50176
	ds_read_b128 v[194:197], v150 offset:49152
	ds_read_b128 v[150:153], v150 offset:50176
	ds_read_b128 v[198:201], v149 offset:49152
	ds_read_b128 v[202:205], v149 offset:50176
	s_barrier
	s_waitcnt lgkmcnt(0)
	v_mfma_f32_16x16x32_bf16 v[20:23], v[0:3], v[178:181], v[60:63]
	v_mfma_f32_16x16x32_bf16 v[56:59], v[16:19], v[178:181], v[56:59]
	v_mfma_f32_16x16x32_bf16 v[60:63], v[0:3], v[186:189], v[52:55]
	v_mfma_f32_16x16x32_bf16 v[206:209], v[16:19], v[186:189], v[48:51]
	v_mfma_f32_16x16x32_bf16 v[44:47], v[0:3], v[194:197], v[44:47]
	v_mfma_f32_16x16x32_bf16 v[40:43], v[16:19], v[194:197], v[40:43]
	v_mfma_f32_16x16x32_bf16 v[0:3], v[0:3], v[198:201], v[36:39]
	v_mfma_f32_16x16x32_bf16 v[210:213], v[16:19], v[198:201], v[32:35]
	v_mfma_f32_16x16x32_bf16 v[52:55], v[4:7], v[182:185], v[20:23]
	v_mfma_f32_16x16x32_bf16 v[48:51], v[174:177], v[182:185], v[56:59]
	v_mfma_f32_16x16x32_bf16 v[36:39], v[4:7], v[190:193], v[60:63]
	v_mfma_f32_16x16x32_bf16 v[32:35], v[174:177], v[190:193], v[206:209]
	v_mfma_f32_16x16x32_bf16 v[20:23], v[4:7], v[150:153], v[44:47]
	v_mfma_f32_16x16x32_bf16 v[16:19], v[174:177], v[150:153], v[40:43]
	v_mfma_f32_16x16x32_bf16 v[4:7], v[4:7], v[202:205], v[0:3]
	v_mfma_f32_16x16x32_bf16 v[0:3], v[174:177], v[202:205], v[210:213]
	v_mfma_f32_16x16x32_bf16 v[28:31], v[224:227], v[178:181], v[28:31]
	v_mfma_f32_16x16x32_bf16 v[24:27], v[232:235], v[178:181], v[24:27]
	v_mfma_f32_16x16x32_bf16 v[40:43], v[224:227], v[186:189], v[134:137]
	v_mfma_f32_16x16x32_bf16 v[134:137], v[232:235], v[186:189], v[138:141]
	v_mfma_f32_16x16x32_bf16 v[12:15], v[224:227], v[194:197], v[12:15]
	v_mfma_f32_16x16x32_bf16 v[8:11], v[232:235], v[194:197], v[8:11]
	v_mfma_f32_16x16x32_bf16 v[138:141], v[224:227], v[198:201], v[170:173]
	v_mfma_f32_16x16x32_bf16 v[158:161], v[232:235], v[198:201], v[158:161]
	v_mfma_f32_16x16x32_bf16 v[60:63], v[228:231], v[182:185], v[28:31]
	v_mfma_f32_16x16x32_bf16 v[56:59], v[154:157], v[182:185], v[24:27]
	v_mfma_f32_16x16x32_bf16 v[44:47], v[228:231], v[190:193], v[40:43]
	v_mfma_f32_16x16x32_bf16 v[40:43], v[154:157], v[190:193], v[134:137]
	v_mfma_f32_16x16x32_bf16 v[28:31], v[228:231], v[150:153], v[12:15]
	v_mfma_f32_16x16x32_bf16 v[24:27], v[154:157], v[150:153], v[8:11]
	v_mfma_f32_16x16x32_bf16 v[12:15], v[228:231], v[202:205], v[138:141]
	v_mfma_f32_16x16x32_bf16 v[8:11], v[154:157], v[202:205], v[158:161]
	v_cmp_gt_u32_e32 vcc, s56, v130
	s_barrier
	s_and_saveexec_b64 s[42:43], vcc
	s_cbranch_execz .LBB0_56
	s_barrier

; #define STAGE(P, BASE, LD, br, kt) do { const char* _g = (const char*)((BASE) + (size_t)(br) * (LD) + (size_t)(kt) * 64); \
;     for (int _i = 0; _i < 2; ++_i) { int _b = tidx * 16 + _i * 8192; int _r, _c; stage_rc(_b, _r, _c); \
;       __builtin_amdgcn_global_load_lds((const unsigned*)(_g + (unsigned)((_r * (LD) + _c) * 2)), (unsigned*)((char*)(P) + _b), 16, 0, 0); } } while (0)
; #define LDA(dst, b, h) for (int m = 0; m < 4; ++m) for (int k = 0; k < 2; ++k) \
;     dst[m][k] = *reinterpret_cast<const bf16x8*>((char*)SA(b, h) + lds_byte(wr * 64 + m * 16 + fr, k * 32 + fq * 8))
; #define LDB(dst, b, h) for (int n = 0; n < 2; ++n) for (int k = 0; k < 2; ++k) \
;     dst[n][k] = *reinterpret_cast<const bf16x8*>((char*)SB(b, h) + lds_byte(wc * 32 + n * 16 + fr, k * 32 + fq * 8))
; #define MMA(ai, bj, At_, Bt_) do { __builtin_amdgcn_s_setprio(1); \
;     for (int k = 0; k < 2; ++k) for (int m = 0; m < 4; ++m) for (int n = 0; n < 2; ++n) \
;       acc[ai][bj][m][n] = __builtin_amdgcn_mfma_f32_16x16x32_bf16(At_[m][k], Bt_[n][k], acc[ai][bj][m][n], 0, 0, 0); \
;     __builtin_amdgcn_s_setprio(0); } while (0)
; #define WAIT_L(n) asm volatile("s_waitcnt lgkmcnt(" #n ")" ::: "memory")
; #define BAR __builtin_amdgcn_s_barrier()
; #define SCHED __builtin_amdgcn_sched_barrier(0)
; template <int EPI, int lda, int ldb, int N, int K>
; __device__ __forceinline__ void gemm_phase(const u16* __restrict__ A, const u16* __restrict__ Bt, const GemmEpi ep, int wv) {
;     ...
;       LDB(B0, 0, 0); SCHED; LDA(At, 0, 0); STAGE(SA(1, 1), Ab, lda, brow + HALF, t + 1);
;       WAIT_L(8); BAR; WAIT_L(0); MMA(0, 0, At, B0); BAR; SCHED;
;       LDB(B1, 0, 1); STAGE(SB(0, 0), Bt, ldb, bcol, t + 2);
;       BAR; WAIT_L(0); MMA(0, 1, At, B1); BAR;
;       LDA(At, 0, 1); STAGE(SA(0, 0), Ab, lda, brow, t + 2);
;       BAR; WAIT_L(0); MMA(1, 0, At, B0); BAR; SCHED;
.LBB0_224:
	ds_read_b128 v[168:171], v164
	ds_read_b128 v[174:177], v164 offset:1024
	ds_read_b128 v[178:181], v164 offset:2048
	ds_read_b128 v[182:185], v164 offset:3072
	v_add_u32_e32 v172, 0xc000, v147
	v_lshl_add_u64 v[238:239], v[136:137], 0, s[44:45]
	v_readfirstlane_b32 s66, v172
	v_add_u32_e32 v173, 0xe000, v147
	v_lshl_add_u64 v[166:167], v[238:239], 0, s[18:19]
	s_mov_b32 m0, s66
	v_lshl_add_u64 v[240:241], v[134:135], 0, s[44:45]
	v_readfirstlane_b32 s66, v173
	ds_read_b128 v[186:189], v155
	ds_read_b128 v[190:193], v155 offset:1024
	ds_read_b128 v[194:197], v154
	ds_read_b128 v[198:201], v154 offset:1024
	ds_read_b128 v[202:205], v153
	ds_read_b128 v[206:209], v153 offset:1024
	ds_read_b128 v[210:213], v152
	ds_read_b128 v[214:217], v152 offset:1024
	global_load_lds_dwordx4 v[166:167], off
	v_lshl_add_u64 v[166:167], v[240:241], 0, s[18:19]
	s_mov_b32 m0, s66
	s_nop 0
	global_load_lds_dwordx4 v[166:167], off
	s_waitcnt lgkmcnt(8)
	s_barrier
	s_waitcnt lgkmcnt(0)
	v_mfma_f32_16x16x32_bf16 v[124:127], v[168:171], v[186:189], v[124:127]
	v_mfma_f32_16x16x32_bf16 v[120:123], v[178:181], v[186:189], v[120:123]
	v_mfma_f32_16x16x32_bf16 v[116:119], v[168:171], v[194:197], v[116:119]
	v_mfma_f32_16x16x32_bf16 v[112:115], v[178:181], v[194:197], v[112:115]
	v_mfma_f32_16x16x32_bf16 v[108:111], v[168:171], v[202:205], v[108:111]
	v_mfma_f32_16x16x32_bf16 v[104:107], v[178:181], v[202:205], v[104:107]
	v_mfma_f32_16x16x32_bf16 v[100:103], v[168:171], v[210:213], v[100:103]
	v_mfma_f32_16x16x32_bf16 v[96:99], v[178:181], v[210:213], v[96:99]
	v_mfma_f32_16x16x32_bf16 v[124:127], v[174:177], v[190:193], v[124:127]
	v_mfma_f32_16x16x32_bf16 v[120:123], v[182:185], v[190:193], v[120:123]
	v_mfma_f32_16x16x32_bf16 v[116:119], v[174:177], v[198:201], v[116:119]
	v_mfma_f32_16x16x32_bf16 v[112:115], v[182:185], v[198:201], v[112:115]
	v_mfma_f32_16x16x32_bf16 v[108:111], v[174:177], v[206:209], v[108:111]
	v_mfma_f32_16x16x32_bf16 v[104:107], v[182:185], v[206:209], v[104:107]
	v_mfma_f32_16x16x32_bf16 v[100:103], v[174:177], v[214:217], v[100:103]
	v_mfma_f32_16x16x32_bf16 v[96:99], v[182:185], v[214:217], v[96:99]
	s_barrier
	v_add_u32_e32 v165, s55, v156
	v_lshl_add_u64 v[242:243], v[144:145], 0, s[44:45]
	v_readfirstlane_b32 s66, v165
	v_lshl_add_u64 v[166:167], v[242:243], 0, s[20:21]
	s_mov_b32 m0, s66
	ds_read_b128 v[218:221], v163
	ds_read_b128 v[222:225], v163 offset:1024
	ds_read_b128 v[226:229], v163 offset:2048
	ds_read_b128 v[230:233], v163 offset:3072
	global_load_lds_dwordx4 v[166:167], off
	v_add_u32_e32 v166, 0x2000, v165
	v_lshl_add_u64 v[244:245], v[142:143], 0, s[44:45]
	v_readfirstlane_b32 s66, v166
	v_lshl_add_u64 v[234:235], v[244:245], 0, s[20:21]
	s_mov_b32 m0, s66
	s_nop 0
	global_load_lds_dwordx4 v[234:235], off
	s_barrier
	s_waitcnt lgkmcnt(0)
	v_mfma_f32_16x16x32_bf16 v[92:95], v[218:221], v[186:189], v[92:95]
	v_mfma_f32_16x16x32_bf16 v[88:91], v[226:229], v[186:189], v[88:91]
	v_mfma_f32_16x16x32_bf16 v[84:87], v[218:221], v[194:197], v[84:87]
	v_mfma_f32_16x16x32_bf16 v[80:83], v[226:229], v[194:197], v[80:83]
	v_mfma_f32_16x16x32_bf16 v[76:79], v[218:221], v[202:205], v[76:79]
	v_mfma_f32_16x16x32_bf16 v[72:75], v[226:229], v[202:205], v[72:75]
	v_mfma_f32_16x16x32_bf16 v[68:71], v[218:221], v[210:213], v[68:71]
	v_mfma_f32_16x16x32_bf16 v[64:67], v[226:229], v[210:213], v[64:67]
	v_mfma_f32_16x16x32_bf16 v[92:95], v[222:225], v[190:193], v[92:95]
	v_mfma_f32_16x16x32_bf16 v[88:91], v[230:233], v[190:193], v[88:91]
	v_mfma_f32_16x16x32_bf16 v[84:87], v[222:225], v[198:201], v[84:87]
	v_mfma_f32_16x16x32_bf16 v[80:83], v[230:233], v[198:201], v[80:83]
	v_mfma_f32_16x16x32_bf16 v[76:79], v[222:225], v[206:209], v[76:79]
	v_mfma_f32_16x16x32_bf16 v[72:75], v[230:233], v[206:209], v[72:75]
	v_mfma_f32_16x16x32_bf16 v[68:71], v[222:225], v[214:217], v[68:71]
	v_mfma_f32_16x16x32_bf16 v[64:67], v[230:233], v[214:217], v[64:67]
	s_barrier
	v_readfirstlane_b32 s66, v147
	v_add_u32_e32 v167, 0x2000, v147
	v_lshl_add_u64 v[234:235], v[238:239], 0, s[22:23]
	s_mov_b32 m0, s66
	v_readfirstlane_b32 s66, v167
	ds_read_b128 v[186:189], v155 offset:16384
	ds_read_b128 v[190:193], v155 offset:17408
	ds_read_b128 v[194:197], v154 offset:16384
	ds_read_b128 v[198:201], v154 offset:17408
	ds_read_b128 v[202:205], v153 offset:16384
	ds_read_b128 v[206:209], v153 offset:17408
	ds_read_b128 v[210:213], v152 offset:16384
	ds_read_b128 v[214:217], v152 offset:17408
	global_load_lds_dwordx4 v[234:235], off
	v_lshl_add_u64 v[234:235], v[240:241], 0, s[22:23]
	s_mov_b32 m0, s66
	s_nop 0
	global_load_lds_dwordx4 v[234:235], off
	s_barrier
	s_waitcnt lgkmcnt(0)
	v_mfma_f32_16x16x32_bf16 v[60:63], v[168:171], v[186:189], v[60:63]
	v_mfma_f32_16x16x32_bf16 v[56:59], v[178:181], v[186:189], v[56:59]
	v_mfma_f32_16x16x32_bf16 v[52:55], v[168:171], v[194:197], v[52:55]
	v_mfma_f32_16x16x32_bf16 v[48:51], v[178:181], v[194:197], v[48:51]
	v_mfma_f32_16x16x32_bf16 v[44:47], v[168:171], v[202:205], v[44:47]
	v_mfma_f32_16x16x32_bf16 v[40:43], v[178:181], v[202:205], v[40:43]
	v_mfma_f32_16x16x32_bf16 v[36:39], v[168:171], v[210:213], v[36:39]
	v_mfma_f32_16x16x32_bf16 v[32:35], v[178:181], v[210:213], v[32:35]
	v_mfma_f32_16x16x32_bf16 v[60:63], v[174:177], v[190:193], v[60:63]
	v_mfma_f32_16x16x32_bf16 v[56:59], v[182:185], v[190:193], v[56:59]
	v_mfma_f32_16x16x32_bf16 v[52:55], v[174:177], v[198:201], v[52:55]
	v_mfma_f32_16x16x32_bf16 v[48:51], v[182:185], v[198:201], v[48:51]
	v_mfma_f32_16x16x32_bf16 v[44:47], v[174:177], v[206:209], v[44:47]
	v_mfma_f32_16x16x32_bf16 v[40:43], v[182:185], v[206:209], v[40:43]
	v_mfma_f32_16x16x32_bf16 v[36:39], v[174:177], v[214:217], v[36:39]
	v_mfma_f32_16x16x32_bf16 v[32:35], v[182:185], v[214:217], v[32:35]
	s_barrier
; #define STAGE(P, BASE, LD, br, kt) do { const char* _g = (const char*)((BASE) + (size_t)(br) * (LD) + (size_t)(kt) * 64); \
;     for (int _i = 0; _i < 2; ++_i) { int _b = tidx * 16 + _i * 8192; int _r, _c; stage_rc(_b, _r, _c); \
;       __builtin_amdgcn_global_load_lds((const unsigned*)(_g + (unsigned)((_r * (LD) + _c) * 2)), (unsigned*)((char*)(P) + _b), 16, 0, 0); } } while (0)
; #define LDA(dst, b, h) for (int m = 0; m < 4; ++m) for (int k = 0; k < 2; ++k) \
;     dst[m][k] = *reinterpret_cast<const bf16x8*>((char*)SA(b, h) + lds_byte(wr * 64 + m * 16 + fr, k * 32 + fq * 8))
; #define LDB(dst, b, h) for (int n = 0; n < 2; ++n) for (int k = 0; k < 2; ++k) \
;     dst[n][k] = *reinterpret_cast<const bf16x8*>((char*)SB(b, h) + lds_byte(wc * 32 + n * 16 + fr, k * 32 + fq * 8))
; #define MMA(ai, bj, At_, Bt_) do { __builtin_amdgcn_s_setprio(1); \
;     for (int k = 0; k < 2; ++k) for (int m = 0; m < 4; ++m) for (int n = 0; n < 2; ++n) \
;       acc[ai][bj][m][n] = __builtin_amdgcn_mfma_f32_16x16x32_bf16(At_[m][k], Bt_[n][k], acc[ai][bj][m][n], 0, 0, 0); \
;     __builtin_amdgcn_s_setprio(0); } while (0)
; #define WAIT_V(n) asm volatile("s_waitcnt vmcnt(" #n ")" ::: "memory")
; #define WAIT_L(n) asm volatile("s_waitcnt lgkmcnt(" #n ")" ::: "memory")
; #define BAR __builtin_amdgcn_s_barrier()
; #define SCHED __builtin_amdgcn_sched_barrier(0)
; template <int EPI, int lda, int ldb, int N, int K>
; __device__ __forceinline__ void gemm_phase(const u16* __restrict__ A, const u16* __restrict__ Bt, const GemmEpi ep, int wv) {
;     ...
;       STAGE(SB(0, 1), Bt, ldb, bcol + HALF, t + 2);
;       WAIT_V(6); BAR; MMA(1, 1, At, B1); BAR;
;       LDB(B0, 1, 0); SCHED; LDA(At, 1, 0); STAGE(SA(0, 1), Ab, lda, brow + HALF, t + 2);
;       WAIT_L(8); BAR; WAIT_L(0); MMA(0, 0, At, B0); BAR; SCHED;
;       LDB(B1, 1, 1); STAGE(SB(1, 0), Bt, ldb, bcol, t + 3);
;       BAR; WAIT_L(0); MMA(0, 1, At, B1); BAR;
	v_add_u32_e32 v168, s56, v156
	v_lshl_add_u64 v[246:247], v[140:141], 0, s[44:45]
	v_readfirstlane_b32 s66, v168
	v_add_u32_e32 v169, 0x2000, v168
	v_lshl_add_u64 v[170:171], v[246:247], 0, s[24:25]
	s_mov_b32 m0, s66
	v_lshl_add_u64 v[248:249], v[138:139], 0, s[44:45]
	v_readfirstlane_b32 s66, v169
	global_load_lds_dwordx4 v[170:171], off
	v_lshl_add_u64 v[170:171], v[248:249], 0, s[24:25]
	s_mov_b32 m0, s66
	s_nop 0
	global_load_lds_dwordx4 v[170:171], off
	s_waitcnt vmcnt(6)
	s_barrier
	v_mfma_f32_16x16x32_bf16 v[28:31], v[218:221], v[186:189], v[28:31]
	v_mfma_f32_16x16x32_bf16 v[24:27], v[226:229], v[186:189], v[24:27]
	v_mfma_f32_16x16x32_bf16 v[20:23], v[218:221], v[194:197], v[20:23]
	v_mfma_f32_16x16x32_bf16 v[16:19], v[226:229], v[194:197], v[16:19]
	v_mfma_f32_16x16x32_bf16 v[12:15], v[218:221], v[202:205], v[12:15]
	v_mfma_f32_16x16x32_bf16 v[8:11], v[226:229], v[202:205], v[8:11]
	v_mfma_f32_16x16x32_bf16 v[4:7], v[218:221], v[210:213], v[4:7]
	v_mfma_f32_16x16x32_bf16 v[0:3], v[226:229], v[210:213], v[0:3]
	v_mfma_f32_16x16x32_bf16 v[28:31], v[222:225], v[190:193], v[28:31]
	v_mfma_f32_16x16x32_bf16 v[24:27], v[230:233], v[190:193], v[24:27]
	v_mfma_f32_16x16x32_bf16 v[20:23], v[222:225], v[198:201], v[20:23]
	v_mfma_f32_16x16x32_bf16 v[16:19], v[230:233], v[198:201], v[16:19]
	v_mfma_f32_16x16x32_bf16 v[12:15], v[222:225], v[206:209], v[12:15]
	v_mfma_f32_16x16x32_bf16 v[8:11], v[230:233], v[206:209], v[8:11]
	v_mfma_f32_16x16x32_bf16 v[4:7], v[222:225], v[214:217], v[4:7]
	v_mfma_f32_16x16x32_bf16 v[0:3], v[230:233], v[214:217], v[0:3]
	s_barrier
	ds_read_b128 v[174:177], v159
	ds_read_b128 v[178:181], v159 offset:1024
	ds_read_b128 v[182:185], v159 offset:2048
	ds_read_b128 v[186:189], v159 offset:3072
	v_add_u32_e32 v170, 0x4000, v147
	v_add_u32_e32 v171, 0x6000, v147
	v_readfirstlane_b32 s66, v170
	v_lshl_add_u64 v[222:223], v[238:239], 0, s[26:27]
	s_mov_b32 m0, s66
	v_readfirstlane_b32 s66, v171
	ds_read_b128 v[190:193], v155 offset:32768
	ds_read_b128 v[194:197], v155 offset:33792
	ds_read_b128 v[198:201], v154 offset:32768
	ds_read_b128 v[202:205], v154 offset:33792
	ds_read_b128 v[206:209], v153 offset:32768
	ds_read_b128 v[210:213], v153 offset:33792
	ds_read_b128 v[214:217], v152 offset:32768
	ds_read_b128 v[218:221], v152 offset:33792
	global_load_lds_dwordx4 v[222:223], off
	v_lshl_add_u64 v[222:223], v[240:241], 0, s[26:27]
	s_mov_b32 m0, s66
	s_nop 0
	global_load_lds_dwordx4 v[222:223], off
	s_waitcnt lgkmcnt(8)
	s_barrier
	s_waitcnt lgkmcnt(0)
	v_mfma_f32_16x16x32_bf16 v[124:127], v[174:177], v[190:193], v[124:127]
	v_mfma_f32_16x16x32_bf16 v[120:123], v[182:185], v[190:193], v[120:123]
	v_mfma_f32_16x16x32_bf16 v[116:119], v[174:177], v[198:201], v[116:119]
	v_mfma_f32_16x16x32_bf16 v[112:115], v[182:185], v[198:201], v[112:115]
	v_mfma_f32_16x16x32_bf16 v[108:111], v[174:177], v[206:209], v[108:111]
	v_mfma_f32_16x16x32_bf16 v[104:107], v[182:185], v[206:209], v[104:107]
	v_mfma_f32_16x16x32_bf16 v[100:103], v[174:177], v[214:217], v[100:103]
	v_mfma_f32_16x16x32_bf16 v[96:99], v[182:185], v[214:217], v[96:99]
	v_mfma_f32_16x16x32_bf16 v[124:127], v[178:181], v[194:197], v[124:127]
	v_mfma_f32_16x16x32_bf16 v[120:123], v[186:189], v[194:197], v[120:123]
	v_mfma_f32_16x16x32_bf16 v[116:119], v[178:181], v[202:205], v[116:119]
	v_mfma_f32_16x16x32_bf16 v[112:115], v[186:189], v[202:205], v[112:115]
	v_mfma_f32_16x16x32_bf16 v[108:111], v[178:181], v[210:213], v[108:111]
	v_mfma_f32_16x16x32_bf16 v[104:107], v[186:189], v[210:213], v[104:107]
	v_mfma_f32_16x16x32_bf16 v[100:103], v[178:181], v[218:221], v[100:103]
	v_mfma_f32_16x16x32_bf16 v[96:99], v[186:189], v[218:221], v[96:99]
	s_barrier
	v_readfirstlane_b32 s66, v158
	v_lshl_add_u64 v[242:243], v[242:243], 0, s[36:37]
	s_mov_b32 m0, s66
	ds_read_b128 v[222:225], v157
	ds_read_b128 v[226:229], v157 offset:1024
	ds_read_b128 v[230:233], v157 offset:2048
	ds_read_b128 v[234:237], v157 offset:3072
	global_load_lds_dwordx4 v[242:243], off
	v_lshl_add_u64 v[242:243], v[244:245], 0, s[36:37]
	v_add_u32_e32 v244, 0x2000, v158
	s_nop 0
	v_readfirstlane_b32 s66, v244
	s_mov_b32 m0, s66
	s_nop 0
	global_load_lds_dwordx4 v[242:243], off
	s_barrier
	s_waitcnt lgkmcnt(0)
	v_mfma_f32_16x16x32_bf16 v[92:95], v[222:225], v[190:193], v[92:95]
	v_mfma_f32_16x16x32_bf16 v[88:91], v[230:233], v[190:193], v[88:91]
	v_mfma_f32_16x16x32_bf16 v[84:87], v[222:225], v[198:201], v[84:87]
	v_mfma_f32_16x16x32_bf16 v[80:83], v[230:233], v[198:201], v[80:83]
	v_mfma_f32_16x16x32_bf16 v[76:79], v[222:225], v[206:209], v[76:79]
	v_mfma_f32_16x16x32_bf16 v[72:75], v[230:233], v[206:209], v[72:75]
	v_mfma_f32_16x16x32_bf16 v[68:71], v[222:225], v[214:217], v[68:71]
	v_mfma_f32_16x16x32_bf16 v[64:67], v[230:233], v[214:217], v[64:67]
	v_mfma_f32_16x16x32_bf16 v[92:95], v[226:229], v[194:197], v[92:95]
	v_mfma_f32_16x16x32_bf16 v[88:91], v[234:237], v[194:197], v[88:91]
	v_mfma_f32_16x16x32_bf16 v[84:87], v[226:229], v[202:205], v[84:87]
	v_mfma_f32_16x16x32_bf16 v[80:83], v[234:237], v[202:205], v[80:83]
	v_mfma_f32_16x16x32_bf16 v[76:79], v[226:229], v[210:213], v[76:79]
	v_mfma_f32_16x16x32_bf16 v[72:75], v[234:237], v[210:213], v[72:75]
	v_mfma_f32_16x16x32_bf16 v[68:71], v[226:229], v[218:221], v[68:71]
	v_mfma_f32_16x16x32_bf16 v[64:67], v[234:237], v[218:221], v[64:67]
	s_barrier
; #define STAGE(P, BASE, LD, br, kt) do { const char* _g = (const char*)((BASE) + (size_t)(br) * (LD) + (size_t)(kt) * 64); \
;     for (int _i = 0; _i < 2; ++_i) { int _b = tidx * 16 + _i * 8192; int _r, _c; stage_rc(_b, _r, _c); \
;       __builtin_amdgcn_global_load_lds((const unsigned*)(_g + (unsigned)((_r * (LD) + _c) * 2)), (unsigned*)((char*)(P) + _b), 16, 0, 0); } } while (0)
; #define LDA(dst, b, h) for (int m = 0; m < 4; ++m) for (int k = 0; k < 2; ++k) \
;     dst[m][k] = *reinterpret_cast<const bf16x8*>((char*)SA(b, h) + lds_byte(wr * 64 + m * 16 + fr, k * 32 + fq * 8))
; #define LDB(dst, b, h) for (int n = 0; n < 2; ++n) for (int k = 0; k < 2; ++k) \
;     dst[n][k] = *reinterpret_cast<const bf16x8*>((char*)SB(b, h) + lds_byte(wc * 32 + n * 16 + fr, k * 32 + fq * 8))
; #define MMA(ai, bj, At_, Bt_) do { __builtin_amdgcn_s_setprio(1); \
;     for (int k = 0; k < 2; ++k) for (int m = 0; m < 4; ++m) for (int n = 0; n < 2; ++n) \
;       acc[ai][bj][m][n] = __builtin_amdgcn_mfma_f32_16x16x32_bf16(At_[m][k], Bt_[n][k], acc[ai][bj][m][n], 0, 0, 0); \
;     __builtin_amdgcn_s_setprio(0); } while (0)
; #define WAIT_V(n) asm volatile("s_waitcnt vmcnt(" #n ")" ::: "memory")
; #define WAIT_L(n) asm volatile("s_waitcnt lgkmcnt(" #n ")" ::: "memory")
; #define BAR __builtin_amdgcn_s_barrier()
; #define SCHED __builtin_amdgcn_sched_barrier(0)
; template <int EPI, int lda, int ldb, int N, int K>
; __device__ __forceinline__ void gemm_phase(const u16* __restrict__ A, const u16* __restrict__ Bt, const GemmEpi ep, int wv) {
;     ...
;       LDA(At, 1, 1); STAGE(SA(1, 0), Ab, lda, brow, t + 3);
;       BAR; WAIT_L(0); MMA(1, 0, At, B0); BAR; SCHED;
;       STAGE(SB(1, 1), Bt, ldb, bcol + HALF, t + 3);
;       WAIT_V(6); BAR; MMA(1, 1, At, B1); BAR;
;     }
;     { LDB(B0, 0, 0); LDA(At, 0, 0); STAGE(SA(1, 1), Ab, lda, brow + HALF, nt - 1);
;       BAR; WAIT_L(0); MMA(0, 0, At, B0); BAR;
;       LDB(B1, 0, 1); BAR; WAIT_L(0); MMA(0, 1, At, B1); BAR;
	v_readfirstlane_b32 s66, v160
	v_lshl_add_u64 v[238:239], v[238:239], 0, s[38:39]
	s_mov_b32 m0, s66
	v_readfirstlane_b32 s66, v161
	ds_read_b128 v[190:193], v155 offset:49152
	ds_read_b128 v[194:197], v155 offset:50176
	ds_read_b128 v[198:201], v154 offset:49152
	ds_read_b128 v[202:205], v154 offset:50176
	ds_read_b128 v[206:209], v153 offset:49152
	ds_read_b128 v[210:213], v153 offset:50176
	ds_read_b128 v[214:217], v152 offset:49152
	ds_read_b128 v[218:221], v152 offset:50176
	global_load_lds_dwordx4 v[238:239], off
	v_lshl_add_u64 v[238:239], v[240:241], 0, s[38:39]
	s_mov_b32 m0, s66
	s_nop 0
	global_load_lds_dwordx4 v[238:239], off
	s_barrier
	s_waitcnt lgkmcnt(0)
	v_mfma_f32_16x16x32_bf16 v[60:63], v[174:177], v[190:193], v[60:63]
	v_mfma_f32_16x16x32_bf16 v[56:59], v[182:185], v[190:193], v[56:59]
	v_mfma_f32_16x16x32_bf16 v[52:55], v[174:177], v[198:201], v[52:55]
	v_mfma_f32_16x16x32_bf16 v[48:51], v[182:185], v[198:201], v[48:51]
	v_mfma_f32_16x16x32_bf16 v[44:47], v[174:177], v[206:209], v[44:47]
	v_mfma_f32_16x16x32_bf16 v[40:43], v[182:185], v[206:209], v[40:43]
	v_mfma_f32_16x16x32_bf16 v[36:39], v[174:177], v[214:217], v[36:39]
	v_mfma_f32_16x16x32_bf16 v[32:35], v[182:185], v[214:217], v[32:35]
	v_mfma_f32_16x16x32_bf16 v[60:63], v[178:181], v[194:197], v[60:63]
	v_mfma_f32_16x16x32_bf16 v[56:59], v[186:189], v[194:197], v[56:59]
	v_mfma_f32_16x16x32_bf16 v[52:55], v[178:181], v[202:205], v[52:55]
	v_mfma_f32_16x16x32_bf16 v[48:51], v[186:189], v[202:205], v[48:51]
	v_mfma_f32_16x16x32_bf16 v[44:47], v[178:181], v[210:213], v[44:47]
	v_mfma_f32_16x16x32_bf16 v[40:43], v[186:189], v[210:213], v[40:43]
	v_mfma_f32_16x16x32_bf16 v[36:39], v[178:181], v[218:221], v[36:39]
	v_mfma_f32_16x16x32_bf16 v[32:35], v[186:189], v[218:221], v[32:35]
	s_barrier
	v_readfirstlane_b32 s66, v162
	v_add_u32_e32 v176, 0x2000, v162
	v_lshl_add_u64 v[174:175], v[246:247], 0, s[42:43]
	s_mov_b32 m0, s66
	v_readfirstlane_b32 s66, v176
	global_load_lds_dwordx4 v[174:175], off
	v_lshl_add_u64 v[174:175], v[248:249], 0, s[42:43]
	s_mov_b32 m0, s66
	s_nop 0
	global_load_lds_dwordx4 v[174:175], off
	s_add_i32 s65, s65, 2
	s_add_u32 s44, s44, 0x100
	s_addc_u32 s45, s45, 0
	s_cmpk_gt_u32 s65, 0x51
	s_waitcnt vmcnt(6)
	s_barrier
	v_mfma_f32_16x16x32_bf16 v[28:31], v[222:225], v[190:193], v[28:31]
	v_mfma_f32_16x16x32_bf16 v[24:27], v[230:233], v[190:193], v[24:27]
	v_mfma_f32_16x16x32_bf16 v[20:23], v[222:225], v[198:201], v[20:23]
	v_mfma_f32_16x16x32_bf16 v[16:19], v[230:233], v[198:201], v[16:19]
	v_mfma_f32_16x16x32_bf16 v[12:15], v[222:225], v[206:209], v[12:15]
	v_mfma_f32_16x16x32_bf16 v[8:11], v[230:233], v[206:209], v[8:11]
	v_mfma_f32_16x16x32_bf16 v[4:7], v[222:225], v[214:217], v[4:7]
	v_mfma_f32_16x16x32_bf16 v[0:3], v[230:233], v[214:217], v[0:3]
	v_mfma_f32_16x16x32_bf16 v[28:31], v[226:229], v[194:197], v[28:31]
	v_mfma_f32_16x16x32_bf16 v[24:27], v[234:237], v[194:197], v[24:27]
	v_mfma_f32_16x16x32_bf16 v[20:23], v[226:229], v[202:205], v[20:23]
	v_mfma_f32_16x16x32_bf16 v[16:19], v[234:237], v[202:205], v[16:19]
	v_mfma_f32_16x16x32_bf16 v[12:15], v[226:229], v[210:213], v[12:15]
	v_mfma_f32_16x16x32_bf16 v[8:11], v[234:237], v[210:213], v[8:11]
	v_mfma_f32_16x16x32_bf16 v[4:7], v[226:229], v[218:221], v[4:7]
	v_mfma_f32_16x16x32_bf16 v[0:3], v[234:237], v[218:221], v[0:3]
	s_barrier
	s_cbranch_scc0 .LBB0_224
	s_add_i32 s44, s14, 0x80
	s_mul_hi_i32 s45, s44, 0x2b00
	s_mulk_i32 s44, 0x2b00
	s_add_u32 s44, s48, s44
	s_addc_u32 s45, s49, s45
	s_add_u32 s44, s44, 0x2a80
	s_addc_u32 s45, s45, 0
	v_readfirstlane_b32 s65, v172
	v_lshl_add_u64 v[160:161], s[44:45], 0, v[128:129]
	s_mov_b32 m0, s65
	ds_read_b128 v[134:137], v164
	ds_read_b128 v[138:141], v164 offset:1024
	ds_read_b128 v[142:145], v164 offset:2048
	ds_read_b128 v[174:177], v164 offset:3072
	ds_read_b128 v[178:181], v155
	ds_read_b128 v[182:185], v155 offset:1024
	ds_read_b128 v[186:189], v154
	ds_read_b128 v[190:193], v154 offset:1024
	ds_read_b128 v[194:197], v153
	ds_read_b128 v[198:201], v153 offset:1024
	ds_read_b128 v[202:205], v152
	ds_read_b128 v[206:209], v152 offset:1024
	global_load_lds_dwordx4 v[160:161], off
	v_lshl_add_u64 v[160:161], s[44:45], 0, v[132:133]
	v_readfirstlane_b32 s44, v173
	s_mov_b32 m0, s44
	s_nop 0
	global_load_lds_dwordx4 v[160:161], off
	s_barrier
	s_waitcnt lgkmcnt(0)
	v_mfma_f32_16x16x32_bf16 v[124:127], v[134:137], v[178:181], v[124:127]
	v_mfma_f32_16x16x32_bf16 v[120:123], v[142:145], v[178:181], v[120:123]
	v_mfma_f32_16x16x32_bf16 v[116:119], v[134:137], v[186:189], v[116:119]
	v_mfma_f32_16x16x32_bf16 v[112:115], v[142:145], v[186:189], v[112:115]
	v_mfma_f32_16x16x32_bf16 v[108:111], v[134:137], v[194:197], v[108:111]
	v_mfma_f32_16x16x32_bf16 v[104:107], v[142:145], v[194:197], v[104:107]
	v_mfma_f32_16x16x32_bf16 v[100:103], v[134:137], v[202:205], v[100:103]
	v_mfma_f32_16x16x32_bf16 v[96:99], v[142:145], v[202:205], v[96:99]
	v_mfma_f32_16x16x32_bf16 v[124:127], v[138:141], v[182:185], v[124:127]
	v_mfma_f32_16x16x32_bf16 v[120:123], v[174:177], v[182:185], v[120:123]
	v_mfma_f32_16x16x32_bf16 v[116:119], v[138:141], v[190:193], v[116:119]
	v_mfma_f32_16x16x32_bf16 v[112:115], v[174:177], v[190:193], v[112:115]
	v_mfma_f32_16x16x32_bf16 v[108:111], v[138:141], v[198:201], v[108:111]
	v_mfma_f32_16x16x32_bf16 v[104:107], v[174:177], v[198:201], v[104:107]
	v_mfma_f32_16x16x32_bf16 v[100:103], v[138:141], v[206:209], v[100:103]
	v_mfma_f32_16x16x32_bf16 v[96:99], v[174:177], v[206:209], v[96:99]
	s_barrier
	ds_read_b128 v[210:213], v163
	ds_read_b128 v[214:217], v163 offset:1024
	ds_read_b128 v[218:221], v163 offset:2048
	ds_read_b128 v[160:163], v163 offset:3072
	s_barrier
; #define LDA(dst, b, h) for (int m = 0; m < 4; ++m) for (int k = 0; k < 2; ++k) \
;     dst[m][k] = *reinterpret_cast<const bf16x8*>((char*)SA(b, h) + lds_byte(wr * 64 + m * 16 + fr, k * 32 + fq * 8))
; #define LDB(dst, b, h) for (int n = 0; n < 2; ++n) for (int k = 0; k < 2; ++k) \
;     dst[n][k] = *reinterpret_cast<const bf16x8*>((char*)SB(b, h) + lds_byte(wc * 32 + n * 16 + fr, k * 32 + fq * 8))
; #define MMA(ai, bj, At_, Bt_) do { __builtin_amdgcn_s_setprio(1); \
;     for (int k = 0; k < 2; ++k) for (int m = 0; m < 4; ++m) for (int n = 0; n < 2; ++n) \
;       acc[ai][bj][m][n] = __builtin_amdgcn_mfma_f32_16x16x32_bf16(At_[m][k], Bt_[n][k], acc[ai][bj][m][n], 0, 0, 0); \
;     __builtin_amdgcn_s_setprio(0); } while (0)
; #define WAIT_V(n) asm volatile("s_waitcnt vmcnt(" #n ")" ::: "memory")
; #define WAIT_L(n) asm volatile("s_waitcnt lgkmcnt(" #n ")" ::: "memory")
; #define BAR __builtin_amdgcn_s_barrier()
; template <int EPI, int lda, int ldb, int N, int K>
; __device__ __forceinline__ void gemm_phase(const u16* __restrict__ A, const u16* __restrict__ Bt, const GemmEpi ep, int wv) {
;     ...
;       LDB(B1, 0, 1); BAR; WAIT_L(0); MMA(0, 1, At, B1); BAR;
;       LDA(At, 0, 1); WAIT_V(4); BAR; WAIT_L(0); MMA(1, 0, At, B0); MMA(1, 1, At, B1); BAR; }
;     { LDB(B0, 1, 0); LDA(At, 1, 0); WAIT_V(2); BAR; WAIT_L(0); MMA(0, 0, At, B0); BAR;
	s_waitcnt lgkmcnt(0)
	v_mfma_f32_16x16x32_bf16 v[92:95], v[210:213], v[178:181], v[92:95]
	v_mfma_f32_16x16x32_bf16 v[88:91], v[218:221], v[178:181], v[88:91]
	v_mfma_f32_16x16x32_bf16 v[76:79], v[210:213], v[194:197], v[76:79]
	v_mfma_f32_16x16x32_bf16 v[72:75], v[218:221], v[194:197], v[72:75]
	v_mfma_f32_16x16x32_bf16 v[84:87], v[210:213], v[186:189], v[84:87]
	v_mfma_f32_16x16x32_bf16 v[80:83], v[218:221], v[186:189], v[80:83]
	v_mfma_f32_16x16x32_bf16 v[68:71], v[210:213], v[202:205], v[68:71]
	v_mfma_f32_16x16x32_bf16 v[64:67], v[218:221], v[202:205], v[64:67]
	v_mfma_f32_16x16x32_bf16 v[92:95], v[214:217], v[182:185], v[92:95]
	v_mfma_f32_16x16x32_bf16 v[88:91], v[160:163], v[182:185], v[88:91]
	v_mfma_f32_16x16x32_bf16 v[76:79], v[214:217], v[198:201], v[76:79]
	v_mfma_f32_16x16x32_bf16 v[72:75], v[160:163], v[198:201], v[72:75]
	v_mfma_f32_16x16x32_bf16 v[178:181], v[214:217], v[190:193], v[84:87]
	v_mfma_f32_16x16x32_bf16 v[182:185], v[160:163], v[190:193], v[80:83]
	v_mfma_f32_16x16x32_bf16 v[186:189], v[214:217], v[206:209], v[68:71]
	v_mfma_f32_16x16x32_bf16 v[190:193], v[160:163], v[206:209], v[64:67]
	s_barrier
	s_nop 0
	ds_read_b128 v[64:67], v155 offset:16384
	ds_read_b128 v[68:71], v155 offset:17408
	ds_read_b128 v[80:83], v154 offset:16384
	ds_read_b128 v[84:87], v154 offset:17408
	ds_read_b128 v[194:197], v153 offset:16384
	ds_read_b128 v[198:201], v153 offset:17408
	ds_read_b128 v[202:205], v152 offset:16384
	ds_read_b128 v[206:209], v152 offset:17408
	s_waitcnt vmcnt(4)
	s_barrier
	s_waitcnt lgkmcnt(0)
	v_mfma_f32_16x16x32_bf16 v[60:63], v[134:137], v[64:67], v[60:63]
	v_mfma_f32_16x16x32_bf16 v[56:59], v[142:145], v[64:67], v[56:59]
	v_mfma_f32_16x16x32_bf16 v[52:55], v[134:137], v[80:83], v[52:55]
	v_mfma_f32_16x16x32_bf16 v[48:51], v[142:145], v[80:83], v[48:51]
	v_mfma_f32_16x16x32_bf16 v[44:47], v[134:137], v[194:197], v[44:47]
	v_mfma_f32_16x16x32_bf16 v[40:43], v[142:145], v[194:197], v[40:43]
	v_mfma_f32_16x16x32_bf16 v[36:39], v[134:137], v[202:205], v[36:39]
	v_mfma_f32_16x16x32_bf16 v[32:35], v[142:145], v[202:205], v[32:35]
	v_mfma_f32_16x16x32_bf16 v[60:63], v[138:141], v[68:71], v[60:63]
	v_mfma_f32_16x16x32_bf16 v[56:59], v[174:177], v[68:71], v[56:59]
	v_mfma_f32_16x16x32_bf16 v[52:55], v[138:141], v[84:87], v[52:55]
	v_mfma_f32_16x16x32_bf16 v[48:51], v[174:177], v[84:87], v[48:51]
	v_mfma_f32_16x16x32_bf16 v[44:47], v[138:141], v[198:201], v[44:47]
	v_mfma_f32_16x16x32_bf16 v[40:43], v[174:177], v[198:201], v[40:43]
	v_mfma_f32_16x16x32_bf16 v[36:39], v[138:141], v[206:209], v[36:39]
	v_mfma_f32_16x16x32_bf16 v[32:35], v[174:177], v[206:209], v[32:35]
	v_mfma_f32_16x16x32_bf16 v[28:31], v[210:213], v[64:67], v[28:31]
	v_mfma_f32_16x16x32_bf16 v[16:19], v[218:221], v[80:83], v[16:19]
	v_mfma_f32_16x16x32_bf16 v[12:15], v[210:213], v[194:197], v[12:15]
	v_mfma_f32_16x16x32_bf16 v[0:3], v[218:221], v[202:205], v[0:3]
	v_mfma_f32_16x16x32_bf16 v[24:27], v[218:221], v[64:67], v[24:27]
	v_mfma_f32_16x16x32_bf16 v[20:23], v[210:213], v[80:83], v[20:23]
	v_mfma_f32_16x16x32_bf16 v[8:11], v[218:221], v[194:197], v[8:11]
	v_mfma_f32_16x16x32_bf16 v[4:7], v[210:213], v[202:205], v[4:7]
	v_mfma_f32_16x16x32_bf16 v[28:31], v[214:217], v[68:71], v[28:31]
	v_mfma_f32_16x16x32_bf16 v[16:19], v[160:163], v[84:87], v[16:19]
	v_mfma_f32_16x16x32_bf16 v[12:15], v[214:217], v[198:201], v[12:15]
	v_mfma_f32_16x16x32_bf16 v[0:3], v[160:163], v[206:209], v[0:3]
	v_mfma_f32_16x16x32_bf16 v[134:137], v[160:163], v[68:71], v[24:27]
	v_mfma_f32_16x16x32_bf16 v[138:141], v[214:217], v[84:87], v[20:23]
	v_mfma_f32_16x16x32_bf16 v[142:145], v[160:163], v[198:201], v[8:11]
	v_mfma_f32_16x16x32_bf16 v[172:175], v[214:217], v[206:209], v[4:7]
	s_barrier
	s_nop 0
	ds_read_b128 v[4:7], v159
	ds_read_b128 v[8:11], v159 offset:1024
	ds_read_b128 v[20:23], v159 offset:2048
	ds_read_b128 v[158:161], v159 offset:3072
	ds_read_b128 v[24:27], v155 offset:32768
	ds_read_b128 v[194:197], v155 offset:33792
	ds_read_b128 v[198:201], v154 offset:32768
	ds_read_b128 v[202:205], v154 offset:33792
	ds_read_b128 v[206:209], v153 offset:32768
	ds_read_b128 v[210:213], v153 offset:33792
	ds_read_b128 v[214:217], v152 offset:32768
	ds_read_b128 v[218:221], v152 offset:33792
	s_waitcnt vmcnt(2)
	s_barrier
; #define LDA(dst, b, h) for (int m = 0; m < 4; ++m) for (int k = 0; k < 2; ++k) \
;     dst[m][k] = *reinterpret_cast<const bf16x8*>((char*)SA(b, h) + lds_byte(wr * 64 + m * 16 + fr, k * 32 + fq * 8))
; #define LDB(dst, b, h) for (int n = 0; n < 2; ++n) for (int k = 0; k < 2; ++k) \
;     dst[n][k] = *reinterpret_cast<const bf16x8*>((char*)SB(b, h) + lds_byte(wc * 32 + n * 16 + fr, k * 32 + fq * 8))
; #define MMA(ai, bj, At_, Bt_) do { __builtin_amdgcn_s_setprio(1); \
;     for (int k = 0; k < 2; ++k) for (int m = 0; m < 4; ++m) for (int n = 0; n < 2; ++n) \
;       acc[ai][bj][m][n] = __builtin_amdgcn_mfma_f32_16x16x32_bf16(At_[m][k], Bt_[n][k], acc[ai][bj][m][n], 0, 0, 0); \
;     __builtin_amdgcn_s_setprio(0); } while (0)
; #define WAIT_V(n) asm volatile("s_waitcnt vmcnt(" #n ")" ::: "memory")
; #define WAIT_L(n) asm volatile("s_waitcnt lgkmcnt(" #n ")" ::: "memory")
; #define BAR __builtin_amdgcn_s_barrier()
; template <int EPI, int lda, int ldb, int N, int K>
; __device__ __forceinline__ void gemm_phase(const u16* __restrict__ A, const u16* __restrict__ Bt, const GemmEpi ep, int wv) {
;     ...
;     { LDB(B0, 1, 0); LDA(At, 1, 0); WAIT_V(2); BAR; WAIT_L(0); MMA(0, 0, At, B0); BAR;
;       LDB(B1, 1, 1); WAIT_V(0); BAR; WAIT_L(0); MMA(0, 1, At, B1); BAR;
;       LDA(At, 1, 1); BAR; WAIT_L(0); MMA(1, 0, At, B0); MMA(1, 1, At, B1); BAR; }
;     if (wr == 0) BAR;
	s_waitcnt lgkmcnt(0)
	v_mfma_f32_16x16x32_bf16 v[64:67], v[4:7], v[24:27], v[124:127]
	v_mfma_f32_16x16x32_bf16 v[68:71], v[20:23], v[24:27], v[120:123]
	v_mfma_f32_16x16x32_bf16 v[80:83], v[4:7], v[198:201], v[116:119]
	v_mfma_f32_16x16x32_bf16 v[84:87], v[20:23], v[198:201], v[112:115]
	v_mfma_f32_16x16x32_bf16 v[108:111], v[4:7], v[206:209], v[108:111]
	v_mfma_f32_16x16x32_bf16 v[104:107], v[20:23], v[206:209], v[104:107]
	v_mfma_f32_16x16x32_bf16 v[120:123], v[4:7], v[214:217], v[100:103]
	v_mfma_f32_16x16x32_bf16 v[124:127], v[20:23], v[214:217], v[96:99]
	v_mfma_f32_16x16x32_bf16 v[116:119], v[8:11], v[194:197], v[64:67]
	v_mfma_f32_16x16x32_bf16 v[112:115], v[158:161], v[194:197], v[68:71]
	v_mfma_f32_16x16x32_bf16 v[100:103], v[8:11], v[202:205], v[80:83]
	v_mfma_f32_16x16x32_bf16 v[96:99], v[158:161], v[202:205], v[84:87]
	v_mfma_f32_16x16x32_bf16 v[84:87], v[8:11], v[210:213], v[108:111]
	v_mfma_f32_16x16x32_bf16 v[80:83], v[158:161], v[210:213], v[104:107]
	v_mfma_f32_16x16x32_bf16 v[68:71], v[8:11], v[218:221], v[120:123]
	v_mfma_f32_16x16x32_bf16 v[64:67], v[158:161], v[218:221], v[124:127]
	s_barrier
	ds_read_b128 v[222:225], v157
	ds_read_b128 v[226:229], v157 offset:1024
	ds_read_b128 v[230:233], v157 offset:2048
	ds_read_b128 v[234:237], v157 offset:3072
	s_waitcnt vmcnt(0)
	s_barrier
	s_waitcnt lgkmcnt(0)
	v_mfma_f32_16x16x32_bf16 v[92:95], v[222:225], v[24:27], v[92:95]
	v_mfma_f32_16x16x32_bf16 v[24:27], v[230:233], v[24:27], v[88:91]
	v_mfma_f32_16x16x32_bf16 v[88:91], v[222:225], v[198:201], v[178:181]
	v_mfma_f32_16x16x32_bf16 v[104:107], v[230:233], v[198:201], v[182:185]
	v_mfma_f32_16x16x32_bf16 v[76:79], v[222:225], v[206:209], v[76:79]
	v_mfma_f32_16x16x32_bf16 v[72:75], v[230:233], v[206:209], v[72:75]
	v_mfma_f32_16x16x32_bf16 v[176:179], v[222:225], v[214:217], v[186:189]
	v_mfma_f32_16x16x32_bf16 v[180:183], v[230:233], v[214:217], v[190:193]
	v_mfma_f32_16x16x32_bf16 v[124:127], v[226:229], v[194:197], v[92:95]
	v_mfma_f32_16x16x32_bf16 v[120:123], v[234:237], v[194:197], v[24:27]
	v_mfma_f32_16x16x32_bf16 v[108:111], v[226:229], v[202:205], v[88:91]
	v_mfma_f32_16x16x32_bf16 v[104:107], v[234:237], v[202:205], v[104:107]
	v_mfma_f32_16x16x32_bf16 v[92:95], v[226:229], v[210:213], v[76:79]
	v_mfma_f32_16x16x32_bf16 v[88:91], v[234:237], v[210:213], v[72:75]
	v_mfma_f32_16x16x32_bf16 v[76:79], v[226:229], v[218:221], v[176:179]
	v_mfma_f32_16x16x32_bf16 v[72:75], v[234:237], v[218:221], v[180:183]
	s_barrier
	ds_read_b128 v[176:179], v155 offset:49152
	ds_read_b128 v[180:183], v155 offset:50176
	ds_read_b128 v[184:187], v154 offset:49152
	ds_read_b128 v[154:157], v154 offset:50176
	ds_read_b128 v[188:191], v153 offset:49152
	ds_read_b128 v[192:195], v153 offset:50176
	ds_read_b128 v[196:199], v152 offset:49152
	ds_read_b128 v[200:203], v152 offset:50176
	s_barrier
	s_waitcnt lgkmcnt(0)
	v_mfma_f32_16x16x32_bf16 v[24:27], v[4:7], v[176:179], v[60:63]
	v_mfma_f32_16x16x32_bf16 v[60:63], v[20:23], v[176:179], v[56:59]
	v_mfma_f32_16x16x32_bf16 v[204:207], v[4:7], v[184:187], v[52:55]
	v_mfma_f32_16x16x32_bf16 v[48:51], v[20:23], v[184:187], v[48:51]
	v_mfma_f32_16x16x32_bf16 v[44:47], v[4:7], v[188:191], v[44:47]
	v_mfma_f32_16x16x32_bf16 v[208:211], v[20:23], v[188:191], v[40:43]
	v_mfma_f32_16x16x32_bf16 v[4:7], v[4:7], v[196:199], v[36:39]
	v_mfma_f32_16x16x32_bf16 v[32:35], v[20:23], v[196:199], v[32:35]
	v_mfma_f32_16x16x32_bf16 v[56:59], v[8:11], v[180:183], v[24:27]
	v_mfma_f32_16x16x32_bf16 v[52:55], v[158:161], v[180:183], v[60:63]
	v_mfma_f32_16x16x32_bf16 v[40:43], v[8:11], v[154:157], v[204:207]
	v_mfma_f32_16x16x32_bf16 v[36:39], v[158:161], v[154:157], v[48:51]
	v_mfma_f32_16x16x32_bf16 v[24:27], v[8:11], v[192:195], v[44:47]
	v_mfma_f32_16x16x32_bf16 v[20:23], v[158:161], v[192:195], v[208:211]
	v_mfma_f32_16x16x32_bf16 v[8:11], v[8:11], v[200:203], v[4:7]
	v_mfma_f32_16x16x32_bf16 v[4:7], v[158:161], v[200:203], v[32:35]
	v_mfma_f32_16x16x32_bf16 v[28:31], v[222:225], v[176:179], v[28:31]
	v_mfma_f32_16x16x32_bf16 v[32:35], v[230:233], v[176:179], v[134:137]
	v_mfma_f32_16x16x32_bf16 v[44:47], v[222:225], v[184:187], v[138:141]
	v_mfma_f32_16x16x32_bf16 v[16:19], v[230:233], v[184:187], v[16:19]
	v_mfma_f32_16x16x32_bf16 v[12:15], v[222:225], v[188:191], v[12:15]
	v_mfma_f32_16x16x32_bf16 v[134:137], v[230:233], v[188:191], v[142:145]
	v_mfma_f32_16x16x32_bf16 v[138:141], v[222:225], v[196:199], v[172:175]
	v_mfma_f32_16x16x32_bf16 v[0:3], v[230:233], v[196:199], v[0:3]
	v_mfma_f32_16x16x32_bf16 v[60:63], v[226:229], v[180:183], v[28:31]
	v_mfma_f32_16x16x32_bf16 v[48:51], v[234:237], v[180:183], v[32:35]
	v_mfma_f32_16x16x32_bf16 v[44:47], v[226:229], v[154:157], v[44:47]
	v_mfma_f32_16x16x32_bf16 v[32:35], v[234:237], v[154:157], v[16:19]
	v_mfma_f32_16x16x32_bf16 v[28:31], v[226:229], v[192:195], v[12:15]
	v_mfma_f32_16x16x32_bf16 v[16:19], v[234:237], v[192:195], v[134:137]
	v_mfma_f32_16x16x32_bf16 v[12:15], v[226:229], v[200:203], v[138:141]
	v_mfma_f32_16x16x32_bf16 v[0:3], v[234:237], v[200:203], v[0:3]
	v_cmp_gt_u32_e32 vcc, s62, v130
	s_barrier
	s_and_saveexec_b64 s[44:45], vcc
	s_cbranch_execz .LBB0_227
	s_barrier

; #define STAGE(P, BASE, LD, br, kt) do { const char* _g = (const char*)((BASE) + (size_t)(br) * (LD) + (size_t)(kt) * 64); \
;     for (int _i = 0; _i < 2; ++_i) { int _b = tidx * 16 + _i * 8192; int _r, _c; stage_rc(_b, _r, _c); \
;       __builtin_amdgcn_global_load_lds((const unsigned*)(_g + (unsigned)((_r * (LD) + _c) * 2)), (unsigned*)((char*)(P) + _b), 16, 0, 0); } } while (0)
; #define LDA(dst, b, h) for (int m = 0; m < 4; ++m) for (int k = 0; k < 2; ++k) \
;     dst[m][k] = *reinterpret_cast<const bf16x8*>((char*)SA(b, h) + lds_byte(wr * 64 + m * 16 + fr, k * 32 + fq * 8))
; #define LDB(dst, b, h) for (int n = 0; n < 2; ++n) for (int k = 0; k < 2; ++k) \
;     dst[n][k] = *reinterpret_cast<const bf16x8*>((char*)SB(b, h) + lds_byte(wc * 32 + n * 16 + fr, k * 32 + fq * 8))
; #define MMA(ai, bj, At_, Bt_) do { __builtin_amdgcn_s_setprio(1); \
;     for (int k = 0; k < 2; ++k) for (int m = 0; m < 4; ++m) for (int n = 0; n < 2; ++n) \
;       acc[ai][bj][m][n] = __builtin_amdgcn_mfma_f32_16x16x32_bf16(At_[m][k], Bt_[n][k], acc[ai][bj][m][n], 0, 0, 0); \
;     __builtin_amdgcn_s_setprio(0); } while (0)
; #define WAIT_L(n) asm volatile("s_waitcnt lgkmcnt(" #n ")" ::: "memory")
; #define BAR __builtin_amdgcn_s_barrier()
; #define SCHED __builtin_amdgcn_sched_barrier(0)
; template <int EPI, int lda, int ldb, int N, int K>
; __device__ __forceinline__ void gemm_phase(const u16* __restrict__ A, const u16* __restrict__ Bt, const GemmEpi ep, int wv) {
;     ...
;     for (int t = 0; t < nt - 2; t += 2) {
;       LDB(B0, 0, 0); SCHED; LDA(At, 0, 0); STAGE(SA(1, 1), Ab, lda, brow + HALF, t + 1);
;       WAIT_L(8); BAR; WAIT_L(0); MMA(0, 0, At, B0); BAR; SCHED;
;       LDB(B1, 0, 1); STAGE(SB(0, 0), Bt, ldb, bcol, t + 2);
;       BAR; WAIT_L(0); MMA(0, 1, At, B1); BAR;
;       LDA(At, 0, 1); STAGE(SA(0, 0), Ab, lda, brow, t + 2);
;       BAR; WAIT_L(0); MMA(1, 0, At, B0); BAR; SCHED;
;       STAGE(SB(0, 1), Bt, ldb, bcol + HALF, t + 2);
.LBB0_340:
	ds_read_b128 v[166:169], v162
	ds_read_b128 v[172:175], v162 offset:1024
	ds_read_b128 v[176:179], v162 offset:2048
	ds_read_b128 v[180:183], v162 offset:3072
	v_add_u32_e32 v170, 0xc000, v149
	v_lshl_add_u64 v[236:237], v[138:139], 0, s[48:49]
	v_readfirstlane_b32 s51, v170
	v_add_u32_e32 v171, 0xe000, v149
	v_lshl_add_u64 v[164:165], v[236:237], 0, s[18:19]
	s_mov_b32 m0, s51
	v_lshl_add_u64 v[238:239], v[140:141], 0, s[48:49]
	v_readfirstlane_b32 s51, v171
	ds_read_b128 v[184:187], v153
	ds_read_b128 v[188:191], v153 offset:1024
	ds_read_b128 v[192:195], v152
	ds_read_b128 v[196:199], v152 offset:1024
	ds_read_b128 v[200:203], v151
	ds_read_b128 v[204:207], v151 offset:1024
	ds_read_b128 v[208:211], v150
	ds_read_b128 v[212:215], v150 offset:1024
	global_load_lds_dwordx4 v[164:165], off
	v_lshl_add_u64 v[164:165], v[238:239], 0, s[18:19]
	s_mov_b32 m0, s51
	s_nop 0
	global_load_lds_dwordx4 v[164:165], off
	s_waitcnt lgkmcnt(8)
	s_barrier
	s_waitcnt lgkmcnt(0)
	v_mfma_f32_16x16x32_bf16 v[124:127], v[184:187], v[166:169], v[124:127]
	v_mfma_f32_16x16x32_bf16 v[120:123], v[184:187], v[176:179], v[120:123]
	v_mfma_f32_16x16x32_bf16 v[116:119], v[192:195], v[166:169], v[116:119]
	v_mfma_f32_16x16x32_bf16 v[112:115], v[192:195], v[176:179], v[112:115]
	v_mfma_f32_16x16x32_bf16 v[108:111], v[200:203], v[166:169], v[108:111]
	v_mfma_f32_16x16x32_bf16 v[104:107], v[200:203], v[176:179], v[104:107]
	v_mfma_f32_16x16x32_bf16 v[100:103], v[208:211], v[166:169], v[100:103]
	v_mfma_f32_16x16x32_bf16 v[96:99], v[208:211], v[176:179], v[96:99]
	v_mfma_f32_16x16x32_bf16 v[124:127], v[188:191], v[172:175], v[124:127]
	v_mfma_f32_16x16x32_bf16 v[120:123], v[188:191], v[180:183], v[120:123]
	v_mfma_f32_16x16x32_bf16 v[116:119], v[196:199], v[172:175], v[116:119]
	v_mfma_f32_16x16x32_bf16 v[112:115], v[196:199], v[180:183], v[112:115]
	v_mfma_f32_16x16x32_bf16 v[108:111], v[204:207], v[172:175], v[108:111]
	v_mfma_f32_16x16x32_bf16 v[104:107], v[204:207], v[180:183], v[104:107]
	v_mfma_f32_16x16x32_bf16 v[100:103], v[212:215], v[172:175], v[100:103]
	v_mfma_f32_16x16x32_bf16 v[96:99], v[212:215], v[180:183], v[96:99]
	s_barrier
	v_add_u32_e32 v163, s62, v155
	v_lshl_add_u64 v[240:241], v[134:135], 0, s[48:49]
	v_readfirstlane_b32 s51, v163
	v_lshl_add_u64 v[164:165], v[240:241], 0, s[20:21]
	s_mov_b32 m0, s51
	ds_read_b128 v[216:219], v161
	ds_read_b128 v[220:223], v161 offset:1024
	ds_read_b128 v[224:227], v161 offset:2048
	ds_read_b128 v[228:231], v161 offset:3072
	global_load_lds_dwordx4 v[164:165], off
	v_add_u32_e32 v164, 0x2000, v163
	v_lshl_add_u64 v[242:243], v[136:137], 0, s[48:49]
	v_readfirstlane_b32 s51, v164
	v_lshl_add_u64 v[232:233], v[242:243], 0, s[20:21]
	s_mov_b32 m0, s51
	s_nop 0
	global_load_lds_dwordx4 v[232:233], off
	s_barrier
	s_waitcnt lgkmcnt(0)
	v_mfma_f32_16x16x32_bf16 v[92:95], v[184:187], v[216:219], v[92:95]
	v_mfma_f32_16x16x32_bf16 v[88:91], v[184:187], v[224:227], v[88:91]
	v_mfma_f32_16x16x32_bf16 v[84:87], v[192:195], v[216:219], v[84:87]
	v_mfma_f32_16x16x32_bf16 v[80:83], v[192:195], v[224:227], v[80:83]
	v_mfma_f32_16x16x32_bf16 v[76:79], v[200:203], v[216:219], v[76:79]
	v_mfma_f32_16x16x32_bf16 v[72:75], v[200:203], v[224:227], v[72:75]
	v_mfma_f32_16x16x32_bf16 v[68:71], v[208:211], v[216:219], v[68:71]
	v_mfma_f32_16x16x32_bf16 v[64:67], v[208:211], v[224:227], v[64:67]
	v_mfma_f32_16x16x32_bf16 v[92:95], v[188:191], v[220:223], v[92:95]
	v_mfma_f32_16x16x32_bf16 v[88:91], v[188:191], v[228:231], v[88:91]
	v_mfma_f32_16x16x32_bf16 v[84:87], v[196:199], v[220:223], v[84:87]
	v_mfma_f32_16x16x32_bf16 v[80:83], v[196:199], v[228:231], v[80:83]
	v_mfma_f32_16x16x32_bf16 v[76:79], v[204:207], v[220:223], v[76:79]
	v_mfma_f32_16x16x32_bf16 v[72:75], v[204:207], v[228:231], v[72:75]
	v_mfma_f32_16x16x32_bf16 v[68:71], v[212:215], v[220:223], v[68:71]
	v_mfma_f32_16x16x32_bf16 v[64:67], v[212:215], v[228:231], v[64:67]
	s_barrier
	v_readfirstlane_b32 s51, v149
	v_add_u32_e32 v165, 0x2000, v149
	v_lshl_add_u64 v[232:233], v[236:237], 0, s[22:23]
	s_mov_b32 m0, s51
	v_readfirstlane_b32 s51, v165
	ds_read_b128 v[184:187], v153 offset:16384
	ds_read_b128 v[188:191], v153 offset:17408
	ds_read_b128 v[192:195], v152 offset:16384
	ds_read_b128 v[196:199], v152 offset:17408
	ds_read_b128 v[200:203], v151 offset:16384
	ds_read_b128 v[204:207], v151 offset:17408
	ds_read_b128 v[208:211], v150 offset:16384
	ds_read_b128 v[212:215], v150 offset:17408
	global_load_lds_dwordx4 v[232:233], off
	v_lshl_add_u64 v[232:233], v[238:239], 0, s[22:23]
	s_mov_b32 m0, s51
	s_nop 0
	global_load_lds_dwordx4 v[232:233], off
	s_barrier
	s_waitcnt lgkmcnt(0)
	v_mfma_f32_16x16x32_bf16 v[60:63], v[184:187], v[166:169], v[60:63]
	v_mfma_f32_16x16x32_bf16 v[56:59], v[184:187], v[176:179], v[56:59]
	v_mfma_f32_16x16x32_bf16 v[52:55], v[192:195], v[166:169], v[52:55]
	v_mfma_f32_16x16x32_bf16 v[48:51], v[192:195], v[176:179], v[48:51]
	v_mfma_f32_16x16x32_bf16 v[44:47], v[200:203], v[166:169], v[44:47]
	v_mfma_f32_16x16x32_bf16 v[40:43], v[200:203], v[176:179], v[40:43]
	v_mfma_f32_16x16x32_bf16 v[36:39], v[208:211], v[166:169], v[36:39]
	v_mfma_f32_16x16x32_bf16 v[32:35], v[208:211], v[176:179], v[32:35]
	v_mfma_f32_16x16x32_bf16 v[60:63], v[188:191], v[172:175], v[60:63]
	v_mfma_f32_16x16x32_bf16 v[56:59], v[188:191], v[180:183], v[56:59]
	v_mfma_f32_16x16x32_bf16 v[52:55], v[196:199], v[172:175], v[52:55]
	v_mfma_f32_16x16x32_bf16 v[48:51], v[196:199], v[180:183], v[48:51]
	v_mfma_f32_16x16x32_bf16 v[44:47], v[204:207], v[172:175], v[44:47]
	v_mfma_f32_16x16x32_bf16 v[40:43], v[204:207], v[180:183], v[40:43]
	v_mfma_f32_16x16x32_bf16 v[36:39], v[212:215], v[172:175], v[36:39]
	v_mfma_f32_16x16x32_bf16 v[32:35], v[212:215], v[180:183], v[32:35]
	s_barrier
; #define STAGE(P, BASE, LD, br, kt) do { const char* _g = (const char*)((BASE) + (size_t)(br) * (LD) + (size_t)(kt) * 64); \
;     for (int _i = 0; _i < 2; ++_i) { int _b = tidx * 16 + _i * 8192; int _r, _c; stage_rc(_b, _r, _c); \
;       __builtin_amdgcn_global_load_lds((const unsigned*)(_g + (unsigned)((_r * (LD) + _c) * 2)), (unsigned*)((char*)(P) + _b), 16, 0, 0); } } while (0)
; #define LDA(dst, b, h) for (int m = 0; m < 4; ++m) for (int k = 0; k < 2; ++k) \
;     dst[m][k] = *reinterpret_cast<const bf16x8*>((char*)SA(b, h) + lds_byte(wr * 64 + m * 16 + fr, k * 32 + fq * 8))
; #define LDB(dst, b, h) for (int n = 0; n < 2; ++n) for (int k = 0; k < 2; ++k) \
;     dst[n][k] = *reinterpret_cast<const bf16x8*>((char*)SB(b, h) + lds_byte(wc * 32 + n * 16 + fr, k * 32 + fq * 8))
; #define MMA(ai, bj, At_, Bt_) do { __builtin_amdgcn_s_setprio(1); \
;     for (int k = 0; k < 2; ++k) for (int m = 0; m < 4; ++m) for (int n = 0; n < 2; ++n) \
;       acc[ai][bj][m][n] = __builtin_amdgcn_mfma_f32_16x16x32_bf16(At_[m][k], Bt_[n][k], acc[ai][bj][m][n], 0, 0, 0); \
;     __builtin_amdgcn_s_setprio(0); } while (0)
; #define WAIT_V(n) asm volatile("s_waitcnt vmcnt(" #n ")" ::: "memory")
; #define WAIT_L(n) asm volatile("s_waitcnt lgkmcnt(" #n ")" ::: "memory")
; #define BAR __builtin_amdgcn_s_barrier()
; #define SCHED __builtin_amdgcn_sched_barrier(0)
; template <int EPI, int lda, int ldb, int N, int K>
; __device__ __forceinline__ void gemm_phase(const u16* __restrict__ A, const u16* __restrict__ Bt, const GemmEpi ep, int wv) {
;     ...
;       STAGE(SB(0, 1), Bt, ldb, bcol + HALF, t + 2);
;       WAIT_V(6); BAR; MMA(1, 1, At, B1); BAR;
;       LDB(B0, 1, 0); SCHED; LDA(At, 1, 0); STAGE(SA(0, 1), Ab, lda, brow + HALF, t + 2);
;       WAIT_L(8); BAR; WAIT_L(0); MMA(0, 0, At, B0); BAR; SCHED;
;       LDB(B1, 1, 1); STAGE(SB(1, 0), Bt, ldb, bcol, t + 3);
;       BAR; WAIT_L(0); MMA(0, 1, At, B1); BAR;
;       LDA(At, 1, 1); STAGE(SA(1, 0), Ab, lda, brow, t + 3);
;       BAR; WAIT_L(0); MMA(1, 0, At, B0); BAR; SCHED;
	v_add_u32_e32 v166, s63, v155
	v_add_u32_e32 v167, 0x2000, v166
	v_readfirstlane_b32 s51, v166
	v_lshl_add_u64 v[168:169], v[240:241], 0, s[24:25]
	s_mov_b32 m0, s51
	v_readfirstlane_b32 s51, v167
	global_load_lds_dwordx4 v[168:169], off
	v_lshl_add_u64 v[168:169], v[242:243], 0, s[24:25]
	s_mov_b32 m0, s51
	s_nop 0
	global_load_lds_dwordx4 v[168:169], off
	s_waitcnt vmcnt(6)
	s_barrier
	v_mfma_f32_16x16x32_bf16 v[28:31], v[184:187], v[216:219], v[28:31]
	v_mfma_f32_16x16x32_bf16 v[24:27], v[184:187], v[224:227], v[24:27]
	v_mfma_f32_16x16x32_bf16 v[20:23], v[192:195], v[216:219], v[20:23]
	v_mfma_f32_16x16x32_bf16 v[16:19], v[192:195], v[224:227], v[16:19]
	v_mfma_f32_16x16x32_bf16 v[12:15], v[200:203], v[216:219], v[12:15]
	v_mfma_f32_16x16x32_bf16 v[8:11], v[200:203], v[224:227], v[8:11]
	v_mfma_f32_16x16x32_bf16 v[4:7], v[208:211], v[216:219], v[4:7]
	v_mfma_f32_16x16x32_bf16 v[0:3], v[208:211], v[224:227], v[0:3]
	v_mfma_f32_16x16x32_bf16 v[28:31], v[188:191], v[220:223], v[28:31]
	v_mfma_f32_16x16x32_bf16 v[24:27], v[188:191], v[228:231], v[24:27]
	v_mfma_f32_16x16x32_bf16 v[20:23], v[196:199], v[220:223], v[20:23]
	v_mfma_f32_16x16x32_bf16 v[16:19], v[196:199], v[228:231], v[16:19]
	v_mfma_f32_16x16x32_bf16 v[12:15], v[204:207], v[220:223], v[12:15]
	v_mfma_f32_16x16x32_bf16 v[8:11], v[204:207], v[228:231], v[8:11]
	v_mfma_f32_16x16x32_bf16 v[4:7], v[212:215], v[220:223], v[4:7]
	v_mfma_f32_16x16x32_bf16 v[0:3], v[212:215], v[228:231], v[0:3]
	s_barrier
	ds_read_b128 v[172:175], v156
	ds_read_b128 v[176:179], v156 offset:1024
	ds_read_b128 v[180:183], v156 offset:2048
	ds_read_b128 v[184:187], v156 offset:3072
	v_add_u32_e32 v168, 0x4000, v149
	v_add_u32_e32 v169, 0x6000, v149
	v_readfirstlane_b32 s51, v168
	v_lshl_add_u64 v[220:221], v[236:237], 0, s[26:27]
	s_mov_b32 m0, s51
	v_readfirstlane_b32 s51, v169
	ds_read_b128 v[188:191], v153 offset:32768
	ds_read_b128 v[192:195], v153 offset:33792
	ds_read_b128 v[196:199], v152 offset:32768
	ds_read_b128 v[200:203], v152 offset:33792
	ds_read_b128 v[204:207], v151 offset:32768
	ds_read_b128 v[208:211], v151 offset:33792
	ds_read_b128 v[212:215], v150 offset:32768
	ds_read_b128 v[216:219], v150 offset:33792
	global_load_lds_dwordx4 v[220:221], off
	v_lshl_add_u64 v[220:221], v[238:239], 0, s[26:27]
	s_mov_b32 m0, s51
	s_nop 0
	global_load_lds_dwordx4 v[220:221], off
	s_waitcnt lgkmcnt(8)
	s_barrier
	s_waitcnt lgkmcnt(0)
	v_mfma_f32_16x16x32_bf16 v[124:127], v[188:191], v[172:175], v[124:127]
	v_mfma_f32_16x16x32_bf16 v[120:123], v[188:191], v[180:183], v[120:123]
	v_mfma_f32_16x16x32_bf16 v[116:119], v[196:199], v[172:175], v[116:119]
	v_mfma_f32_16x16x32_bf16 v[112:115], v[196:199], v[180:183], v[112:115]
	v_mfma_f32_16x16x32_bf16 v[108:111], v[204:207], v[172:175], v[108:111]
	v_mfma_f32_16x16x32_bf16 v[104:107], v[204:207], v[180:183], v[104:107]
	v_mfma_f32_16x16x32_bf16 v[100:103], v[212:215], v[172:175], v[100:103]
	v_mfma_f32_16x16x32_bf16 v[96:99], v[212:215], v[180:183], v[96:99]
	v_mfma_f32_16x16x32_bf16 v[124:127], v[192:195], v[176:179], v[124:127]
	v_mfma_f32_16x16x32_bf16 v[120:123], v[192:195], v[184:187], v[120:123]
	v_mfma_f32_16x16x32_bf16 v[116:119], v[200:203], v[176:179], v[116:119]
	v_mfma_f32_16x16x32_bf16 v[112:115], v[200:203], v[184:187], v[112:115]
	v_mfma_f32_16x16x32_bf16 v[108:111], v[208:211], v[176:179], v[108:111]
	v_mfma_f32_16x16x32_bf16 v[104:107], v[208:211], v[184:187], v[104:107]
	v_mfma_f32_16x16x32_bf16 v[100:103], v[216:219], v[176:179], v[100:103]
	v_mfma_f32_16x16x32_bf16 v[96:99], v[216:219], v[184:187], v[96:99]
	s_barrier
	v_readfirstlane_b32 s51, v157
	v_add_u32_e32 v246, 0x2000, v157
	v_lshl_add_u64 v[244:245], v[240:241], 0, s[36:37]
	s_mov_b32 m0, s51
	v_readfirstlane_b32 s51, v246
	ds_read_b128 v[220:223], v154
	ds_read_b128 v[224:227], v154 offset:1024
	ds_read_b128 v[228:231], v154 offset:2048
	ds_read_b128 v[232:235], v154 offset:3072
	global_load_lds_dwordx4 v[244:245], off
	v_lshl_add_u64 v[244:245], v[242:243], 0, s[36:37]
	s_mov_b32 m0, s51
	s_nop 0
	global_load_lds_dwordx4 v[244:245], off
	s_barrier
	s_waitcnt lgkmcnt(0)
	v_mfma_f32_16x16x32_bf16 v[92:95], v[188:191], v[220:223], v[92:95]
	v_mfma_f32_16x16x32_bf16 v[88:91], v[188:191], v[228:231], v[88:91]
	v_mfma_f32_16x16x32_bf16 v[84:87], v[196:199], v[220:223], v[84:87]
	v_mfma_f32_16x16x32_bf16 v[80:83], v[196:199], v[228:231], v[80:83]
	v_mfma_f32_16x16x32_bf16 v[76:79], v[204:207], v[220:223], v[76:79]
	v_mfma_f32_16x16x32_bf16 v[72:75], v[204:207], v[228:231], v[72:75]
	v_mfma_f32_16x16x32_bf16 v[68:71], v[212:215], v[220:223], v[68:71]
	v_mfma_f32_16x16x32_bf16 v[64:67], v[212:215], v[228:231], v[64:67]
	v_mfma_f32_16x16x32_bf16 v[92:95], v[192:195], v[224:227], v[92:95]
	v_mfma_f32_16x16x32_bf16 v[88:91], v[192:195], v[232:235], v[88:91]
	v_mfma_f32_16x16x32_bf16 v[84:87], v[200:203], v[224:227], v[84:87]
	v_mfma_f32_16x16x32_bf16 v[80:83], v[200:203], v[232:235], v[80:83]
	v_mfma_f32_16x16x32_bf16 v[76:79], v[208:211], v[224:227], v[76:79]
	v_mfma_f32_16x16x32_bf16 v[72:75], v[208:211], v[232:235], v[72:75]
	v_mfma_f32_16x16x32_bf16 v[68:71], v[216:219], v[224:227], v[68:71]
	v_mfma_f32_16x16x32_bf16 v[64:67], v[216:219], v[232:235], v[64:67]
	s_barrier
	v_readfirstlane_b32 s51, v158
	v_lshl_add_u64 v[236:237], v[236:237], 0, s[38:39]
	s_mov_b32 m0, s51
	v_readfirstlane_b32 s51, v159
	ds_read_b128 v[188:191], v153 offset:49152
	ds_read_b128 v[192:195], v153 offset:50176
	ds_read_b128 v[196:199], v152 offset:49152
	ds_read_b128 v[200:203], v152 offset:50176
	ds_read_b128 v[204:207], v151 offset:49152
	ds_read_b128 v[208:211], v151 offset:50176
	ds_read_b128 v[212:215], v150 offset:49152
	ds_read_b128 v[216:219], v150 offset:50176
	global_load_lds_dwordx4 v[236:237], off
	v_lshl_add_u64 v[236:237], v[238:239], 0, s[38:39]
	s_mov_b32 m0, s51
	s_nop 0
	global_load_lds_dwordx4 v[236:237], off
	s_barrier
; #define STAGE(P, BASE, LD, br, kt) do { const char* _g = (const char*)((BASE) + (size_t)(br) * (LD) + (size_t)(kt) * 64); \
;     for (int _i = 0; _i < 2; ++_i) { int _b = tidx * 16 + _i * 8192; int _r, _c; stage_rc(_b, _r, _c); \
;       __builtin_amdgcn_global_load_lds((const unsigned*)(_g + (unsigned)((_r * (LD) + _c) * 2)), (unsigned*)((char*)(P) + _b), 16, 0, 0); } } while (0)
; #define LDA(dst, b, h) for (int m = 0; m < 4; ++m) for (int k = 0; k < 2; ++k) \
;     dst[m][k] = *reinterpret_cast<const bf16x8*>((char*)SA(b, h) + lds_byte(wr * 64 + m * 16 + fr, k * 32 + fq * 8))
; #define LDB(dst, b, h) for (int n = 0; n < 2; ++n) for (int k = 0; k < 2; ++k) \
;     dst[n][k] = *reinterpret_cast<const bf16x8*>((char*)SB(b, h) + lds_byte(wc * 32 + n * 16 + fr, k * 32 + fq * 8))
; #define MMA(ai, bj, At_, Bt_) do { __builtin_amdgcn_s_setprio(1); \
;     for (int k = 0; k < 2; ++k) for (int m = 0; m < 4; ++m) for (int n = 0; n < 2; ++n) \
;       acc[ai][bj][m][n] = __builtin_amdgcn_mfma_f32_16x16x32_bf16(At_[m][k], Bt_[n][k], acc[ai][bj][m][n], 0, 0, 0); \
;     __builtin_amdgcn_s_setprio(0); } while (0)
; #define WAIT_V(n) asm volatile("s_waitcnt vmcnt(" #n ")" ::: "memory")
; #define WAIT_L(n) asm volatile("s_waitcnt lgkmcnt(" #n ")" ::: "memory")
; #define BAR __builtin_amdgcn_s_barrier()
; #define SCHED __builtin_amdgcn_sched_barrier(0)
; template <int EPI, int lda, int ldb, int N, int K>
; __device__ __forceinline__ void gemm_phase(const u16* __restrict__ A, const u16* __restrict__ Bt, const GemmEpi ep, int wv) {
;     ...
;       BAR; WAIT_L(0); MMA(1, 0, At, B0); BAR; SCHED;
;       STAGE(SB(1, 1), Bt, ldb, bcol + HALF, t + 3);
;       WAIT_V(6); BAR; MMA(1, 1, At, B1); BAR;
;     }
;     { LDB(B0, 0, 0); LDA(At, 0, 0); STAGE(SA(1, 1), Ab, lda, brow + HALF, nt - 1);
;       BAR; WAIT_L(0); MMA(0, 0, At, B0); BAR;
	s_waitcnt lgkmcnt(0)
	v_mfma_f32_16x16x32_bf16 v[60:63], v[188:191], v[172:175], v[60:63]
	v_mfma_f32_16x16x32_bf16 v[56:59], v[188:191], v[180:183], v[56:59]
	v_mfma_f32_16x16x32_bf16 v[52:55], v[196:199], v[172:175], v[52:55]
	v_mfma_f32_16x16x32_bf16 v[48:51], v[196:199], v[180:183], v[48:51]
	v_mfma_f32_16x16x32_bf16 v[44:47], v[204:207], v[172:175], v[44:47]
	v_mfma_f32_16x16x32_bf16 v[40:43], v[204:207], v[180:183], v[40:43]
	v_mfma_f32_16x16x32_bf16 v[36:39], v[212:215], v[172:175], v[36:39]
	v_mfma_f32_16x16x32_bf16 v[32:35], v[212:215], v[180:183], v[32:35]
	v_mfma_f32_16x16x32_bf16 v[60:63], v[192:195], v[176:179], v[60:63]
	v_mfma_f32_16x16x32_bf16 v[56:59], v[192:195], v[184:187], v[56:59]
	v_mfma_f32_16x16x32_bf16 v[52:55], v[200:203], v[176:179], v[52:55]
	v_mfma_f32_16x16x32_bf16 v[48:51], v[200:203], v[184:187], v[48:51]
	v_mfma_f32_16x16x32_bf16 v[44:47], v[208:211], v[176:179], v[44:47]
	v_mfma_f32_16x16x32_bf16 v[40:43], v[208:211], v[184:187], v[40:43]
	v_mfma_f32_16x16x32_bf16 v[36:39], v[216:219], v[176:179], v[36:39]
	v_mfma_f32_16x16x32_bf16 v[32:35], v[216:219], v[184:187], v[32:35]
	s_barrier
	v_readfirstlane_b32 s51, v160
	v_add_u32_e32 v174, 0x2000, v160
	v_lshl_add_u64 v[172:173], v[240:241], 0, s[42:43]
	s_mov_b32 m0, s51
	v_readfirstlane_b32 s51, v174
	global_load_lds_dwordx4 v[172:173], off
	v_lshl_add_u64 v[172:173], v[242:243], 0, s[42:43]
	s_mov_b32 m0, s51
	s_nop 0
	global_load_lds_dwordx4 v[172:173], off
	s_add_i32 s50, s50, 2
	s_add_u32 s48, s48, 0x100
	s_addc_u32 s49, s49, 0
	s_cmp_gt_u32 s50, 27
	s_waitcnt vmcnt(6)
	s_barrier
	v_mfma_f32_16x16x32_bf16 v[28:31], v[188:191], v[220:223], v[28:31]
	v_mfma_f32_16x16x32_bf16 v[24:27], v[188:191], v[228:231], v[24:27]
	v_mfma_f32_16x16x32_bf16 v[20:23], v[196:199], v[220:223], v[20:23]
	v_mfma_f32_16x16x32_bf16 v[16:19], v[196:199], v[228:231], v[16:19]
	v_mfma_f32_16x16x32_bf16 v[12:15], v[204:207], v[220:223], v[12:15]
	v_mfma_f32_16x16x32_bf16 v[8:11], v[204:207], v[228:231], v[8:11]
	v_mfma_f32_16x16x32_bf16 v[4:7], v[212:215], v[220:223], v[4:7]
	v_mfma_f32_16x16x32_bf16 v[0:3], v[212:215], v[228:231], v[0:3]
	v_mfma_f32_16x16x32_bf16 v[28:31], v[192:195], v[224:227], v[28:31]
	v_mfma_f32_16x16x32_bf16 v[24:27], v[192:195], v[232:235], v[24:27]
	v_mfma_f32_16x16x32_bf16 v[20:23], v[200:203], v[224:227], v[20:23]
	v_mfma_f32_16x16x32_bf16 v[16:19], v[200:203], v[232:235], v[16:19]
	v_mfma_f32_16x16x32_bf16 v[12:15], v[208:211], v[224:227], v[12:15]
	v_mfma_f32_16x16x32_bf16 v[8:11], v[208:211], v[232:235], v[8:11]
	v_mfma_f32_16x16x32_bf16 v[4:7], v[216:219], v[224:227], v[4:7]
	v_mfma_f32_16x16x32_bf16 v[0:3], v[216:219], v[232:235], v[0:3]
	s_barrier
	s_cbranch_scc0 .LBB0_340
	s_add_i32 s48, s46, 0x80
	s_mul_hi_i32 s49, s48, 0x1080
	s_mulk_i32 s48, 0x1080
	s_add_u32 s48, s31, s48
	s_addc_u32 s49, s56, s49
	v_lshl_add_u64 v[158:159], s[48:49], 0, v[128:129]
	v_readfirstlane_b32 s50, v170
	v_lshl_add_u64 v[158:159], v[158:159], 0, s[44:45]
	s_mov_b32 m0, s50
	ds_read_b128 v[134:137], v162
	ds_read_b128 v[138:141], v162 offset:1024
	ds_read_b128 v[172:175], v162 offset:2048
	ds_read_b128 v[176:179], v162 offset:3072
	ds_read_b128 v[180:183], v153
	ds_read_b128 v[184:187], v153 offset:1024
	ds_read_b128 v[188:191], v152
	ds_read_b128 v[192:195], v152 offset:1024
	ds_read_b128 v[196:199], v151
	ds_read_b128 v[200:203], v151 offset:1024
	ds_read_b128 v[204:207], v150
	ds_read_b128 v[208:211], v150 offset:1024
	global_load_lds_dwordx4 v[158:159], off
	v_lshl_add_u64 v[158:159], s[48:49], 0, v[132:133]
	v_readfirstlane_b32 s48, v171
	v_lshl_add_u64 v[158:159], v[158:159], 0, s[44:45]
	s_mov_b32 m0, s48
	s_nop 0
	global_load_lds_dwordx4 v[158:159], off
	s_barrier
	s_waitcnt lgkmcnt(0)
	v_mfma_f32_16x16x32_bf16 v[124:127], v[180:183], v[134:137], v[124:127]
	v_mfma_f32_16x16x32_bf16 v[120:123], v[180:183], v[172:175], v[120:123]
	v_mfma_f32_16x16x32_bf16 v[116:119], v[188:191], v[134:137], v[116:119]
	v_mfma_f32_16x16x32_bf16 v[112:115], v[188:191], v[172:175], v[112:115]
	v_mfma_f32_16x16x32_bf16 v[108:111], v[196:199], v[134:137], v[108:111]
	v_mfma_f32_16x16x32_bf16 v[104:107], v[196:199], v[172:175], v[104:107]
	v_mfma_f32_16x16x32_bf16 v[100:103], v[204:207], v[134:137], v[100:103]
	v_mfma_f32_16x16x32_bf16 v[96:99], v[204:207], v[172:175], v[96:99]
	v_mfma_f32_16x16x32_bf16 v[124:127], v[184:187], v[138:141], v[124:127]
	v_mfma_f32_16x16x32_bf16 v[120:123], v[184:187], v[176:179], v[120:123]
	v_mfma_f32_16x16x32_bf16 v[116:119], v[192:195], v[138:141], v[116:119]
	v_mfma_f32_16x16x32_bf16 v[112:115], v[192:195], v[176:179], v[112:115]
	v_mfma_f32_16x16x32_bf16 v[108:111], v[200:203], v[138:141], v[108:111]
	v_mfma_f32_16x16x32_bf16 v[104:107], v[200:203], v[176:179], v[104:107]
	v_mfma_f32_16x16x32_bf16 v[100:103], v[208:211], v[138:141], v[100:103]
	v_mfma_f32_16x16x32_bf16 v[96:99], v[208:211], v[176:179], v[96:99]
	s_barrier
	ds_read_b128 v[212:215], v161
	ds_read_b128 v[216:219], v161 offset:1024
	ds_read_b128 v[220:223], v161 offset:2048
	ds_read_b128 v[158:161], v161 offset:3072
	s_barrier
; #define LDA(dst, b, h) for (int m = 0; m < 4; ++m) for (int k = 0; k < 2; ++k) \
;     dst[m][k] = *reinterpret_cast<const bf16x8*>((char*)SA(b, h) + lds_byte(wr * 64 + m * 16 + fr, k * 32 + fq * 8))
; #define LDB(dst, b, h) for (int n = 0; n < 2; ++n) for (int k = 0; k < 2; ++k) \
;     dst[n][k] = *reinterpret_cast<const bf16x8*>((char*)SB(b, h) + lds_byte(wc * 32 + n * 16 + fr, k * 32 + fq * 8))
; #define MMA(ai, bj, At_, Bt_) do { __builtin_amdgcn_s_setprio(1); \
;     for (int k = 0; k < 2; ++k) for (int m = 0; m < 4; ++m) for (int n = 0; n < 2; ++n) \
;       acc[ai][bj][m][n] = __builtin_amdgcn_mfma_f32_16x16x32_bf16(At_[m][k], Bt_[n][k], acc[ai][bj][m][n], 0, 0, 0); \
;     __builtin_amdgcn_s_setprio(0); } while (0)
; #define WAIT_V(n) asm volatile("s_waitcnt vmcnt(" #n ")" ::: "memory")
; #define WAIT_L(n) asm volatile("s_waitcnt lgkmcnt(" #n ")" ::: "memory")
; #define BAR __builtin_amdgcn_s_barrier()
; template <int EPI, int lda, int ldb, int N, int K>
; __device__ __forceinline__ void gemm_phase(const u16* __restrict__ A, const u16* __restrict__ Bt, const GemmEpi ep, int wv) {
;     ...
;       LDB(B1, 0, 1); BAR; WAIT_L(0); MMA(0, 1, At, B1); BAR;
;       LDA(At, 0, 1); WAIT_V(4); BAR; WAIT_L(0); MMA(1, 0, At, B0); MMA(1, 1, At, B1); BAR; }
;     { LDB(B0, 1, 0); LDA(At, 1, 0); WAIT_V(2); BAR; WAIT_L(0); MMA(0, 0, At, B0); BAR;
	s_waitcnt lgkmcnt(0)
	v_mfma_f32_16x16x32_bf16 v[92:95], v[180:183], v[212:215], v[92:95]
	v_mfma_f32_16x16x32_bf16 v[88:91], v[180:183], v[220:223], v[88:91]
	v_mfma_f32_16x16x32_bf16 v[76:79], v[196:199], v[212:215], v[76:79]
	v_mfma_f32_16x16x32_bf16 v[72:75], v[196:199], v[220:223], v[72:75]
	v_mfma_f32_16x16x32_bf16 v[68:71], v[204:207], v[212:215], v[68:71]
	v_mfma_f32_16x16x32_bf16 v[64:67], v[204:207], v[220:223], v[64:67]
	v_mfma_f32_16x16x32_bf16 v[84:87], v[188:191], v[212:215], v[84:87]
	v_mfma_f32_16x16x32_bf16 v[80:83], v[188:191], v[220:223], v[80:83]
	v_mfma_f32_16x16x32_bf16 v[92:95], v[184:187], v[216:219], v[92:95]
	v_mfma_f32_16x16x32_bf16 v[88:91], v[184:187], v[158:161], v[88:91]
	v_mfma_f32_16x16x32_bf16 v[76:79], v[200:203], v[216:219], v[76:79]
	v_mfma_f32_16x16x32_bf16 v[72:75], v[200:203], v[158:161], v[72:75]
	v_mfma_f32_16x16x32_bf16 v[68:71], v[208:211], v[216:219], v[68:71]
	v_mfma_f32_16x16x32_bf16 v[64:67], v[208:211], v[158:161], v[64:67]
	v_mfma_f32_16x16x32_bf16 v[180:183], v[192:195], v[216:219], v[84:87]
	v_mfma_f32_16x16x32_bf16 v[184:187], v[192:195], v[158:161], v[80:83]
	s_barrier
	s_nop 0
	ds_read_b128 v[80:83], v153 offset:16384
	ds_read_b128 v[84:87], v153 offset:17408
	ds_read_b128 v[188:191], v152 offset:16384
	ds_read_b128 v[192:195], v152 offset:17408
	ds_read_b128 v[196:199], v151 offset:16384
	ds_read_b128 v[200:203], v151 offset:17408
	ds_read_b128 v[204:207], v150 offset:16384
	ds_read_b128 v[208:211], v150 offset:17408
	s_waitcnt vmcnt(4)
	s_barrier
	s_waitcnt lgkmcnt(0)
	v_mfma_f32_16x16x32_bf16 v[60:63], v[80:83], v[134:137], v[60:63]
	v_mfma_f32_16x16x32_bf16 v[44:47], v[196:199], v[134:137], v[44:47]
	v_mfma_f32_16x16x32_bf16 v[40:43], v[196:199], v[172:175], v[40:43]
	v_mfma_f32_16x16x32_bf16 v[36:39], v[204:207], v[134:137], v[36:39]
	v_mfma_f32_16x16x32_bf16 v[32:35], v[204:207], v[172:175], v[32:35]
	v_mfma_f32_16x16x32_bf16 v[56:59], v[80:83], v[172:175], v[56:59]
	v_mfma_f32_16x16x32_bf16 v[52:55], v[188:191], v[134:137], v[52:55]
	v_mfma_f32_16x16x32_bf16 v[48:51], v[188:191], v[172:175], v[48:51]
	v_mfma_f32_16x16x32_bf16 v[60:63], v[84:87], v[138:141], v[60:63]
	v_mfma_f32_16x16x32_bf16 v[44:47], v[200:203], v[138:141], v[44:47]
	v_mfma_f32_16x16x32_bf16 v[40:43], v[200:203], v[176:179], v[40:43]
	v_mfma_f32_16x16x32_bf16 v[36:39], v[208:211], v[138:141], v[36:39]
	v_mfma_f32_16x16x32_bf16 v[32:35], v[208:211], v[176:179], v[32:35]
	v_mfma_f32_16x16x32_bf16 v[134:137], v[84:87], v[176:179], v[56:59]
	v_mfma_f32_16x16x32_bf16 v[170:173], v[192:195], v[138:141], v[52:55]
	v_mfma_f32_16x16x32_bf16 v[224:227], v[192:195], v[176:179], v[48:51]
	v_mfma_f32_16x16x32_bf16 v[28:31], v[80:83], v[212:215], v[28:31]
	v_mfma_f32_16x16x32_bf16 v[20:23], v[188:191], v[212:215], v[20:23]
	v_mfma_f32_16x16x32_bf16 v[12:15], v[196:199], v[212:215], v[12:15]
	v_mfma_f32_16x16x32_bf16 v[4:7], v[204:207], v[212:215], v[4:7]
	v_mfma_f32_16x16x32_bf16 v[24:27], v[80:83], v[220:223], v[24:27]
	v_mfma_f32_16x16x32_bf16 v[16:19], v[188:191], v[220:223], v[16:19]
	v_mfma_f32_16x16x32_bf16 v[8:11], v[196:199], v[220:223], v[8:11]
	v_mfma_f32_16x16x32_bf16 v[0:3], v[204:207], v[220:223], v[0:3]
	v_mfma_f32_16x16x32_bf16 v[28:31], v[84:87], v[216:219], v[28:31]
	v_mfma_f32_16x16x32_bf16 v[20:23], v[192:195], v[216:219], v[20:23]
	v_mfma_f32_16x16x32_bf16 v[12:15], v[200:203], v[216:219], v[12:15]
	v_mfma_f32_16x16x32_bf16 v[4:7], v[208:211], v[216:219], v[4:7]
	v_mfma_f32_16x16x32_bf16 v[138:141], v[84:87], v[158:161], v[24:27]
	v_mfma_f32_16x16x32_bf16 v[174:177], v[192:195], v[158:161], v[16:19]
	v_mfma_f32_16x16x32_bf16 v[188:191], v[200:203], v[158:161], v[8:11]
	v_mfma_f32_16x16x32_bf16 v[158:161], v[208:211], v[158:161], v[0:3]
	s_barrier
	s_nop 0
	ds_read_b128 v[0:3], v156
	ds_read_b128 v[8:11], v156 offset:1024
	ds_read_b128 v[16:19], v156 offset:2048
	ds_read_b128 v[192:195], v156 offset:3072
	ds_read_b128 v[24:27], v153 offset:32768
	ds_read_b128 v[56:59], v153 offset:33792
	ds_read_b128 v[196:199], v152 offset:32768
	ds_read_b128 v[200:203], v152 offset:33792
	ds_read_b128 v[204:207], v151 offset:32768
	ds_read_b128 v[208:211], v151 offset:33792
	ds_read_b128 v[212:215], v150 offset:32768
	ds_read_b128 v[216:219], v150 offset:33792
	s_waitcnt vmcnt(2)
	s_barrier
; #define LDA(dst, b, h) for (int m = 0; m < 4; ++m) for (int k = 0; k < 2; ++k) \
;     dst[m][k] = *reinterpret_cast<const bf16x8*>((char*)SA(b, h) + lds_byte(wr * 64 + m * 16 + fr, k * 32 + fq * 8))
; #define LDB(dst, b, h) for (int n = 0; n < 2; ++n) for (int k = 0; k < 2; ++k) \
;     dst[n][k] = *reinterpret_cast<const bf16x8*>((char*)SB(b, h) + lds_byte(wc * 32 + n * 16 + fr, k * 32 + fq * 8))
; #define MMA(ai, bj, At_, Bt_) do { __builtin_amdgcn_s_setprio(1); \
;     for (int k = 0; k < 2; ++k) for (int m = 0; m < 4; ++m) for (int n = 0; n < 2; ++n) \
;       acc[ai][bj][m][n] = __builtin_amdgcn_mfma_f32_16x16x32_bf16(At_[m][k], Bt_[n][k], acc[ai][bj][m][n], 0, 0, 0); \
;     __builtin_amdgcn_s_setprio(0); } while (0)
; #define WAIT_V(n) asm volatile("s_waitcnt vmcnt(" #n ")" ::: "memory")
; #define WAIT_L(n) asm volatile("s_waitcnt lgkmcnt(" #n ")" ::: "memory")
; #define BAR __builtin_amdgcn_s_barrier()
; template <int EPI, int lda, int ldb, int N, int K>
; __device__ __forceinline__ void gemm_phase(const u16* __restrict__ A, const u16* __restrict__ Bt, const GemmEpi ep, int wv) {
;     ...
;     { LDB(B0, 1, 0); LDA(At, 1, 0); WAIT_V(2); BAR; WAIT_L(0); MMA(0, 0, At, B0); BAR;
;       LDB(B1, 1, 1); WAIT_V(0); BAR; WAIT_L(0); MMA(0, 1, At, B1); BAR;
;       LDA(At, 1, 1); BAR; WAIT_L(0); MMA(1, 0, At, B0); MMA(1, 1, At, B1); BAR; }
;     if (wr == 0) BAR;
	s_waitcnt lgkmcnt(0)
	v_mfma_f32_16x16x32_bf16 v[48:51], v[24:27], v[0:3], v[124:127]
	v_mfma_f32_16x16x32_bf16 v[52:55], v[24:27], v[16:19], v[120:123]
	v_mfma_f32_16x16x32_bf16 v[80:83], v[196:199], v[0:3], v[116:119]
	v_mfma_f32_16x16x32_bf16 v[84:87], v[196:199], v[16:19], v[112:115]
	v_mfma_f32_16x16x32_bf16 v[108:111], v[204:207], v[0:3], v[108:111]
	v_mfma_f32_16x16x32_bf16 v[104:107], v[204:207], v[16:19], v[104:107]
	v_mfma_f32_16x16x32_bf16 v[112:115], v[212:215], v[0:3], v[100:103]
	v_mfma_f32_16x16x32_bf16 v[120:123], v[212:215], v[16:19], v[96:99]
	v_mfma_f32_16x16x32_bf16 v[124:127], v[56:59], v[8:11], v[48:51]
	v_mfma_f32_16x16x32_bf16 v[116:119], v[56:59], v[192:195], v[52:55]
	v_mfma_f32_16x16x32_bf16 v[100:103], v[200:203], v[8:11], v[80:83]
	v_mfma_f32_16x16x32_bf16 v[96:99], v[200:203], v[192:195], v[84:87]
	v_mfma_f32_16x16x32_bf16 v[84:87], v[208:211], v[8:11], v[108:111]
	v_mfma_f32_16x16x32_bf16 v[80:83], v[208:211], v[192:195], v[104:107]
	v_mfma_f32_16x16x32_bf16 v[52:55], v[216:219], v[8:11], v[112:115]
	v_mfma_f32_16x16x32_bf16 v[48:51], v[216:219], v[192:195], v[120:123]
	s_barrier
	ds_read_b128 v[220:223], v154
	ds_read_b128 v[228:231], v154 offset:1024
	ds_read_b128 v[232:235], v154 offset:2048
	ds_read_b128 v[154:157], v154 offset:3072
	s_waitcnt vmcnt(0)
	s_barrier
	s_waitcnt lgkmcnt(0)
	v_mfma_f32_16x16x32_bf16 v[92:95], v[24:27], v[220:223], v[92:95]
	v_mfma_f32_16x16x32_bf16 v[24:27], v[24:27], v[232:235], v[88:91]
	v_mfma_f32_16x16x32_bf16 v[88:91], v[196:199], v[220:223], v[180:183]
	v_mfma_f32_16x16x32_bf16 v[104:107], v[196:199], v[232:235], v[184:187]
	v_mfma_f32_16x16x32_bf16 v[76:79], v[204:207], v[220:223], v[76:79]
	v_mfma_f32_16x16x32_bf16 v[72:75], v[204:207], v[232:235], v[72:75]
	v_mfma_f32_16x16x32_bf16 v[68:71], v[212:215], v[220:223], v[68:71]
	v_mfma_f32_16x16x32_bf16 v[64:67], v[212:215], v[232:235], v[64:67]
	v_mfma_f32_16x16x32_bf16 v[120:123], v[56:59], v[228:231], v[92:95]
	v_mfma_f32_16x16x32_bf16 v[112:115], v[56:59], v[154:157], v[24:27]
	v_mfma_f32_16x16x32_bf16 v[108:111], v[200:203], v[228:231], v[88:91]
	v_mfma_f32_16x16x32_bf16 v[104:107], v[200:203], v[154:157], v[104:107]
	v_mfma_f32_16x16x32_bf16 v[92:95], v[208:211], v[228:231], v[76:79]
	v_mfma_f32_16x16x32_bf16 v[88:91], v[208:211], v[154:157], v[72:75]
	v_mfma_f32_16x16x32_bf16 v[68:71], v[216:219], v[228:231], v[68:71]
	v_mfma_f32_16x16x32_bf16 v[56:59], v[216:219], v[154:157], v[64:67]
	s_barrier
	s_nop 0
	ds_read_b128 v[64:67], v153 offset:49152
	ds_read_b128 v[178:181], v153 offset:50176
	ds_read_b128 v[76:79], v152 offset:49152
	ds_read_b128 v[182:185], v152 offset:50176
	ds_read_b128 v[196:199], v151 offset:49152
	ds_read_b128 v[200:203], v151 offset:50176
	ds_read_b128 v[204:207], v150 offset:49152
	ds_read_b128 v[150:153], v150 offset:50176
	s_barrier
	s_waitcnt lgkmcnt(0)
	v_mfma_f32_16x16x32_bf16 v[24:27], v[64:67], v[0:3], v[60:63]
	v_mfma_f32_16x16x32_bf16 v[60:63], v[64:67], v[16:19], v[134:137]
	v_mfma_f32_16x16x32_bf16 v[134:137], v[76:79], v[0:3], v[170:173]
	v_mfma_f32_16x16x32_bf16 v[170:173], v[76:79], v[16:19], v[224:227]
	v_mfma_f32_16x16x32_bf16 v[44:47], v[196:199], v[0:3], v[44:47]
	v_mfma_f32_16x16x32_bf16 v[208:211], v[196:199], v[16:19], v[40:43]
	v_mfma_f32_16x16x32_bf16 v[0:3], v[204:207], v[0:3], v[36:39]
	v_mfma_f32_16x16x32_bf16 v[36:39], v[204:207], v[16:19], v[32:35]
	v_mfma_f32_16x16x32_bf16 v[72:75], v[178:181], v[8:11], v[24:27]
	v_mfma_f32_16x16x32_bf16 v[60:63], v[178:181], v[192:195], v[60:63]
	v_mfma_f32_16x16x32_bf16 v[40:43], v[182:185], v[8:11], v[134:137]
	v_mfma_f32_16x16x32_bf16 v[32:35], v[182:185], v[192:195], v[170:173]
	v_mfma_f32_16x16x32_bf16 v[24:27], v[200:203], v[8:11], v[44:47]
	v_mfma_f32_16x16x32_bf16 v[16:19], v[200:203], v[192:195], v[208:211]
	v_mfma_f32_16x16x32_bf16 v[8:11], v[150:153], v[8:11], v[0:3]
	v_mfma_f32_16x16x32_bf16 v[0:3], v[150:153], v[192:195], v[36:39]
	v_mfma_f32_16x16x32_bf16 v[28:31], v[64:67], v[220:223], v[28:31]
	v_mfma_f32_16x16x32_bf16 v[36:39], v[64:67], v[232:235], v[138:141]
	v_mfma_f32_16x16x32_bf16 v[20:23], v[76:79], v[220:223], v[20:23]
	v_mfma_f32_16x16x32_bf16 v[134:137], v[76:79], v[232:235], v[174:177]
	v_mfma_f32_16x16x32_bf16 v[12:15], v[196:199], v[220:223], v[12:15]
	v_mfma_f32_16x16x32_bf16 v[138:141], v[196:199], v[232:235], v[188:191]
	v_mfma_f32_16x16x32_bf16 v[4:7], v[204:207], v[220:223], v[4:7]
	v_mfma_f32_16x16x32_bf16 v[158:161], v[204:207], v[232:235], v[158:161]
	v_mfma_f32_16x16x32_bf16 v[76:79], v[178:181], v[228:231], v[28:31]
	v_mfma_f32_16x16x32_bf16 v[64:67], v[178:181], v[154:157], v[36:39]
	v_mfma_f32_16x16x32_bf16 v[44:47], v[182:185], v[228:231], v[20:23]
	v_mfma_f32_16x16x32_bf16 v[36:39], v[182:185], v[154:157], v[134:137]
	v_mfma_f32_16x16x32_bf16 v[28:31], v[200:203], v[228:231], v[12:15]
	v_mfma_f32_16x16x32_bf16 v[20:23], v[200:203], v[154:157], v[138:141]
	v_mfma_f32_16x16x32_bf16 v[12:15], v[150:153], v[228:231], v[4:7]
	v_mfma_f32_16x16x32_bf16 v[4:7], v[150:153], v[154:157], v[158:161]
	v_cmp_gt_u32_e32 vcc, s64, v130
	s_barrier
	s_and_saveexec_b64 s[48:49], vcc
	s_cbranch_execz .LBB0_343
	s_barrier

; #define STAGE(P, BASE, LD, br, kt) do { const char* _g = (const char*)((BASE) + (size_t)(br) * (LD) + (size_t)(kt) * 64); \
;     for (int _i = 0; _i < 2; ++_i) { int _b = tidx * 16 + _i * 8192; int _r, _c; stage_rc(_b, _r, _c); \
;       __builtin_amdgcn_global_load_lds((const unsigned*)(_g + (unsigned)((_r * (LD) + _c) * 2)), (unsigned*)((char*)(P) + _b), 16, 0, 0); } } while (0)
; #define LDA(dst, b, h) for (int m = 0; m < 4; ++m) for (int k = 0; k < 2; ++k) \
;     dst[m][k] = *reinterpret_cast<const bf16x8*>((char*)SA(b, h) + lds_byte(wr * 64 + m * 16 + fr, k * 32 + fq * 8))
; #define LDB(dst, b, h) for (int n = 0; n < 2; ++n) for (int k = 0; k < 2; ++k) \
;     dst[n][k] = *reinterpret_cast<const bf16x8*>((char*)SB(b, h) + lds_byte(wc * 32 + n * 16 + fr, k * 32 + fq * 8))
; #define MMA(ai, bj, At_, Bt_) do { __builtin_amdgcn_s_setprio(1); \
;     for (int k = 0; k < 2; ++k) for (int m = 0; m < 4; ++m) for (int n = 0; n < 2; ++n) \
;       acc[ai][bj][m][n] = __builtin_amdgcn_mfma_f32_16x16x32_bf16(At_[m][k], Bt_[n][k], acc[ai][bj][m][n], 0, 0, 0); \
;     __builtin_amdgcn_s_setprio(0); } while (0)
; #define WAIT_L(n) asm volatile("s_waitcnt lgkmcnt(" #n ")" ::: "memory")
; #define BAR __builtin_amdgcn_s_barrier()
; #define SCHED __builtin_amdgcn_sched_barrier(0)
; template <int EPI, int lda, int ldb, int N, int K>
; __device__ __forceinline__ void gemm_phase(const u16* __restrict__ A, const u16* __restrict__ Bt, const GemmEpi ep, int wv) {
;     ...
;     for (int t = 0; t < nt - 2; t += 2) {
;       LDB(B0, 0, 0); SCHED; LDA(At, 0, 0); STAGE(SA(1, 1), Ab, lda, brow + HALF, t + 1);
;       WAIT_L(8); BAR; WAIT_L(0); MMA(0, 0, At, B0); BAR; SCHED;
;       LDB(B1, 0, 1); STAGE(SB(0, 0), Bt, ldb, bcol, t + 2);
;       BAR; WAIT_L(0); MMA(0, 1, At, B1); BAR;
;       LDA(At, 0, 1); STAGE(SA(0, 0), Ab, lda, brow, t + 2);
;       BAR; WAIT_L(0); MMA(1, 0, At, B0); BAR; SCHED;
;       STAGE(SB(0, 1), Bt, ldb, bcol + HALF, t + 2);
.LBB0_654:
	ds_read_b128 v[164:167], v160
	ds_read_b128 v[170:173], v160 offset:1024
	ds_read_b128 v[174:177], v160 offset:2048
	ds_read_b128 v[178:181], v160 offset:3072
	v_add_u32_e32 v168, 0xc000, v143
	v_lshl_add_u64 v[234:235], v[138:139], 0, s[52:53]
	v_readfirstlane_b32 s55, v168
	v_add_u32_e32 v169, 0xe000, v143
	v_lshl_add_u64 v[162:163], v[234:235], 0, s[20:21]
	s_mov_b32 m0, s55
	v_lshl_add_u64 v[236:237], v[140:141], 0, s[52:53]
	v_readfirstlane_b32 s55, v169
	ds_read_b128 v[182:185], v151
	ds_read_b128 v[186:189], v151 offset:1024
	ds_read_b128 v[190:193], v150
	ds_read_b128 v[194:197], v150 offset:1024
	ds_read_b128 v[198:201], v149
	ds_read_b128 v[202:205], v149 offset:1024
	ds_read_b128 v[206:209], v148
	ds_read_b128 v[210:213], v148 offset:1024
	global_load_lds_dwordx4 v[162:163], off
	v_lshl_add_u64 v[162:163], v[236:237], 0, s[20:21]
	s_mov_b32 m0, s55
	s_nop 0
	global_load_lds_dwordx4 v[162:163], off
	s_waitcnt lgkmcnt(8)
	s_barrier
	s_waitcnt lgkmcnt(0)
	v_mfma_f32_16x16x32_bf16 v[124:127], v[164:167], v[182:185], v[124:127]
	v_mfma_f32_16x16x32_bf16 v[120:123], v[174:177], v[182:185], v[120:123]
	v_mfma_f32_16x16x32_bf16 v[116:119], v[164:167], v[190:193], v[116:119]
	v_mfma_f32_16x16x32_bf16 v[112:115], v[174:177], v[190:193], v[112:115]
	v_mfma_f32_16x16x32_bf16 v[108:111], v[164:167], v[198:201], v[108:111]
	v_mfma_f32_16x16x32_bf16 v[104:107], v[174:177], v[198:201], v[104:107]
	v_mfma_f32_16x16x32_bf16 v[100:103], v[164:167], v[206:209], v[100:103]
	v_mfma_f32_16x16x32_bf16 v[96:99], v[174:177], v[206:209], v[96:99]
	v_mfma_f32_16x16x32_bf16 v[124:127], v[170:173], v[186:189], v[124:127]
	v_mfma_f32_16x16x32_bf16 v[120:123], v[178:181], v[186:189], v[120:123]
	v_mfma_f32_16x16x32_bf16 v[116:119], v[170:173], v[194:197], v[116:119]
	v_mfma_f32_16x16x32_bf16 v[112:115], v[178:181], v[194:197], v[112:115]
	v_mfma_f32_16x16x32_bf16 v[108:111], v[170:173], v[202:205], v[108:111]
	v_mfma_f32_16x16x32_bf16 v[104:107], v[178:181], v[202:205], v[104:107]
	v_mfma_f32_16x16x32_bf16 v[100:103], v[170:173], v[210:213], v[100:103]
	v_mfma_f32_16x16x32_bf16 v[96:99], v[178:181], v[210:213], v[96:99]
	s_barrier
	v_add_u32_e32 v161, s65, v153
	v_lshl_add_u64 v[238:239], v[134:135], 0, s[52:53]
	v_readfirstlane_b32 s55, v161
	v_lshl_add_u64 v[162:163], v[238:239], 0, s[22:23]
	s_mov_b32 m0, s55
	ds_read_b128 v[214:217], v159
	ds_read_b128 v[218:221], v159 offset:1024
	ds_read_b128 v[222:225], v159 offset:2048
	ds_read_b128 v[226:229], v159 offset:3072
	global_load_lds_dwordx4 v[162:163], off
	v_add_u32_e32 v162, 0x2000, v161
	v_lshl_add_u64 v[240:241], v[136:137], 0, s[52:53]
	v_readfirstlane_b32 s55, v162
	v_lshl_add_u64 v[230:231], v[240:241], 0, s[22:23]
	s_mov_b32 m0, s55
	s_nop 0
	global_load_lds_dwordx4 v[230:231], off
	s_barrier
	s_waitcnt lgkmcnt(0)
	v_mfma_f32_16x16x32_bf16 v[92:95], v[214:217], v[182:185], v[92:95]
	v_mfma_f32_16x16x32_bf16 v[88:91], v[222:225], v[182:185], v[88:91]
	v_mfma_f32_16x16x32_bf16 v[84:87], v[214:217], v[190:193], v[84:87]
	v_mfma_f32_16x16x32_bf16 v[80:83], v[222:225], v[190:193], v[80:83]
	v_mfma_f32_16x16x32_bf16 v[76:79], v[214:217], v[198:201], v[76:79]
	v_mfma_f32_16x16x32_bf16 v[72:75], v[222:225], v[198:201], v[72:75]
	v_mfma_f32_16x16x32_bf16 v[68:71], v[214:217], v[206:209], v[68:71]
	v_mfma_f32_16x16x32_bf16 v[64:67], v[222:225], v[206:209], v[64:67]
	v_mfma_f32_16x16x32_bf16 v[92:95], v[218:221], v[186:189], v[92:95]
	v_mfma_f32_16x16x32_bf16 v[88:91], v[226:229], v[186:189], v[88:91]
	v_mfma_f32_16x16x32_bf16 v[84:87], v[218:221], v[194:197], v[84:87]
	v_mfma_f32_16x16x32_bf16 v[80:83], v[226:229], v[194:197], v[80:83]
	v_mfma_f32_16x16x32_bf16 v[76:79], v[218:221], v[202:205], v[76:79]
	v_mfma_f32_16x16x32_bf16 v[72:75], v[226:229], v[202:205], v[72:75]
	v_mfma_f32_16x16x32_bf16 v[68:71], v[218:221], v[210:213], v[68:71]
	v_mfma_f32_16x16x32_bf16 v[64:67], v[226:229], v[210:213], v[64:67]
	s_barrier
	v_readfirstlane_b32 s55, v143
	v_add_u32_e32 v163, 0x2000, v143
	v_lshl_add_u64 v[230:231], v[234:235], 0, s[24:25]
	s_mov_b32 m0, s55
	v_readfirstlane_b32 s55, v163
	ds_read_b128 v[182:185], v151 offset:16384
	ds_read_b128 v[186:189], v151 offset:17408
	ds_read_b128 v[190:193], v150 offset:16384
	ds_read_b128 v[194:197], v150 offset:17408
	ds_read_b128 v[198:201], v149 offset:16384
	ds_read_b128 v[202:205], v149 offset:17408
	ds_read_b128 v[206:209], v148 offset:16384
	ds_read_b128 v[210:213], v148 offset:17408
	global_load_lds_dwordx4 v[230:231], off
	v_lshl_add_u64 v[230:231], v[236:237], 0, s[24:25]
	s_mov_b32 m0, s55
	s_nop 0
	global_load_lds_dwordx4 v[230:231], off
	s_barrier
	s_waitcnt lgkmcnt(0)
	v_mfma_f32_16x16x32_bf16 v[60:63], v[164:167], v[182:185], v[60:63]
	v_mfma_f32_16x16x32_bf16 v[56:59], v[174:177], v[182:185], v[56:59]
	v_mfma_f32_16x16x32_bf16 v[52:55], v[164:167], v[190:193], v[52:55]
	v_mfma_f32_16x16x32_bf16 v[48:51], v[174:177], v[190:193], v[48:51]
	v_mfma_f32_16x16x32_bf16 v[44:47], v[164:167], v[198:201], v[44:47]
	v_mfma_f32_16x16x32_bf16 v[40:43], v[174:177], v[198:201], v[40:43]
	v_mfma_f32_16x16x32_bf16 v[36:39], v[164:167], v[206:209], v[36:39]
	v_mfma_f32_16x16x32_bf16 v[32:35], v[174:177], v[206:209], v[32:35]
	v_mfma_f32_16x16x32_bf16 v[60:63], v[170:173], v[186:189], v[60:63]
	v_mfma_f32_16x16x32_bf16 v[56:59], v[178:181], v[186:189], v[56:59]
	v_mfma_f32_16x16x32_bf16 v[52:55], v[170:173], v[194:197], v[52:55]
	v_mfma_f32_16x16x32_bf16 v[48:51], v[178:181], v[194:197], v[48:51]
	v_mfma_f32_16x16x32_bf16 v[44:47], v[170:173], v[202:205], v[44:47]
	v_mfma_f32_16x16x32_bf16 v[40:43], v[178:181], v[202:205], v[40:43]
	v_mfma_f32_16x16x32_bf16 v[36:39], v[170:173], v[210:213], v[36:39]
	v_mfma_f32_16x16x32_bf16 v[32:35], v[178:181], v[210:213], v[32:35]
	s_barrier
; #define STAGE(P, BASE, LD, br, kt) do { const char* _g = (const char*)((BASE) + (size_t)(br) * (LD) + (size_t)(kt) * 64); \
;     for (int _i = 0; _i < 2; ++_i) { int _b = tidx * 16 + _i * 8192; int _r, _c; stage_rc(_b, _r, _c); \
;       __builtin_amdgcn_global_load_lds((const unsigned*)(_g + (unsigned)((_r * (LD) + _c) * 2)), (unsigned*)((char*)(P) + _b), 16, 0, 0); } } while (0)
; #define LDA(dst, b, h) for (int m = 0; m < 4; ++m) for (int k = 0; k < 2; ++k) \
;     dst[m][k] = *reinterpret_cast<const bf16x8*>((char*)SA(b, h) + lds_byte(wr * 64 + m * 16 + fr, k * 32 + fq * 8))
; #define LDB(dst, b, h) for (int n = 0; n < 2; ++n) for (int k = 0; k < 2; ++k) \
;     dst[n][k] = *reinterpret_cast<const bf16x8*>((char*)SB(b, h) + lds_byte(wc * 32 + n * 16 + fr, k * 32 + fq * 8))
; #define MMA(ai, bj, At_, Bt_) do { __builtin_amdgcn_s_setprio(1); \
;     for (int k = 0; k < 2; ++k) for (int m = 0; m < 4; ++m) for (int n = 0; n < 2; ++n) \
;       acc[ai][bj][m][n] = __builtin_amdgcn_mfma_f32_16x16x32_bf16(At_[m][k], Bt_[n][k], acc[ai][bj][m][n], 0, 0, 0); \
;     __builtin_amdgcn_s_setprio(0); } while (0)
; #define WAIT_V(n) asm volatile("s_waitcnt vmcnt(" #n ")" ::: "memory")
; #define WAIT_L(n) asm volatile("s_waitcnt lgkmcnt(" #n ")" ::: "memory")
; #define BAR __builtin_amdgcn_s_barrier()
; #define SCHED __builtin_amdgcn_sched_barrier(0)
; template <int EPI, int lda, int ldb, int N, int K>
; __device__ __forceinline__ void gemm_phase(const u16* __restrict__ A, const u16* __restrict__ Bt, const GemmEpi ep, int wv) {
;     ...
;       STAGE(SB(0, 1), Bt, ldb, bcol + HALF, t + 2);
;       WAIT_V(6); BAR; MMA(1, 1, At, B1); BAR;
;       LDB(B0, 1, 0); SCHED; LDA(At, 1, 0); STAGE(SA(0, 1), Ab, lda, brow + HALF, t + 2);
;       WAIT_L(8); BAR; WAIT_L(0); MMA(0, 0, At, B0); BAR; SCHED;
;       LDB(B1, 1, 1); STAGE(SB(1, 0), Bt, ldb, bcol, t + 3);
;       BAR; WAIT_L(0); MMA(0, 1, At, B1); BAR;
;       LDA(At, 1, 1); STAGE(SA(1, 0), Ab, lda, brow, t + 3);
;       BAR; WAIT_L(0); MMA(1, 0, At, B0); BAR; SCHED;
	v_add_u32_e32 v164, s66, v153
	v_add_u32_e32 v165, 0x2000, v164
	v_readfirstlane_b32 s55, v164
	v_lshl_add_u64 v[166:167], v[238:239], 0, s[26:27]
	s_mov_b32 m0, s55
	v_readfirstlane_b32 s55, v165
	global_load_lds_dwordx4 v[166:167], off
	v_lshl_add_u64 v[166:167], v[240:241], 0, s[26:27]
	s_mov_b32 m0, s55
	s_nop 0
	global_load_lds_dwordx4 v[166:167], off
	s_waitcnt vmcnt(6)
	s_barrier
	v_mfma_f32_16x16x32_bf16 v[28:31], v[214:217], v[182:185], v[28:31]
	v_mfma_f32_16x16x32_bf16 v[24:27], v[222:225], v[182:185], v[24:27]
	v_mfma_f32_16x16x32_bf16 v[20:23], v[214:217], v[190:193], v[20:23]
	v_mfma_f32_16x16x32_bf16 v[16:19], v[222:225], v[190:193], v[16:19]
	v_mfma_f32_16x16x32_bf16 v[12:15], v[214:217], v[198:201], v[12:15]
	v_mfma_f32_16x16x32_bf16 v[8:11], v[222:225], v[198:201], v[8:11]
	v_mfma_f32_16x16x32_bf16 v[4:7], v[214:217], v[206:209], v[4:7]
	v_mfma_f32_16x16x32_bf16 v[0:3], v[222:225], v[206:209], v[0:3]
	v_mfma_f32_16x16x32_bf16 v[28:31], v[218:221], v[186:189], v[28:31]
	v_mfma_f32_16x16x32_bf16 v[24:27], v[226:229], v[186:189], v[24:27]
	v_mfma_f32_16x16x32_bf16 v[20:23], v[218:221], v[194:197], v[20:23]
	v_mfma_f32_16x16x32_bf16 v[16:19], v[226:229], v[194:197], v[16:19]
	v_mfma_f32_16x16x32_bf16 v[12:15], v[218:221], v[202:205], v[12:15]
	v_mfma_f32_16x16x32_bf16 v[8:11], v[226:229], v[202:205], v[8:11]
	v_mfma_f32_16x16x32_bf16 v[4:7], v[218:221], v[210:213], v[4:7]
	v_mfma_f32_16x16x32_bf16 v[0:3], v[226:229], v[210:213], v[0:3]
	s_barrier
	ds_read_b128 v[170:173], v154
	ds_read_b128 v[174:177], v154 offset:1024
	ds_read_b128 v[178:181], v154 offset:2048
	ds_read_b128 v[182:185], v154 offset:3072
	v_add_u32_e32 v166, 0x4000, v143
	v_add_u32_e32 v167, 0x6000, v143
	v_readfirstlane_b32 s55, v166
	v_lshl_add_u64 v[218:219], v[234:235], 0, s[42:43]
	s_mov_b32 m0, s55
	v_readfirstlane_b32 s55, v167
	ds_read_b128 v[186:189], v151 offset:32768
	ds_read_b128 v[190:193], v151 offset:33792
	ds_read_b128 v[194:197], v150 offset:32768
	ds_read_b128 v[198:201], v150 offset:33792
	ds_read_b128 v[202:205], v149 offset:32768
	ds_read_b128 v[206:209], v149 offset:33792
	ds_read_b128 v[210:213], v148 offset:32768
	ds_read_b128 v[214:217], v148 offset:33792
	global_load_lds_dwordx4 v[218:219], off
	v_lshl_add_u64 v[218:219], v[236:237], 0, s[42:43]
	s_mov_b32 m0, s55
	s_nop 0
	global_load_lds_dwordx4 v[218:219], off
	s_waitcnt lgkmcnt(8)
	s_barrier
	s_waitcnt lgkmcnt(0)
	v_mfma_f32_16x16x32_bf16 v[124:127], v[170:173], v[186:189], v[124:127]
	v_mfma_f32_16x16x32_bf16 v[120:123], v[178:181], v[186:189], v[120:123]
	v_mfma_f32_16x16x32_bf16 v[116:119], v[170:173], v[194:197], v[116:119]
	v_mfma_f32_16x16x32_bf16 v[112:115], v[178:181], v[194:197], v[112:115]
	v_mfma_f32_16x16x32_bf16 v[108:111], v[170:173], v[202:205], v[108:111]
	v_mfma_f32_16x16x32_bf16 v[104:107], v[178:181], v[202:205], v[104:107]
	v_mfma_f32_16x16x32_bf16 v[100:103], v[170:173], v[210:213], v[100:103]
	v_mfma_f32_16x16x32_bf16 v[96:99], v[178:181], v[210:213], v[96:99]
	v_mfma_f32_16x16x32_bf16 v[124:127], v[174:177], v[190:193], v[124:127]
	v_mfma_f32_16x16x32_bf16 v[120:123], v[182:185], v[190:193], v[120:123]
	v_mfma_f32_16x16x32_bf16 v[116:119], v[174:177], v[198:201], v[116:119]
	v_mfma_f32_16x16x32_bf16 v[112:115], v[182:185], v[198:201], v[112:115]
	v_mfma_f32_16x16x32_bf16 v[108:111], v[174:177], v[206:209], v[108:111]
	v_mfma_f32_16x16x32_bf16 v[104:107], v[182:185], v[206:209], v[104:107]
	v_mfma_f32_16x16x32_bf16 v[100:103], v[174:177], v[214:217], v[100:103]
	v_mfma_f32_16x16x32_bf16 v[96:99], v[182:185], v[214:217], v[96:99]
	s_barrier
	v_readfirstlane_b32 s55, v155
	v_add_u32_e32 v244, 0x2000, v155
	v_lshl_add_u64 v[242:243], v[238:239], 0, s[44:45]
	s_mov_b32 m0, s55
	v_readfirstlane_b32 s55, v244
	ds_read_b128 v[218:221], v152
	ds_read_b128 v[222:225], v152 offset:1024
	ds_read_b128 v[226:229], v152 offset:2048
	ds_read_b128 v[230:233], v152 offset:3072
	global_load_lds_dwordx4 v[242:243], off
	v_lshl_add_u64 v[242:243], v[240:241], 0, s[44:45]
	s_mov_b32 m0, s55
	s_nop 0
	global_load_lds_dwordx4 v[242:243], off
	s_barrier
	s_waitcnt lgkmcnt(0)
	v_mfma_f32_16x16x32_bf16 v[92:95], v[218:221], v[186:189], v[92:95]
	v_mfma_f32_16x16x32_bf16 v[88:91], v[226:229], v[186:189], v[88:91]
	v_mfma_f32_16x16x32_bf16 v[84:87], v[218:221], v[194:197], v[84:87]
	v_mfma_f32_16x16x32_bf16 v[80:83], v[226:229], v[194:197], v[80:83]
	v_mfma_f32_16x16x32_bf16 v[76:79], v[218:221], v[202:205], v[76:79]
	v_mfma_f32_16x16x32_bf16 v[72:75], v[226:229], v[202:205], v[72:75]
	v_mfma_f32_16x16x32_bf16 v[68:71], v[218:221], v[210:213], v[68:71]
	v_mfma_f32_16x16x32_bf16 v[64:67], v[226:229], v[210:213], v[64:67]
	v_mfma_f32_16x16x32_bf16 v[92:95], v[222:225], v[190:193], v[92:95]
	v_mfma_f32_16x16x32_bf16 v[88:91], v[230:233], v[190:193], v[88:91]
	v_mfma_f32_16x16x32_bf16 v[84:87], v[222:225], v[198:201], v[84:87]
	v_mfma_f32_16x16x32_bf16 v[80:83], v[230:233], v[198:201], v[80:83]
	v_mfma_f32_16x16x32_bf16 v[76:79], v[222:225], v[206:209], v[76:79]
	v_mfma_f32_16x16x32_bf16 v[72:75], v[230:233], v[206:209], v[72:75]
	v_mfma_f32_16x16x32_bf16 v[68:71], v[222:225], v[214:217], v[68:71]
	v_mfma_f32_16x16x32_bf16 v[64:67], v[230:233], v[214:217], v[64:67]
	s_barrier
	v_readfirstlane_b32 s55, v156
	v_lshl_add_u64 v[234:235], v[234:235], 0, s[46:47]
	s_mov_b32 m0, s55
	v_readfirstlane_b32 s55, v157
	ds_read_b128 v[186:189], v151 offset:49152
	ds_read_b128 v[190:193], v151 offset:50176
	ds_read_b128 v[194:197], v150 offset:49152
	ds_read_b128 v[198:201], v150 offset:50176
	ds_read_b128 v[202:205], v149 offset:49152
	ds_read_b128 v[206:209], v149 offset:50176
	ds_read_b128 v[210:213], v148 offset:49152
	ds_read_b128 v[214:217], v148 offset:50176
	global_load_lds_dwordx4 v[234:235], off
	v_lshl_add_u64 v[234:235], v[236:237], 0, s[46:47]
	s_mov_b32 m0, s55
	s_nop 0
	global_load_lds_dwordx4 v[234:235], off
	s_barrier
; #define STAGE(P, BASE, LD, br, kt) do { const char* _g = (const char*)((BASE) + (size_t)(br) * (LD) + (size_t)(kt) * 64); \
;     for (int _i = 0; _i < 2; ++_i) { int _b = tidx * 16 + _i * 8192; int _r, _c; stage_rc(_b, _r, _c); \
;       __builtin_amdgcn_global_load_lds((const unsigned*)(_g + (unsigned)((_r * (LD) + _c) * 2)), (unsigned*)((char*)(P) + _b), 16, 0, 0); } } while (0)
; #define LDA(dst, b, h) for (int m = 0; m < 4; ++m) for (int k = 0; k < 2; ++k) \
;     dst[m][k] = *reinterpret_cast<const bf16x8*>((char*)SA(b, h) + lds_byte(wr * 64 + m * 16 + fr, k * 32 + fq * 8))
; #define LDB(dst, b, h) for (int n = 0; n < 2; ++n) for (int k = 0; k < 2; ++k) \
;     dst[n][k] = *reinterpret_cast<const bf16x8*>((char*)SB(b, h) + lds_byte(wc * 32 + n * 16 + fr, k * 32 + fq * 8))
; #define MMA(ai, bj, At_, Bt_) do { __builtin_amdgcn_s_setprio(1); \
;     for (int k = 0; k < 2; ++k) for (int m = 0; m < 4; ++m) for (int n = 0; n < 2; ++n) \
;       acc[ai][bj][m][n] = __builtin_amdgcn_mfma_f32_16x16x32_bf16(At_[m][k], Bt_[n][k], acc[ai][bj][m][n], 0, 0, 0); \
;     __builtin_amdgcn_s_setprio(0); } while (0)
; #define WAIT_V(n) asm volatile("s_waitcnt vmcnt(" #n ")" ::: "memory")
; #define WAIT_L(n) asm volatile("s_waitcnt lgkmcnt(" #n ")" ::: "memory")
; #define BAR __builtin_amdgcn_s_barrier()
; #define SCHED __builtin_amdgcn_sched_barrier(0)
; template <int EPI, int lda, int ldb, int N, int K>
; __device__ __forceinline__ void gemm_phase(const u16* __restrict__ A, const u16* __restrict__ Bt, const GemmEpi ep, int wv) {
;     ...
;       BAR; WAIT_L(0); MMA(1, 0, At, B0); BAR; SCHED;
;       STAGE(SB(1, 1), Bt, ldb, bcol + HALF, t + 3);
;       WAIT_V(6); BAR; MMA(1, 1, At, B1); BAR;
;     }
;     { LDB(B0, 0, 0); LDA(At, 0, 0); STAGE(SA(1, 1), Ab, lda, brow + HALF, nt - 1);
;       BAR; WAIT_L(0); MMA(0, 0, At, B0); BAR;
	s_waitcnt lgkmcnt(0)
	v_mfma_f32_16x16x32_bf16 v[60:63], v[170:173], v[186:189], v[60:63]
	v_mfma_f32_16x16x32_bf16 v[56:59], v[178:181], v[186:189], v[56:59]
	v_mfma_f32_16x16x32_bf16 v[52:55], v[170:173], v[194:197], v[52:55]
	v_mfma_f32_16x16x32_bf16 v[48:51], v[178:181], v[194:197], v[48:51]
	v_mfma_f32_16x16x32_bf16 v[44:47], v[170:173], v[202:205], v[44:47]
	v_mfma_f32_16x16x32_bf16 v[40:43], v[178:181], v[202:205], v[40:43]
	v_mfma_f32_16x16x32_bf16 v[36:39], v[170:173], v[210:213], v[36:39]
	v_mfma_f32_16x16x32_bf16 v[32:35], v[178:181], v[210:213], v[32:35]
	v_mfma_f32_16x16x32_bf16 v[60:63], v[174:177], v[190:193], v[60:63]
	v_mfma_f32_16x16x32_bf16 v[56:59], v[182:185], v[190:193], v[56:59]
	v_mfma_f32_16x16x32_bf16 v[52:55], v[174:177], v[198:201], v[52:55]
	v_mfma_f32_16x16x32_bf16 v[48:51], v[182:185], v[198:201], v[48:51]
	v_mfma_f32_16x16x32_bf16 v[44:47], v[174:177], v[206:209], v[44:47]
	v_mfma_f32_16x16x32_bf16 v[40:43], v[182:185], v[206:209], v[40:43]
	v_mfma_f32_16x16x32_bf16 v[36:39], v[174:177], v[214:217], v[36:39]
	v_mfma_f32_16x16x32_bf16 v[32:35], v[182:185], v[214:217], v[32:35]
	s_barrier
	v_readfirstlane_b32 s55, v158
	v_add_u32_e32 v172, 0x2000, v158
	v_lshl_add_u64 v[170:171], v[238:239], 0, s[48:49]
	s_mov_b32 m0, s55
	v_readfirstlane_b32 s55, v172
	global_load_lds_dwordx4 v[170:171], off
	v_lshl_add_u64 v[170:171], v[240:241], 0, s[48:49]
	s_mov_b32 m0, s55
	s_nop 0
	global_load_lds_dwordx4 v[170:171], off
	s_add_i32 s54, s54, 2
	s_add_u32 s52, s52, 0x100
	s_addc_u32 s53, s53, 0
	s_cmp_gt_u32 s54, 27
	s_waitcnt vmcnt(6)
	s_barrier
	v_mfma_f32_16x16x32_bf16 v[28:31], v[218:221], v[186:189], v[28:31]
	v_mfma_f32_16x16x32_bf16 v[24:27], v[226:229], v[186:189], v[24:27]
	v_mfma_f32_16x16x32_bf16 v[20:23], v[218:221], v[194:197], v[20:23]
	v_mfma_f32_16x16x32_bf16 v[16:19], v[226:229], v[194:197], v[16:19]
	v_mfma_f32_16x16x32_bf16 v[12:15], v[218:221], v[202:205], v[12:15]
	v_mfma_f32_16x16x32_bf16 v[8:11], v[226:229], v[202:205], v[8:11]
	v_mfma_f32_16x16x32_bf16 v[4:7], v[218:221], v[210:213], v[4:7]
	v_mfma_f32_16x16x32_bf16 v[0:3], v[226:229], v[210:213], v[0:3]
	v_mfma_f32_16x16x32_bf16 v[28:31], v[222:225], v[190:193], v[28:31]
	v_mfma_f32_16x16x32_bf16 v[24:27], v[230:233], v[190:193], v[24:27]
	v_mfma_f32_16x16x32_bf16 v[20:23], v[222:225], v[198:201], v[20:23]
	v_mfma_f32_16x16x32_bf16 v[16:19], v[230:233], v[198:201], v[16:19]
	v_mfma_f32_16x16x32_bf16 v[12:15], v[222:225], v[206:209], v[12:15]
	v_mfma_f32_16x16x32_bf16 v[8:11], v[230:233], v[206:209], v[8:11]
	v_mfma_f32_16x16x32_bf16 v[4:7], v[222:225], v[214:217], v[4:7]
	v_mfma_f32_16x16x32_bf16 v[0:3], v[230:233], v[214:217], v[0:3]
	s_barrier
	s_cbranch_scc0 .LBB0_654
	s_lshl_b64 s[52:53], s[16:17], 12
	s_add_u32 s52, s14, s52
	s_addc_u32 s53, s15, s53
	s_add_u32 s52, s52, 0x80000
	s_addc_u32 s53, s53, 0
	v_lshl_add_u64 v[156:157], s[52:53], 0, v[128:129]
	v_readfirstlane_b32 s54, v168
	v_lshl_add_u64 v[156:157], v[156:157], 0, s[50:51]
	s_mov_b32 m0, s54
	ds_read_b128 v[134:137], v160
	ds_read_b128 v[138:141], v160 offset:1024
	ds_read_b128 v[170:173], v160 offset:2048
	ds_read_b128 v[174:177], v160 offset:3072
	ds_read_b128 v[178:181], v151
	ds_read_b128 v[182:185], v151 offset:1024
	ds_read_b128 v[186:189], v150
	ds_read_b128 v[190:193], v150 offset:1024
	ds_read_b128 v[194:197], v149
	ds_read_b128 v[198:201], v149 offset:1024
	ds_read_b128 v[202:205], v148
	ds_read_b128 v[206:209], v148 offset:1024
	global_load_lds_dwordx4 v[156:157], off
	v_lshl_add_u64 v[156:157], s[52:53], 0, v[132:133]
	v_readfirstlane_b32 s52, v169
	v_lshl_add_u64 v[156:157], v[156:157], 0, s[50:51]
	s_mov_b32 m0, s52
	s_nop 0
	global_load_lds_dwordx4 v[156:157], off
	s_barrier
	s_waitcnt lgkmcnt(0)
	v_mfma_f32_16x16x32_bf16 v[124:127], v[134:137], v[178:181], v[124:127]
	v_mfma_f32_16x16x32_bf16 v[120:123], v[170:173], v[178:181], v[120:123]
	v_mfma_f32_16x16x32_bf16 v[116:119], v[134:137], v[186:189], v[116:119]
	v_mfma_f32_16x16x32_bf16 v[112:115], v[170:173], v[186:189], v[112:115]
	v_mfma_f32_16x16x32_bf16 v[108:111], v[134:137], v[194:197], v[108:111]
	v_mfma_f32_16x16x32_bf16 v[104:107], v[170:173], v[194:197], v[104:107]
	v_mfma_f32_16x16x32_bf16 v[100:103], v[134:137], v[202:205], v[100:103]
	v_mfma_f32_16x16x32_bf16 v[96:99], v[170:173], v[202:205], v[96:99]
	v_mfma_f32_16x16x32_bf16 v[124:127], v[138:141], v[182:185], v[124:127]
	v_mfma_f32_16x16x32_bf16 v[120:123], v[174:177], v[182:185], v[120:123]
	v_mfma_f32_16x16x32_bf16 v[116:119], v[138:141], v[190:193], v[116:119]
	v_mfma_f32_16x16x32_bf16 v[112:115], v[174:177], v[190:193], v[112:115]
	v_mfma_f32_16x16x32_bf16 v[108:111], v[138:141], v[198:201], v[108:111]
	v_mfma_f32_16x16x32_bf16 v[104:107], v[174:177], v[198:201], v[104:107]
	v_mfma_f32_16x16x32_bf16 v[100:103], v[138:141], v[206:209], v[100:103]
	v_mfma_f32_16x16x32_bf16 v[96:99], v[174:177], v[206:209], v[96:99]
	s_barrier
	ds_read_b128 v[210:213], v159
	ds_read_b128 v[214:217], v159 offset:1024
	ds_read_b128 v[218:221], v159 offset:2048
	ds_read_b128 v[156:159], v159 offset:3072
	s_barrier
; #define LDA(dst, b, h) for (int m = 0; m < 4; ++m) for (int k = 0; k < 2; ++k) \
;     dst[m][k] = *reinterpret_cast<const bf16x8*>((char*)SA(b, h) + lds_byte(wr * 64 + m * 16 + fr, k * 32 + fq * 8))
; #define LDB(dst, b, h) for (int n = 0; n < 2; ++n) for (int k = 0; k < 2; ++k) \
;     dst[n][k] = *reinterpret_cast<const bf16x8*>((char*)SB(b, h) + lds_byte(wc * 32 + n * 16 + fr, k * 32 + fq * 8))
; #define MMA(ai, bj, At_, Bt_) do { __builtin_amdgcn_s_setprio(1); \
;     for (int k = 0; k < 2; ++k) for (int m = 0; m < 4; ++m) for (int n = 0; n < 2; ++n) \
;       acc[ai][bj][m][n] = __builtin_amdgcn_mfma_f32_16x16x32_bf16(At_[m][k], Bt_[n][k], acc[ai][bj][m][n], 0, 0, 0); \
;     __builtin_amdgcn_s_setprio(0); } while (0)
; #define WAIT_V(n) asm volatile("s_waitcnt vmcnt(" #n ")" ::: "memory")
; #define WAIT_L(n) asm volatile("s_waitcnt lgkmcnt(" #n ")" ::: "memory")
; #define BAR __builtin_amdgcn_s_barrier()
; template <int EPI, int lda, int ldb, int N, int K>
; __device__ __forceinline__ void gemm_phase(const u16* __restrict__ A, const u16* __restrict__ Bt, const GemmEpi ep, int wv) {
;     ...
;       LDB(B1, 0, 1); BAR; WAIT_L(0); MMA(0, 1, At, B1); BAR;
;       LDA(At, 0, 1); WAIT_V(4); BAR; WAIT_L(0); MMA(1, 0, At, B0); MMA(1, 1, At, B1); BAR; }
;     { LDB(B0, 1, 0); LDA(At, 1, 0); WAIT_V(2); BAR; WAIT_L(0); MMA(0, 0, At, B0); BAR;
	s_waitcnt lgkmcnt(0)
	v_mfma_f32_16x16x32_bf16 v[92:95], v[210:213], v[178:181], v[92:95]
	v_mfma_f32_16x16x32_bf16 v[88:91], v[218:221], v[178:181], v[88:91]
	v_mfma_f32_16x16x32_bf16 v[76:79], v[210:213], v[194:197], v[76:79]
	v_mfma_f32_16x16x32_bf16 v[72:75], v[218:221], v[194:197], v[72:75]
	v_mfma_f32_16x16x32_bf16 v[84:87], v[210:213], v[186:189], v[84:87]
	v_mfma_f32_16x16x32_bf16 v[80:83], v[218:221], v[186:189], v[80:83]
	v_mfma_f32_16x16x32_bf16 v[68:71], v[210:213], v[202:205], v[68:71]
	v_mfma_f32_16x16x32_bf16 v[64:67], v[218:221], v[202:205], v[64:67]
	v_mfma_f32_16x16x32_bf16 v[92:95], v[214:217], v[182:185], v[92:95]
	v_mfma_f32_16x16x32_bf16 v[88:91], v[156:159], v[182:185], v[88:91]
	v_mfma_f32_16x16x32_bf16 v[76:79], v[214:217], v[198:201], v[76:79]
	v_mfma_f32_16x16x32_bf16 v[72:75], v[156:159], v[198:201], v[72:75]
	v_mfma_f32_16x16x32_bf16 v[178:181], v[214:217], v[190:193], v[84:87]
	v_mfma_f32_16x16x32_bf16 v[182:185], v[156:159], v[190:193], v[80:83]
	v_mfma_f32_16x16x32_bf16 v[186:189], v[214:217], v[206:209], v[68:71]
	v_mfma_f32_16x16x32_bf16 v[190:193], v[156:159], v[206:209], v[64:67]
	s_barrier
	s_nop 0
	ds_read_b128 v[64:67], v151 offset:16384
	ds_read_b128 v[68:71], v151 offset:17408
	ds_read_b128 v[80:83], v150 offset:16384
	ds_read_b128 v[84:87], v150 offset:17408
	ds_read_b128 v[194:197], v149 offset:16384
	ds_read_b128 v[198:201], v149 offset:17408
	ds_read_b128 v[202:205], v148 offset:16384
	ds_read_b128 v[206:209], v148 offset:17408
	s_waitcnt vmcnt(4)
	s_barrier
	s_waitcnt lgkmcnt(0)
	v_mfma_f32_16x16x32_bf16 v[60:63], v[134:137], v[64:67], v[60:63]
	v_mfma_f32_16x16x32_bf16 v[56:59], v[170:173], v[64:67], v[56:59]
	v_mfma_f32_16x16x32_bf16 v[52:55], v[134:137], v[80:83], v[52:55]
	v_mfma_f32_16x16x32_bf16 v[48:51], v[170:173], v[80:83], v[48:51]
	v_mfma_f32_16x16x32_bf16 v[44:47], v[134:137], v[194:197], v[44:47]
	v_mfma_f32_16x16x32_bf16 v[40:43], v[170:173], v[194:197], v[40:43]
	v_mfma_f32_16x16x32_bf16 v[36:39], v[134:137], v[202:205], v[36:39]
	v_mfma_f32_16x16x32_bf16 v[32:35], v[170:173], v[202:205], v[32:35]
	v_mfma_f32_16x16x32_bf16 v[60:63], v[138:141], v[68:71], v[60:63]
	v_mfma_f32_16x16x32_bf16 v[56:59], v[174:177], v[68:71], v[56:59]
	v_mfma_f32_16x16x32_bf16 v[52:55], v[138:141], v[84:87], v[52:55]
	v_mfma_f32_16x16x32_bf16 v[48:51], v[174:177], v[84:87], v[48:51]
	v_mfma_f32_16x16x32_bf16 v[44:47], v[138:141], v[198:201], v[44:47]
	v_mfma_f32_16x16x32_bf16 v[40:43], v[174:177], v[198:201], v[40:43]
	v_mfma_f32_16x16x32_bf16 v[36:39], v[138:141], v[206:209], v[36:39]
	v_mfma_f32_16x16x32_bf16 v[32:35], v[174:177], v[206:209], v[32:35]
	v_mfma_f32_16x16x32_bf16 v[28:31], v[210:213], v[64:67], v[28:31]
	v_mfma_f32_16x16x32_bf16 v[20:23], v[210:213], v[80:83], v[20:23]
	v_mfma_f32_16x16x32_bf16 v[12:15], v[210:213], v[194:197], v[12:15]
	v_mfma_f32_16x16x32_bf16 v[4:7], v[210:213], v[202:205], v[4:7]
	v_mfma_f32_16x16x32_bf16 v[24:27], v[218:221], v[64:67], v[24:27]
	v_mfma_f32_16x16x32_bf16 v[16:19], v[218:221], v[80:83], v[16:19]
	v_mfma_f32_16x16x32_bf16 v[8:11], v[218:221], v[194:197], v[8:11]
	v_mfma_f32_16x16x32_bf16 v[0:3], v[218:221], v[202:205], v[0:3]
	v_mfma_f32_16x16x32_bf16 v[28:31], v[214:217], v[68:71], v[28:31]
	v_mfma_f32_16x16x32_bf16 v[20:23], v[214:217], v[84:87], v[20:23]
	v_mfma_f32_16x16x32_bf16 v[12:15], v[214:217], v[198:201], v[12:15]
	v_mfma_f32_16x16x32_bf16 v[4:7], v[214:217], v[206:209], v[4:7]
	v_mfma_f32_16x16x32_bf16 v[134:137], v[156:159], v[68:71], v[24:27]
	v_mfma_f32_16x16x32_bf16 v[138:141], v[156:159], v[84:87], v[16:19]
	v_mfma_f32_16x16x32_bf16 v[168:171], v[156:159], v[198:201], v[8:11]
	v_mfma_f32_16x16x32_bf16 v[156:159], v[156:159], v[206:209], v[0:3]
	s_barrier
	s_nop 0
	ds_read_b128 v[0:3], v154
	ds_read_b128 v[8:11], v154 offset:1024
	ds_read_b128 v[16:19], v154 offset:2048
	ds_read_b128 v[172:175], v154 offset:3072
	ds_read_b128 v[24:27], v151 offset:32768
	ds_read_b128 v[194:197], v151 offset:33792
	ds_read_b128 v[198:201], v150 offset:32768
	ds_read_b128 v[202:205], v150 offset:33792
	ds_read_b128 v[206:209], v149 offset:32768
	ds_read_b128 v[210:213], v149 offset:33792
	ds_read_b128 v[214:217], v148 offset:32768
	ds_read_b128 v[218:221], v148 offset:33792
	s_waitcnt vmcnt(2)
	s_barrier
; #define LDA(dst, b, h) for (int m = 0; m < 4; ++m) for (int k = 0; k < 2; ++k) \
;     dst[m][k] = *reinterpret_cast<const bf16x8*>((char*)SA(b, h) + lds_byte(wr * 64 + m * 16 + fr, k * 32 + fq * 8))
; #define LDB(dst, b, h) for (int n = 0; n < 2; ++n) for (int k = 0; k < 2; ++k) \
;     dst[n][k] = *reinterpret_cast<const bf16x8*>((char*)SB(b, h) + lds_byte(wc * 32 + n * 16 + fr, k * 32 + fq * 8))
; #define MMA(ai, bj, At_, Bt_) do { __builtin_amdgcn_s_setprio(1); \
;     for (int k = 0; k < 2; ++k) for (int m = 0; m < 4; ++m) for (int n = 0; n < 2; ++n) \
;       acc[ai][bj][m][n] = __builtin_amdgcn_mfma_f32_16x16x32_bf16(At_[m][k], Bt_[n][k], acc[ai][bj][m][n], 0, 0, 0); \
;     __builtin_amdgcn_s_setprio(0); } while (0)
; #define WAIT_V(n) asm volatile("s_waitcnt vmcnt(" #n ")" ::: "memory")
; #define WAIT_L(n) asm volatile("s_waitcnt lgkmcnt(" #n ")" ::: "memory")
; #define BAR __builtin_amdgcn_s_barrier()
; template <int EPI, int lda, int ldb, int N, int K>
; __device__ __forceinline__ void gemm_phase(const u16* __restrict__ A, const u16* __restrict__ Bt, const GemmEpi ep, int wv) {
;     ...
;     { LDB(B0, 1, 0); LDA(At, 1, 0); WAIT_V(2); BAR; WAIT_L(0); MMA(0, 0, At, B0); BAR;
;       LDB(B1, 1, 1); WAIT_V(0); BAR; WAIT_L(0); MMA(0, 1, At, B1); BAR;
;       LDA(At, 1, 1); BAR; WAIT_L(0); MMA(1, 0, At, B0); MMA(1, 1, At, B1); BAR; }
;     if (wr == 0) BAR;
	s_waitcnt lgkmcnt(0)
	v_mfma_f32_16x16x32_bf16 v[64:67], v[0:3], v[24:27], v[124:127]
	v_mfma_f32_16x16x32_bf16 v[68:71], v[16:19], v[24:27], v[120:123]
	v_mfma_f32_16x16x32_bf16 v[80:83], v[0:3], v[198:201], v[116:119]
	v_mfma_f32_16x16x32_bf16 v[84:87], v[16:19], v[198:201], v[112:115]
	v_mfma_f32_16x16x32_bf16 v[108:111], v[0:3], v[206:209], v[108:111]
	v_mfma_f32_16x16x32_bf16 v[104:107], v[16:19], v[206:209], v[104:107]
	v_mfma_f32_16x16x32_bf16 v[120:123], v[0:3], v[214:217], v[100:103]
	v_mfma_f32_16x16x32_bf16 v[124:127], v[16:19], v[214:217], v[96:99]
	v_mfma_f32_16x16x32_bf16 v[116:119], v[8:11], v[194:197], v[64:67]
	v_mfma_f32_16x16x32_bf16 v[112:115], v[172:175], v[194:197], v[68:71]
	v_mfma_f32_16x16x32_bf16 v[100:103], v[8:11], v[202:205], v[80:83]
	v_mfma_f32_16x16x32_bf16 v[96:99], v[172:175], v[202:205], v[84:87]
	v_mfma_f32_16x16x32_bf16 v[84:87], v[8:11], v[210:213], v[108:111]
	v_mfma_f32_16x16x32_bf16 v[80:83], v[172:175], v[210:213], v[104:107]
	v_mfma_f32_16x16x32_bf16 v[68:71], v[8:11], v[218:221], v[120:123]
	v_mfma_f32_16x16x32_bf16 v[64:67], v[172:175], v[218:221], v[124:127]
	s_barrier
	ds_read_b128 v[222:225], v152
	ds_read_b128 v[226:229], v152 offset:1024
	ds_read_b128 v[230:233], v152 offset:2048
	ds_read_b128 v[152:155], v152 offset:3072
	s_waitcnt vmcnt(0)
	s_barrier
	s_waitcnt lgkmcnt(0)
	v_mfma_f32_16x16x32_bf16 v[92:95], v[222:225], v[24:27], v[92:95]
	v_mfma_f32_16x16x32_bf16 v[24:27], v[230:233], v[24:27], v[88:91]
	v_mfma_f32_16x16x32_bf16 v[88:91], v[222:225], v[198:201], v[178:181]
	v_mfma_f32_16x16x32_bf16 v[104:107], v[230:233], v[198:201], v[182:185]
	v_mfma_f32_16x16x32_bf16 v[76:79], v[222:225], v[206:209], v[76:79]
	v_mfma_f32_16x16x32_bf16 v[72:75], v[230:233], v[206:209], v[72:75]
	v_mfma_f32_16x16x32_bf16 v[176:179], v[222:225], v[214:217], v[186:189]
	v_mfma_f32_16x16x32_bf16 v[180:183], v[230:233], v[214:217], v[190:193]
	v_mfma_f32_16x16x32_bf16 v[124:127], v[226:229], v[194:197], v[92:95]
	v_mfma_f32_16x16x32_bf16 v[120:123], v[152:155], v[194:197], v[24:27]
	v_mfma_f32_16x16x32_bf16 v[108:111], v[226:229], v[202:205], v[88:91]
	v_mfma_f32_16x16x32_bf16 v[104:107], v[152:155], v[202:205], v[104:107]
	v_mfma_f32_16x16x32_bf16 v[92:95], v[226:229], v[210:213], v[76:79]
	v_mfma_f32_16x16x32_bf16 v[88:91], v[152:155], v[210:213], v[72:75]
	v_mfma_f32_16x16x32_bf16 v[76:79], v[226:229], v[218:221], v[176:179]
	v_mfma_f32_16x16x32_bf16 v[72:75], v[152:155], v[218:221], v[180:183]
	s_barrier
	ds_read_b128 v[176:179], v151 offset:49152
	ds_read_b128 v[180:183], v151 offset:50176
	ds_read_b128 v[184:187], v150 offset:49152
	ds_read_b128 v[188:191], v150 offset:50176
	ds_read_b128 v[192:195], v149 offset:49152
	ds_read_b128 v[196:199], v149 offset:50176
	ds_read_b128 v[200:203], v148 offset:49152
	ds_read_b128 v[148:151], v148 offset:50176
	s_barrier
	s_waitcnt lgkmcnt(0)
	v_mfma_f32_16x16x32_bf16 v[24:27], v[0:3], v[176:179], v[60:63]
	v_mfma_f32_16x16x32_bf16 v[60:63], v[16:19], v[176:179], v[56:59]
	v_mfma_f32_16x16x32_bf16 v[52:55], v[0:3], v[184:187], v[52:55]
	v_mfma_f32_16x16x32_bf16 v[204:207], v[16:19], v[184:187], v[48:51]
	v_mfma_f32_16x16x32_bf16 v[44:47], v[0:3], v[192:195], v[44:47]
	v_mfma_f32_16x16x32_bf16 v[208:211], v[16:19], v[192:195], v[40:43]
	v_mfma_f32_16x16x32_bf16 v[0:3], v[0:3], v[200:203], v[36:39]
	v_mfma_f32_16x16x32_bf16 v[36:39], v[16:19], v[200:203], v[32:35]
	v_mfma_f32_16x16x32_bf16 v[56:59], v[8:11], v[180:183], v[24:27]
	v_mfma_f32_16x16x32_bf16 v[48:51], v[172:175], v[180:183], v[60:63]
	v_mfma_f32_16x16x32_bf16 v[40:43], v[8:11], v[188:191], v[52:55]
	v_mfma_f32_16x16x32_bf16 v[32:35], v[172:175], v[188:191], v[204:207]
	v_mfma_f32_16x16x32_bf16 v[24:27], v[8:11], v[196:199], v[44:47]
	v_mfma_f32_16x16x32_bf16 v[16:19], v[172:175], v[196:199], v[208:211]
	v_mfma_f32_16x16x32_bf16 v[8:11], v[8:11], v[148:151], v[0:3]
	v_mfma_f32_16x16x32_bf16 v[0:3], v[172:175], v[148:151], v[36:39]
	v_mfma_f32_16x16x32_bf16 v[28:31], v[222:225], v[176:179], v[28:31]
	v_mfma_f32_16x16x32_bf16 v[36:39], v[230:233], v[176:179], v[134:137]
	v_mfma_f32_16x16x32_bf16 v[20:23], v[222:225], v[184:187], v[20:23]
	v_mfma_f32_16x16x32_bf16 v[134:137], v[230:233], v[184:187], v[138:141]
	v_mfma_f32_16x16x32_bf16 v[12:15], v[222:225], v[192:195], v[12:15]
	v_mfma_f32_16x16x32_bf16 v[138:141], v[230:233], v[192:195], v[168:171]
	v_mfma_f32_16x16x32_bf16 v[4:7], v[222:225], v[200:203], v[4:7]
	v_mfma_f32_16x16x32_bf16 v[156:159], v[230:233], v[200:203], v[156:159]
	v_mfma_f32_16x16x32_bf16 v[60:63], v[226:229], v[180:183], v[28:31]
	v_mfma_f32_16x16x32_bf16 v[52:55], v[152:155], v[180:183], v[36:39]
	v_mfma_f32_16x16x32_bf16 v[44:47], v[226:229], v[188:191], v[20:23]
	v_mfma_f32_16x16x32_bf16 v[36:39], v[152:155], v[188:191], v[134:137]
	v_mfma_f32_16x16x32_bf16 v[28:31], v[226:229], v[196:199], v[12:15]
	v_mfma_f32_16x16x32_bf16 v[20:23], v[152:155], v[196:199], v[138:141]
	v_mfma_f32_16x16x32_bf16 v[12:15], v[226:229], v[148:151], v[4:7]
	v_mfma_f32_16x16x32_bf16 v[4:7], v[152:155], v[148:151], v[156:159]
	v_cmp_gt_u32_e32 vcc, s70, v130
	s_barrier
	s_and_saveexec_b64 s[52:53], vcc
	s_cbranch_execz .LBB0_657
	s_barrier

; #define STAGE(P, BASE, LD, br, kt) do { const char* _g = (const char*)((BASE) + (size_t)(br) * (LD) + (size_t)(kt) * 64); \
;     for (int _i = 0; _i < 2; ++_i) { int _b = tidx * 16 + _i * 8192; int _r, _c; stage_rc(_b, _r, _c); \
;       __builtin_amdgcn_global_load_lds((const unsigned*)(_g + (unsigned)((_r * (LD) + _c) * 2)), (unsigned*)((char*)(P) + _b), 16, 0, 0); } } while (0)
; #define LDA(dst, b, h) for (int m = 0; m < 4; ++m) for (int k = 0; k < 2; ++k) \
;     dst[m][k] = *reinterpret_cast<const bf16x8*>((char*)SA(b, h) + lds_byte(wr * 64 + m * 16 + fr, k * 32 + fq * 8))
; #define LDB(dst, b, h) for (int n = 0; n < 2; ++n) for (int k = 0; k < 2; ++k) \
;     dst[n][k] = *reinterpret_cast<const bf16x8*>((char*)SB(b, h) + lds_byte(wc * 32 + n * 16 + fr, k * 32 + fq * 8))
; #define MMA(ai, bj, At_, Bt_) do { __builtin_amdgcn_s_setprio(1); \
;     for (int k = 0; k < 2; ++k) for (int m = 0; m < 4; ++m) for (int n = 0; n < 2; ++n) \
;       acc[ai][bj][m][n] = __builtin_amdgcn_mfma_f32_16x16x32_bf16(At_[m][k], Bt_[n][k], acc[ai][bj][m][n], 0, 0, 0); \
;     __builtin_amdgcn_s_setprio(0); } while (0)
; #define WAIT_L(n) asm volatile("s_waitcnt lgkmcnt(" #n ")" ::: "memory")
; #define BAR __builtin_amdgcn_s_barrier()
; #define SCHED __builtin_amdgcn_sched_barrier(0)
; template <int EPI, int lda, int ldb, int N, int K>
; __device__ __forceinline__ void gemm_phase(const u16* __restrict__ A, const u16* __restrict__ Bt, const GemmEpi ep, int wv) {
;     ...
;     for (int t = 0; t < nt - 2; t += 2) {
;       LDB(B0, 0, 0); SCHED; LDA(At, 0, 0); STAGE(SA(1, 1), Ab, lda, brow + HALF, t + 1);
;       WAIT_L(8); BAR; WAIT_L(0); MMA(0, 0, At, B0); BAR; SCHED;
;       LDB(B1, 0, 1); STAGE(SB(0, 0), Bt, ldb, bcol, t + 2);
;       BAR; WAIT_L(0); MMA(0, 1, At, B1); BAR;
;       LDA(At, 0, 1); STAGE(SA(0, 0), Ab, lda, brow, t + 2);
;       BAR; WAIT_L(0); MMA(1, 0, At, B0); BAR; SCHED;
;       STAGE(SB(0, 1), Bt, ldb, bcol + HALF, t + 2);
.LBB0_770:
	ds_read_b128 v[172:175], v161
	ds_read_b128 v[176:179], v161 offset:1024
	ds_read_b128 v[180:183], v161 offset:2048
	ds_read_b128 v[184:187], v161 offset:3072
	v_add_u32_e32 v169, 0xc000, v148
	v_lshl_add_u64 v[236:237], v[136:137], 0, s[50:51]
	v_readfirstlane_b32 s53, v169
	v_add_u32_e32 v170, 0xe000, v148
	v_lshl_add_u64 v[162:163], v[236:237], 0, s[18:19]
	s_mov_b32 m0, s53
	v_lshl_add_u64 v[238:239], v[134:135], 0, s[50:51]
	v_readfirstlane_b32 s53, v170
	ds_read_b128 v[164:167], v152
	ds_read_b128 v[188:191], v152 offset:1024
	ds_read_b128 v[192:195], v151
	ds_read_b128 v[196:199], v151 offset:1024
	ds_read_b128 v[200:203], v150
	ds_read_b128 v[204:207], v150 offset:1024
	ds_read_b128 v[208:211], v149
	ds_read_b128 v[212:215], v149 offset:1024
	global_load_lds_dwordx4 v[162:163], off
	v_lshl_add_u64 v[162:163], v[238:239], 0, s[18:19]
	s_mov_b32 m0, s53
	s_nop 0
	global_load_lds_dwordx4 v[162:163], off
	s_waitcnt lgkmcnt(8)
	s_barrier
	s_waitcnt lgkmcnt(0)
	v_mfma_f32_16x16x32_bf16 v[124:127], v[172:175], v[164:167], v[124:127]
	v_mfma_f32_16x16x32_bf16 v[120:123], v[180:183], v[164:167], v[120:123]
	v_mfma_f32_16x16x32_bf16 v[116:119], v[172:175], v[192:195], v[116:119]
	v_mfma_f32_16x16x32_bf16 v[112:115], v[180:183], v[192:195], v[112:115]
	v_mfma_f32_16x16x32_bf16 v[108:111], v[172:175], v[200:203], v[108:111]
	v_mfma_f32_16x16x32_bf16 v[104:107], v[180:183], v[200:203], v[104:107]
	v_mfma_f32_16x16x32_bf16 v[100:103], v[172:175], v[208:211], v[100:103]
	v_mfma_f32_16x16x32_bf16 v[96:99], v[180:183], v[208:211], v[96:99]
	v_mfma_f32_16x16x32_bf16 v[124:127], v[176:179], v[188:191], v[124:127]
	v_mfma_f32_16x16x32_bf16 v[120:123], v[184:187], v[188:191], v[120:123]
	v_mfma_f32_16x16x32_bf16 v[116:119], v[176:179], v[196:199], v[116:119]
	v_mfma_f32_16x16x32_bf16 v[112:115], v[184:187], v[196:199], v[112:115]
	v_mfma_f32_16x16x32_bf16 v[108:111], v[176:179], v[204:207], v[108:111]
	v_mfma_f32_16x16x32_bf16 v[104:107], v[184:187], v[204:207], v[104:107]
	v_mfma_f32_16x16x32_bf16 v[100:103], v[176:179], v[212:215], v[100:103]
	v_mfma_f32_16x16x32_bf16 v[96:99], v[184:187], v[212:215], v[96:99]
	s_barrier
	v_add_u32_e32 v162, s64, v153
	v_lshl_add_u64 v[240:241], v[140:141], 0, s[50:51]
	v_readfirstlane_b32 s53, v162
	v_add_u32_e32 v163, 0x2000, v162
	v_lshl_add_u64 v[232:233], v[240:241], 0, s[20:21]
	s_mov_b32 m0, s53
	v_lshl_add_u64 v[242:243], v[138:139], 0, s[50:51]
	v_readfirstlane_b32 s53, v163
	ds_read_b128 v[216:219], v160
	ds_read_b128 v[220:223], v160 offset:1024
	ds_read_b128 v[224:227], v160 offset:2048
	ds_read_b128 v[228:231], v160 offset:3072
	global_load_lds_dwordx4 v[232:233], off
	v_lshl_add_u64 v[232:233], v[242:243], 0, s[20:21]
	s_mov_b32 m0, s53
	s_nop 0
	global_load_lds_dwordx4 v[232:233], off
	s_barrier
	s_waitcnt lgkmcnt(0)
	v_mfma_f32_16x16x32_bf16 v[92:95], v[216:219], v[164:167], v[92:95]
	v_mfma_f32_16x16x32_bf16 v[88:91], v[224:227], v[164:167], v[88:91]
	v_mfma_f32_16x16x32_bf16 v[84:87], v[216:219], v[192:195], v[84:87]
	v_mfma_f32_16x16x32_bf16 v[80:83], v[224:227], v[192:195], v[80:83]
	v_mfma_f32_16x16x32_bf16 v[76:79], v[216:219], v[200:203], v[76:79]
	v_mfma_f32_16x16x32_bf16 v[72:75], v[224:227], v[200:203], v[72:75]
	v_mfma_f32_16x16x32_bf16 v[68:71], v[216:219], v[208:211], v[68:71]
	v_mfma_f32_16x16x32_bf16 v[64:67], v[224:227], v[208:211], v[64:67]
	v_mfma_f32_16x16x32_bf16 v[92:95], v[220:223], v[188:191], v[92:95]
	v_mfma_f32_16x16x32_bf16 v[88:91], v[228:231], v[188:191], v[88:91]
	v_mfma_f32_16x16x32_bf16 v[84:87], v[220:223], v[196:199], v[84:87]
	v_mfma_f32_16x16x32_bf16 v[80:83], v[228:231], v[196:199], v[80:83]
	v_mfma_f32_16x16x32_bf16 v[76:79], v[220:223], v[204:207], v[76:79]
	v_mfma_f32_16x16x32_bf16 v[72:75], v[228:231], v[204:207], v[72:75]
	v_mfma_f32_16x16x32_bf16 v[68:71], v[220:223], v[212:215], v[68:71]
	v_mfma_f32_16x16x32_bf16 v[64:67], v[228:231], v[212:215], v[64:67]
	s_barrier
	v_readfirstlane_b32 s53, v148
	v_lshl_add_u64 v[164:165], v[236:237], 0, s[22:23]
	s_mov_b32 m0, s53
	ds_read_b128 v[188:191], v152 offset:16384
	ds_read_b128 v[192:195], v152 offset:17408
	ds_read_b128 v[196:199], v151 offset:16384
	ds_read_b128 v[200:203], v151 offset:17408
	ds_read_b128 v[204:207], v150 offset:16384
	ds_read_b128 v[208:211], v150 offset:17408
	ds_read_b128 v[212:215], v149 offset:16384
	ds_read_b128 v[232:235], v149 offset:17408
	global_load_lds_dwordx4 v[164:165], off
	v_add_u32_e32 v164, 0x2000, v148
	v_lshl_add_u64 v[166:167], v[238:239], 0, s[22:23]
	v_readfirstlane_b32 s53, v164
	s_mov_b32 m0, s53
	s_nop 0
	global_load_lds_dwordx4 v[166:167], off
	s_barrier
	s_waitcnt lgkmcnt(0)
	v_mfma_f32_16x16x32_bf16 v[60:63], v[172:175], v[188:191], v[60:63]
	v_mfma_f32_16x16x32_bf16 v[56:59], v[180:183], v[188:191], v[56:59]
	v_mfma_f32_16x16x32_bf16 v[52:55], v[172:175], v[196:199], v[52:55]
	v_mfma_f32_16x16x32_bf16 v[48:51], v[180:183], v[196:199], v[48:51]
	v_mfma_f32_16x16x32_bf16 v[44:47], v[172:175], v[204:207], v[44:47]
	v_mfma_f32_16x16x32_bf16 v[40:43], v[180:183], v[204:207], v[40:43]
	v_mfma_f32_16x16x32_bf16 v[36:39], v[172:175], v[212:215], v[36:39]
	v_mfma_f32_16x16x32_bf16 v[32:35], v[180:183], v[212:215], v[32:35]
	v_mfma_f32_16x16x32_bf16 v[60:63], v[176:179], v[192:195], v[60:63]
	v_mfma_f32_16x16x32_bf16 v[56:59], v[184:187], v[192:195], v[56:59]
	v_mfma_f32_16x16x32_bf16 v[52:55], v[176:179], v[200:203], v[52:55]
	v_mfma_f32_16x16x32_bf16 v[48:51], v[184:187], v[200:203], v[48:51]
	v_mfma_f32_16x16x32_bf16 v[44:47], v[176:179], v[208:211], v[44:47]
	v_mfma_f32_16x16x32_bf16 v[40:43], v[184:187], v[208:211], v[40:43]
	v_mfma_f32_16x16x32_bf16 v[36:39], v[176:179], v[232:235], v[36:39]
	v_mfma_f32_16x16x32_bf16 v[32:35], v[184:187], v[232:235], v[32:35]
	s_barrier
; #define STAGE(P, BASE, LD, br, kt) do { const char* _g = (const char*)((BASE) + (size_t)(br) * (LD) + (size_t)(kt) * 64); \
;     for (int _i = 0; _i < 2; ++_i) { int _b = tidx * 16 + _i * 8192; int _r, _c; stage_rc(_b, _r, _c); \
;       __builtin_amdgcn_global_load_lds((const unsigned*)(_g + (unsigned)((_r * (LD) + _c) * 2)), (unsigned*)((char*)(P) + _b), 16, 0, 0); } } while (0)
; #define LDA(dst, b, h) for (int m = 0; m < 4; ++m) for (int k = 0; k < 2; ++k) \
;     dst[m][k] = *reinterpret_cast<const bf16x8*>((char*)SA(b, h) + lds_byte(wr * 64 + m * 16 + fr, k * 32 + fq * 8))
; #define LDB(dst, b, h) for (int n = 0; n < 2; ++n) for (int k = 0; k < 2; ++k) \
;     dst[n][k] = *reinterpret_cast<const bf16x8*>((char*)SB(b, h) + lds_byte(wc * 32 + n * 16 + fr, k * 32 + fq * 8))
; #define MMA(ai, bj, At_, Bt_) do { __builtin_amdgcn_s_setprio(1); \
;     for (int k = 0; k < 2; ++k) for (int m = 0; m < 4; ++m) for (int n = 0; n < 2; ++n) \
;       acc[ai][bj][m][n] = __builtin_amdgcn_mfma_f32_16x16x32_bf16(At_[m][k], Bt_[n][k], acc[ai][bj][m][n], 0, 0, 0); \
;     __builtin_amdgcn_s_setprio(0); } while (0)
; #define WAIT_V(n) asm volatile("s_waitcnt vmcnt(" #n ")" ::: "memory")
; #define WAIT_L(n) asm volatile("s_waitcnt lgkmcnt(" #n ")" ::: "memory")
; #define BAR __builtin_amdgcn_s_barrier()
; #define SCHED __builtin_amdgcn_sched_barrier(0)
; template <int EPI, int lda, int ldb, int N, int K>
; __device__ __forceinline__ void gemm_phase(const u16* __restrict__ A, const u16* __restrict__ Bt, const GemmEpi ep, int wv) {
;     ...
;       STAGE(SB(0, 1), Bt, ldb, bcol + HALF, t + 2);
;       WAIT_V(6); BAR; MMA(1, 1, At, B1); BAR;
;       LDB(B0, 1, 0); SCHED; LDA(At, 1, 0); STAGE(SA(0, 1), Ab, lda, brow + HALF, t + 2);
;       WAIT_L(8); BAR; WAIT_L(0); MMA(0, 0, At, B0); BAR; SCHED;
;       LDB(B1, 1, 1); STAGE(SB(1, 0), Bt, ldb, bcol, t + 3);
;       BAR; WAIT_L(0); MMA(0, 1, At, B1); BAR;
;       LDA(At, 1, 1); STAGE(SA(1, 0), Ab, lda, brow, t + 3);
;       BAR; WAIT_L(0); MMA(1, 0, At, B0); BAR; SCHED;
	v_add_u32_e32 v165, s65, v153
	v_lshl_add_u64 v[166:167], v[240:241], 0, s[24:25]
	v_readfirstlane_b32 s53, v165
	s_mov_b32 m0, s53
	v_lshl_add_u64 v[172:173], v[242:243], 0, s[24:25]
	global_load_lds_dwordx4 v[166:167], off
	v_add_u32_e32 v166, 0x2000, v165
	s_nop 0
	v_readfirstlane_b32 s53, v166
	s_mov_b32 m0, s53
	s_nop 0
	global_load_lds_dwordx4 v[172:173], off
	s_waitcnt vmcnt(6)
	s_barrier
	v_mfma_f32_16x16x32_bf16 v[28:31], v[216:219], v[188:191], v[28:31]
	v_mfma_f32_16x16x32_bf16 v[24:27], v[224:227], v[188:191], v[24:27]
	v_mfma_f32_16x16x32_bf16 v[20:23], v[216:219], v[196:199], v[20:23]
	v_mfma_f32_16x16x32_bf16 v[16:19], v[224:227], v[196:199], v[16:19]
	v_mfma_f32_16x16x32_bf16 v[12:15], v[216:219], v[204:207], v[12:15]
	v_mfma_f32_16x16x32_bf16 v[8:11], v[224:227], v[204:207], v[8:11]
	v_mfma_f32_16x16x32_bf16 v[4:7], v[216:219], v[212:215], v[4:7]
	v_mfma_f32_16x16x32_bf16 v[0:3], v[224:227], v[212:215], v[0:3]
	v_mfma_f32_16x16x32_bf16 v[28:31], v[220:223], v[192:195], v[28:31]
	v_mfma_f32_16x16x32_bf16 v[24:27], v[228:231], v[192:195], v[24:27]
	v_mfma_f32_16x16x32_bf16 v[20:23], v[220:223], v[200:203], v[20:23]
	v_mfma_f32_16x16x32_bf16 v[16:19], v[228:231], v[200:203], v[16:19]
	v_mfma_f32_16x16x32_bf16 v[12:15], v[220:223], v[208:211], v[12:15]
	v_mfma_f32_16x16x32_bf16 v[8:11], v[228:231], v[208:211], v[8:11]
	v_mfma_f32_16x16x32_bf16 v[4:7], v[220:223], v[232:235], v[4:7]
	v_mfma_f32_16x16x32_bf16 v[0:3], v[228:231], v[232:235], v[0:3]
	s_barrier
	ds_read_b128 v[172:175], v156
	ds_read_b128 v[176:179], v156 offset:1024
	ds_read_b128 v[180:183], v156 offset:2048
	ds_read_b128 v[184:187], v156 offset:3072
	v_add_u32_e32 v167, 0x4000, v148
	v_add_u32_e32 v168, 0x6000, v148
	v_readfirstlane_b32 s53, v167
	v_lshl_add_u64 v[220:221], v[236:237], 0, s[26:27]
	s_mov_b32 m0, s53
	v_readfirstlane_b32 s53, v168
	ds_read_b128 v[188:191], v152 offset:32768
	ds_read_b128 v[192:195], v152 offset:33792
	ds_read_b128 v[196:199], v151 offset:32768
	ds_read_b128 v[200:203], v151 offset:33792
	ds_read_b128 v[204:207], v150 offset:32768
	ds_read_b128 v[208:211], v150 offset:33792
	ds_read_b128 v[212:215], v149 offset:32768
	ds_read_b128 v[216:219], v149 offset:33792
	global_load_lds_dwordx4 v[220:221], off
	v_lshl_add_u64 v[220:221], v[238:239], 0, s[26:27]
	s_mov_b32 m0, s53
	s_nop 0
	global_load_lds_dwordx4 v[220:221], off
	s_waitcnt lgkmcnt(8)
	s_barrier
	s_waitcnt lgkmcnt(0)
	v_mfma_f32_16x16x32_bf16 v[124:127], v[172:175], v[188:191], v[124:127]
	v_mfma_f32_16x16x32_bf16 v[120:123], v[180:183], v[188:191], v[120:123]
	v_mfma_f32_16x16x32_bf16 v[116:119], v[172:175], v[196:199], v[116:119]
	v_mfma_f32_16x16x32_bf16 v[112:115], v[180:183], v[196:199], v[112:115]
	v_mfma_f32_16x16x32_bf16 v[108:111], v[172:175], v[204:207], v[108:111]
	v_mfma_f32_16x16x32_bf16 v[104:107], v[180:183], v[204:207], v[104:107]
	v_mfma_f32_16x16x32_bf16 v[100:103], v[172:175], v[212:215], v[100:103]
	v_mfma_f32_16x16x32_bf16 v[96:99], v[180:183], v[212:215], v[96:99]
	v_mfma_f32_16x16x32_bf16 v[124:127], v[176:179], v[192:195], v[124:127]
	v_mfma_f32_16x16x32_bf16 v[120:123], v[184:187], v[192:195], v[120:123]
	v_mfma_f32_16x16x32_bf16 v[116:119], v[176:179], v[200:203], v[116:119]
	v_mfma_f32_16x16x32_bf16 v[112:115], v[184:187], v[200:203], v[112:115]
	v_mfma_f32_16x16x32_bf16 v[108:111], v[176:179], v[208:211], v[108:111]
	v_mfma_f32_16x16x32_bf16 v[104:107], v[184:187], v[208:211], v[104:107]
	v_mfma_f32_16x16x32_bf16 v[100:103], v[176:179], v[216:219], v[100:103]
	v_mfma_f32_16x16x32_bf16 v[96:99], v[184:187], v[216:219], v[96:99]
	s_barrier
	v_readfirstlane_b32 s53, v155
	v_add_u32_e32 v171, 0x2000, v155
	v_lshl_add_u64 v[244:245], v[240:241], 0, s[40:41]
	s_mov_b32 m0, s53
	v_readfirstlane_b32 s53, v171
	ds_read_b128 v[220:223], v154
	ds_read_b128 v[224:227], v154 offset:1024
	ds_read_b128 v[228:231], v154 offset:2048
	ds_read_b128 v[232:235], v154 offset:3072
	global_load_lds_dwordx4 v[244:245], off
	v_lshl_add_u64 v[244:245], v[242:243], 0, s[40:41]
	s_mov_b32 m0, s53
	s_nop 0
	global_load_lds_dwordx4 v[244:245], off
	s_barrier
	s_waitcnt lgkmcnt(0)
	v_mfma_f32_16x16x32_bf16 v[92:95], v[220:223], v[188:191], v[92:95]
	v_mfma_f32_16x16x32_bf16 v[88:91], v[228:231], v[188:191], v[88:91]
	v_mfma_f32_16x16x32_bf16 v[84:87], v[220:223], v[196:199], v[84:87]
	v_mfma_f32_16x16x32_bf16 v[80:83], v[228:231], v[196:199], v[80:83]
	v_mfma_f32_16x16x32_bf16 v[76:79], v[220:223], v[204:207], v[76:79]
	v_mfma_f32_16x16x32_bf16 v[72:75], v[228:231], v[204:207], v[72:75]
	v_mfma_f32_16x16x32_bf16 v[68:71], v[220:223], v[212:215], v[68:71]
	v_mfma_f32_16x16x32_bf16 v[64:67], v[228:231], v[212:215], v[64:67]
	v_mfma_f32_16x16x32_bf16 v[92:95], v[224:227], v[192:195], v[92:95]
	v_mfma_f32_16x16x32_bf16 v[88:91], v[232:235], v[192:195], v[88:91]
	v_mfma_f32_16x16x32_bf16 v[84:87], v[224:227], v[200:203], v[84:87]
	v_mfma_f32_16x16x32_bf16 v[80:83], v[232:235], v[200:203], v[80:83]
	v_mfma_f32_16x16x32_bf16 v[76:79], v[224:227], v[208:211], v[76:79]
	v_mfma_f32_16x16x32_bf16 v[72:75], v[232:235], v[208:211], v[72:75]
	v_mfma_f32_16x16x32_bf16 v[68:71], v[224:227], v[216:219], v[68:71]
	v_mfma_f32_16x16x32_bf16 v[64:67], v[232:235], v[216:219], v[64:67]
	s_barrier
	v_readfirstlane_b32 s53, v157
	v_lshl_add_u64 v[236:237], v[236:237], 0, s[42:43]
	s_mov_b32 m0, s53
	v_readfirstlane_b32 s53, v158
	ds_read_b128 v[188:191], v152 offset:49152
	ds_read_b128 v[192:195], v152 offset:50176
	ds_read_b128 v[196:199], v151 offset:49152
	ds_read_b128 v[200:203], v151 offset:50176
	ds_read_b128 v[204:207], v150 offset:49152
	ds_read_b128 v[208:211], v150 offset:50176
	ds_read_b128 v[212:215], v149 offset:49152
	ds_read_b128 v[216:219], v149 offset:50176
	global_load_lds_dwordx4 v[236:237], off
	v_lshl_add_u64 v[236:237], v[238:239], 0, s[42:43]
	s_mov_b32 m0, s53
	s_nop 0
	global_load_lds_dwordx4 v[236:237], off
	s_barrier
; #define STAGE(P, BASE, LD, br, kt) do { const char* _g = (const char*)((BASE) + (size_t)(br) * (LD) + (size_t)(kt) * 64); \
;     for (int _i = 0; _i < 2; ++_i) { int _b = tidx * 16 + _i * 8192; int _r, _c; stage_rc(_b, _r, _c); \
;       __builtin_amdgcn_global_load_lds((const unsigned*)(_g + (unsigned)((_r * (LD) + _c) * 2)), (unsigned*)((char*)(P) + _b), 16, 0, 0); } } while (0)
; #define LDA(dst, b, h) for (int m = 0; m < 4; ++m) for (int k = 0; k < 2; ++k) \
;     dst[m][k] = *reinterpret_cast<const bf16x8*>((char*)SA(b, h) + lds_byte(wr * 64 + m * 16 + fr, k * 32 + fq * 8))
; #define LDB(dst, b, h) for (int n = 0; n < 2; ++n) for (int k = 0; k < 2; ++k) \
;     dst[n][k] = *reinterpret_cast<const bf16x8*>((char*)SB(b, h) + lds_byte(wc * 32 + n * 16 + fr, k * 32 + fq * 8))
; #define MMA(ai, bj, At_, Bt_) do { __builtin_amdgcn_s_setprio(1); \
;     for (int k = 0; k < 2; ++k) for (int m = 0; m < 4; ++m) for (int n = 0; n < 2; ++n) \
;       acc[ai][bj][m][n] = __builtin_amdgcn_mfma_f32_16x16x32_bf16(At_[m][k], Bt_[n][k], acc[ai][bj][m][n], 0, 0, 0); \
;     __builtin_amdgcn_s_setprio(0); } while (0)
; #define WAIT_V(n) asm volatile("s_waitcnt vmcnt(" #n ")" ::: "memory")
; #define WAIT_L(n) asm volatile("s_waitcnt lgkmcnt(" #n ")" ::: "memory")
; #define BAR __builtin_amdgcn_s_barrier()
; #define SCHED __builtin_amdgcn_sched_barrier(0)
; template <int EPI, int lda, int ldb, int N, int K>
; __device__ __forceinline__ void gemm_phase(const u16* __restrict__ A, const u16* __restrict__ Bt, const GemmEpi ep, int wv) {
;     ...
;       BAR; WAIT_L(0); MMA(1, 0, At, B0); BAR; SCHED;
;       STAGE(SB(1, 1), Bt, ldb, bcol + HALF, t + 3);
;       WAIT_V(6); BAR; MMA(1, 1, At, B1); BAR;
;     }
;     { LDB(B0, 0, 0); LDA(At, 0, 0); STAGE(SA(1, 1), Ab, lda, brow + HALF, nt - 1);
;       BAR; WAIT_L(0); MMA(0, 0, At, B0); BAR;
	s_waitcnt lgkmcnt(0)
	v_mfma_f32_16x16x32_bf16 v[60:63], v[172:175], v[188:191], v[60:63]
	v_mfma_f32_16x16x32_bf16 v[56:59], v[180:183], v[188:191], v[56:59]
	v_mfma_f32_16x16x32_bf16 v[52:55], v[172:175], v[196:199], v[52:55]
	v_mfma_f32_16x16x32_bf16 v[48:51], v[180:183], v[196:199], v[48:51]
	v_mfma_f32_16x16x32_bf16 v[44:47], v[172:175], v[204:207], v[44:47]
	v_mfma_f32_16x16x32_bf16 v[40:43], v[180:183], v[204:207], v[40:43]
	v_mfma_f32_16x16x32_bf16 v[36:39], v[172:175], v[212:215], v[36:39]
	v_mfma_f32_16x16x32_bf16 v[32:35], v[180:183], v[212:215], v[32:35]
	v_mfma_f32_16x16x32_bf16 v[60:63], v[176:179], v[192:195], v[60:63]
	v_mfma_f32_16x16x32_bf16 v[56:59], v[184:187], v[192:195], v[56:59]
	v_mfma_f32_16x16x32_bf16 v[52:55], v[176:179], v[200:203], v[52:55]
	v_mfma_f32_16x16x32_bf16 v[48:51], v[184:187], v[200:203], v[48:51]
	v_mfma_f32_16x16x32_bf16 v[44:47], v[176:179], v[208:211], v[44:47]
	v_mfma_f32_16x16x32_bf16 v[40:43], v[184:187], v[208:211], v[40:43]
	v_mfma_f32_16x16x32_bf16 v[36:39], v[176:179], v[216:219], v[36:39]
	v_mfma_f32_16x16x32_bf16 v[32:35], v[184:187], v[216:219], v[32:35]
	s_barrier
	v_readfirstlane_b32 s53, v159
	v_add_u32_e32 v171, 0x2000, v159
	v_lshl_add_u64 v[172:173], v[240:241], 0, s[44:45]
	s_mov_b32 m0, s53
	v_readfirstlane_b32 s53, v171
	global_load_lds_dwordx4 v[172:173], off
	v_lshl_add_u64 v[172:173], v[242:243], 0, s[44:45]
	s_mov_b32 m0, s53
	s_nop 0
	global_load_lds_dwordx4 v[172:173], off
	s_add_i32 s52, s52, 2
	s_add_u32 s50, s50, 0x100
	s_addc_u32 s51, s51, 0
	s_cmp_gt_u32 s52, 27
	s_waitcnt vmcnt(6)
	s_barrier
	v_mfma_f32_16x16x32_bf16 v[28:31], v[220:223], v[188:191], v[28:31]
	v_mfma_f32_16x16x32_bf16 v[24:27], v[228:231], v[188:191], v[24:27]
	v_mfma_f32_16x16x32_bf16 v[20:23], v[220:223], v[196:199], v[20:23]
	v_mfma_f32_16x16x32_bf16 v[16:19], v[228:231], v[196:199], v[16:19]
	v_mfma_f32_16x16x32_bf16 v[12:15], v[220:223], v[204:207], v[12:15]
	v_mfma_f32_16x16x32_bf16 v[8:11], v[228:231], v[204:207], v[8:11]
	v_mfma_f32_16x16x32_bf16 v[4:7], v[220:223], v[212:215], v[4:7]
	v_mfma_f32_16x16x32_bf16 v[0:3], v[228:231], v[212:215], v[0:3]
	v_mfma_f32_16x16x32_bf16 v[28:31], v[224:227], v[192:195], v[28:31]
	v_mfma_f32_16x16x32_bf16 v[24:27], v[232:235], v[192:195], v[24:27]
	v_mfma_f32_16x16x32_bf16 v[20:23], v[224:227], v[200:203], v[20:23]
	v_mfma_f32_16x16x32_bf16 v[16:19], v[232:235], v[200:203], v[16:19]
	v_mfma_f32_16x16x32_bf16 v[12:15], v[224:227], v[208:211], v[12:15]
	v_mfma_f32_16x16x32_bf16 v[8:11], v[232:235], v[208:211], v[8:11]
	v_mfma_f32_16x16x32_bf16 v[4:7], v[224:227], v[216:219], v[4:7]
	v_mfma_f32_16x16x32_bf16 v[0:3], v[232:235], v[216:219], v[0:3]
	s_barrier
	s_cbranch_scc0 .LBB0_770
	s_add_i32 s50, s48, 0x80
	s_mul_hi_i32 s51, s50, 0x1080
	s_mulk_i32 s50, 0x1080
	s_add_u32 s50, s61, s50
	s_addc_u32 s51, s62, s51
	v_lshl_add_u64 v[158:159], s[50:51], 0, v[128:129]
	v_readfirstlane_b32 s52, v169
	v_lshl_add_u64 v[158:159], v[158:159], 0, s[46:47]
	s_mov_b32 m0, s52
	ds_read_b128 v[134:137], v161
	ds_read_b128 v[138:141], v161 offset:1024
	ds_read_b128 v[172:175], v161 offset:2048
	ds_read_b128 v[176:179], v161 offset:3072
	ds_read_b128 v[180:183], v152
	ds_read_b128 v[184:187], v152 offset:1024
	ds_read_b128 v[188:191], v151
	ds_read_b128 v[192:195], v151 offset:1024
	ds_read_b128 v[196:199], v150
	ds_read_b128 v[200:203], v150 offset:1024
	ds_read_b128 v[204:207], v149
	ds_read_b128 v[208:211], v149 offset:1024
	global_load_lds_dwordx4 v[158:159], off
	v_lshl_add_u64 v[158:159], s[50:51], 0, v[132:133]
	v_readfirstlane_b32 s50, v170
	v_lshl_add_u64 v[158:159], v[158:159], 0, s[46:47]
	s_mov_b32 m0, s50
	s_nop 0
	global_load_lds_dwordx4 v[158:159], off
	s_barrier
	s_waitcnt lgkmcnt(0)
	v_mfma_f32_16x16x32_bf16 v[124:127], v[134:137], v[180:183], v[124:127]
	v_mfma_f32_16x16x32_bf16 v[120:123], v[172:175], v[180:183], v[120:123]
	v_mfma_f32_16x16x32_bf16 v[116:119], v[134:137], v[188:191], v[116:119]
	v_mfma_f32_16x16x32_bf16 v[112:115], v[172:175], v[188:191], v[112:115]
	v_mfma_f32_16x16x32_bf16 v[108:111], v[134:137], v[196:199], v[108:111]
	v_mfma_f32_16x16x32_bf16 v[104:107], v[172:175], v[196:199], v[104:107]
	v_mfma_f32_16x16x32_bf16 v[100:103], v[134:137], v[204:207], v[100:103]
	v_mfma_f32_16x16x32_bf16 v[96:99], v[172:175], v[204:207], v[96:99]
	v_mfma_f32_16x16x32_bf16 v[124:127], v[138:141], v[184:187], v[124:127]
	v_mfma_f32_16x16x32_bf16 v[120:123], v[176:179], v[184:187], v[120:123]
	v_mfma_f32_16x16x32_bf16 v[116:119], v[138:141], v[192:195], v[116:119]
	v_mfma_f32_16x16x32_bf16 v[112:115], v[176:179], v[192:195], v[112:115]
	v_mfma_f32_16x16x32_bf16 v[108:111], v[138:141], v[200:203], v[108:111]
	v_mfma_f32_16x16x32_bf16 v[104:107], v[176:179], v[200:203], v[104:107]
	v_mfma_f32_16x16x32_bf16 v[100:103], v[138:141], v[208:211], v[100:103]
	v_mfma_f32_16x16x32_bf16 v[96:99], v[176:179], v[208:211], v[96:99]
	s_barrier
	ds_read_b128 v[212:215], v160
	ds_read_b128 v[216:219], v160 offset:1024
	ds_read_b128 v[220:223], v160 offset:2048
	ds_read_b128 v[158:161], v160 offset:3072
	s_barrier
; #define LDA(dst, b, h) for (int m = 0; m < 4; ++m) for (int k = 0; k < 2; ++k) \
;     dst[m][k] = *reinterpret_cast<const bf16x8*>((char*)SA(b, h) + lds_byte(wr * 64 + m * 16 + fr, k * 32 + fq * 8))
; #define LDB(dst, b, h) for (int n = 0; n < 2; ++n) for (int k = 0; k < 2; ++k) \
;     dst[n][k] = *reinterpret_cast<const bf16x8*>((char*)SB(b, h) + lds_byte(wc * 32 + n * 16 + fr, k * 32 + fq * 8))
; #define MMA(ai, bj, At_, Bt_) do { __builtin_amdgcn_s_setprio(1); \
;     for (int k = 0; k < 2; ++k) for (int m = 0; m < 4; ++m) for (int n = 0; n < 2; ++n) \
;       acc[ai][bj][m][n] = __builtin_amdgcn_mfma_f32_16x16x32_bf16(At_[m][k], Bt_[n][k], acc[ai][bj][m][n], 0, 0, 0); \
;     __builtin_amdgcn_s_setprio(0); } while (0)
; #define WAIT_V(n) asm volatile("s_waitcnt vmcnt(" #n ")" ::: "memory")
; #define WAIT_L(n) asm volatile("s_waitcnt lgkmcnt(" #n ")" ::: "memory")
; #define BAR __builtin_amdgcn_s_barrier()
; template <int EPI, int lda, int ldb, int N, int K>
; __device__ __forceinline__ void gemm_phase(const u16* __restrict__ A, const u16* __restrict__ Bt, const GemmEpi ep, int wv) {
;     ...
;       LDB(B1, 0, 1); BAR; WAIT_L(0); MMA(0, 1, At, B1); BAR;
;       LDA(At, 0, 1); WAIT_V(4); BAR; WAIT_L(0); MMA(1, 0, At, B0); MMA(1, 1, At, B1); BAR; }
;     { LDB(B0, 1, 0); LDA(At, 1, 0); WAIT_V(2); BAR; WAIT_L(0); MMA(0, 0, At, B0); BAR;
	s_waitcnt lgkmcnt(0)
	v_mfma_f32_16x16x32_bf16 v[92:95], v[212:215], v[180:183], v[92:95]
	v_mfma_f32_16x16x32_bf16 v[88:91], v[220:223], v[180:183], v[88:91]
	v_mfma_f32_16x16x32_bf16 v[76:79], v[212:215], v[196:199], v[76:79]
	v_mfma_f32_16x16x32_bf16 v[72:75], v[220:223], v[196:199], v[72:75]
	v_mfma_f32_16x16x32_bf16 v[84:87], v[212:215], v[188:191], v[84:87]
	v_mfma_f32_16x16x32_bf16 v[80:83], v[220:223], v[188:191], v[80:83]
	v_mfma_f32_16x16x32_bf16 v[68:71], v[212:215], v[204:207], v[68:71]
	v_mfma_f32_16x16x32_bf16 v[64:67], v[220:223], v[204:207], v[64:67]
	v_mfma_f32_16x16x32_bf16 v[92:95], v[216:219], v[184:187], v[92:95]
	v_mfma_f32_16x16x32_bf16 v[88:91], v[158:161], v[184:187], v[88:91]
	v_mfma_f32_16x16x32_bf16 v[76:79], v[216:219], v[200:203], v[76:79]
	v_mfma_f32_16x16x32_bf16 v[72:75], v[158:161], v[200:203], v[72:75]
	v_mfma_f32_16x16x32_bf16 v[180:183], v[216:219], v[192:195], v[84:87]
	v_mfma_f32_16x16x32_bf16 v[184:187], v[158:161], v[192:195], v[80:83]
	v_mfma_f32_16x16x32_bf16 v[188:191], v[216:219], v[208:211], v[68:71]
	v_mfma_f32_16x16x32_bf16 v[192:195], v[158:161], v[208:211], v[64:67]
	s_barrier
	s_nop 0
	ds_read_b128 v[64:67], v152 offset:16384
	ds_read_b128 v[68:71], v152 offset:17408
	ds_read_b128 v[80:83], v151 offset:16384
	ds_read_b128 v[84:87], v151 offset:17408
	ds_read_b128 v[196:199], v150 offset:16384
	ds_read_b128 v[200:203], v150 offset:17408
	ds_read_b128 v[204:207], v149 offset:16384
	ds_read_b128 v[208:211], v149 offset:17408
	s_waitcnt vmcnt(4)
	s_barrier
	s_waitcnt lgkmcnt(0)
	v_mfma_f32_16x16x32_bf16 v[60:63], v[134:137], v[64:67], v[60:63]
	v_mfma_f32_16x16x32_bf16 v[56:59], v[172:175], v[64:67], v[56:59]
	v_mfma_f32_16x16x32_bf16 v[52:55], v[134:137], v[80:83], v[52:55]
	v_mfma_f32_16x16x32_bf16 v[48:51], v[172:175], v[80:83], v[48:51]
	v_mfma_f32_16x16x32_bf16 v[44:47], v[134:137], v[196:199], v[44:47]
	v_mfma_f32_16x16x32_bf16 v[40:43], v[172:175], v[196:199], v[40:43]
	v_mfma_f32_16x16x32_bf16 v[36:39], v[134:137], v[204:207], v[36:39]
	v_mfma_f32_16x16x32_bf16 v[32:35], v[172:175], v[204:207], v[32:35]
	v_mfma_f32_16x16x32_bf16 v[60:63], v[138:141], v[68:71], v[60:63]
	v_mfma_f32_16x16x32_bf16 v[56:59], v[176:179], v[68:71], v[56:59]
	v_mfma_f32_16x16x32_bf16 v[52:55], v[138:141], v[84:87], v[52:55]
	v_mfma_f32_16x16x32_bf16 v[48:51], v[176:179], v[84:87], v[48:51]
	v_mfma_f32_16x16x32_bf16 v[44:47], v[138:141], v[200:203], v[44:47]
	v_mfma_f32_16x16x32_bf16 v[40:43], v[176:179], v[200:203], v[40:43]
	v_mfma_f32_16x16x32_bf16 v[36:39], v[138:141], v[208:211], v[36:39]
	v_mfma_f32_16x16x32_bf16 v[32:35], v[176:179], v[208:211], v[32:35]
	v_mfma_f32_16x16x32_bf16 v[28:31], v[212:215], v[64:67], v[28:31]
	v_mfma_f32_16x16x32_bf16 v[24:27], v[220:223], v[64:67], v[24:27]
	v_mfma_f32_16x16x32_bf16 v[12:15], v[212:215], v[196:199], v[12:15]
	v_mfma_f32_16x16x32_bf16 v[8:11], v[220:223], v[196:199], v[8:11]
	v_mfma_f32_16x16x32_bf16 v[20:23], v[212:215], v[80:83], v[20:23]
	v_mfma_f32_16x16x32_bf16 v[16:19], v[220:223], v[80:83], v[16:19]
	v_mfma_f32_16x16x32_bf16 v[4:7], v[212:215], v[204:207], v[4:7]
	v_mfma_f32_16x16x32_bf16 v[0:3], v[220:223], v[204:207], v[0:3]
	v_mfma_f32_16x16x32_bf16 v[28:31], v[216:219], v[68:71], v[28:31]
	v_mfma_f32_16x16x32_bf16 v[24:27], v[158:161], v[68:71], v[24:27]
	v_mfma_f32_16x16x32_bf16 v[12:15], v[216:219], v[200:203], v[12:15]
	v_mfma_f32_16x16x32_bf16 v[8:11], v[158:161], v[200:203], v[8:11]
	v_mfma_f32_16x16x32_bf16 v[134:137], v[216:219], v[84:87], v[20:23]
	v_mfma_f32_16x16x32_bf16 v[138:141], v[158:161], v[84:87], v[16:19]
	v_mfma_f32_16x16x32_bf16 v[170:173], v[216:219], v[208:211], v[4:7]
	v_mfma_f32_16x16x32_bf16 v[158:161], v[158:161], v[208:211], v[0:3]
	s_barrier
	s_nop 0
	ds_read_b128 v[0:3], v156
	ds_read_b128 v[4:7], v156 offset:1024
	ds_read_b128 v[16:19], v156 offset:2048
	ds_read_b128 v[174:177], v156 offset:3072
	ds_read_b128 v[20:23], v152 offset:32768
	ds_read_b128 v[196:199], v152 offset:33792
	ds_read_b128 v[200:203], v151 offset:32768
	ds_read_b128 v[204:207], v151 offset:33792
	ds_read_b128 v[208:211], v150 offset:32768
	ds_read_b128 v[212:215], v150 offset:33792
	ds_read_b128 v[216:219], v149 offset:32768
	ds_read_b128 v[220:223], v149 offset:33792
	s_waitcnt vmcnt(2)
	s_barrier
; #define LDA(dst, b, h) for (int m = 0; m < 4; ++m) for (int k = 0; k < 2; ++k) \
;     dst[m][k] = *reinterpret_cast<const bf16x8*>((char*)SA(b, h) + lds_byte(wr * 64 + m * 16 + fr, k * 32 + fq * 8))
; #define LDB(dst, b, h) for (int n = 0; n < 2; ++n) for (int k = 0; k < 2; ++k) \
;     dst[n][k] = *reinterpret_cast<const bf16x8*>((char*)SB(b, h) + lds_byte(wc * 32 + n * 16 + fr, k * 32 + fq * 8))
; #define MMA(ai, bj, At_, Bt_) do { __builtin_amdgcn_s_setprio(1); \
;     for (int k = 0; k < 2; ++k) for (int m = 0; m < 4; ++m) for (int n = 0; n < 2; ++n) \
;       acc[ai][bj][m][n] = __builtin_amdgcn_mfma_f32_16x16x32_bf16(At_[m][k], Bt_[n][k], acc[ai][bj][m][n], 0, 0, 0); \
;     __builtin_amdgcn_s_setprio(0); } while (0)
; #define WAIT_V(n) asm volatile("s_waitcnt vmcnt(" #n ")" ::: "memory")
; #define WAIT_L(n) asm volatile("s_waitcnt lgkmcnt(" #n ")" ::: "memory")
; #define BAR __builtin_amdgcn_s_barrier()
; template <int EPI, int lda, int ldb, int N, int K>
; __device__ __forceinline__ void gemm_phase(const u16* __restrict__ A, const u16* __restrict__ Bt, const GemmEpi ep, int wv) {
;     ...
;     { LDB(B0, 1, 0); LDA(At, 1, 0); WAIT_V(2); BAR; WAIT_L(0); MMA(0, 0, At, B0); BAR;
;       LDB(B1, 1, 1); WAIT_V(0); BAR; WAIT_L(0); MMA(0, 1, At, B1); BAR;
;       LDA(At, 1, 1); BAR; WAIT_L(0); MMA(1, 0, At, B0); MMA(1, 1, At, B1); BAR; }
;     if (wr == 0) BAR;
	s_waitcnt lgkmcnt(0)
	v_mfma_f32_16x16x32_bf16 v[64:67], v[0:3], v[20:23], v[124:127]
	v_mfma_f32_16x16x32_bf16 v[68:71], v[16:19], v[20:23], v[120:123]
	v_mfma_f32_16x16x32_bf16 v[80:83], v[0:3], v[200:203], v[116:119]
	v_mfma_f32_16x16x32_bf16 v[84:87], v[16:19], v[200:203], v[112:115]
	v_mfma_f32_16x16x32_bf16 v[108:111], v[0:3], v[208:211], v[108:111]
	v_mfma_f32_16x16x32_bf16 v[104:107], v[16:19], v[208:211], v[104:107]
	v_mfma_f32_16x16x32_bf16 v[120:123], v[0:3], v[216:219], v[100:103]
	v_mfma_f32_16x16x32_bf16 v[124:127], v[16:19], v[216:219], v[96:99]
	v_mfma_f32_16x16x32_bf16 v[116:119], v[4:7], v[196:199], v[64:67]
	v_mfma_f32_16x16x32_bf16 v[112:115], v[174:177], v[196:199], v[68:71]
	v_mfma_f32_16x16x32_bf16 v[100:103], v[4:7], v[204:207], v[80:83]
	v_mfma_f32_16x16x32_bf16 v[96:99], v[174:177], v[204:207], v[84:87]
	v_mfma_f32_16x16x32_bf16 v[84:87], v[4:7], v[212:215], v[108:111]
	v_mfma_f32_16x16x32_bf16 v[80:83], v[174:177], v[212:215], v[104:107]
	v_mfma_f32_16x16x32_bf16 v[68:71], v[4:7], v[220:223], v[120:123]
	v_mfma_f32_16x16x32_bf16 v[64:67], v[174:177], v[220:223], v[124:127]
	s_barrier
	ds_read_b128 v[224:227], v154
	ds_read_b128 v[228:231], v154 offset:1024
	ds_read_b128 v[232:235], v154 offset:2048
	ds_read_b128 v[154:157], v154 offset:3072
	s_waitcnt vmcnt(0)
	s_barrier
	s_waitcnt lgkmcnt(0)
	v_mfma_f32_16x16x32_bf16 v[92:95], v[224:227], v[20:23], v[92:95]
	v_mfma_f32_16x16x32_bf16 v[20:23], v[232:235], v[20:23], v[88:91]
	v_mfma_f32_16x16x32_bf16 v[88:91], v[224:227], v[200:203], v[180:183]
	v_mfma_f32_16x16x32_bf16 v[104:107], v[232:235], v[200:203], v[184:187]
	v_mfma_f32_16x16x32_bf16 v[76:79], v[224:227], v[208:211], v[76:79]
	v_mfma_f32_16x16x32_bf16 v[72:75], v[232:235], v[208:211], v[72:75]
	v_mfma_f32_16x16x32_bf16 v[178:181], v[224:227], v[216:219], v[188:191]
	v_mfma_f32_16x16x32_bf16 v[182:185], v[232:235], v[216:219], v[192:195]
	v_mfma_f32_16x16x32_bf16 v[124:127], v[228:231], v[196:199], v[92:95]
	v_mfma_f32_16x16x32_bf16 v[120:123], v[154:157], v[196:199], v[20:23]
	v_mfma_f32_16x16x32_bf16 v[108:111], v[228:231], v[204:207], v[88:91]
	v_mfma_f32_16x16x32_bf16 v[104:107], v[154:157], v[204:207], v[104:107]
	v_mfma_f32_16x16x32_bf16 v[92:95], v[228:231], v[212:215], v[76:79]
	v_mfma_f32_16x16x32_bf16 v[88:91], v[154:157], v[212:215], v[72:75]
	v_mfma_f32_16x16x32_bf16 v[76:79], v[228:231], v[220:223], v[178:181]
	v_mfma_f32_16x16x32_bf16 v[72:75], v[154:157], v[220:223], v[182:185]
	s_barrier
	ds_read_b128 v[178:181], v152 offset:49152
	ds_read_b128 v[182:185], v152 offset:50176
	ds_read_b128 v[186:189], v151 offset:49152
	ds_read_b128 v[190:193], v151 offset:50176
	ds_read_b128 v[194:197], v150 offset:49152
	ds_read_b128 v[150:153], v150 offset:50176
	ds_read_b128 v[198:201], v149 offset:49152
	ds_read_b128 v[202:205], v149 offset:50176
	s_barrier
	s_waitcnt lgkmcnt(0)
	v_mfma_f32_16x16x32_bf16 v[20:23], v[0:3], v[178:181], v[60:63]
	v_mfma_f32_16x16x32_bf16 v[56:59], v[16:19], v[178:181], v[56:59]
	v_mfma_f32_16x16x32_bf16 v[60:63], v[0:3], v[186:189], v[52:55]
	v_mfma_f32_16x16x32_bf16 v[206:209], v[16:19], v[186:189], v[48:51]
	v_mfma_f32_16x16x32_bf16 v[44:47], v[0:3], v[194:197], v[44:47]
	v_mfma_f32_16x16x32_bf16 v[40:43], v[16:19], v[194:197], v[40:43]
	v_mfma_f32_16x16x32_bf16 v[0:3], v[0:3], v[198:201], v[36:39]
	v_mfma_f32_16x16x32_bf16 v[210:213], v[16:19], v[198:201], v[32:35]
	v_mfma_f32_16x16x32_bf16 v[52:55], v[4:7], v[182:185], v[20:23]
	v_mfma_f32_16x16x32_bf16 v[48:51], v[174:177], v[182:185], v[56:59]
	v_mfma_f32_16x16x32_bf16 v[36:39], v[4:7], v[190:193], v[60:63]
	v_mfma_f32_16x16x32_bf16 v[32:35], v[174:177], v[190:193], v[206:209]
	v_mfma_f32_16x16x32_bf16 v[20:23], v[4:7], v[150:153], v[44:47]
	v_mfma_f32_16x16x32_bf16 v[16:19], v[174:177], v[150:153], v[40:43]
	v_mfma_f32_16x16x32_bf16 v[4:7], v[4:7], v[202:205], v[0:3]
	v_mfma_f32_16x16x32_bf16 v[0:3], v[174:177], v[202:205], v[210:213]
	v_mfma_f32_16x16x32_bf16 v[28:31], v[224:227], v[178:181], v[28:31]
	v_mfma_f32_16x16x32_bf16 v[24:27], v[232:235], v[178:181], v[24:27]
	v_mfma_f32_16x16x32_bf16 v[40:43], v[224:227], v[186:189], v[134:137]
	v_mfma_f32_16x16x32_bf16 v[134:137], v[232:235], v[186:189], v[138:141]
	v_mfma_f32_16x16x32_bf16 v[12:15], v[224:227], v[194:197], v[12:15]
	v_mfma_f32_16x16x32_bf16 v[8:11], v[232:235], v[194:197], v[8:11]
	v_mfma_f32_16x16x32_bf16 v[138:141], v[224:227], v[198:201], v[170:173]
	v_mfma_f32_16x16x32_bf16 v[158:161], v[232:235], v[198:201], v[158:161]
	v_mfma_f32_16x16x32_bf16 v[60:63], v[228:231], v[182:185], v[28:31]
	v_mfma_f32_16x16x32_bf16 v[56:59], v[154:157], v[182:185], v[24:27]
	v_mfma_f32_16x16x32_bf16 v[44:47], v[228:231], v[190:193], v[40:43]
	v_mfma_f32_16x16x32_bf16 v[40:43], v[154:157], v[190:193], v[134:137]
	v_mfma_f32_16x16x32_bf16 v[28:31], v[228:231], v[150:153], v[12:15]
	v_mfma_f32_16x16x32_bf16 v[24:27], v[154:157], v[150:153], v[8:11]
	v_mfma_f32_16x16x32_bf16 v[12:15], v[228:231], v[202:205], v[138:141]
	v_mfma_f32_16x16x32_bf16 v[8:11], v[154:157], v[202:205], v[158:161]
	v_cmp_gt_u32_e32 vcc, s66, v130
	s_barrier
	s_and_saveexec_b64 s[50:51], vcc
	s_cbranch_execz .LBB0_773
	s_barrier

; #define STAGE(P, BASE, LD, br, kt) do { const char* _g = (const char*)((BASE) + (size_t)(br) * (LD) + (size_t)(kt) * 64); \
;     for (int _i = 0; _i < 2; ++_i) { int _b = tidx * 16 + _i * 8192; int _r, _c; stage_rc(_b, _r, _c); \
;       __builtin_amdgcn_global_load_lds((const unsigned*)(_g + (unsigned)((_r * (LD) + _c) * 2)), (unsigned*)((char*)(P) + _b), 16, 0, 0); } } while (0)
; #define LDA(dst, b, h) for (int m = 0; m < 4; ++m) for (int k = 0; k < 2; ++k) \
;     dst[m][k] = *reinterpret_cast<const bf16x8*>((char*)SA(b, h) + lds_byte(wr * 64 + m * 16 + fr, k * 32 + fq * 8))
; #define LDB(dst, b, h) for (int n = 0; n < 2; ++n) for (int k = 0; k < 2; ++k) \
;     dst[n][k] = *reinterpret_cast<const bf16x8*>((char*)SB(b, h) + lds_byte(wc * 32 + n * 16 + fr, k * 32 + fq * 8))
; #define MMA(ai, bj, At_, Bt_) do { __builtin_amdgcn_s_setprio(1); \
;     for (int k = 0; k < 2; ++k) for (int m = 0; m < 4; ++m) for (int n = 0; n < 2; ++n) \
;       acc[ai][bj][m][n] = __builtin_amdgcn_mfma_f32_16x16x32_bf16(At_[m][k], Bt_[n][k], acc[ai][bj][m][n], 0, 0, 0); \
;     __builtin_amdgcn_s_setprio(0); } while (0)
; #define WAIT_L(n) asm volatile("s_waitcnt lgkmcnt(" #n ")" ::: "memory")
; #define BAR __builtin_amdgcn_s_barrier()
; #define SCHED __builtin_amdgcn_sched_barrier(0)
; template <int EPI, int lda, int ldb, int N, int K>
; __device__ __forceinline__ void gemm_phase(const u16* __restrict__ A, const u16* __restrict__ Bt, const GemmEpi ep, int wv) {
;     ...
;     for (int t = 0; t < nt - 2; t += 2) {
;       LDB(B0, 0, 0); SCHED; LDA(At, 0, 0); STAGE(SA(1, 1), Ab, lda, brow + HALF, t + 1);
;       WAIT_L(8); BAR; WAIT_L(0); MMA(0, 0, At, B0); BAR; SCHED;
;       LDB(B1, 0, 1); STAGE(SB(0, 0), Bt, ldb, bcol, t + 2);
;       BAR; WAIT_L(0); MMA(0, 1, At, B1); BAR;
;       LDA(At, 0, 1); STAGE(SA(0, 0), Ab, lda, brow, t + 2);
;       BAR; WAIT_L(0); MMA(1, 0, At, B0); BAR; SCHED;
;       STAGE(SB(0, 1), Bt, ldb, bcol + HALF, t + 2);
.LBB0_838:
	ds_read_b128 v[168:171], v164
	ds_read_b128 v[174:177], v164 offset:1024
	ds_read_b128 v[178:181], v164 offset:2048
	ds_read_b128 v[182:185], v164 offset:3072
	v_add_u32_e32 v172, 0xc000, v147
	v_lshl_add_u64 v[238:239], v[136:137], 0, s[50:51]
	v_readfirstlane_b32 s73, v172
	v_add_u32_e32 v173, 0xe000, v147
	v_lshl_add_u64 v[166:167], v[238:239], 0, s[22:23]
	s_mov_b32 m0, s73
	v_lshl_add_u64 v[240:241], v[134:135], 0, s[50:51]
	v_readfirstlane_b32 s73, v173
	ds_read_b128 v[186:189], v155
	ds_read_b128 v[190:193], v155 offset:1024
	ds_read_b128 v[194:197], v154
	ds_read_b128 v[198:201], v154 offset:1024
	ds_read_b128 v[202:205], v153
	ds_read_b128 v[206:209], v153 offset:1024
	ds_read_b128 v[210:213], v152
	ds_read_b128 v[214:217], v152 offset:1024
	global_load_lds_dwordx4 v[166:167], off
	v_lshl_add_u64 v[166:167], v[240:241], 0, s[22:23]
	s_mov_b32 m0, s73
	s_nop 0
	global_load_lds_dwordx4 v[166:167], off
	s_waitcnt lgkmcnt(8)
	s_barrier
	s_waitcnt lgkmcnt(0)
	v_mfma_f32_16x16x32_bf16 v[124:127], v[168:171], v[186:189], v[124:127]
	v_mfma_f32_16x16x32_bf16 v[120:123], v[178:181], v[186:189], v[120:123]
	v_mfma_f32_16x16x32_bf16 v[116:119], v[168:171], v[194:197], v[116:119]
	v_mfma_f32_16x16x32_bf16 v[112:115], v[178:181], v[194:197], v[112:115]
	v_mfma_f32_16x16x32_bf16 v[108:111], v[168:171], v[202:205], v[108:111]
	v_mfma_f32_16x16x32_bf16 v[104:107], v[178:181], v[202:205], v[104:107]
	v_mfma_f32_16x16x32_bf16 v[100:103], v[168:171], v[210:213], v[100:103]
	v_mfma_f32_16x16x32_bf16 v[96:99], v[178:181], v[210:213], v[96:99]
	v_mfma_f32_16x16x32_bf16 v[124:127], v[174:177], v[190:193], v[124:127]
	v_mfma_f32_16x16x32_bf16 v[120:123], v[182:185], v[190:193], v[120:123]
	v_mfma_f32_16x16x32_bf16 v[116:119], v[174:177], v[198:201], v[116:119]
	v_mfma_f32_16x16x32_bf16 v[112:115], v[182:185], v[198:201], v[112:115]
	v_mfma_f32_16x16x32_bf16 v[108:111], v[174:177], v[206:209], v[108:111]
	v_mfma_f32_16x16x32_bf16 v[104:107], v[182:185], v[206:209], v[104:107]
	v_mfma_f32_16x16x32_bf16 v[100:103], v[174:177], v[214:217], v[100:103]
	v_mfma_f32_16x16x32_bf16 v[96:99], v[182:185], v[214:217], v[96:99]
	s_barrier
	v_add_u32_e32 v165, s63, v156
	v_lshl_add_u64 v[242:243], v[144:145], 0, s[50:51]
	v_readfirstlane_b32 s73, v165
	v_lshl_add_u64 v[166:167], v[242:243], 0, s[24:25]
	s_mov_b32 m0, s73
	ds_read_b128 v[218:221], v163
	ds_read_b128 v[222:225], v163 offset:1024
	ds_read_b128 v[226:229], v163 offset:2048
	ds_read_b128 v[230:233], v163 offset:3072
	global_load_lds_dwordx4 v[166:167], off
	v_add_u32_e32 v166, 0x2000, v165
	v_lshl_add_u64 v[244:245], v[142:143], 0, s[50:51]
	v_readfirstlane_b32 s73, v166
	v_lshl_add_u64 v[234:235], v[244:245], 0, s[24:25]
	s_mov_b32 m0, s73
	s_nop 0
	global_load_lds_dwordx4 v[234:235], off
	s_barrier
	s_waitcnt lgkmcnt(0)
	v_mfma_f32_16x16x32_bf16 v[92:95], v[218:221], v[186:189], v[92:95]
	v_mfma_f32_16x16x32_bf16 v[88:91], v[226:229], v[186:189], v[88:91]
	v_mfma_f32_16x16x32_bf16 v[84:87], v[218:221], v[194:197], v[84:87]
	v_mfma_f32_16x16x32_bf16 v[80:83], v[226:229], v[194:197], v[80:83]
	v_mfma_f32_16x16x32_bf16 v[76:79], v[218:221], v[202:205], v[76:79]
	v_mfma_f32_16x16x32_bf16 v[72:75], v[226:229], v[202:205], v[72:75]
	v_mfma_f32_16x16x32_bf16 v[68:71], v[218:221], v[210:213], v[68:71]
	v_mfma_f32_16x16x32_bf16 v[64:67], v[226:229], v[210:213], v[64:67]
	v_mfma_f32_16x16x32_bf16 v[92:95], v[222:225], v[190:193], v[92:95]
	v_mfma_f32_16x16x32_bf16 v[88:91], v[230:233], v[190:193], v[88:91]
	v_mfma_f32_16x16x32_bf16 v[84:87], v[222:225], v[198:201], v[84:87]
	v_mfma_f32_16x16x32_bf16 v[80:83], v[230:233], v[198:201], v[80:83]
	v_mfma_f32_16x16x32_bf16 v[76:79], v[222:225], v[206:209], v[76:79]
	v_mfma_f32_16x16x32_bf16 v[72:75], v[230:233], v[206:209], v[72:75]
	v_mfma_f32_16x16x32_bf16 v[68:71], v[222:225], v[214:217], v[68:71]
	v_mfma_f32_16x16x32_bf16 v[64:67], v[230:233], v[214:217], v[64:67]
	s_barrier
	v_readfirstlane_b32 s73, v147
	v_add_u32_e32 v167, 0x2000, v147
	v_lshl_add_u64 v[234:235], v[238:239], 0, s[26:27]
	s_mov_b32 m0, s73
	v_readfirstlane_b32 s73, v167
	ds_read_b128 v[186:189], v155 offset:16384
	ds_read_b128 v[190:193], v155 offset:17408
	ds_read_b128 v[194:197], v154 offset:16384
	ds_read_b128 v[198:201], v154 offset:17408
	ds_read_b128 v[202:205], v153 offset:16384
	ds_read_b128 v[206:209], v153 offset:17408
	ds_read_b128 v[210:213], v152 offset:16384
	ds_read_b128 v[214:217], v152 offset:17408
	global_load_lds_dwordx4 v[234:235], off
	v_lshl_add_u64 v[234:235], v[240:241], 0, s[26:27]
	s_mov_b32 m0, s73
	s_nop 0
	global_load_lds_dwordx4 v[234:235], off
	s_barrier
	s_waitcnt lgkmcnt(0)
	v_mfma_f32_16x16x32_bf16 v[60:63], v[168:171], v[186:189], v[60:63]
	v_mfma_f32_16x16x32_bf16 v[56:59], v[178:181], v[186:189], v[56:59]
	v_mfma_f32_16x16x32_bf16 v[52:55], v[168:171], v[194:197], v[52:55]
	v_mfma_f32_16x16x32_bf16 v[48:51], v[178:181], v[194:197], v[48:51]
	v_mfma_f32_16x16x32_bf16 v[44:47], v[168:171], v[202:205], v[44:47]
	v_mfma_f32_16x16x32_bf16 v[40:43], v[178:181], v[202:205], v[40:43]
	v_mfma_f32_16x16x32_bf16 v[36:39], v[168:171], v[210:213], v[36:39]
	v_mfma_f32_16x16x32_bf16 v[32:35], v[178:181], v[210:213], v[32:35]
	v_mfma_f32_16x16x32_bf16 v[60:63], v[174:177], v[190:193], v[60:63]
	v_mfma_f32_16x16x32_bf16 v[56:59], v[182:185], v[190:193], v[56:59]
	v_mfma_f32_16x16x32_bf16 v[52:55], v[174:177], v[198:201], v[52:55]
	v_mfma_f32_16x16x32_bf16 v[48:51], v[182:185], v[198:201], v[48:51]
	v_mfma_f32_16x16x32_bf16 v[44:47], v[174:177], v[206:209], v[44:47]
	v_mfma_f32_16x16x32_bf16 v[40:43], v[182:185], v[206:209], v[40:43]
	v_mfma_f32_16x16x32_bf16 v[36:39], v[174:177], v[214:217], v[36:39]
	v_mfma_f32_16x16x32_bf16 v[32:35], v[182:185], v[214:217], v[32:35]
	s_barrier
; #define STAGE(P, BASE, LD, br, kt) do { const char* _g = (const char*)((BASE) + (size_t)(br) * (LD) + (size_t)(kt) * 64); \
;     for (int _i = 0; _i < 2; ++_i) { int _b = tidx * 16 + _i * 8192; int _r, _c; stage_rc(_b, _r, _c); \
;       __builtin_amdgcn_global_load_lds((const unsigned*)(_g + (unsigned)((_r * (LD) + _c) * 2)), (unsigned*)((char*)(P) + _b), 16, 0, 0); } } while (0)
; #define LDA(dst, b, h) for (int m = 0; m < 4; ++m) for (int k = 0; k < 2; ++k) \
;     dst[m][k] = *reinterpret_cast<const bf16x8*>((char*)SA(b, h) + lds_byte(wr * 64 + m * 16 + fr, k * 32 + fq * 8))
; #define LDB(dst, b, h) for (int n = 0; n < 2; ++n) for (int k = 0; k < 2; ++k) \
;     dst[n][k] = *reinterpret_cast<const bf16x8*>((char*)SB(b, h) + lds_byte(wc * 32 + n * 16 + fr, k * 32 + fq * 8))
; #define MMA(ai, bj, At_, Bt_) do { __builtin_amdgcn_s_setprio(1); \
;     for (int k = 0; k < 2; ++k) for (int m = 0; m < 4; ++m) for (int n = 0; n < 2; ++n) \
;       acc[ai][bj][m][n] = __builtin_amdgcn_mfma_f32_16x16x32_bf16(At_[m][k], Bt_[n][k], acc[ai][bj][m][n], 0, 0, 0); \
;     __builtin_amdgcn_s_setprio(0); } while (0)
; #define WAIT_V(n) asm volatile("s_waitcnt vmcnt(" #n ")" ::: "memory")
; #define WAIT_L(n) asm volatile("s_waitcnt lgkmcnt(" #n ")" ::: "memory")
; #define BAR __builtin_amdgcn_s_barrier()
; #define SCHED __builtin_amdgcn_sched_barrier(0)
; template <int EPI, int lda, int ldb, int N, int K>
; __device__ __forceinline__ void gemm_phase(const u16* __restrict__ A, const u16* __restrict__ Bt, const GemmEpi ep, int wv) {
;     ...
;       STAGE(SB(0, 1), Bt, ldb, bcol + HALF, t + 2);
;       WAIT_V(6); BAR; MMA(1, 1, At, B1); BAR;
;       LDB(B0, 1, 0); SCHED; LDA(At, 1, 0); STAGE(SA(0, 1), Ab, lda, brow + HALF, t + 2);
;       WAIT_L(8); BAR; WAIT_L(0); MMA(0, 0, At, B0); BAR; SCHED;
;       LDB(B1, 1, 1); STAGE(SB(1, 0), Bt, ldb, bcol, t + 3);
;       BAR; WAIT_L(0); MMA(0, 1, At, B1); BAR;
;       LDA(At, 1, 1); STAGE(SA(1, 0), Ab, lda, brow, t + 3);
;       BAR; WAIT_L(0); MMA(1, 0, At, B0); BAR; SCHED;
	v_add_u32_e32 v168, s64, v156
	v_lshl_add_u64 v[246:247], v[140:141], 0, s[50:51]
	v_readfirstlane_b32 s73, v168
	v_add_u32_e32 v169, 0x2000, v168
	v_lshl_add_u64 v[170:171], v[246:247], 0, s[40:41]
	s_mov_b32 m0, s73
	v_lshl_add_u64 v[248:249], v[138:139], 0, s[50:51]
	v_readfirstlane_b32 s73, v169
	global_load_lds_dwordx4 v[170:171], off
	v_lshl_add_u64 v[170:171], v[248:249], 0, s[40:41]
	s_mov_b32 m0, s73
	s_nop 0
	global_load_lds_dwordx4 v[170:171], off
	s_waitcnt vmcnt(6)
	s_barrier
	v_mfma_f32_16x16x32_bf16 v[28:31], v[218:221], v[186:189], v[28:31]
	v_mfma_f32_16x16x32_bf16 v[24:27], v[226:229], v[186:189], v[24:27]
	v_mfma_f32_16x16x32_bf16 v[20:23], v[218:221], v[194:197], v[20:23]
	v_mfma_f32_16x16x32_bf16 v[16:19], v[226:229], v[194:197], v[16:19]
	v_mfma_f32_16x16x32_bf16 v[12:15], v[218:221], v[202:205], v[12:15]
	v_mfma_f32_16x16x32_bf16 v[8:11], v[226:229], v[202:205], v[8:11]
	v_mfma_f32_16x16x32_bf16 v[4:7], v[218:221], v[210:213], v[4:7]
	v_mfma_f32_16x16x32_bf16 v[0:3], v[226:229], v[210:213], v[0:3]
	v_mfma_f32_16x16x32_bf16 v[28:31], v[222:225], v[190:193], v[28:31]
	v_mfma_f32_16x16x32_bf16 v[24:27], v[230:233], v[190:193], v[24:27]
	v_mfma_f32_16x16x32_bf16 v[20:23], v[222:225], v[198:201], v[20:23]
	v_mfma_f32_16x16x32_bf16 v[16:19], v[230:233], v[198:201], v[16:19]
	v_mfma_f32_16x16x32_bf16 v[12:15], v[222:225], v[206:209], v[12:15]
	v_mfma_f32_16x16x32_bf16 v[8:11], v[230:233], v[206:209], v[8:11]
	v_mfma_f32_16x16x32_bf16 v[4:7], v[222:225], v[214:217], v[4:7]
	v_mfma_f32_16x16x32_bf16 v[0:3], v[230:233], v[214:217], v[0:3]
	s_barrier
	ds_read_b128 v[174:177], v159
	ds_read_b128 v[178:181], v159 offset:1024
	ds_read_b128 v[182:185], v159 offset:2048
	ds_read_b128 v[186:189], v159 offset:3072
	v_add_u32_e32 v170, 0x4000, v147
	v_add_u32_e32 v171, 0x6000, v147
	v_readfirstlane_b32 s73, v170
	v_lshl_add_u64 v[222:223], v[238:239], 0, s[42:43]
	s_mov_b32 m0, s73
	v_readfirstlane_b32 s73, v171
	ds_read_b128 v[190:193], v155 offset:32768
	ds_read_b128 v[194:197], v155 offset:33792
	ds_read_b128 v[198:201], v154 offset:32768
	ds_read_b128 v[202:205], v154 offset:33792
	ds_read_b128 v[206:209], v153 offset:32768
	ds_read_b128 v[210:213], v153 offset:33792
	ds_read_b128 v[214:217], v152 offset:32768
	ds_read_b128 v[218:221], v152 offset:33792
	global_load_lds_dwordx4 v[222:223], off
	v_lshl_add_u64 v[222:223], v[240:241], 0, s[42:43]
	s_mov_b32 m0, s73
	s_nop 0
	global_load_lds_dwordx4 v[222:223], off
	s_waitcnt lgkmcnt(8)
	s_barrier
	s_waitcnt lgkmcnt(0)
	v_mfma_f32_16x16x32_bf16 v[124:127], v[174:177], v[190:193], v[124:127]
	v_mfma_f32_16x16x32_bf16 v[120:123], v[182:185], v[190:193], v[120:123]
	v_mfma_f32_16x16x32_bf16 v[116:119], v[174:177], v[198:201], v[116:119]
	v_mfma_f32_16x16x32_bf16 v[112:115], v[182:185], v[198:201], v[112:115]
	v_mfma_f32_16x16x32_bf16 v[108:111], v[174:177], v[206:209], v[108:111]
	v_mfma_f32_16x16x32_bf16 v[104:107], v[182:185], v[206:209], v[104:107]
	v_mfma_f32_16x16x32_bf16 v[100:103], v[174:177], v[214:217], v[100:103]
	v_mfma_f32_16x16x32_bf16 v[96:99], v[182:185], v[214:217], v[96:99]
	v_mfma_f32_16x16x32_bf16 v[124:127], v[178:181], v[194:197], v[124:127]
	v_mfma_f32_16x16x32_bf16 v[120:123], v[186:189], v[194:197], v[120:123]
	v_mfma_f32_16x16x32_bf16 v[116:119], v[178:181], v[202:205], v[116:119]
	v_mfma_f32_16x16x32_bf16 v[112:115], v[186:189], v[202:205], v[112:115]
	v_mfma_f32_16x16x32_bf16 v[108:111], v[178:181], v[210:213], v[108:111]
	v_mfma_f32_16x16x32_bf16 v[104:107], v[186:189], v[210:213], v[104:107]
	v_mfma_f32_16x16x32_bf16 v[100:103], v[178:181], v[218:221], v[100:103]
	v_mfma_f32_16x16x32_bf16 v[96:99], v[186:189], v[218:221], v[96:99]
	s_barrier
	v_readfirstlane_b32 s73, v158
	v_lshl_add_u64 v[242:243], v[242:243], 0, s[44:45]
	s_mov_b32 m0, s73
	ds_read_b128 v[222:225], v157
	ds_read_b128 v[226:229], v157 offset:1024
	ds_read_b128 v[230:233], v157 offset:2048
	ds_read_b128 v[234:237], v157 offset:3072
	global_load_lds_dwordx4 v[242:243], off
	v_lshl_add_u64 v[242:243], v[244:245], 0, s[44:45]
	v_add_u32_e32 v244, 0x2000, v158
	s_nop 0
	v_readfirstlane_b32 s73, v244
	s_mov_b32 m0, s73
	s_nop 0
	global_load_lds_dwordx4 v[242:243], off
	s_barrier
	s_waitcnt lgkmcnt(0)
	v_mfma_f32_16x16x32_bf16 v[92:95], v[222:225], v[190:193], v[92:95]
	v_mfma_f32_16x16x32_bf16 v[88:91], v[230:233], v[190:193], v[88:91]
	v_mfma_f32_16x16x32_bf16 v[84:87], v[222:225], v[198:201], v[84:87]
	v_mfma_f32_16x16x32_bf16 v[80:83], v[230:233], v[198:201], v[80:83]
	v_mfma_f32_16x16x32_bf16 v[76:79], v[222:225], v[206:209], v[76:79]
	v_mfma_f32_16x16x32_bf16 v[72:75], v[230:233], v[206:209], v[72:75]
	v_mfma_f32_16x16x32_bf16 v[68:71], v[222:225], v[214:217], v[68:71]
	v_mfma_f32_16x16x32_bf16 v[64:67], v[230:233], v[214:217], v[64:67]
	v_mfma_f32_16x16x32_bf16 v[92:95], v[226:229], v[194:197], v[92:95]
	v_mfma_f32_16x16x32_bf16 v[88:91], v[234:237], v[194:197], v[88:91]
	v_mfma_f32_16x16x32_bf16 v[84:87], v[226:229], v[202:205], v[84:87]
	v_mfma_f32_16x16x32_bf16 v[80:83], v[234:237], v[202:205], v[80:83]
	v_mfma_f32_16x16x32_bf16 v[76:79], v[226:229], v[210:213], v[76:79]
	v_mfma_f32_16x16x32_bf16 v[72:75], v[234:237], v[210:213], v[72:75]
	v_mfma_f32_16x16x32_bf16 v[68:71], v[226:229], v[218:221], v[68:71]
	v_mfma_f32_16x16x32_bf16 v[64:67], v[234:237], v[218:221], v[64:67]
	s_barrier
; #define STAGE(P, BASE, LD, br, kt) do { const char* _g = (const char*)((BASE) + (size_t)(br) * (LD) + (size_t)(kt) * 64); \
;     for (int _i = 0; _i < 2; ++_i) { int _b = tidx * 16 + _i * 8192; int _r, _c; stage_rc(_b, _r, _c); \
;       __builtin_amdgcn_global_load_lds((const unsigned*)(_g + (unsigned)((_r * (LD) + _c) * 2)), (unsigned*)((char*)(P) + _b), 16, 0, 0); } } while (0)
; #define LDA(dst, b, h) for (int m = 0; m < 4; ++m) for (int k = 0; k < 2; ++k) \
;     dst[m][k] = *reinterpret_cast<const bf16x8*>((char*)SA(b, h) + lds_byte(wr * 64 + m * 16 + fr, k * 32 + fq * 8))
; #define LDB(dst, b, h) for (int n = 0; n < 2; ++n) for (int k = 0; k < 2; ++k) \
;     dst[n][k] = *reinterpret_cast<const bf16x8*>((char*)SB(b, h) + lds_byte(wc * 32 + n * 16 + fr, k * 32 + fq * 8))
; #define MMA(ai, bj, At_, Bt_) do { __builtin_amdgcn_s_setprio(1); \
;     for (int k = 0; k < 2; ++k) for (int m = 0; m < 4; ++m) for (int n = 0; n < 2; ++n) \
;       acc[ai][bj][m][n] = __builtin_amdgcn_mfma_f32_16x16x32_bf16(At_[m][k], Bt_[n][k], acc[ai][bj][m][n], 0, 0, 0); \
;     __builtin_amdgcn_s_setprio(0); } while (0)
; #define WAIT_V(n) asm volatile("s_waitcnt vmcnt(" #n ")" ::: "memory")
; #define WAIT_L(n) asm volatile("s_waitcnt lgkmcnt(" #n ")" ::: "memory")
; #define BAR __builtin_amdgcn_s_barrier()
; #define SCHED __builtin_amdgcn_sched_barrier(0)
; template <int EPI, int lda, int ldb, int N, int K>
; __device__ __forceinline__ void gemm_phase(const u16* __restrict__ A, const u16* __restrict__ Bt, const GemmEpi ep, int wv) {
;     ...
;       BAR; WAIT_L(0); MMA(1, 0, At, B0); BAR; SCHED;
;       STAGE(SB(1, 1), Bt, ldb, bcol + HALF, t + 3);
;       WAIT_V(6); BAR; MMA(1, 1, At, B1); BAR;
;     }
;     { LDB(B0, 0, 0); LDA(At, 0, 0); STAGE(SA(1, 1), Ab, lda, brow + HALF, nt - 1);
;       BAR; WAIT_L(0); MMA(0, 0, At, B0); BAR;
	v_readfirstlane_b32 s73, v160
	v_lshl_add_u64 v[238:239], v[238:239], 0, s[46:47]
	s_mov_b32 m0, s73
	v_readfirstlane_b32 s73, v161
	ds_read_b128 v[190:193], v155 offset:49152
	ds_read_b128 v[194:197], v155 offset:50176
	ds_read_b128 v[198:201], v154 offset:49152
	ds_read_b128 v[202:205], v154 offset:50176
	ds_read_b128 v[206:209], v153 offset:49152
	ds_read_b128 v[210:213], v153 offset:50176
	ds_read_b128 v[214:217], v152 offset:49152
	ds_read_b128 v[218:221], v152 offset:50176
	global_load_lds_dwordx4 v[238:239], off
	v_lshl_add_u64 v[238:239], v[240:241], 0, s[46:47]
	s_mov_b32 m0, s73
	s_nop 0
	global_load_lds_dwordx4 v[238:239], off
	s_barrier
	s_waitcnt lgkmcnt(0)
	v_mfma_f32_16x16x32_bf16 v[60:63], v[174:177], v[190:193], v[60:63]
	v_mfma_f32_16x16x32_bf16 v[56:59], v[182:185], v[190:193], v[56:59]
	v_mfma_f32_16x16x32_bf16 v[52:55], v[174:177], v[198:201], v[52:55]
	v_mfma_f32_16x16x32_bf16 v[48:51], v[182:185], v[198:201], v[48:51]
	v_mfma_f32_16x16x32_bf16 v[44:47], v[174:177], v[206:209], v[44:47]
	v_mfma_f32_16x16x32_bf16 v[40:43], v[182:185], v[206:209], v[40:43]
	v_mfma_f32_16x16x32_bf16 v[36:39], v[174:177], v[214:217], v[36:39]
	v_mfma_f32_16x16x32_bf16 v[32:35], v[182:185], v[214:217], v[32:35]
	v_mfma_f32_16x16x32_bf16 v[60:63], v[178:181], v[194:197], v[60:63]
	v_mfma_f32_16x16x32_bf16 v[56:59], v[186:189], v[194:197], v[56:59]
	v_mfma_f32_16x16x32_bf16 v[52:55], v[178:181], v[202:205], v[52:55]
	v_mfma_f32_16x16x32_bf16 v[48:51], v[186:189], v[202:205], v[48:51]
	v_mfma_f32_16x16x32_bf16 v[44:47], v[178:181], v[210:213], v[44:47]
	v_mfma_f32_16x16x32_bf16 v[40:43], v[186:189], v[210:213], v[40:43]
	v_mfma_f32_16x16x32_bf16 v[36:39], v[178:181], v[218:221], v[36:39]
	v_mfma_f32_16x16x32_bf16 v[32:35], v[186:189], v[218:221], v[32:35]
	s_barrier
	v_readfirstlane_b32 s73, v162
	v_add_u32_e32 v176, 0x2000, v162
	v_lshl_add_u64 v[174:175], v[246:247], 0, s[48:49]
	s_mov_b32 m0, s73
	v_readfirstlane_b32 s73, v176
	global_load_lds_dwordx4 v[174:175], off
	v_lshl_add_u64 v[174:175], v[248:249], 0, s[48:49]
	s_mov_b32 m0, s73
	s_nop 0
	global_load_lds_dwordx4 v[174:175], off
	s_add_i32 s72, s72, 2
	s_add_u32 s50, s50, 0x100
	s_addc_u32 s51, s51, 0
	s_cmpk_gt_u32 s72, 0x51
	s_waitcnt vmcnt(6)
	s_barrier
	v_mfma_f32_16x16x32_bf16 v[28:31], v[222:225], v[190:193], v[28:31]
	v_mfma_f32_16x16x32_bf16 v[24:27], v[230:233], v[190:193], v[24:27]
	v_mfma_f32_16x16x32_bf16 v[20:23], v[222:225], v[198:201], v[20:23]
	v_mfma_f32_16x16x32_bf16 v[16:19], v[230:233], v[198:201], v[16:19]
	v_mfma_f32_16x16x32_bf16 v[12:15], v[222:225], v[206:209], v[12:15]
	v_mfma_f32_16x16x32_bf16 v[8:11], v[230:233], v[206:209], v[8:11]
	v_mfma_f32_16x16x32_bf16 v[4:7], v[222:225], v[214:217], v[4:7]
	v_mfma_f32_16x16x32_bf16 v[0:3], v[230:233], v[214:217], v[0:3]
	v_mfma_f32_16x16x32_bf16 v[28:31], v[226:229], v[194:197], v[28:31]
	v_mfma_f32_16x16x32_bf16 v[24:27], v[234:237], v[194:197], v[24:27]
	v_mfma_f32_16x16x32_bf16 v[20:23], v[226:229], v[202:205], v[20:23]
	v_mfma_f32_16x16x32_bf16 v[16:19], v[234:237], v[202:205], v[16:19]
	v_mfma_f32_16x16x32_bf16 v[12:15], v[226:229], v[210:213], v[12:15]
	v_mfma_f32_16x16x32_bf16 v[8:11], v[234:237], v[210:213], v[8:11]
	v_mfma_f32_16x16x32_bf16 v[4:7], v[226:229], v[218:221], v[4:7]
	v_mfma_f32_16x16x32_bf16 v[0:3], v[234:237], v[218:221], v[0:3]
	s_barrier
	s_cbranch_scc0 .LBB0_838
	s_add_i32 s50, s18, 0x80
	s_mul_hi_i32 s51, s50, 0x2b00
	s_mulk_i32 s50, 0x2b00
	s_add_u32 s50, s56, s50
	s_addc_u32 s51, s57, s51
	s_add_u32 s50, s50, 0x2a80
	s_addc_u32 s51, s51, 0
	v_readfirstlane_b32 s72, v172
	v_lshl_add_u64 v[160:161], s[50:51], 0, v[128:129]
	s_mov_b32 m0, s72
	ds_read_b128 v[134:137], v164
	ds_read_b128 v[138:141], v164 offset:1024
	ds_read_b128 v[142:145], v164 offset:2048
	ds_read_b128 v[174:177], v164 offset:3072
	ds_read_b128 v[178:181], v155
	ds_read_b128 v[182:185], v155 offset:1024
	ds_read_b128 v[186:189], v154
	ds_read_b128 v[190:193], v154 offset:1024
	ds_read_b128 v[194:197], v153
	ds_read_b128 v[198:201], v153 offset:1024
	ds_read_b128 v[202:205], v152
	ds_read_b128 v[206:209], v152 offset:1024
	global_load_lds_dwordx4 v[160:161], off
	v_lshl_add_u64 v[160:161], s[50:51], 0, v[132:133]
	v_readfirstlane_b32 s50, v173
	s_mov_b32 m0, s50
	s_nop 0
	global_load_lds_dwordx4 v[160:161], off
	s_barrier
	s_waitcnt lgkmcnt(0)
	v_mfma_f32_16x16x32_bf16 v[124:127], v[134:137], v[178:181], v[124:127]
	v_mfma_f32_16x16x32_bf16 v[120:123], v[142:145], v[178:181], v[120:123]
	v_mfma_f32_16x16x32_bf16 v[116:119], v[134:137], v[186:189], v[116:119]
	v_mfma_f32_16x16x32_bf16 v[112:115], v[142:145], v[186:189], v[112:115]
	v_mfma_f32_16x16x32_bf16 v[108:111], v[134:137], v[194:197], v[108:111]
	v_mfma_f32_16x16x32_bf16 v[104:107], v[142:145], v[194:197], v[104:107]
	v_mfma_f32_16x16x32_bf16 v[100:103], v[134:137], v[202:205], v[100:103]
	v_mfma_f32_16x16x32_bf16 v[96:99], v[142:145], v[202:205], v[96:99]
	v_mfma_f32_16x16x32_bf16 v[124:127], v[138:141], v[182:185], v[124:127]
	v_mfma_f32_16x16x32_bf16 v[120:123], v[174:177], v[182:185], v[120:123]
	v_mfma_f32_16x16x32_bf16 v[116:119], v[138:141], v[190:193], v[116:119]
	v_mfma_f32_16x16x32_bf16 v[112:115], v[174:177], v[190:193], v[112:115]
	v_mfma_f32_16x16x32_bf16 v[108:111], v[138:141], v[198:201], v[108:111]
	v_mfma_f32_16x16x32_bf16 v[104:107], v[174:177], v[198:201], v[104:107]
	v_mfma_f32_16x16x32_bf16 v[100:103], v[138:141], v[206:209], v[100:103]
	v_mfma_f32_16x16x32_bf16 v[96:99], v[174:177], v[206:209], v[96:99]
	s_barrier
	ds_read_b128 v[210:213], v163
	ds_read_b128 v[214:217], v163 offset:1024
	ds_read_b128 v[218:221], v163 offset:2048
	ds_read_b128 v[160:163], v163 offset:3072
	s_barrier
; #define LDA(dst, b, h) for (int m = 0; m < 4; ++m) for (int k = 0; k < 2; ++k) \
;     dst[m][k] = *reinterpret_cast<const bf16x8*>((char*)SA(b, h) + lds_byte(wr * 64 + m * 16 + fr, k * 32 + fq * 8))
; #define LDB(dst, b, h) for (int n = 0; n < 2; ++n) for (int k = 0; k < 2; ++k) \
;     dst[n][k] = *reinterpret_cast<const bf16x8*>((char*)SB(b, h) + lds_byte(wc * 32 + n * 16 + fr, k * 32 + fq * 8))
; #define MMA(ai, bj, At_, Bt_) do { __builtin_amdgcn_s_setprio(1); \
;     for (int k = 0; k < 2; ++k) for (int m = 0; m < 4; ++m) for (int n = 0; n < 2; ++n) \
;       acc[ai][bj][m][n] = __builtin_amdgcn_mfma_f32_16x16x32_bf16(At_[m][k], Bt_[n][k], acc[ai][bj][m][n], 0, 0, 0); \
;     __builtin_amdgcn_s_setprio(0); } while (0)
; #define WAIT_V(n) asm volatile("s_waitcnt vmcnt(" #n ")" ::: "memory")
; #define WAIT_L(n) asm volatile("s_waitcnt lgkmcnt(" #n ")" ::: "memory")
; #define BAR __builtin_amdgcn_s_barrier()
; template <int EPI, int lda, int ldb, int N, int K>
; __device__ __forceinline__ void gemm_phase(const u16* __restrict__ A, const u16* __restrict__ Bt, const GemmEpi ep, int wv) {
;     ...
;       LDB(B1, 0, 1); BAR; WAIT_L(0); MMA(0, 1, At, B1); BAR;
;       LDA(At, 0, 1); WAIT_V(4); BAR; WAIT_L(0); MMA(1, 0, At, B0); MMA(1, 1, At, B1); BAR; }
;     { LDB(B0, 1, 0); LDA(At, 1, 0); WAIT_V(2); BAR; WAIT_L(0); MMA(0, 0, At, B0); BAR;
	s_waitcnt lgkmcnt(0)
	v_mfma_f32_16x16x32_bf16 v[92:95], v[210:213], v[178:181], v[92:95]
	v_mfma_f32_16x16x32_bf16 v[88:91], v[218:221], v[178:181], v[88:91]
	v_mfma_f32_16x16x32_bf16 v[76:79], v[210:213], v[194:197], v[76:79]
	v_mfma_f32_16x16x32_bf16 v[72:75], v[218:221], v[194:197], v[72:75]
	v_mfma_f32_16x16x32_bf16 v[84:87], v[210:213], v[186:189], v[84:87]
	v_mfma_f32_16x16x32_bf16 v[80:83], v[218:221], v[186:189], v[80:83]
	v_mfma_f32_16x16x32_bf16 v[68:71], v[210:213], v[202:205], v[68:71]
	v_mfma_f32_16x16x32_bf16 v[64:67], v[218:221], v[202:205], v[64:67]
	v_mfma_f32_16x16x32_bf16 v[92:95], v[214:217], v[182:185], v[92:95]
	v_mfma_f32_16x16x32_bf16 v[88:91], v[160:163], v[182:185], v[88:91]
	v_mfma_f32_16x16x32_bf16 v[76:79], v[214:217], v[198:201], v[76:79]
	v_mfma_f32_16x16x32_bf16 v[72:75], v[160:163], v[198:201], v[72:75]
	v_mfma_f32_16x16x32_bf16 v[178:181], v[214:217], v[190:193], v[84:87]
	v_mfma_f32_16x16x32_bf16 v[182:185], v[160:163], v[190:193], v[80:83]
	v_mfma_f32_16x16x32_bf16 v[186:189], v[214:217], v[206:209], v[68:71]
	v_mfma_f32_16x16x32_bf16 v[190:193], v[160:163], v[206:209], v[64:67]
	s_barrier
	s_nop 0
	ds_read_b128 v[64:67], v155 offset:16384
	ds_read_b128 v[68:71], v155 offset:17408
	ds_read_b128 v[80:83], v154 offset:16384
	ds_read_b128 v[84:87], v154 offset:17408
	ds_read_b128 v[194:197], v153 offset:16384
	ds_read_b128 v[198:201], v153 offset:17408
	ds_read_b128 v[202:205], v152 offset:16384
	ds_read_b128 v[206:209], v152 offset:17408
	s_waitcnt vmcnt(4)
	s_barrier
	s_waitcnt lgkmcnt(0)
	v_mfma_f32_16x16x32_bf16 v[60:63], v[134:137], v[64:67], v[60:63]
	v_mfma_f32_16x16x32_bf16 v[56:59], v[142:145], v[64:67], v[56:59]
	v_mfma_f32_16x16x32_bf16 v[52:55], v[134:137], v[80:83], v[52:55]
	v_mfma_f32_16x16x32_bf16 v[48:51], v[142:145], v[80:83], v[48:51]
	v_mfma_f32_16x16x32_bf16 v[44:47], v[134:137], v[194:197], v[44:47]
	v_mfma_f32_16x16x32_bf16 v[40:43], v[142:145], v[194:197], v[40:43]
	v_mfma_f32_16x16x32_bf16 v[36:39], v[134:137], v[202:205], v[36:39]
	v_mfma_f32_16x16x32_bf16 v[32:35], v[142:145], v[202:205], v[32:35]
	v_mfma_f32_16x16x32_bf16 v[60:63], v[138:141], v[68:71], v[60:63]
	v_mfma_f32_16x16x32_bf16 v[56:59], v[174:177], v[68:71], v[56:59]
	v_mfma_f32_16x16x32_bf16 v[52:55], v[138:141], v[84:87], v[52:55]
	v_mfma_f32_16x16x32_bf16 v[48:51], v[174:177], v[84:87], v[48:51]
	v_mfma_f32_16x16x32_bf16 v[44:47], v[138:141], v[198:201], v[44:47]
	v_mfma_f32_16x16x32_bf16 v[40:43], v[174:177], v[198:201], v[40:43]
	v_mfma_f32_16x16x32_bf16 v[36:39], v[138:141], v[206:209], v[36:39]
	v_mfma_f32_16x16x32_bf16 v[32:35], v[174:177], v[206:209], v[32:35]
	v_mfma_f32_16x16x32_bf16 v[28:31], v[210:213], v[64:67], v[28:31]
	v_mfma_f32_16x16x32_bf16 v[16:19], v[218:221], v[80:83], v[16:19]
	v_mfma_f32_16x16x32_bf16 v[12:15], v[210:213], v[194:197], v[12:15]
	v_mfma_f32_16x16x32_bf16 v[0:3], v[218:221], v[202:205], v[0:3]
	v_mfma_f32_16x16x32_bf16 v[24:27], v[218:221], v[64:67], v[24:27]
	v_mfma_f32_16x16x32_bf16 v[20:23], v[210:213], v[80:83], v[20:23]
	v_mfma_f32_16x16x32_bf16 v[8:11], v[218:221], v[194:197], v[8:11]
	v_mfma_f32_16x16x32_bf16 v[4:7], v[210:213], v[202:205], v[4:7]
	v_mfma_f32_16x16x32_bf16 v[28:31], v[214:217], v[68:71], v[28:31]
	v_mfma_f32_16x16x32_bf16 v[16:19], v[160:163], v[84:87], v[16:19]
	v_mfma_f32_16x16x32_bf16 v[12:15], v[214:217], v[198:201], v[12:15]
	v_mfma_f32_16x16x32_bf16 v[0:3], v[160:163], v[206:209], v[0:3]
	v_mfma_f32_16x16x32_bf16 v[134:137], v[160:163], v[68:71], v[24:27]
	v_mfma_f32_16x16x32_bf16 v[138:141], v[214:217], v[84:87], v[20:23]
	v_mfma_f32_16x16x32_bf16 v[142:145], v[160:163], v[198:201], v[8:11]
	v_mfma_f32_16x16x32_bf16 v[172:175], v[214:217], v[206:209], v[4:7]
	s_barrier
	s_nop 0
	ds_read_b128 v[4:7], v159
	ds_read_b128 v[8:11], v159 offset:1024
	ds_read_b128 v[20:23], v159 offset:2048
	ds_read_b128 v[158:161], v159 offset:3072
	ds_read_b128 v[24:27], v155 offset:32768
	ds_read_b128 v[194:197], v155 offset:33792
	ds_read_b128 v[198:201], v154 offset:32768
	ds_read_b128 v[202:205], v154 offset:33792
	ds_read_b128 v[206:209], v153 offset:32768
	ds_read_b128 v[210:213], v153 offset:33792
	ds_read_b128 v[214:217], v152 offset:32768
	ds_read_b128 v[218:221], v152 offset:33792
	s_waitcnt vmcnt(2)
	s_barrier
; #define LDA(dst, b, h) for (int m = 0; m < 4; ++m) for (int k = 0; k < 2; ++k) \
;     dst[m][k] = *reinterpret_cast<const bf16x8*>((char*)SA(b, h) + lds_byte(wr * 64 + m * 16 + fr, k * 32 + fq * 8))
; #define LDB(dst, b, h) for (int n = 0; n < 2; ++n) for (int k = 0; k < 2; ++k) \
;     dst[n][k] = *reinterpret_cast<const bf16x8*>((char*)SB(b, h) + lds_byte(wc * 32 + n * 16 + fr, k * 32 + fq * 8))
; #define MMA(ai, bj, At_, Bt_) do { __builtin_amdgcn_s_setprio(1); \
;     for (int k = 0; k < 2; ++k) for (int m = 0; m < 4; ++m) for (int n = 0; n < 2; ++n) \
;       acc[ai][bj][m][n] = __builtin_amdgcn_mfma_f32_16x16x32_bf16(At_[m][k], Bt_[n][k], acc[ai][bj][m][n], 0, 0, 0); \
;     __builtin_amdgcn_s_setprio(0); } while (0)
; #define WAIT_V(n) asm volatile("s_waitcnt vmcnt(" #n ")" ::: "memory")
; #define WAIT_L(n) asm volatile("s_waitcnt lgkmcnt(" #n ")" ::: "memory")
; #define BAR __builtin_amdgcn_s_barrier()
; template <int EPI, int lda, int ldb, int N, int K>
; __device__ __forceinline__ void gemm_phase(const u16* __restrict__ A, const u16* __restrict__ Bt, const GemmEpi ep, int wv) {
;     ...
;     { LDB(B0, 1, 0); LDA(At, 1, 0); WAIT_V(2); BAR; WAIT_L(0); MMA(0, 0, At, B0); BAR;
;       LDB(B1, 1, 1); WAIT_V(0); BAR; WAIT_L(0); MMA(0, 1, At, B1); BAR;
;       LDA(At, 1, 1); BAR; WAIT_L(0); MMA(1, 0, At, B0); MMA(1, 1, At, B1); BAR; }
;     if (wr == 0) BAR;
	s_waitcnt lgkmcnt(0)
	v_mfma_f32_16x16x32_bf16 v[64:67], v[4:7], v[24:27], v[124:127]
	v_mfma_f32_16x16x32_bf16 v[68:71], v[20:23], v[24:27], v[120:123]
	v_mfma_f32_16x16x32_bf16 v[80:83], v[4:7], v[198:201], v[116:119]
	v_mfma_f32_16x16x32_bf16 v[84:87], v[20:23], v[198:201], v[112:115]
	v_mfma_f32_16x16x32_bf16 v[108:111], v[4:7], v[206:209], v[108:111]
	v_mfma_f32_16x16x32_bf16 v[104:107], v[20:23], v[206:209], v[104:107]
	v_mfma_f32_16x16x32_bf16 v[120:123], v[4:7], v[214:217], v[100:103]
	v_mfma_f32_16x16x32_bf16 v[124:127], v[20:23], v[214:217], v[96:99]
	v_mfma_f32_16x16x32_bf16 v[116:119], v[8:11], v[194:197], v[64:67]
	v_mfma_f32_16x16x32_bf16 v[112:115], v[158:161], v[194:197], v[68:71]
	v_mfma_f32_16x16x32_bf16 v[100:103], v[8:11], v[202:205], v[80:83]
	v_mfma_f32_16x16x32_bf16 v[96:99], v[158:161], v[202:205], v[84:87]
	v_mfma_f32_16x16x32_bf16 v[84:87], v[8:11], v[210:213], v[108:111]
	v_mfma_f32_16x16x32_bf16 v[80:83], v[158:161], v[210:213], v[104:107]
	v_mfma_f32_16x16x32_bf16 v[68:71], v[8:11], v[218:221], v[120:123]
	v_mfma_f32_16x16x32_bf16 v[64:67], v[158:161], v[218:221], v[124:127]
	s_barrier
	ds_read_b128 v[222:225], v157
	ds_read_b128 v[226:229], v157 offset:1024
	ds_read_b128 v[230:233], v157 offset:2048
	ds_read_b128 v[234:237], v157 offset:3072
	s_waitcnt vmcnt(0)
	s_barrier
	s_waitcnt lgkmcnt(0)
	v_mfma_f32_16x16x32_bf16 v[92:95], v[222:225], v[24:27], v[92:95]
	v_mfma_f32_16x16x32_bf16 v[24:27], v[230:233], v[24:27], v[88:91]
	v_mfma_f32_16x16x32_bf16 v[88:91], v[222:225], v[198:201], v[178:181]
	v_mfma_f32_16x16x32_bf16 v[104:107], v[230:233], v[198:201], v[182:185]
	v_mfma_f32_16x16x32_bf16 v[76:79], v[222:225], v[206:209], v[76:79]
	v_mfma_f32_16x16x32_bf16 v[72:75], v[230:233], v[206:209], v[72:75]
	v_mfma_f32_16x16x32_bf16 v[176:179], v[222:225], v[214:217], v[186:189]
	v_mfma_f32_16x16x32_bf16 v[180:183], v[230:233], v[214:217], v[190:193]
	v_mfma_f32_16x16x32_bf16 v[124:127], v[226:229], v[194:197], v[92:95]
	v_mfma_f32_16x16x32_bf16 v[120:123], v[234:237], v[194:197], v[24:27]
	v_mfma_f32_16x16x32_bf16 v[108:111], v[226:229], v[202:205], v[88:91]
	v_mfma_f32_16x16x32_bf16 v[104:107], v[234:237], v[202:205], v[104:107]
	v_mfma_f32_16x16x32_bf16 v[92:95], v[226:229], v[210:213], v[76:79]
	v_mfma_f32_16x16x32_bf16 v[88:91], v[234:237], v[210:213], v[72:75]
	v_mfma_f32_16x16x32_bf16 v[76:79], v[226:229], v[218:221], v[176:179]
	v_mfma_f32_16x16x32_bf16 v[72:75], v[234:237], v[218:221], v[180:183]
	s_barrier
	ds_read_b128 v[176:179], v155 offset:49152
	ds_read_b128 v[180:183], v155 offset:50176
	ds_read_b128 v[184:187], v154 offset:49152
	ds_read_b128 v[154:157], v154 offset:50176
	ds_read_b128 v[188:191], v153 offset:49152
	ds_read_b128 v[192:195], v153 offset:50176
	ds_read_b128 v[196:199], v152 offset:49152
	ds_read_b128 v[200:203], v152 offset:50176
	s_barrier
	s_waitcnt lgkmcnt(0)
	v_mfma_f32_16x16x32_bf16 v[24:27], v[4:7], v[176:179], v[60:63]
	v_mfma_f32_16x16x32_bf16 v[60:63], v[20:23], v[176:179], v[56:59]
	v_mfma_f32_16x16x32_bf16 v[204:207], v[4:7], v[184:187], v[52:55]
	v_mfma_f32_16x16x32_bf16 v[48:51], v[20:23], v[184:187], v[48:51]
	v_mfma_f32_16x16x32_bf16 v[44:47], v[4:7], v[188:191], v[44:47]
	v_mfma_f32_16x16x32_bf16 v[208:211], v[20:23], v[188:191], v[40:43]
	v_mfma_f32_16x16x32_bf16 v[4:7], v[4:7], v[196:199], v[36:39]
	v_mfma_f32_16x16x32_bf16 v[32:35], v[20:23], v[196:199], v[32:35]
	v_mfma_f32_16x16x32_bf16 v[56:59], v[8:11], v[180:183], v[24:27]
	v_mfma_f32_16x16x32_bf16 v[52:55], v[158:161], v[180:183], v[60:63]
	v_mfma_f32_16x16x32_bf16 v[40:43], v[8:11], v[154:157], v[204:207]
	v_mfma_f32_16x16x32_bf16 v[36:39], v[158:161], v[154:157], v[48:51]
	v_mfma_f32_16x16x32_bf16 v[24:27], v[8:11], v[192:195], v[44:47]
	v_mfma_f32_16x16x32_bf16 v[20:23], v[158:161], v[192:195], v[208:211]
	v_mfma_f32_16x16x32_bf16 v[8:11], v[8:11], v[200:203], v[4:7]
	v_mfma_f32_16x16x32_bf16 v[4:7], v[158:161], v[200:203], v[32:35]
	v_mfma_f32_16x16x32_bf16 v[28:31], v[222:225], v[176:179], v[28:31]
	v_mfma_f32_16x16x32_bf16 v[32:35], v[230:233], v[176:179], v[134:137]
	v_mfma_f32_16x16x32_bf16 v[44:47], v[222:225], v[184:187], v[138:141]
	v_mfma_f32_16x16x32_bf16 v[16:19], v[230:233], v[184:187], v[16:19]
	v_mfma_f32_16x16x32_bf16 v[12:15], v[222:225], v[188:191], v[12:15]
	v_mfma_f32_16x16x32_bf16 v[134:137], v[230:233], v[188:191], v[142:145]
	v_mfma_f32_16x16x32_bf16 v[138:141], v[222:225], v[196:199], v[172:175]
	v_mfma_f32_16x16x32_bf16 v[0:3], v[230:233], v[196:199], v[0:3]
	v_mfma_f32_16x16x32_bf16 v[60:63], v[226:229], v[180:183], v[28:31]
	v_mfma_f32_16x16x32_bf16 v[48:51], v[234:237], v[180:183], v[32:35]
	v_mfma_f32_16x16x32_bf16 v[44:47], v[226:229], v[154:157], v[44:47]
	v_mfma_f32_16x16x32_bf16 v[32:35], v[234:237], v[154:157], v[16:19]
	v_mfma_f32_16x16x32_bf16 v[28:31], v[226:229], v[192:195], v[12:15]
	v_mfma_f32_16x16x32_bf16 v[16:19], v[234:237], v[192:195], v[134:137]
	v_mfma_f32_16x16x32_bf16 v[12:15], v[226:229], v[200:203], v[138:141]
	v_mfma_f32_16x16x32_bf16 v[0:3], v[234:237], v[200:203], v[0:3]
	v_cmp_gt_u32_e32 vcc, s69, v130
	s_barrier
	s_and_saveexec_b64 s[50:51], vcc
	s_cbranch_execz .LBB0_841
	s_barrier

; #define STAGE(P, BASE, LD, br, kt) do { const char* _g = (const char*)((BASE) + (size_t)(br) * (LD) + (size_t)(kt) * 64); \
;     for (int _i = 0; _i < 2; ++_i) { int _b = tidx * 16 + _i * 8192; int _r, _c; stage_rc(_b, _r, _c); \
;       __builtin_amdgcn_global_load_lds((const unsigned*)(_g + (unsigned)((_r * (LD) + _c) * 2)), (unsigned*)((char*)(P) + _b), 16, 0, 0); } } while (0)
; #define LDA(dst, b, h) for (int m = 0; m < 4; ++m) for (int k = 0; k < 2; ++k) \
;     dst[m][k] = *reinterpret_cast<const bf16x8*>((char*)SA(b, h) + lds_byte(wr * 64 + m * 16 + fr, k * 32 + fq * 8))
; #define LDB(dst, b, h) for (int n = 0; n < 2; ++n) for (int k = 0; k < 2; ++k) \
;     dst[n][k] = *reinterpret_cast<const bf16x8*>((char*)SB(b, h) + lds_byte(wc * 32 + n * 16 + fr, k * 32 + fq * 8))
; #define MMA(ai, bj, At_, Bt_) do { __builtin_amdgcn_s_setprio(1); \
;     for (int k = 0; k < 2; ++k) for (int m = 0; m < 4; ++m) for (int n = 0; n < 2; ++n) \
;       acc[ai][bj][m][n] = __builtin_amdgcn_mfma_f32_16x16x32_bf16(At_[m][k], Bt_[n][k], acc[ai][bj][m][n], 0, 0, 0); \
;     __builtin_amdgcn_s_setprio(0); } while (0)
; #define WAIT_L(n) asm volatile("s_waitcnt lgkmcnt(" #n ")" ::: "memory")
; #define BAR __builtin_amdgcn_s_barrier()
; #define SCHED __builtin_amdgcn_sched_barrier(0)
; template <int EPI, int lda, int ldb, int N, int K>
; __device__ __forceinline__ void gemm_phase(const u16* __restrict__ A, const u16* __restrict__ Bt, const GemmEpi ep, int wv) {
;     ...
;     for (int t = 0; t < nt - 2; t += 2) {
;       LDB(B0, 0, 0); SCHED; LDA(At, 0, 0); STAGE(SA(1, 1), Ab, lda, brow + HALF, t + 1);
;       WAIT_L(8); BAR; WAIT_L(0); MMA(0, 0, At, B0); BAR; SCHED;
;       LDB(B1, 0, 1); STAGE(SB(0, 0), Bt, ldb, bcol, t + 2);
;       BAR; WAIT_L(0); MMA(0, 1, At, B1); BAR;
;       LDA(At, 0, 1); STAGE(SA(0, 0), Ab, lda, brow, t + 2);
;       BAR; WAIT_L(0); MMA(1, 0, At, B0); BAR; SCHED;
;       STAGE(SB(0, 1), Bt, ldb, bcol + HALF, t + 2);
.LBB0_1147:
	ds_read_b128 v[172:175], v161
	ds_read_b128 v[176:179], v161 offset:1024
	ds_read_b128 v[180:183], v161 offset:2048
	ds_read_b128 v[184:187], v161 offset:3072
	v_add_u32_e32 v169, 0xc000, v148
	v_lshl_add_u64 v[236:237], v[138:139], 0, s[60:61]
	v_readfirstlane_b32 s63, v169
	v_add_u32_e32 v170, 0xe000, v148
	v_lshl_add_u64 v[162:163], v[236:237], 0, s[22:23]
	s_mov_b32 m0, s63
	v_lshl_add_u64 v[238:239], v[140:141], 0, s[60:61]
	v_readfirstlane_b32 s63, v170
	ds_read_b128 v[164:167], v152
	ds_read_b128 v[188:191], v152 offset:1024
	ds_read_b128 v[192:195], v151
	ds_read_b128 v[196:199], v151 offset:1024
	ds_read_b128 v[200:203], v150
	ds_read_b128 v[204:207], v150 offset:1024
	ds_read_b128 v[208:211], v149
	ds_read_b128 v[212:215], v149 offset:1024
	global_load_lds_dwordx4 v[162:163], off
	v_lshl_add_u64 v[162:163], v[238:239], 0, s[22:23]
	s_mov_b32 m0, s63
	s_nop 0
	global_load_lds_dwordx4 v[162:163], off
	s_waitcnt lgkmcnt(8)
	s_barrier
	s_waitcnt lgkmcnt(0)
	v_mfma_f32_16x16x32_bf16 v[124:127], v[164:167], v[172:175], v[124:127]
	v_mfma_f32_16x16x32_bf16 v[120:123], v[164:167], v[180:183], v[120:123]
	v_mfma_f32_16x16x32_bf16 v[116:119], v[192:195], v[172:175], v[116:119]
	v_mfma_f32_16x16x32_bf16 v[112:115], v[192:195], v[180:183], v[112:115]
	v_mfma_f32_16x16x32_bf16 v[108:111], v[200:203], v[172:175], v[108:111]
	v_mfma_f32_16x16x32_bf16 v[104:107], v[200:203], v[180:183], v[104:107]
	v_mfma_f32_16x16x32_bf16 v[100:103], v[208:211], v[172:175], v[100:103]
	v_mfma_f32_16x16x32_bf16 v[96:99], v[208:211], v[180:183], v[96:99]
	v_mfma_f32_16x16x32_bf16 v[124:127], v[188:191], v[176:179], v[124:127]
	v_mfma_f32_16x16x32_bf16 v[120:123], v[188:191], v[184:187], v[120:123]
	v_mfma_f32_16x16x32_bf16 v[116:119], v[196:199], v[176:179], v[116:119]
	v_mfma_f32_16x16x32_bf16 v[112:115], v[196:199], v[184:187], v[112:115]
	v_mfma_f32_16x16x32_bf16 v[108:111], v[204:207], v[176:179], v[108:111]
	v_mfma_f32_16x16x32_bf16 v[104:107], v[204:207], v[184:187], v[104:107]
	v_mfma_f32_16x16x32_bf16 v[100:103], v[212:215], v[176:179], v[100:103]
	v_mfma_f32_16x16x32_bf16 v[96:99], v[212:215], v[184:187], v[96:99]
	s_barrier
	v_add_u32_e32 v162, s75, v154
	v_lshl_add_u64 v[240:241], v[134:135], 0, s[60:61]
	v_readfirstlane_b32 s63, v162
	v_add_u32_e32 v163, 0x2000, v162
	v_lshl_add_u64 v[232:233], v[240:241], 0, s[24:25]
	s_mov_b32 m0, s63
	v_lshl_add_u64 v[242:243], v[136:137], 0, s[60:61]
	v_readfirstlane_b32 s63, v163
	ds_read_b128 v[216:219], v160
	ds_read_b128 v[220:223], v160 offset:1024
	ds_read_b128 v[224:227], v160 offset:2048
	ds_read_b128 v[228:231], v160 offset:3072
	global_load_lds_dwordx4 v[232:233], off
	v_lshl_add_u64 v[232:233], v[242:243], 0, s[24:25]
	s_mov_b32 m0, s63
	s_nop 0
	global_load_lds_dwordx4 v[232:233], off
	s_barrier
	s_waitcnt lgkmcnt(0)
	v_mfma_f32_16x16x32_bf16 v[92:95], v[164:167], v[216:219], v[92:95]
	v_mfma_f32_16x16x32_bf16 v[88:91], v[164:167], v[224:227], v[88:91]
	v_mfma_f32_16x16x32_bf16 v[84:87], v[192:195], v[216:219], v[84:87]
	v_mfma_f32_16x16x32_bf16 v[80:83], v[192:195], v[224:227], v[80:83]
	v_mfma_f32_16x16x32_bf16 v[76:79], v[200:203], v[216:219], v[76:79]
	v_mfma_f32_16x16x32_bf16 v[72:75], v[200:203], v[224:227], v[72:75]
	v_mfma_f32_16x16x32_bf16 v[68:71], v[208:211], v[216:219], v[68:71]
	v_mfma_f32_16x16x32_bf16 v[64:67], v[208:211], v[224:227], v[64:67]
	v_mfma_f32_16x16x32_bf16 v[92:95], v[188:191], v[220:223], v[92:95]
	v_mfma_f32_16x16x32_bf16 v[88:91], v[188:191], v[228:231], v[88:91]
	v_mfma_f32_16x16x32_bf16 v[84:87], v[196:199], v[220:223], v[84:87]
	v_mfma_f32_16x16x32_bf16 v[80:83], v[196:199], v[228:231], v[80:83]
	v_mfma_f32_16x16x32_bf16 v[76:79], v[204:207], v[220:223], v[76:79]
	v_mfma_f32_16x16x32_bf16 v[72:75], v[204:207], v[228:231], v[72:75]
	v_mfma_f32_16x16x32_bf16 v[68:71], v[212:215], v[220:223], v[68:71]
	v_mfma_f32_16x16x32_bf16 v[64:67], v[212:215], v[228:231], v[64:67]
	s_barrier
	v_readfirstlane_b32 s63, v148
	v_lshl_add_u64 v[164:165], v[236:237], 0, s[26:27]
	s_mov_b32 m0, s63
	ds_read_b128 v[188:191], v152 offset:16384
	ds_read_b128 v[192:195], v152 offset:17408
	ds_read_b128 v[196:199], v151 offset:16384
	ds_read_b128 v[200:203], v151 offset:17408
	ds_read_b128 v[204:207], v150 offset:16384
	ds_read_b128 v[208:211], v150 offset:17408
	ds_read_b128 v[212:215], v149 offset:16384
	ds_read_b128 v[232:235], v149 offset:17408
	global_load_lds_dwordx4 v[164:165], off
	v_add_u32_e32 v164, 0x2000, v148
	v_lshl_add_u64 v[166:167], v[238:239], 0, s[26:27]
	v_readfirstlane_b32 s63, v164
	s_mov_b32 m0, s63
	s_nop 0
	global_load_lds_dwordx4 v[166:167], off
	s_barrier
	s_waitcnt lgkmcnt(0)
	v_mfma_f32_16x16x32_bf16 v[60:63], v[188:191], v[172:175], v[60:63]
	v_mfma_f32_16x16x32_bf16 v[56:59], v[188:191], v[180:183], v[56:59]
	v_mfma_f32_16x16x32_bf16 v[52:55], v[196:199], v[172:175], v[52:55]
	v_mfma_f32_16x16x32_bf16 v[48:51], v[196:199], v[180:183], v[48:51]
	v_mfma_f32_16x16x32_bf16 v[44:47], v[204:207], v[172:175], v[44:47]
	v_mfma_f32_16x16x32_bf16 v[40:43], v[204:207], v[180:183], v[40:43]
	v_mfma_f32_16x16x32_bf16 v[36:39], v[212:215], v[172:175], v[36:39]
	v_mfma_f32_16x16x32_bf16 v[32:35], v[212:215], v[180:183], v[32:35]
	v_mfma_f32_16x16x32_bf16 v[60:63], v[192:195], v[176:179], v[60:63]
	v_mfma_f32_16x16x32_bf16 v[56:59], v[192:195], v[184:187], v[56:59]
	v_mfma_f32_16x16x32_bf16 v[52:55], v[200:203], v[176:179], v[52:55]
	v_mfma_f32_16x16x32_bf16 v[48:51], v[200:203], v[184:187], v[48:51]
	v_mfma_f32_16x16x32_bf16 v[44:47], v[208:211], v[176:179], v[44:47]
	v_mfma_f32_16x16x32_bf16 v[40:43], v[208:211], v[184:187], v[40:43]
	v_mfma_f32_16x16x32_bf16 v[36:39], v[232:235], v[176:179], v[36:39]
	v_mfma_f32_16x16x32_bf16 v[32:35], v[232:235], v[184:187], v[32:35]
	s_barrier
; #define STAGE(P, BASE, LD, br, kt) do { const char* _g = (const char*)((BASE) + (size_t)(br) * (LD) + (size_t)(kt) * 64); \
;     for (int _i = 0; _i < 2; ++_i) { int _b = tidx * 16 + _i * 8192; int _r, _c; stage_rc(_b, _r, _c); \
;       __builtin_amdgcn_global_load_lds((const unsigned*)(_g + (unsigned)((_r * (LD) + _c) * 2)), (unsigned*)((char*)(P) + _b), 16, 0, 0); } } while (0)
; #define LDA(dst, b, h) for (int m = 0; m < 4; ++m) for (int k = 0; k < 2; ++k) \
;     dst[m][k] = *reinterpret_cast<const bf16x8*>((char*)SA(b, h) + lds_byte(wr * 64 + m * 16 + fr, k * 32 + fq * 8))
; #define LDB(dst, b, h) for (int n = 0; n < 2; ++n) for (int k = 0; k < 2; ++k) \
;     dst[n][k] = *reinterpret_cast<const bf16x8*>((char*)SB(b, h) + lds_byte(wc * 32 + n * 16 + fr, k * 32 + fq * 8))
; #define MMA(ai, bj, At_, Bt_) do { __builtin_amdgcn_s_setprio(1); \
;     for (int k = 0; k < 2; ++k) for (int m = 0; m < 4; ++m) for (int n = 0; n < 2; ++n) \
;       acc[ai][bj][m][n] = __builtin_amdgcn_mfma_f32_16x16x32_bf16(At_[m][k], Bt_[n][k], acc[ai][bj][m][n], 0, 0, 0); \
;     __builtin_amdgcn_s_setprio(0); } while (0)
; #define WAIT_V(n) asm volatile("s_waitcnt vmcnt(" #n ")" ::: "memory")
; #define WAIT_L(n) asm volatile("s_waitcnt lgkmcnt(" #n ")" ::: "memory")
; #define BAR __builtin_amdgcn_s_barrier()
; #define SCHED __builtin_amdgcn_sched_barrier(0)
; template <int EPI, int lda, int ldb, int N, int K>
; __device__ __forceinline__ void gemm_phase(const u16* __restrict__ A, const u16* __restrict__ Bt, const GemmEpi ep, int wv) {
;     ...
;       STAGE(SB(0, 1), Bt, ldb, bcol + HALF, t + 2);
;       WAIT_V(6); BAR; MMA(1, 1, At, B1); BAR;
;       LDB(B0, 1, 0); SCHED; LDA(At, 1, 0); STAGE(SA(0, 1), Ab, lda, brow + HALF, t + 2);
;       WAIT_L(8); BAR; WAIT_L(0); MMA(0, 0, At, B0); BAR; SCHED;
;       LDB(B1, 1, 1); STAGE(SB(1, 0), Bt, ldb, bcol, t + 3);
;       BAR; WAIT_L(0); MMA(0, 1, At, B1); BAR;
;       LDA(At, 1, 1); STAGE(SA(1, 0), Ab, lda, brow, t + 3);
;       BAR; WAIT_L(0); MMA(1, 0, At, B0); BAR; SCHED;
	v_add_u32_e32 v165, s76, v154
	v_lshl_add_u64 v[166:167], v[240:241], 0, s[40:41]
	v_readfirstlane_b32 s63, v165
	s_mov_b32 m0, s63
	v_lshl_add_u64 v[172:173], v[242:243], 0, s[40:41]
	global_load_lds_dwordx4 v[166:167], off
	v_add_u32_e32 v166, 0x2000, v165
	s_nop 0
	v_readfirstlane_b32 s63, v166
	s_mov_b32 m0, s63
	s_nop 0
	global_load_lds_dwordx4 v[172:173], off
	s_waitcnt vmcnt(6)
	s_barrier
	v_mfma_f32_16x16x32_bf16 v[28:31], v[188:191], v[216:219], v[28:31]
	v_mfma_f32_16x16x32_bf16 v[24:27], v[188:191], v[224:227], v[24:27]
	v_mfma_f32_16x16x32_bf16 v[20:23], v[196:199], v[216:219], v[20:23]
	v_mfma_f32_16x16x32_bf16 v[16:19], v[196:199], v[224:227], v[16:19]
	v_mfma_f32_16x16x32_bf16 v[12:15], v[204:207], v[216:219], v[12:15]
	v_mfma_f32_16x16x32_bf16 v[8:11], v[204:207], v[224:227], v[8:11]
	v_mfma_f32_16x16x32_bf16 v[4:7], v[212:215], v[216:219], v[4:7]
	v_mfma_f32_16x16x32_bf16 v[0:3], v[212:215], v[224:227], v[0:3]
	v_mfma_f32_16x16x32_bf16 v[28:31], v[192:195], v[220:223], v[28:31]
	v_mfma_f32_16x16x32_bf16 v[24:27], v[192:195], v[228:231], v[24:27]
	v_mfma_f32_16x16x32_bf16 v[20:23], v[200:203], v[220:223], v[20:23]
	v_mfma_f32_16x16x32_bf16 v[16:19], v[200:203], v[228:231], v[16:19]
	v_mfma_f32_16x16x32_bf16 v[12:15], v[208:211], v[220:223], v[12:15]
	v_mfma_f32_16x16x32_bf16 v[8:11], v[208:211], v[228:231], v[8:11]
	v_mfma_f32_16x16x32_bf16 v[4:7], v[232:235], v[220:223], v[4:7]
	v_mfma_f32_16x16x32_bf16 v[0:3], v[232:235], v[228:231], v[0:3]
	s_barrier
	ds_read_b128 v[172:175], v155
	ds_read_b128 v[176:179], v155 offset:1024
	ds_read_b128 v[180:183], v155 offset:2048
	ds_read_b128 v[184:187], v155 offset:3072
	v_add_u32_e32 v167, 0x4000, v148
	v_add_u32_e32 v168, 0x6000, v148
	v_readfirstlane_b32 s63, v167
	v_lshl_add_u64 v[220:221], v[236:237], 0, s[42:43]
	s_mov_b32 m0, s63
	v_readfirstlane_b32 s63, v168
	ds_read_b128 v[188:191], v152 offset:32768
	ds_read_b128 v[192:195], v152 offset:33792
	ds_read_b128 v[196:199], v151 offset:32768
	ds_read_b128 v[200:203], v151 offset:33792
	ds_read_b128 v[204:207], v150 offset:32768
	ds_read_b128 v[208:211], v150 offset:33792
	ds_read_b128 v[212:215], v149 offset:32768
	ds_read_b128 v[216:219], v149 offset:33792
	global_load_lds_dwordx4 v[220:221], off
	v_lshl_add_u64 v[220:221], v[238:239], 0, s[42:43]
	s_mov_b32 m0, s63
	s_nop 0
	global_load_lds_dwordx4 v[220:221], off
	s_waitcnt lgkmcnt(8)
	s_barrier
	s_waitcnt lgkmcnt(0)
	v_mfma_f32_16x16x32_bf16 v[124:127], v[188:191], v[172:175], v[124:127]
	v_mfma_f32_16x16x32_bf16 v[120:123], v[188:191], v[180:183], v[120:123]
	v_mfma_f32_16x16x32_bf16 v[116:119], v[196:199], v[172:175], v[116:119]
	v_mfma_f32_16x16x32_bf16 v[112:115], v[196:199], v[180:183], v[112:115]
	v_mfma_f32_16x16x32_bf16 v[108:111], v[204:207], v[172:175], v[108:111]
	v_mfma_f32_16x16x32_bf16 v[104:107], v[204:207], v[180:183], v[104:107]
	v_mfma_f32_16x16x32_bf16 v[100:103], v[212:215], v[172:175], v[100:103]
	v_mfma_f32_16x16x32_bf16 v[96:99], v[212:215], v[180:183], v[96:99]
	v_mfma_f32_16x16x32_bf16 v[124:127], v[192:195], v[176:179], v[124:127]
	v_mfma_f32_16x16x32_bf16 v[120:123], v[192:195], v[184:187], v[120:123]
	v_mfma_f32_16x16x32_bf16 v[116:119], v[200:203], v[176:179], v[116:119]
	v_mfma_f32_16x16x32_bf16 v[112:115], v[200:203], v[184:187], v[112:115]
	v_mfma_f32_16x16x32_bf16 v[108:111], v[208:211], v[176:179], v[108:111]
	v_mfma_f32_16x16x32_bf16 v[104:107], v[208:211], v[184:187], v[104:107]
	v_mfma_f32_16x16x32_bf16 v[100:103], v[216:219], v[176:179], v[100:103]
	v_mfma_f32_16x16x32_bf16 v[96:99], v[216:219], v[184:187], v[96:99]
	s_barrier
	v_readfirstlane_b32 s63, v156
	v_add_u32_e32 v171, 0x2000, v156
	v_lshl_add_u64 v[244:245], v[240:241], 0, s[44:45]
	s_mov_b32 m0, s63
	v_readfirstlane_b32 s63, v171
	ds_read_b128 v[220:223], v153
	ds_read_b128 v[224:227], v153 offset:1024
	ds_read_b128 v[228:231], v153 offset:2048
	ds_read_b128 v[232:235], v153 offset:3072
	global_load_lds_dwordx4 v[244:245], off
	v_lshl_add_u64 v[244:245], v[242:243], 0, s[44:45]
	s_mov_b32 m0, s63
	s_nop 0
	global_load_lds_dwordx4 v[244:245], off
	s_barrier
	s_waitcnt lgkmcnt(0)
	v_mfma_f32_16x16x32_bf16 v[92:95], v[188:191], v[220:223], v[92:95]
	v_mfma_f32_16x16x32_bf16 v[88:91], v[188:191], v[228:231], v[88:91]
	v_mfma_f32_16x16x32_bf16 v[84:87], v[196:199], v[220:223], v[84:87]
	v_mfma_f32_16x16x32_bf16 v[80:83], v[196:199], v[228:231], v[80:83]
	v_mfma_f32_16x16x32_bf16 v[76:79], v[204:207], v[220:223], v[76:79]
	v_mfma_f32_16x16x32_bf16 v[72:75], v[204:207], v[228:231], v[72:75]
	v_mfma_f32_16x16x32_bf16 v[68:71], v[212:215], v[220:223], v[68:71]
	v_mfma_f32_16x16x32_bf16 v[64:67], v[212:215], v[228:231], v[64:67]
	v_mfma_f32_16x16x32_bf16 v[92:95], v[192:195], v[224:227], v[92:95]
	v_mfma_f32_16x16x32_bf16 v[88:91], v[192:195], v[232:235], v[88:91]
	v_mfma_f32_16x16x32_bf16 v[84:87], v[200:203], v[224:227], v[84:87]
	v_mfma_f32_16x16x32_bf16 v[80:83], v[200:203], v[232:235], v[80:83]
	v_mfma_f32_16x16x32_bf16 v[76:79], v[208:211], v[224:227], v[76:79]
	v_mfma_f32_16x16x32_bf16 v[72:75], v[208:211], v[232:235], v[72:75]
	v_mfma_f32_16x16x32_bf16 v[68:71], v[216:219], v[224:227], v[68:71]
	v_mfma_f32_16x16x32_bf16 v[64:67], v[216:219], v[232:235], v[64:67]
	s_barrier
	v_readfirstlane_b32 s63, v157
	v_lshl_add_u64 v[236:237], v[236:237], 0, s[46:47]
	s_mov_b32 m0, s63
	v_readfirstlane_b32 s63, v158
	ds_read_b128 v[188:191], v152 offset:49152
	ds_read_b128 v[192:195], v152 offset:50176
	ds_read_b128 v[196:199], v151 offset:49152
	ds_read_b128 v[200:203], v151 offset:50176
	ds_read_b128 v[204:207], v150 offset:49152
	ds_read_b128 v[208:211], v150 offset:50176
	ds_read_b128 v[212:215], v149 offset:49152
	ds_read_b128 v[216:219], v149 offset:50176
	global_load_lds_dwordx4 v[236:237], off
	v_lshl_add_u64 v[236:237], v[238:239], 0, s[46:47]
	s_mov_b32 m0, s63
	s_nop 0
	global_load_lds_dwordx4 v[236:237], off
	s_barrier
; #define STAGE(P, BASE, LD, br, kt) do { const char* _g = (const char*)((BASE) + (size_t)(br) * (LD) + (size_t)(kt) * 64); \
;     for (int _i = 0; _i < 2; ++_i) { int _b = tidx * 16 + _i * 8192; int _r, _c; stage_rc(_b, _r, _c); \
;       __builtin_amdgcn_global_load_lds((const unsigned*)(_g + (unsigned)((_r * (LD) + _c) * 2)), (unsigned*)((char*)(P) + _b), 16, 0, 0); } } while (0)
; #define LDA(dst, b, h) for (int m = 0; m < 4; ++m) for (int k = 0; k < 2; ++k) \
;     dst[m][k] = *reinterpret_cast<const bf16x8*>((char*)SA(b, h) + lds_byte(wr * 64 + m * 16 + fr, k * 32 + fq * 8))
; #define LDB(dst, b, h) for (int n = 0; n < 2; ++n) for (int k = 0; k < 2; ++k) \
;     dst[n][k] = *reinterpret_cast<const bf16x8*>((char*)SB(b, h) + lds_byte(wc * 32 + n * 16 + fr, k * 32 + fq * 8))
; #define MMA(ai, bj, At_, Bt_) do { __builtin_amdgcn_s_setprio(1); \
;     for (int k = 0; k < 2; ++k) for (int m = 0; m < 4; ++m) for (int n = 0; n < 2; ++n) \
;       acc[ai][bj][m][n] = __builtin_amdgcn_mfma_f32_16x16x32_bf16(At_[m][k], Bt_[n][k], acc[ai][bj][m][n], 0, 0, 0); \
;     __builtin_amdgcn_s_setprio(0); } while (0)
; #define WAIT_V(n) asm volatile("s_waitcnt vmcnt(" #n ")" ::: "memory")
; #define WAIT_L(n) asm volatile("s_waitcnt lgkmcnt(" #n ")" ::: "memory")
; #define BAR __builtin_amdgcn_s_barrier()
; #define SCHED __builtin_amdgcn_sched_barrier(0)
; template <int EPI, int lda, int ldb, int N, int K>
; __device__ __forceinline__ void gemm_phase(const u16* __restrict__ A, const u16* __restrict__ Bt, const GemmEpi ep, int wv) {
;     ...
;       LDA(At, 1, 1); STAGE(SA(1, 0), Ab, lda, brow, t + 3);
;       BAR; WAIT_L(0); MMA(1, 0, At, B0); BAR; SCHED;
;       STAGE(SB(1, 1), Bt, ldb, bcol + HALF, t + 3);
;       WAIT_V(6); BAR; MMA(1, 1, At, B1); BAR;
;     }
;     { LDB(B0, 0, 0); LDA(At, 0, 0); STAGE(SA(1, 1), Ab, lda, brow + HALF, nt - 1);
;       BAR; WAIT_L(0); MMA(0, 0, At, B0); BAR;
;       LDB(B1, 0, 1); BAR; WAIT_L(0); MMA(0, 1, At, B1); BAR;
	s_waitcnt lgkmcnt(0)
	v_mfma_f32_16x16x32_bf16 v[60:63], v[188:191], v[172:175], v[60:63]
	v_mfma_f32_16x16x32_bf16 v[56:59], v[188:191], v[180:183], v[56:59]
	v_mfma_f32_16x16x32_bf16 v[52:55], v[196:199], v[172:175], v[52:55]
	v_mfma_f32_16x16x32_bf16 v[48:51], v[196:199], v[180:183], v[48:51]
	v_mfma_f32_16x16x32_bf16 v[44:47], v[204:207], v[172:175], v[44:47]
	v_mfma_f32_16x16x32_bf16 v[40:43], v[204:207], v[180:183], v[40:43]
	v_mfma_f32_16x16x32_bf16 v[36:39], v[212:215], v[172:175], v[36:39]
	v_mfma_f32_16x16x32_bf16 v[32:35], v[212:215], v[180:183], v[32:35]
	v_mfma_f32_16x16x32_bf16 v[60:63], v[192:195], v[176:179], v[60:63]
	v_mfma_f32_16x16x32_bf16 v[56:59], v[192:195], v[184:187], v[56:59]
	v_mfma_f32_16x16x32_bf16 v[52:55], v[200:203], v[176:179], v[52:55]
	v_mfma_f32_16x16x32_bf16 v[48:51], v[200:203], v[184:187], v[48:51]
	v_mfma_f32_16x16x32_bf16 v[44:47], v[208:211], v[176:179], v[44:47]
	v_mfma_f32_16x16x32_bf16 v[40:43], v[208:211], v[184:187], v[40:43]
	v_mfma_f32_16x16x32_bf16 v[36:39], v[216:219], v[176:179], v[36:39]
	v_mfma_f32_16x16x32_bf16 v[32:35], v[216:219], v[184:187], v[32:35]
	s_barrier
	v_readfirstlane_b32 s63, v159
	v_add_u32_e32 v171, 0x2000, v159
	v_lshl_add_u64 v[172:173], v[240:241], 0, s[48:49]
	s_mov_b32 m0, s63
	v_readfirstlane_b32 s63, v171
	global_load_lds_dwordx4 v[172:173], off
	v_lshl_add_u64 v[172:173], v[242:243], 0, s[48:49]
	s_mov_b32 m0, s63
	s_nop 0
	global_load_lds_dwordx4 v[172:173], off
	s_add_i32 s62, s62, 2
	s_add_u32 s60, s60, 0x100
	s_addc_u32 s61, s61, 0
	s_cmp_gt_u32 s62, 27
	s_waitcnt vmcnt(6)
	s_barrier
	v_mfma_f32_16x16x32_bf16 v[28:31], v[188:191], v[220:223], v[28:31]
	v_mfma_f32_16x16x32_bf16 v[24:27], v[188:191], v[228:231], v[24:27]
	v_mfma_f32_16x16x32_bf16 v[20:23], v[196:199], v[220:223], v[20:23]
	v_mfma_f32_16x16x32_bf16 v[16:19], v[196:199], v[228:231], v[16:19]
	v_mfma_f32_16x16x32_bf16 v[12:15], v[204:207], v[220:223], v[12:15]
	v_mfma_f32_16x16x32_bf16 v[8:11], v[204:207], v[228:231], v[8:11]
	v_mfma_f32_16x16x32_bf16 v[4:7], v[212:215], v[220:223], v[4:7]
	v_mfma_f32_16x16x32_bf16 v[0:3], v[212:215], v[228:231], v[0:3]
	v_mfma_f32_16x16x32_bf16 v[28:31], v[192:195], v[224:227], v[28:31]
	v_mfma_f32_16x16x32_bf16 v[24:27], v[192:195], v[232:235], v[24:27]
	v_mfma_f32_16x16x32_bf16 v[20:23], v[200:203], v[224:227], v[20:23]
	v_mfma_f32_16x16x32_bf16 v[16:19], v[200:203], v[232:235], v[16:19]
	v_mfma_f32_16x16x32_bf16 v[12:15], v[208:211], v[224:227], v[12:15]
	v_mfma_f32_16x16x32_bf16 v[8:11], v[208:211], v[232:235], v[8:11]
	v_mfma_f32_16x16x32_bf16 v[4:7], v[216:219], v[224:227], v[4:7]
	v_mfma_f32_16x16x32_bf16 v[0:3], v[216:219], v[232:235], v[0:3]
	s_barrier
	s_cbranch_scc0 .LBB0_1147
	s_add_i32 s60, s58, 0x80
	s_mul_hi_i32 s61, s60, 0x1080
	s_mulk_i32 s60, 0x1080
	s_add_u32 s60, s69, s60
	s_addc_u32 s61, s70, s61
	v_lshl_add_u64 v[208:209], s[60:61], 0, v[128:129]
	v_readfirstlane_b32 s62, v169
	v_lshl_add_u64 v[208:209], v[208:209], 0, s[50:51]
	s_mov_b32 m0, s62
	ds_read_b128 v[134:137], v161
	ds_read_b128 v[138:141], v161 offset:1024
	ds_read_b128 v[156:159], v161 offset:2048
	ds_read_b128 v[172:175], v161 offset:3072
	ds_read_b128 v[176:179], v152
	ds_read_b128 v[180:183], v152 offset:1024
	ds_read_b128 v[184:187], v151
	ds_read_b128 v[188:191], v151 offset:1024
	ds_read_b128 v[192:195], v150
	ds_read_b128 v[196:199], v150 offset:1024
	ds_read_b128 v[200:203], v149
	ds_read_b128 v[204:207], v149 offset:1024
	global_load_lds_dwordx4 v[208:209], off
	v_lshl_add_u64 v[208:209], s[60:61], 0, v[132:133]
	v_readfirstlane_b32 s60, v170
	v_lshl_add_u64 v[208:209], v[208:209], 0, s[50:51]
	s_mov_b32 m0, s60
	s_nop 0
	global_load_lds_dwordx4 v[208:209], off
	s_barrier
	s_waitcnt lgkmcnt(0)
	v_mfma_f32_16x16x32_bf16 v[124:127], v[176:179], v[134:137], v[124:127]
	v_mfma_f32_16x16x32_bf16 v[120:123], v[176:179], v[156:159], v[120:123]
	v_mfma_f32_16x16x32_bf16 v[116:119], v[184:187], v[134:137], v[116:119]
	v_mfma_f32_16x16x32_bf16 v[112:115], v[184:187], v[156:159], v[112:115]
	v_mfma_f32_16x16x32_bf16 v[108:111], v[192:195], v[134:137], v[108:111]
	v_mfma_f32_16x16x32_bf16 v[104:107], v[192:195], v[156:159], v[104:107]
	v_mfma_f32_16x16x32_bf16 v[100:103], v[200:203], v[134:137], v[100:103]
	v_mfma_f32_16x16x32_bf16 v[96:99], v[200:203], v[156:159], v[96:99]
	v_mfma_f32_16x16x32_bf16 v[124:127], v[180:183], v[138:141], v[124:127]
	v_mfma_f32_16x16x32_bf16 v[120:123], v[180:183], v[172:175], v[120:123]
	v_mfma_f32_16x16x32_bf16 v[116:119], v[188:191], v[138:141], v[116:119]
	v_mfma_f32_16x16x32_bf16 v[112:115], v[188:191], v[172:175], v[112:115]
	v_mfma_f32_16x16x32_bf16 v[108:111], v[196:199], v[138:141], v[108:111]
	v_mfma_f32_16x16x32_bf16 v[104:107], v[196:199], v[172:175], v[104:107]
	v_mfma_f32_16x16x32_bf16 v[100:103], v[204:207], v[138:141], v[100:103]
	v_mfma_f32_16x16x32_bf16 v[96:99], v[204:207], v[172:175], v[96:99]
	s_barrier
	ds_read_b128 v[208:211], v160
	ds_read_b128 v[212:215], v160 offset:1024
	ds_read_b128 v[216:219], v160 offset:2048
	ds_read_b128 v[220:223], v160 offset:3072
	s_barrier
; #define LDA(dst, b, h) for (int m = 0; m < 4; ++m) for (int k = 0; k < 2; ++k) \
;     dst[m][k] = *reinterpret_cast<const bf16x8*>((char*)SA(b, h) + lds_byte(wr * 64 + m * 16 + fr, k * 32 + fq * 8))
; #define LDB(dst, b, h) for (int n = 0; n < 2; ++n) for (int k = 0; k < 2; ++k) \
;     dst[n][k] = *reinterpret_cast<const bf16x8*>((char*)SB(b, h) + lds_byte(wc * 32 + n * 16 + fr, k * 32 + fq * 8))
; #define MMA(ai, bj, At_, Bt_) do { __builtin_amdgcn_s_setprio(1); \
;     for (int k = 0; k < 2; ++k) for (int m = 0; m < 4; ++m) for (int n = 0; n < 2; ++n) \
;       acc[ai][bj][m][n] = __builtin_amdgcn_mfma_f32_16x16x32_bf16(At_[m][k], Bt_[n][k], acc[ai][bj][m][n], 0, 0, 0); \
;     __builtin_amdgcn_s_setprio(0); } while (0)
; #define WAIT_V(n) asm volatile("s_waitcnt vmcnt(" #n ")" ::: "memory")
; #define WAIT_L(n) asm volatile("s_waitcnt lgkmcnt(" #n ")" ::: "memory")
; #define BAR __builtin_amdgcn_s_barrier()
; template <int EPI, int lda, int ldb, int N, int K>
; __device__ __forceinline__ void gemm_phase(const u16* __restrict__ A, const u16* __restrict__ Bt, const GemmEpi ep, int wv) {
;     ...
;       LDB(B1, 0, 1); BAR; WAIT_L(0); MMA(0, 1, At, B1); BAR;
;       LDA(At, 0, 1); WAIT_V(4); BAR; WAIT_L(0); MMA(1, 0, At, B0); MMA(1, 1, At, B1); BAR; }
;     { LDB(B0, 1, 0); LDA(At, 1, 0); WAIT_V(2); BAR; WAIT_L(0); MMA(0, 0, At, B0); BAR;
	s_waitcnt lgkmcnt(0)
	v_mfma_f32_16x16x32_bf16 v[92:95], v[176:179], v[208:211], v[92:95]
	v_mfma_f32_16x16x32_bf16 v[88:91], v[176:179], v[216:219], v[88:91]
	v_mfma_f32_16x16x32_bf16 v[76:79], v[192:195], v[208:211], v[76:79]
	v_mfma_f32_16x16x32_bf16 v[72:75], v[192:195], v[216:219], v[72:75]
	v_mfma_f32_16x16x32_bf16 v[84:87], v[184:187], v[208:211], v[84:87]
	v_mfma_f32_16x16x32_bf16 v[80:83], v[184:187], v[216:219], v[80:83]
	v_mfma_f32_16x16x32_bf16 v[68:71], v[200:203], v[208:211], v[68:71]
	v_mfma_f32_16x16x32_bf16 v[64:67], v[200:203], v[216:219], v[64:67]
	v_mfma_f32_16x16x32_bf16 v[92:95], v[180:183], v[212:215], v[92:95]
	v_mfma_f32_16x16x32_bf16 v[88:91], v[180:183], v[220:223], v[88:91]
	v_mfma_f32_16x16x32_bf16 v[76:79], v[196:199], v[212:215], v[76:79]
	v_mfma_f32_16x16x32_bf16 v[72:75], v[196:199], v[220:223], v[72:75]
	v_mfma_f32_16x16x32_bf16 v[176:179], v[188:191], v[212:215], v[84:87]
	v_mfma_f32_16x16x32_bf16 v[180:183], v[188:191], v[220:223], v[80:83]
	v_mfma_f32_16x16x32_bf16 v[184:187], v[204:207], v[212:215], v[68:71]
	v_mfma_f32_16x16x32_bf16 v[188:191], v[204:207], v[220:223], v[64:67]
	s_barrier
	s_nop 0
	ds_read_b128 v[64:67], v152 offset:16384
	ds_read_b128 v[68:71], v152 offset:17408
	ds_read_b128 v[80:83], v151 offset:16384
	ds_read_b128 v[84:87], v151 offset:17408
	ds_read_b128 v[192:195], v150 offset:16384
	ds_read_b128 v[196:199], v150 offset:17408
	ds_read_b128 v[200:203], v149 offset:16384
	ds_read_b128 v[204:207], v149 offset:17408
	s_waitcnt vmcnt(4)
	s_barrier
	s_waitcnt lgkmcnt(0)
	v_mfma_f32_16x16x32_bf16 v[60:63], v[64:67], v[134:137], v[60:63]
	v_mfma_f32_16x16x32_bf16 v[56:59], v[64:67], v[156:159], v[56:59]
	v_mfma_f32_16x16x32_bf16 v[52:55], v[80:83], v[134:137], v[52:55]
	v_mfma_f32_16x16x32_bf16 v[48:51], v[80:83], v[156:159], v[48:51]
	v_mfma_f32_16x16x32_bf16 v[44:47], v[192:195], v[134:137], v[44:47]
	v_mfma_f32_16x16x32_bf16 v[40:43], v[192:195], v[156:159], v[40:43]
	v_mfma_f32_16x16x32_bf16 v[36:39], v[200:203], v[134:137], v[36:39]
	v_mfma_f32_16x16x32_bf16 v[32:35], v[200:203], v[156:159], v[32:35]
	v_mfma_f32_16x16x32_bf16 v[60:63], v[68:71], v[138:141], v[60:63]
	v_mfma_f32_16x16x32_bf16 v[56:59], v[68:71], v[172:175], v[56:59]
	v_mfma_f32_16x16x32_bf16 v[52:55], v[84:87], v[138:141], v[52:55]
	v_mfma_f32_16x16x32_bf16 v[48:51], v[84:87], v[172:175], v[48:51]
	v_mfma_f32_16x16x32_bf16 v[44:47], v[196:199], v[138:141], v[44:47]
	v_mfma_f32_16x16x32_bf16 v[40:43], v[196:199], v[172:175], v[40:43]
	v_mfma_f32_16x16x32_bf16 v[36:39], v[204:207], v[138:141], v[36:39]
	v_mfma_f32_16x16x32_bf16 v[32:35], v[204:207], v[172:175], v[32:35]
	v_mfma_f32_16x16x32_bf16 v[28:31], v[64:67], v[208:211], v[28:31]
	v_mfma_f32_16x16x32_bf16 v[24:27], v[64:67], v[216:219], v[24:27]
	v_mfma_f32_16x16x32_bf16 v[12:15], v[192:195], v[208:211], v[12:15]
	v_mfma_f32_16x16x32_bf16 v[8:11], v[192:195], v[216:219], v[8:11]
	v_mfma_f32_16x16x32_bf16 v[20:23], v[80:83], v[208:211], v[20:23]
	v_mfma_f32_16x16x32_bf16 v[16:19], v[80:83], v[216:219], v[16:19]
	v_mfma_f32_16x16x32_bf16 v[4:7], v[200:203], v[208:211], v[4:7]
	v_mfma_f32_16x16x32_bf16 v[0:3], v[200:203], v[216:219], v[0:3]
	v_mfma_f32_16x16x32_bf16 v[28:31], v[68:71], v[212:215], v[28:31]
	v_mfma_f32_16x16x32_bf16 v[24:27], v[68:71], v[220:223], v[24:27]
	v_mfma_f32_16x16x32_bf16 v[12:15], v[196:199], v[212:215], v[12:15]
	v_mfma_f32_16x16x32_bf16 v[8:11], v[196:199], v[220:223], v[8:11]
	v_mfma_f32_16x16x32_bf16 v[134:137], v[84:87], v[212:215], v[20:23]
	v_mfma_f32_16x16x32_bf16 v[138:141], v[84:87], v[220:223], v[16:19]
	v_mfma_f32_16x16x32_bf16 v[156:159], v[204:207], v[212:215], v[4:7]
	v_mfma_f32_16x16x32_bf16 v[170:173], v[204:207], v[220:223], v[0:3]
	s_barrier
	s_nop 0
	ds_read_b128 v[0:3], v155
	ds_read_b128 v[4:7], v155 offset:1024
	ds_read_b128 v[16:19], v155 offset:2048
	ds_read_b128 v[192:195], v155 offset:3072
	ds_read_b128 v[20:23], v152 offset:32768
	ds_read_b128 v[196:199], v152 offset:33792
	ds_read_b128 v[200:203], v151 offset:32768
	ds_read_b128 v[204:207], v151 offset:33792
	ds_read_b128 v[208:211], v150 offset:32768
	ds_read_b128 v[212:215], v150 offset:33792
	ds_read_b128 v[216:219], v149 offset:32768
	ds_read_b128 v[220:223], v149 offset:33792
	s_waitcnt vmcnt(2)
	s_barrier
; #define LDA(dst, b, h) for (int m = 0; m < 4; ++m) for (int k = 0; k < 2; ++k) \
;     dst[m][k] = *reinterpret_cast<const bf16x8*>((char*)SA(b, h) + lds_byte(wr * 64 + m * 16 + fr, k * 32 + fq * 8))
; #define LDB(dst, b, h) for (int n = 0; n < 2; ++n) for (int k = 0; k < 2; ++k) \
;     dst[n][k] = *reinterpret_cast<const bf16x8*>((char*)SB(b, h) + lds_byte(wc * 32 + n * 16 + fr, k * 32 + fq * 8))
; #define MMA(ai, bj, At_, Bt_) do { __builtin_amdgcn_s_setprio(1); \
;     for (int k = 0; k < 2; ++k) for (int m = 0; m < 4; ++m) for (int n = 0; n < 2; ++n) \
;       acc[ai][bj][m][n] = __builtin_amdgcn_mfma_f32_16x16x32_bf16(At_[m][k], Bt_[n][k], acc[ai][bj][m][n], 0, 0, 0); \
;     __builtin_amdgcn_s_setprio(0); } while (0)
; #define WAIT_V(n) asm volatile("s_waitcnt vmcnt(" #n ")" ::: "memory")
; #define WAIT_L(n) asm volatile("s_waitcnt lgkmcnt(" #n ")" ::: "memory")
; #define BAR __builtin_amdgcn_s_barrier()
; template <int EPI, int lda, int ldb, int N, int K>
; __device__ __forceinline__ void gemm_phase(const u16* __restrict__ A, const u16* __restrict__ Bt, const GemmEpi ep, int wv) {
;     ...
;     { LDB(B0, 1, 0); LDA(At, 1, 0); WAIT_V(2); BAR; WAIT_L(0); MMA(0, 0, At, B0); BAR;
;       LDB(B1, 1, 1); WAIT_V(0); BAR; WAIT_L(0); MMA(0, 1, At, B1); BAR;
;       LDA(At, 1, 1); BAR; WAIT_L(0); MMA(1, 0, At, B0); MMA(1, 1, At, B1); BAR; }
;     if (wr == 0) BAR;
	s_waitcnt lgkmcnt(0)
	v_mfma_f32_16x16x32_bf16 v[64:67], v[20:23], v[0:3], v[124:127]
	v_mfma_f32_16x16x32_bf16 v[68:71], v[20:23], v[16:19], v[120:123]
	v_mfma_f32_16x16x32_bf16 v[80:83], v[200:203], v[0:3], v[116:119]
	v_mfma_f32_16x16x32_bf16 v[84:87], v[200:203], v[16:19], v[112:115]
	v_mfma_f32_16x16x32_bf16 v[108:111], v[208:211], v[0:3], v[108:111]
	v_mfma_f32_16x16x32_bf16 v[104:107], v[208:211], v[16:19], v[104:107]
	v_mfma_f32_16x16x32_bf16 v[120:123], v[216:219], v[0:3], v[100:103]
	v_mfma_f32_16x16x32_bf16 v[124:127], v[216:219], v[16:19], v[96:99]
	v_mfma_f32_16x16x32_bf16 v[116:119], v[196:199], v[4:7], v[64:67]
	v_mfma_f32_16x16x32_bf16 v[112:115], v[196:199], v[192:195], v[68:71]
	v_mfma_f32_16x16x32_bf16 v[100:103], v[204:207], v[4:7], v[80:83]
	v_mfma_f32_16x16x32_bf16 v[96:99], v[204:207], v[192:195], v[84:87]
	v_mfma_f32_16x16x32_bf16 v[84:87], v[212:215], v[4:7], v[108:111]
	v_mfma_f32_16x16x32_bf16 v[80:83], v[212:215], v[192:195], v[104:107]
	v_mfma_f32_16x16x32_bf16 v[68:71], v[220:223], v[4:7], v[120:123]
	v_mfma_f32_16x16x32_bf16 v[64:67], v[220:223], v[192:195], v[124:127]
	s_barrier
	ds_read_b128 v[224:227], v153
	ds_read_b128 v[228:231], v153 offset:1024
	ds_read_b128 v[232:235], v153 offset:2048
	ds_read_b128 v[236:239], v153 offset:3072
	s_waitcnt vmcnt(0)
	s_barrier
	s_waitcnt lgkmcnt(0)
	v_mfma_f32_16x16x32_bf16 v[92:95], v[20:23], v[224:227], v[92:95]
	v_mfma_f32_16x16x32_bf16 v[20:23], v[20:23], v[232:235], v[88:91]
	v_mfma_f32_16x16x32_bf16 v[88:91], v[200:203], v[224:227], v[176:179]
	v_mfma_f32_16x16x32_bf16 v[104:107], v[200:203], v[232:235], v[180:183]
	v_mfma_f32_16x16x32_bf16 v[76:79], v[208:211], v[224:227], v[76:79]
	v_mfma_f32_16x16x32_bf16 v[72:75], v[208:211], v[232:235], v[72:75]
	v_mfma_f32_16x16x32_bf16 v[174:177], v[216:219], v[224:227], v[184:187]
	v_mfma_f32_16x16x32_bf16 v[178:181], v[216:219], v[232:235], v[188:191]
	v_mfma_f32_16x16x32_bf16 v[124:127], v[196:199], v[228:231], v[92:95]
	v_mfma_f32_16x16x32_bf16 v[120:123], v[196:199], v[236:239], v[20:23]
	v_mfma_f32_16x16x32_bf16 v[108:111], v[204:207], v[228:231], v[88:91]
	v_mfma_f32_16x16x32_bf16 v[104:107], v[204:207], v[236:239], v[104:107]
	v_mfma_f32_16x16x32_bf16 v[92:95], v[212:215], v[228:231], v[76:79]
	v_mfma_f32_16x16x32_bf16 v[88:91], v[212:215], v[236:239], v[72:75]
	v_mfma_f32_16x16x32_bf16 v[76:79], v[220:223], v[228:231], v[174:177]
	v_mfma_f32_16x16x32_bf16 v[72:75], v[220:223], v[236:239], v[178:181]
	s_barrier
	ds_read_b128 v[174:177], v152 offset:49152
	ds_read_b128 v[152:155], v152 offset:50176
	ds_read_b128 v[178:181], v151 offset:49152
	ds_read_b128 v[182:185], v151 offset:50176
	ds_read_b128 v[186:189], v150 offset:49152
	ds_read_b128 v[196:199], v150 offset:50176
	ds_read_b128 v[200:203], v149 offset:49152
	ds_read_b128 v[204:207], v149 offset:50176
	s_barrier
	s_waitcnt lgkmcnt(0)
	v_mfma_f32_16x16x32_bf16 v[20:23], v[174:177], v[0:3], v[60:63]
	v_mfma_f32_16x16x32_bf16 v[56:59], v[174:177], v[16:19], v[56:59]
	v_mfma_f32_16x16x32_bf16 v[60:63], v[178:181], v[0:3], v[52:55]
	v_mfma_f32_16x16x32_bf16 v[208:211], v[178:181], v[16:19], v[48:51]
	v_mfma_f32_16x16x32_bf16 v[44:47], v[186:189], v[0:3], v[44:47]
	v_mfma_f32_16x16x32_bf16 v[40:43], v[186:189], v[16:19], v[40:43]
	v_mfma_f32_16x16x32_bf16 v[0:3], v[200:203], v[0:3], v[36:39]
	v_mfma_f32_16x16x32_bf16 v[212:215], v[200:203], v[16:19], v[32:35]
	v_mfma_f32_16x16x32_bf16 v[52:55], v[152:155], v[4:7], v[20:23]
	v_mfma_f32_16x16x32_bf16 v[48:51], v[152:155], v[192:195], v[56:59]
	v_mfma_f32_16x16x32_bf16 v[36:39], v[182:185], v[4:7], v[60:63]
	v_mfma_f32_16x16x32_bf16 v[32:35], v[182:185], v[192:195], v[208:211]
	v_mfma_f32_16x16x32_bf16 v[20:23], v[196:199], v[4:7], v[44:47]
	v_mfma_f32_16x16x32_bf16 v[16:19], v[196:199], v[192:195], v[40:43]
	v_mfma_f32_16x16x32_bf16 v[4:7], v[204:207], v[4:7], v[0:3]
	v_mfma_f32_16x16x32_bf16 v[0:3], v[204:207], v[192:195], v[212:215]
	v_mfma_f32_16x16x32_bf16 v[28:31], v[174:177], v[224:227], v[28:31]
	v_mfma_f32_16x16x32_bf16 v[24:27], v[174:177], v[232:235], v[24:27]
	v_mfma_f32_16x16x32_bf16 v[40:43], v[178:181], v[224:227], v[134:137]
	v_mfma_f32_16x16x32_bf16 v[134:137], v[178:181], v[232:235], v[138:141]
	v_mfma_f32_16x16x32_bf16 v[12:15], v[186:189], v[224:227], v[12:15]
	v_mfma_f32_16x16x32_bf16 v[8:11], v[186:189], v[232:235], v[8:11]
	v_mfma_f32_16x16x32_bf16 v[138:141], v[200:203], v[224:227], v[156:159]
	v_mfma_f32_16x16x32_bf16 v[156:159], v[200:203], v[232:235], v[170:173]
	v_mfma_f32_16x16x32_bf16 v[60:63], v[152:155], v[228:231], v[28:31]
	v_mfma_f32_16x16x32_bf16 v[56:59], v[152:155], v[236:239], v[24:27]
	v_mfma_f32_16x16x32_bf16 v[44:47], v[182:185], v[228:231], v[40:43]
	v_mfma_f32_16x16x32_bf16 v[40:43], v[182:185], v[236:239], v[134:137]
	v_mfma_f32_16x16x32_bf16 v[28:31], v[196:199], v[228:231], v[12:15]
	v_mfma_f32_16x16x32_bf16 v[24:27], v[196:199], v[236:239], v[8:11]
	v_mfma_f32_16x16x32_bf16 v[12:15], v[204:207], v[228:231], v[138:141]
	v_mfma_f32_16x16x32_bf16 v[8:11], v[204:207], v[236:239], v[156:159]
	v_cmp_gt_u32_e32 vcc, s80, v130
	s_barrier
	s_and_saveexec_b64 s[60:61], vcc
	s_cbranch_execz .LBB0_1150
	s_barrier

; #define STAGE(P, BASE, LD, br, kt) do { const char* _g = (const char*)((BASE) + (size_t)(br) * (LD) + (size_t)(kt) * 64); \
;     for (int _i = 0; _i < 2; ++_i) { int _b = tidx * 16 + _i * 8192; int _r, _c; stage_rc(_b, _r, _c); \
;       __builtin_amdgcn_global_load_lds((const unsigned*)(_g + (unsigned)((_r * (LD) + _c) * 2)), (unsigned*)((char*)(P) + _b), 16, 0, 0); } } while (0)
; #define LDA(dst, b, h) for (int m = 0; m < 4; ++m) for (int k = 0; k < 2; ++k) \
;     dst[m][k] = *reinterpret_cast<const bf16x8*>((char*)SA(b, h) + lds_byte(wr * 64 + m * 16 + fr, k * 32 + fq * 8))
; #define LDB(dst, b, h) for (int n = 0; n < 2; ++n) for (int k = 0; k < 2; ++k) \
;     dst[n][k] = *reinterpret_cast<const bf16x8*>((char*)SB(b, h) + lds_byte(wc * 32 + n * 16 + fr, k * 32 + fq * 8))
; #define MMA(ai, bj, At_, Bt_) do { __builtin_amdgcn_s_setprio(1); \
;     for (int k = 0; k < 2; ++k) for (int m = 0; m < 4; ++m) for (int n = 0; n < 2; ++n) \
;       acc[ai][bj][m][n] = __builtin_amdgcn_mfma_f32_16x16x32_bf16(At_[m][k], Bt_[n][k], acc[ai][bj][m][n], 0, 0, 0); \
;     __builtin_amdgcn_s_setprio(0); } while (0)
; #define WAIT_V(n) asm volatile("s_waitcnt vmcnt(" #n ")" ::: "memory")
; #define WAIT_L(n) asm volatile("s_waitcnt lgkmcnt(" #n ")" ::: "memory")
; #define BAR __builtin_amdgcn_s_barrier()
; #define SCHED __builtin_amdgcn_sched_barrier(0)
; template <int EPI, int lda, int ldb, int N, int K>
; __device__ __forceinline__ void gemm_phase(const u16* __restrict__ A, const u16* __restrict__ Bt, const GemmEpi ep, int wv) {
;     ...
;     if (wr == 1) BAR;
;     WAIT_V(4); BAR;
;     STAGE(SB(1, 0), Bt, ldb, bcol, 1); STAGE(SA(1, 0), Ab, lda, brow, 1); STAGE(SB(1, 1), Bt, ldb, bcol + HALF, 1);
;     WAIT_V(6); BAR;
;     for (int t = 0; t < nt - 2; t += 2) {
;       LDB(B0, 0, 0); SCHED; LDA(At, 0, 0); STAGE(SA(1, 1), Ab, lda, brow + HALF, t + 1);
;       WAIT_L(8); BAR; WAIT_L(0); MMA(0, 0, At, B0); BAR; SCHED;
;       LDB(B1, 0, 1); STAGE(SB(0, 0), Bt, ldb, bcol, t + 2);
;       BAR; WAIT_L(0); MMA(0, 1, At, B1); BAR;
;       LDA(At, 0, 1); STAGE(SA(0, 0), Ab, lda, brow, t + 2);
;       BAR; WAIT_L(0); MMA(1, 0, At, B0); BAR; SCHED;
.LBB0_1248:
	s_or_b64 exec, exec, s[54:55]
	v_mov_b32_e32 v1, v129
	v_add_u32_e32 v7, s60, v6
	v_lshl_add_u64 v[12:13], s[46:47], 0, v[128:129]
	v_lshl_add_u64 v[14:15], s[46:47], 0, v[0:1]
	v_lshl_add_u64 v[2:3], s[52:53], 0, v[128:129]
	v_lshl_add_u64 v[0:1], s[52:53], 0, v[0:1]
	v_readfirstlane_b32 s53, v7
	v_add_u32_e32 v7, 0x2000, v7
	v_mov_b32_e32 v5, v129
	v_mov_b32_e32 v17, v129
	v_lshl_add_u64 v[26:27], v[12:13], 0, s[40:41]
	s_mov_b32 m0, s53
	v_readfirstlane_b32 s52, v7
	v_add_u32_e32 v7, 0x8000, v23
	v_lshl_add_u64 v[8:9], s[50:51], 0, v[4:5]
	v_lshl_add_u64 v[10:11], s[50:51], 0, v[16:17]
	s_waitcnt vmcnt(4)
	s_barrier
	global_load_lds_dwordx4 v[26:27], off
	v_lshl_add_u64 v[26:27], v[14:15], 0, s[40:41]
	s_mov_b32 m0, s52
	v_readfirstlane_b32 s51, v7
	v_add_u32_e32 v7, 0xa000, v23
	global_load_lds_dwordx4 v[26:27], off
	v_lshl_add_u64 v[26:27], v[8:9], 0, s[40:41]
	s_mov_b32 m0, s51
	v_readfirstlane_b32 s50, v7
	v_add_u32_e32 v25, s61, v6
	global_load_lds_dwordx4 v[26:27], off
	v_lshl_add_u64 v[26:27], v[10:11], 0, s[40:41]
	s_mov_b32 m0, s50
	v_readfirstlane_b32 s13, v25
	v_add_u32_e32 v25, 0x2000, v25
	global_load_lds_dwordx4 v[26:27], off
	v_lshl_add_u64 v[26:27], v[2:3], 0, s[40:41]
	s_mov_b32 m0, s13
	v_readfirstlane_b32 s11, v25
	global_load_lds_dwordx4 v[26:27], off
	v_lshl_add_u64 v[6:7], v[0:1], 0, s[40:41]
	s_mov_b32 m0, s11
	v_and_b32_e32 v132, 15, v20
	global_load_lds_dwordx4 v[6:7], off
	v_bfe_u32 v128, v20, 4, 2
	v_lshlrev_b32_e32 v7, 2, v20
	v_bfe_u32 v131, v130, 6, 2
	v_lshlrev_b32_e32 v25, 4, v128
	v_lshlrev_b32_e32 v6, 6, v132
	v_and_b32_e32 v50, 32, v7
	v_lshlrev_b32_e32 v126, 12, v131
	v_bitop3_b32 v127, v25, v50, v6 bitop3:0x36
	v_add3_u32 v133, s58, v127, v126
	s_waitcnt vmcnt(6)
	s_barrier
	ds_read_b128 v[26:29], v133
	ds_read_b128 v[30:33], v133 offset:1024
	ds_read_b128 v[34:37], v133 offset:2048
	ds_read_b128 v[38:41], v133 offset:3072
	v_lshl_add_u64 v[6:7], s[48:49], 0, v[4:5]
	v_lshl_add_u64 v[4:5], s[48:49], 0, v[16:17]
	v_lshlrev_b32_e32 v17, 6, v20
	v_and_b32_e32 v17, 0x3c0, v17
	v_add_u32_e32 v20, 0xc000, v23
	v_lshlrev_b32_e32 v16, 13, v143
	v_bitop3_b32 v17, v17, v50, v25 bitop3:0x36
	v_readfirstlane_b32 s47, v20
	v_add_u32_e32 v20, 0xe000, v23
	v_add3_u32 v228, 0, v127, v16
	v_add3_u32 v229, 0, v17, v16
	v_lshl_add_u64 v[16:17], v[6:7], 0, s[40:41]
	s_mov_b32 m0, s47
	v_readfirstlane_b32 s46, v20
	ds_read_b128 v[42:45], v228
	ds_read_b128 v[46:49], v228 offset:1024
	ds_read_b128 v[50:53], v229 offset:2048
	ds_read_b128 v[54:57], v229 offset:3072
	ds_read_b128 v[58:61], v229 offset:4096
	ds_read_b128 v[62:65], v229 offset:5120
	ds_read_b128 v[66:69], v229 offset:6144
	ds_read_b128 v[70:73], v229 offset:7168
	global_load_lds_dwordx4 v[16:17], off
	v_lshl_add_u64 v[16:17], v[4:5], 0, s[40:41]
	s_mov_b32 m0, s46
	s_nop 0
	global_load_lds_dwordx4 v[16:17], off
	s_waitcnt lgkmcnt(8)
	s_barrier
	s_waitcnt lgkmcnt(0)
	v_mfma_f32_16x16x32_bf16 v[74:77], v[42:45], v[26:29], 0
	v_mfma_f32_16x16x32_bf16 v[78:81], v[42:45], v[34:37], 0
	v_mfma_f32_16x16x32_bf16 v[82:85], v[50:53], v[26:29], 0
	v_mfma_f32_16x16x32_bf16 v[86:89], v[50:53], v[34:37], 0
	v_mfma_f32_16x16x32_bf16 v[90:93], v[58:61], v[26:29], 0
	v_mfma_f32_16x16x32_bf16 v[94:97], v[58:61], v[34:37], 0
	v_mfma_f32_16x16x32_bf16 v[98:101], v[66:69], v[26:29], 0
	v_mfma_f32_16x16x32_bf16 v[102:105], v[66:69], v[34:37], 0
	v_mfma_f32_16x16x32_bf16 v[74:77], v[46:49], v[30:33], v[74:77]
	v_mfma_f32_16x16x32_bf16 v[78:81], v[46:49], v[38:41], v[78:81]
	v_mfma_f32_16x16x32_bf16 v[82:85], v[54:57], v[30:33], v[82:85]
	v_mfma_f32_16x16x32_bf16 v[86:89], v[54:57], v[38:41], v[86:89]
	v_mfma_f32_16x16x32_bf16 v[90:93], v[62:65], v[30:33], v[90:93]
	v_mfma_f32_16x16x32_bf16 v[94:97], v[62:65], v[38:41], v[94:97]
	v_mfma_f32_16x16x32_bf16 v[98:101], v[70:73], v[30:33], v[98:101]
	v_mfma_f32_16x16x32_bf16 v[102:105], v[70:73], v[38:41], v[102:105]
	s_barrier
	v_readfirstlane_b32 s48, v21
	v_add_u32_e32 v20, 0x2000, v21
	v_add3_u32 v224, s59, v127, v126
	v_lshl_add_u64 v[16:17], v[12:13], 0, s[42:43]
	s_mov_b32 m0, s48
	v_readfirstlane_b32 s48, v20
	ds_read_b128 v[106:109], v224
	ds_read_b128 v[110:113], v224 offset:1024
	ds_read_b128 v[114:117], v224 offset:2048
	ds_read_b128 v[118:121], v224 offset:3072
	global_load_lds_dwordx4 v[16:17], off
	v_lshl_add_u64 v[16:17], v[14:15], 0, s[42:43]
	s_mov_b32 m0, s48
	s_nop 0
	global_load_lds_dwordx4 v[16:17], off
	s_barrier
	s_waitcnt lgkmcnt(0)
	v_mfma_f32_16x16x32_bf16 v[122:125], v[42:45], v[106:109], 0
	v_mfma_f32_16x16x32_bf16 v[42:45], v[42:45], v[114:117], 0
	v_mfma_f32_16x16x32_bf16 v[134:137], v[50:53], v[106:109], 0
	v_mfma_f32_16x16x32_bf16 v[50:53], v[50:53], v[114:117], 0
	v_mfma_f32_16x16x32_bf16 v[144:147], v[58:61], v[106:109], 0
	v_mfma_f32_16x16x32_bf16 v[58:61], v[58:61], v[114:117], 0
	v_mfma_f32_16x16x32_bf16 v[148:151], v[66:69], v[106:109], 0
	v_mfma_f32_16x16x32_bf16 v[66:69], v[66:69], v[114:117], 0
	v_mfma_f32_16x16x32_bf16 v[122:125], v[46:49], v[110:113], v[122:125]
	v_mfma_f32_16x16x32_bf16 v[42:45], v[46:49], v[118:121], v[42:45]
	v_mfma_f32_16x16x32_bf16 v[46:49], v[54:57], v[110:113], v[134:137]
	v_mfma_f32_16x16x32_bf16 v[50:53], v[54:57], v[118:121], v[50:53]
	v_mfma_f32_16x16x32_bf16 v[54:57], v[62:65], v[110:113], v[144:147]
	v_mfma_f32_16x16x32_bf16 v[58:61], v[62:65], v[118:121], v[58:61]
	v_mfma_f32_16x16x32_bf16 v[62:65], v[70:73], v[110:113], v[148:151]
	v_mfma_f32_16x16x32_bf16 v[66:69], v[70:73], v[118:121], v[66:69]
	s_barrier
; #define STAGE(P, BASE, LD, br, kt) do { const char* _g = (const char*)((BASE) + (size_t)(br) * (LD) + (size_t)(kt) * 64); \
;     for (int _i = 0; _i < 2; ++_i) { int _b = tidx * 16 + _i * 8192; int _r, _c; stage_rc(_b, _r, _c); \
;       __builtin_amdgcn_global_load_lds((const unsigned*)(_g + (unsigned)((_r * (LD) + _c) * 2)), (unsigned*)((char*)(P) + _b), 16, 0, 0); } } while (0)
; #define LDA(dst, b, h) for (int m = 0; m < 4; ++m) for (int k = 0; k < 2; ++k) \
;     dst[m][k] = *reinterpret_cast<const bf16x8*>((char*)SA(b, h) + lds_byte(wr * 64 + m * 16 + fr, k * 32 + fq * 8))
; #define LDB(dst, b, h) for (int n = 0; n < 2; ++n) for (int k = 0; k < 2; ++k) \
;     dst[n][k] = *reinterpret_cast<const bf16x8*>((char*)SB(b, h) + lds_byte(wc * 32 + n * 16 + fr, k * 32 + fq * 8))
; #define MMA(ai, bj, At_, Bt_) do { __builtin_amdgcn_s_setprio(1); \
;     for (int k = 0; k < 2; ++k) for (int m = 0; m < 4; ++m) for (int n = 0; n < 2; ++n) \
;       acc[ai][bj][m][n] = __builtin_amdgcn_mfma_f32_16x16x32_bf16(At_[m][k], Bt_[n][k], acc[ai][bj][m][n], 0, 0, 0); \
;     __builtin_amdgcn_s_setprio(0); } while (0)
; #define WAIT_V(n) asm volatile("s_waitcnt vmcnt(" #n ")" ::: "memory")
; #define WAIT_L(n) asm volatile("s_waitcnt lgkmcnt(" #n ")" ::: "memory")
; #define BAR __builtin_amdgcn_s_barrier()
; #define SCHED __builtin_amdgcn_sched_barrier(0)
; template <int EPI, int lda, int ldb, int N, int K>
; __device__ __forceinline__ void gemm_phase(const u16* __restrict__ A, const u16* __restrict__ Bt, const GemmEpi ep, int wv) {
;     ...
;       LDA(At, 0, 1); STAGE(SA(0, 0), Ab, lda, brow, t + 2);
;       BAR; WAIT_L(0); MMA(1, 0, At, B0); BAR; SCHED;
;       STAGE(SB(0, 1), Bt, ldb, bcol + HALF, t + 2);
;       WAIT_V(6); BAR; MMA(1, 1, At, B1); BAR;
;       LDB(B0, 1, 0); SCHED; LDA(At, 1, 0); STAGE(SA(0, 1), Ab, lda, brow + HALF, t + 2);
;       WAIT_L(8); BAR; WAIT_L(0); MMA(0, 0, At, B0); BAR; SCHED;
;       LDB(B1, 1, 1); STAGE(SB(1, 0), Bt, ldb, bcol, t + 3);
	v_readfirstlane_b32 s48, v23
	v_lshl_add_u64 v[16:17], v[8:9], 0, s[42:43]
	s_mov_b32 m0, s48
	v_readfirstlane_b32 s48, v24
	ds_read_b128 v[70:73], v228 offset:16384
	ds_read_b128 v[134:137], v228 offset:17408
	ds_read_b128 v[144:147], v229 offset:18432
	ds_read_b128 v[148:151], v229 offset:19456
	ds_read_b128 v[152:155], v229 offset:20480
	ds_read_b128 v[156:159], v229 offset:21504
	ds_read_b128 v[160:163], v229 offset:22528
	ds_read_b128 v[164:167], v229 offset:23552
	global_load_lds_dwordx4 v[16:17], off
	v_lshl_add_u64 v[16:17], v[10:11], 0, s[42:43]
	s_mov_b32 m0, s48
	s_nop 0
	global_load_lds_dwordx4 v[16:17], off
	s_barrier
	s_waitcnt lgkmcnt(0)
	v_mfma_f32_16x16x32_bf16 v[168:171], v[70:73], v[26:29], 0
	v_mfma_f32_16x16x32_bf16 v[172:175], v[70:73], v[34:37], 0
	v_mfma_f32_16x16x32_bf16 v[176:179], v[144:147], v[26:29], 0
	v_mfma_f32_16x16x32_bf16 v[180:183], v[144:147], v[34:37], 0
	v_mfma_f32_16x16x32_bf16 v[184:187], v[152:155], v[26:29], 0
	v_mfma_f32_16x16x32_bf16 v[188:191], v[152:155], v[34:37], 0
	v_mfma_f32_16x16x32_bf16 v[24:27], v[160:163], v[26:29], 0
	v_mfma_f32_16x16x32_bf16 v[34:37], v[160:163], v[34:37], 0
	v_mfma_f32_16x16x32_bf16 v[168:171], v[134:137], v[30:33], v[168:171]
	v_mfma_f32_16x16x32_bf16 v[176:179], v[148:151], v[30:33], v[176:179]
	v_mfma_f32_16x16x32_bf16 v[184:187], v[156:159], v[30:33], v[184:187]
	v_mfma_f32_16x16x32_bf16 v[24:27], v[164:167], v[30:33], v[24:27]
	v_mfma_f32_16x16x32_bf16 v[28:31], v[164:167], v[38:41], v[34:37]
	v_mfma_f32_16x16x32_bf16 v[172:175], v[134:137], v[38:41], v[172:175]
	v_mfma_f32_16x16x32_bf16 v[180:183], v[148:151], v[38:41], v[180:183]
	v_mfma_f32_16x16x32_bf16 v[188:191], v[156:159], v[38:41], v[188:191]
	s_barrier
	v_readfirstlane_b32 s48, v22
	v_add_u32_e32 v20, 0x2000, v22
	v_lshl_add_u64 v[16:17], v[2:3], 0, s[42:43]
	s_mov_b32 m0, s48
	v_readfirstlane_b32 s48, v20
	global_load_lds_dwordx4 v[16:17], off
	v_lshl_add_u64 v[16:17], v[0:1], 0, s[42:43]
	s_mov_b32 m0, s48
	s_nop 0
	global_load_lds_dwordx4 v[16:17], off
	s_waitcnt vmcnt(6)
	s_barrier
	v_mfma_f32_16x16x32_bf16 v[20:23], v[70:73], v[106:109], 0
	v_mfma_f32_16x16x32_bf16 v[32:35], v[70:73], v[114:117], 0
	v_mfma_f32_16x16x32_bf16 v[36:39], v[144:147], v[106:109], 0
	v_mfma_f32_16x16x32_bf16 v[70:73], v[144:147], v[114:117], 0
	v_mfma_f32_16x16x32_bf16 v[144:147], v[152:155], v[106:109], 0
	v_mfma_f32_16x16x32_bf16 v[152:155], v[152:155], v[114:117], 0
	v_mfma_f32_16x16x32_bf16 v[106:109], v[160:163], v[106:109], 0
	v_mfma_f32_16x16x32_bf16 v[114:117], v[160:163], v[114:117], 0
	v_mfma_f32_16x16x32_bf16 v[20:23], v[134:137], v[110:113], v[20:23]
	v_mfma_f32_16x16x32_bf16 v[32:35], v[134:137], v[118:121], v[32:35]
	v_mfma_f32_16x16x32_bf16 v[36:39], v[148:151], v[110:113], v[36:39]
	v_mfma_f32_16x16x32_bf16 v[70:73], v[148:151], v[118:121], v[70:73]
	v_mfma_f32_16x16x32_bf16 v[134:137], v[156:159], v[110:113], v[144:147]
	v_mfma_f32_16x16x32_bf16 v[106:109], v[164:167], v[110:113], v[106:109]
	v_mfma_f32_16x16x32_bf16 v[110:113], v[164:167], v[118:121], v[114:117]
	v_mfma_f32_16x16x32_bf16 v[144:147], v[156:159], v[118:121], v[152:155]
	s_barrier
	v_add3_u32 v225, s60, v127, v126
	ds_read_b128 v[114:117], v225
	ds_read_b128 v[118:121], v225 offset:1024
	ds_read_b128 v[148:151], v225 offset:2048
	ds_read_b128 v[152:155], v225 offset:3072
	v_readfirstlane_b32 s48, v18
	v_lshl_add_u64 v[16:17], v[6:7], 0, s[42:43]
	s_mov_b32 m0, s48
	v_readfirstlane_b32 s48, v19
	ds_read_b128 v[156:159], v228 offset:32768
	ds_read_b128 v[160:163], v228 offset:33792
	ds_read_b128 v[164:167], v229 offset:34816
	ds_read_b128 v[192:195], v229 offset:35840
	ds_read_b128 v[196:199], v229 offset:36864
	ds_read_b128 v[200:203], v229 offset:37888
	ds_read_b128 v[204:207], v229 offset:38912
	ds_read_b128 v[208:211], v229 offset:39936
	global_load_lds_dwordx4 v[16:17], off
	v_lshl_add_u64 v[16:17], v[4:5], 0, s[42:43]
	s_mov_b32 m0, s48
	s_nop 0
	global_load_lds_dwordx4 v[16:17], off
	s_waitcnt lgkmcnt(8)
	s_barrier
	s_waitcnt lgkmcnt(0)
	v_mfma_f32_16x16x32_bf16 v[16:19], v[156:159], v[114:117], v[74:77]
	v_mfma_f32_16x16x32_bf16 v[74:77], v[156:159], v[148:151], v[78:81]
	v_mfma_f32_16x16x32_bf16 v[78:81], v[164:167], v[114:117], v[82:85]
	v_mfma_f32_16x16x32_bf16 v[82:85], v[164:167], v[148:151], v[86:89]
	v_mfma_f32_16x16x32_bf16 v[86:89], v[196:199], v[114:117], v[90:93]
	v_mfma_f32_16x16x32_bf16 v[90:93], v[196:199], v[148:151], v[94:97]
	v_mfma_f32_16x16x32_bf16 v[94:97], v[204:207], v[114:117], v[98:101]
	v_mfma_f32_16x16x32_bf16 v[98:101], v[204:207], v[148:151], v[102:105]
	v_mfma_f32_16x16x32_bf16 v[16:19], v[160:163], v[118:121], v[16:19]
	v_mfma_f32_16x16x32_bf16 v[74:77], v[160:163], v[152:155], v[74:77]
	v_mfma_f32_16x16x32_bf16 v[78:81], v[192:195], v[118:121], v[78:81]
	v_mfma_f32_16x16x32_bf16 v[82:85], v[192:195], v[152:155], v[82:85]
	v_mfma_f32_16x16x32_bf16 v[86:89], v[200:203], v[118:121], v[86:89]
	v_mfma_f32_16x16x32_bf16 v[90:93], v[200:203], v[152:155], v[90:93]
	v_mfma_f32_16x16x32_bf16 v[94:97], v[208:211], v[118:121], v[94:97]
	v_mfma_f32_16x16x32_bf16 v[98:101], v[208:211], v[152:155], v[98:101]
	s_barrier
	s_mov_b32 m0, s53
	v_add3_u32 v226, s61, v127, v126
	v_lshl_add_u64 v[12:13], v[12:13], 0, s[44:45]
	ds_read_b128 v[102:105], v226
	ds_read_b128 v[212:215], v226 offset:1024
	ds_read_b128 v[216:219], v226 offset:2048
	ds_read_b128 v[220:223], v226 offset:3072
	global_load_lds_dwordx4 v[12:13], off
	v_lshl_add_u64 v[12:13], v[14:15], 0, s[44:45]
	s_mov_b32 m0, s52
	s_nop 0
	global_load_lds_dwordx4 v[12:13], off
	s_barrier
; #define STAGE(P, BASE, LD, br, kt) do { const char* _g = (const char*)((BASE) + (size_t)(br) * (LD) + (size_t)(kt) * 64); \
;     for (int _i = 0; _i < 2; ++_i) { int _b = tidx * 16 + _i * 8192; int _r, _c; stage_rc(_b, _r, _c); \
;       __builtin_amdgcn_global_load_lds((const unsigned*)(_g + (unsigned)((_r * (LD) + _c) * 2)), (unsigned*)((char*)(P) + _b), 16, 0, 0); } } while (0)
; #define LDA(dst, b, h) for (int m = 0; m < 4; ++m) for (int k = 0; k < 2; ++k) \
;     dst[m][k] = *reinterpret_cast<const bf16x8*>((char*)SA(b, h) + lds_byte(wr * 64 + m * 16 + fr, k * 32 + fq * 8))
; #define LDB(dst, b, h) for (int n = 0; n < 2; ++n) for (int k = 0; k < 2; ++k) \
;     dst[n][k] = *reinterpret_cast<const bf16x8*>((char*)SB(b, h) + lds_byte(wc * 32 + n * 16 + fr, k * 32 + fq * 8))
; #define MMA(ai, bj, At_, Bt_) do { __builtin_amdgcn_s_setprio(1); \
;     for (int k = 0; k < 2; ++k) for (int m = 0; m < 4; ++m) for (int n = 0; n < 2; ++n) \
;       acc[ai][bj][m][n] = __builtin_amdgcn_mfma_f32_16x16x32_bf16(At_[m][k], Bt_[n][k], acc[ai][bj][m][n], 0, 0, 0); \
;     __builtin_amdgcn_s_setprio(0); } while (0)
; #define WAIT_V(n) asm volatile("s_waitcnt vmcnt(" #n ")" ::: "memory")
; #define WAIT_L(n) asm volatile("s_waitcnt lgkmcnt(" #n ")" ::: "memory")
; #define BAR __builtin_amdgcn_s_barrier()
; #define SCHED __builtin_amdgcn_sched_barrier(0)
; template <int EPI, int lda, int ldb, int N, int K>
; __device__ __forceinline__ void gemm_phase(const u16* __restrict__ A, const u16* __restrict__ Bt, const GemmEpi ep, int wv) {
;     ...
;       BAR; WAIT_L(0); MMA(0, 1, At, B1); BAR;
;       LDA(At, 1, 1); STAGE(SA(1, 0), Ab, lda, brow, t + 3);
;       BAR; WAIT_L(0); MMA(1, 0, At, B0); BAR; SCHED;
;       STAGE(SB(1, 1), Bt, ldb, bcol + HALF, t + 3);
;       WAIT_V(6); BAR; MMA(1, 1, At, B1); BAR;
;     }
;     { LDB(B0, 0, 0); LDA(At, 0, 0); STAGE(SA(1, 1), Ab, lda, brow + HALF, nt - 1);
;       BAR; WAIT_L(0); MMA(0, 0, At, B0); BAR;
	s_waitcnt lgkmcnt(0)
	v_mfma_f32_16x16x32_bf16 v[12:15], v[156:159], v[102:105], v[122:125]
	v_mfma_f32_16x16x32_bf16 v[40:43], v[156:159], v[216:219], v[42:45]
	v_mfma_f32_16x16x32_bf16 v[44:47], v[164:167], v[102:105], v[46:49]
	v_mfma_f32_16x16x32_bf16 v[48:51], v[164:167], v[216:219], v[50:53]
	v_mfma_f32_16x16x32_bf16 v[52:55], v[196:199], v[102:105], v[54:57]
	v_mfma_f32_16x16x32_bf16 v[56:59], v[196:199], v[216:219], v[58:61]
	v_mfma_f32_16x16x32_bf16 v[60:63], v[204:207], v[102:105], v[62:65]
	v_mfma_f32_16x16x32_bf16 v[64:67], v[204:207], v[216:219], v[66:69]
	v_mfma_f32_16x16x32_bf16 v[12:15], v[160:163], v[212:215], v[12:15]
	v_mfma_f32_16x16x32_bf16 v[40:43], v[160:163], v[220:223], v[40:43]
	v_mfma_f32_16x16x32_bf16 v[44:47], v[192:195], v[212:215], v[44:47]
	v_mfma_f32_16x16x32_bf16 v[48:51], v[192:195], v[220:223], v[48:51]
	v_mfma_f32_16x16x32_bf16 v[52:55], v[200:203], v[212:215], v[52:55]
	v_mfma_f32_16x16x32_bf16 v[56:59], v[200:203], v[220:223], v[56:59]
	v_mfma_f32_16x16x32_bf16 v[60:63], v[208:211], v[212:215], v[60:63]
	v_mfma_f32_16x16x32_bf16 v[64:67], v[208:211], v[220:223], v[64:67]
	s_barrier
	s_mov_b32 m0, s51
	v_lshl_add_u64 v[8:9], v[8:9], 0, s[44:45]
	ds_read_b128 v[122:125], v228 offset:49152
	ds_read_b128 v[156:159], v228 offset:50176
	ds_read_b128 v[160:163], v229 offset:51200
	ds_read_b128 v[164:167], v229 offset:52224
	ds_read_b128 v[192:195], v229 offset:53248
	ds_read_b128 v[196:199], v229 offset:54272
	ds_read_b128 v[200:203], v229 offset:55296
	ds_read_b128 v[204:207], v229 offset:56320
	global_load_lds_dwordx4 v[8:9], off
	v_lshl_add_u64 v[8:9], v[10:11], 0, s[44:45]
	s_mov_b32 m0, s50
	s_nop 0
	global_load_lds_dwordx4 v[8:9], off
	s_barrier
	s_waitcnt lgkmcnt(0)
	v_mfma_f32_16x16x32_bf16 v[8:11], v[122:125], v[114:117], v[168:171]
	v_mfma_f32_16x16x32_bf16 v[168:171], v[122:125], v[148:151], v[172:175]
	v_mfma_f32_16x16x32_bf16 v[24:27], v[200:203], v[114:117], v[24:27]
	v_mfma_f32_16x16x32_bf16 v[28:31], v[200:203], v[148:151], v[28:31]
	v_mfma_f32_16x16x32_bf16 v[172:175], v[160:163], v[114:117], v[176:179]
	v_mfma_f32_16x16x32_bf16 v[176:179], v[160:163], v[148:151], v[180:183]
	v_mfma_f32_16x16x32_bf16 v[180:183], v[192:195], v[114:117], v[184:187]
	v_mfma_f32_16x16x32_bf16 v[184:187], v[192:195], v[148:151], v[188:191]
	v_mfma_f32_16x16x32_bf16 v[8:11], v[156:159], v[118:121], v[8:11]
	v_mfma_f32_16x16x32_bf16 v[114:117], v[156:159], v[152:155], v[168:171]
	v_mfma_f32_16x16x32_bf16 v[24:27], v[204:207], v[118:121], v[24:27]
	v_mfma_f32_16x16x32_bf16 v[28:31], v[204:207], v[152:155], v[28:31]
	v_mfma_f32_16x16x32_bf16 v[148:151], v[164:167], v[118:121], v[172:175]
	v_mfma_f32_16x16x32_bf16 v[168:171], v[164:167], v[152:155], v[176:179]
	v_mfma_f32_16x16x32_bf16 v[172:175], v[196:199], v[118:121], v[180:183]
	v_mfma_f32_16x16x32_bf16 v[176:179], v[196:199], v[152:155], v[184:187]
	s_barrier
	s_mov_b32 m0, s13
	v_lshl_add_u64 v[2:3], v[2:3], 0, s[44:45]
	global_load_lds_dwordx4 v[2:3], off
	v_lshl_add_u64 v[0:1], v[0:1], 0, s[44:45]
	s_mov_b32 m0, s11
	s_nop 0
	global_load_lds_dwordx4 v[0:1], off
	s_waitcnt vmcnt(6)
	s_barrier
	v_mfma_f32_16x16x32_bf16 v[0:3], v[122:125], v[102:105], v[20:23]
	v_mfma_f32_16x16x32_bf16 v[20:23], v[122:125], v[216:219], v[32:35]
	v_mfma_f32_16x16x32_bf16 v[32:35], v[160:163], v[102:105], v[36:39]
	v_mfma_f32_16x16x32_bf16 v[36:39], v[160:163], v[216:219], v[70:73]
	v_mfma_f32_16x16x32_bf16 v[68:71], v[192:195], v[102:105], v[134:137]
	v_mfma_f32_16x16x32_bf16 v[118:121], v[192:195], v[216:219], v[144:147]
	v_mfma_f32_16x16x32_bf16 v[102:105], v[200:203], v[102:105], v[106:109]
	v_mfma_f32_16x16x32_bf16 v[106:109], v[200:203], v[216:219], v[110:113]
	v_mfma_f32_16x16x32_bf16 v[0:3], v[156:159], v[212:215], v[0:3]
	v_mfma_f32_16x16x32_bf16 v[20:23], v[156:159], v[220:223], v[20:23]
	v_mfma_f32_16x16x32_bf16 v[32:35], v[164:167], v[212:215], v[32:35]
	v_mfma_f32_16x16x32_bf16 v[36:39], v[164:167], v[220:223], v[36:39]
	v_mfma_f32_16x16x32_bf16 v[68:71], v[196:199], v[212:215], v[68:71]
	v_mfma_f32_16x16x32_bf16 v[110:113], v[196:199], v[220:223], v[118:121]
	v_mfma_f32_16x16x32_bf16 v[102:105], v[204:207], v[212:215], v[102:105]
	v_mfma_f32_16x16x32_bf16 v[106:109], v[204:207], v[220:223], v[106:109]
	s_barrier
	s_mov_b32 m0, s47
	v_lshl_add_u64 v[6:7], v[6:7], 0, s[44:45]
	ds_read_b128 v[118:121], v133
	ds_read_b128 v[122:125], v133 offset:1024
	ds_read_b128 v[134:137], v133 offset:2048
	ds_read_b128 v[144:147], v133 offset:3072
	ds_read_b128 v[152:155], v228
	ds_read_b128 v[156:159], v228 offset:1024
	ds_read_b128 v[160:163], v229 offset:2048
	ds_read_b128 v[164:167], v229 offset:3072
	ds_read_b128 v[180:183], v229 offset:4096
	ds_read_b128 v[184:187], v229 offset:5120
	ds_read_b128 v[188:191], v229 offset:6144
	ds_read_b128 v[192:195], v229 offset:7168
	global_load_lds_dwordx4 v[6:7], off
	v_lshl_add_u64 v[4:5], v[4:5], 0, s[44:45]
	s_mov_b32 m0, s46
	s_nop 0
	global_load_lds_dwordx4 v[4:5], off
	s_barrier
	s_waitcnt lgkmcnt(0)
	v_mfma_f32_16x16x32_bf16 v[4:7], v[152:155], v[118:121], v[16:19]
	v_mfma_f32_16x16x32_bf16 v[16:19], v[152:155], v[134:137], v[74:77]
	v_mfma_f32_16x16x32_bf16 v[72:75], v[160:163], v[118:121], v[78:81]
	v_mfma_f32_16x16x32_bf16 v[76:79], v[160:163], v[134:137], v[82:85]
	v_mfma_f32_16x16x32_bf16 v[80:83], v[180:183], v[118:121], v[86:89]
	v_mfma_f32_16x16x32_bf16 v[84:87], v[180:183], v[134:137], v[90:93]
	v_mfma_f32_16x16x32_bf16 v[88:91], v[188:191], v[118:121], v[94:97]
	v_mfma_f32_16x16x32_bf16 v[92:95], v[188:191], v[134:137], v[98:101]
	v_mfma_f32_16x16x32_bf16 v[4:7], v[156:159], v[122:125], v[4:7]
	v_mfma_f32_16x16x32_bf16 v[16:19], v[156:159], v[144:147], v[16:19]
	v_mfma_f32_16x16x32_bf16 v[72:75], v[164:167], v[122:125], v[72:75]
	v_mfma_f32_16x16x32_bf16 v[76:79], v[164:167], v[144:147], v[76:79]
	v_mfma_f32_16x16x32_bf16 v[80:83], v[184:187], v[122:125], v[80:83]
	v_mfma_f32_16x16x32_bf16 v[84:87], v[184:187], v[144:147], v[84:87]
	v_mfma_f32_16x16x32_bf16 v[88:91], v[192:195], v[122:125], v[88:91]
	v_mfma_f32_16x16x32_bf16 v[92:95], v[192:195], v[144:147], v[92:95]
	s_barrier
; #define LDA(dst, b, h) for (int m = 0; m < 4; ++m) for (int k = 0; k < 2; ++k) \
;     dst[m][k] = *reinterpret_cast<const bf16x8*>((char*)SA(b, h) + lds_byte(wr * 64 + m * 16 + fr, k * 32 + fq * 8))
; #define LDB(dst, b, h) for (int n = 0; n < 2; ++n) for (int k = 0; k < 2; ++k) \
;     dst[n][k] = *reinterpret_cast<const bf16x8*>((char*)SB(b, h) + lds_byte(wc * 32 + n * 16 + fr, k * 32 + fq * 8))
; #define MMA(ai, bj, At_, Bt_) do { __builtin_amdgcn_s_setprio(1); \
;     for (int k = 0; k < 2; ++k) for (int m = 0; m < 4; ++m) for (int n = 0; n < 2; ++n) \
;       acc[ai][bj][m][n] = __builtin_amdgcn_mfma_f32_16x16x32_bf16(At_[m][k], Bt_[n][k], acc[ai][bj][m][n], 0, 0, 0); \
;     __builtin_amdgcn_s_setprio(0); } while (0)
; #define WAIT_V(n) asm volatile("s_waitcnt vmcnt(" #n ")" ::: "memory")
; #define WAIT_L(n) asm volatile("s_waitcnt lgkmcnt(" #n ")" ::: "memory")
; #define BAR __builtin_amdgcn_s_barrier()
; template <int EPI, int lda, int ldb, int N, int K>
; __device__ __forceinline__ void gemm_phase(const u16* __restrict__ A, const u16* __restrict__ Bt, const GemmEpi ep, int wv) {
;     ...
;       LDB(B1, 0, 1); BAR; WAIT_L(0); MMA(0, 1, At, B1); BAR;
;       LDA(At, 0, 1); WAIT_V(4); BAR; WAIT_L(0); MMA(1, 0, At, B0); MMA(1, 1, At, B1); BAR; }
;     { LDB(B0, 1, 0); LDA(At, 1, 0); WAIT_V(2); BAR; WAIT_L(0); MMA(0, 0, At, B0); BAR;
	ds_read_b128 v[96:99], v224
	ds_read_b128 v[196:199], v224 offset:1024
	ds_read_b128 v[200:203], v224 offset:2048
	ds_read_b128 v[204:207], v224 offset:3072
	s_barrier
	s_waitcnt lgkmcnt(0)
	v_mfma_f32_16x16x32_bf16 v[12:15], v[152:155], v[96:99], v[12:15]
	v_mfma_f32_16x16x32_bf16 v[40:43], v[152:155], v[200:203], v[40:43]
	v_mfma_f32_16x16x32_bf16 v[52:55], v[180:183], v[96:99], v[52:55]
	v_mfma_f32_16x16x32_bf16 v[56:59], v[180:183], v[200:203], v[56:59]
	v_mfma_f32_16x16x32_bf16 v[64:67], v[188:191], v[200:203], v[64:67]
	v_mfma_f32_16x16x32_bf16 v[44:47], v[160:163], v[96:99], v[44:47]
	v_mfma_f32_16x16x32_bf16 v[48:51], v[160:163], v[200:203], v[48:51]
	v_mfma_f32_16x16x32_bf16 v[60:63], v[188:191], v[96:99], v[60:63]
	v_mfma_f32_16x16x32_bf16 v[12:15], v[156:159], v[196:199], v[12:15]
	v_mfma_f32_16x16x32_bf16 v[40:43], v[156:159], v[204:207], v[40:43]
	v_mfma_f32_16x16x32_bf16 v[52:55], v[184:187], v[196:199], v[52:55]
	v_mfma_f32_16x16x32_bf16 v[56:59], v[184:187], v[204:207], v[56:59]
	v_mfma_f32_16x16x32_bf16 v[64:67], v[192:195], v[204:207], v[64:67]
	v_mfma_f32_16x16x32_bf16 v[152:155], v[164:167], v[196:199], v[44:47]
	v_mfma_f32_16x16x32_bf16 v[156:159], v[164:167], v[204:207], v[48:51]
	v_mfma_f32_16x16x32_bf16 v[160:163], v[192:195], v[196:199], v[60:63]
	s_barrier
	ds_read_b128 v[44:47], v228 offset:16384
	ds_read_b128 v[48:51], v228 offset:17408
	ds_read_b128 v[60:63], v229 offset:18432
	ds_read_b128 v[164:167], v229 offset:19456
	ds_read_b128 v[180:183], v229 offset:20480
	ds_read_b128 v[184:187], v229 offset:21504
	ds_read_b128 v[188:191], v229 offset:22528
	ds_read_b128 v[192:195], v229 offset:23552
	s_waitcnt vmcnt(4)
	s_barrier
	s_waitcnt lgkmcnt(0)
	v_mfma_f32_16x16x32_bf16 v[8:11], v[44:47], v[118:121], v[8:11]
	v_mfma_f32_16x16x32_bf16 v[24:27], v[188:191], v[118:121], v[24:27]
	v_mfma_f32_16x16x32_bf16 v[28:31], v[188:191], v[134:137], v[28:31]
	v_mfma_f32_16x16x32_bf16 v[114:117], v[44:47], v[134:137], v[114:117]
	v_mfma_f32_16x16x32_bf16 v[148:151], v[60:63], v[118:121], v[148:151]
	v_mfma_f32_16x16x32_bf16 v[168:171], v[60:63], v[134:137], v[168:171]
	v_mfma_f32_16x16x32_bf16 v[172:175], v[180:183], v[118:121], v[172:175]
	v_mfma_f32_16x16x32_bf16 v[176:179], v[180:183], v[134:137], v[176:179]
	v_mfma_f32_16x16x32_bf16 v[8:11], v[48:51], v[122:125], v[8:11]
	v_mfma_f32_16x16x32_bf16 v[24:27], v[192:195], v[122:125], v[24:27]
	v_mfma_f32_16x16x32_bf16 v[28:31], v[192:195], v[144:147], v[28:31]
	v_mfma_f32_16x16x32_bf16 v[134:137], v[48:51], v[144:147], v[114:117]
	v_mfma_f32_16x16x32_bf16 v[148:151], v[164:167], v[122:125], v[148:151]
	v_mfma_f32_16x16x32_bf16 v[168:171], v[164:167], v[144:147], v[168:171]
	v_mfma_f32_16x16x32_bf16 v[172:175], v[184:187], v[122:125], v[172:175]
	v_mfma_f32_16x16x32_bf16 v[176:179], v[184:187], v[144:147], v[176:179]
	v_mfma_f32_16x16x32_bf16 v[0:3], v[44:47], v[96:99], v[0:3]
	v_mfma_f32_16x16x32_bf16 v[20:23], v[44:47], v[200:203], v[20:23]
	v_mfma_f32_16x16x32_bf16 v[44:47], v[180:183], v[96:99], v[68:71]
	v_mfma_f32_16x16x32_bf16 v[68:71], v[188:191], v[96:99], v[102:105]
	v_mfma_f32_16x16x32_bf16 v[32:35], v[60:63], v[96:99], v[32:35]
	v_mfma_f32_16x16x32_bf16 v[36:39], v[60:63], v[200:203], v[36:39]
	v_mfma_f32_16x16x32_bf16 v[60:63], v[180:183], v[200:203], v[110:113]
	v_mfma_f32_16x16x32_bf16 v[96:99], v[188:191], v[200:203], v[106:109]
	v_mfma_f32_16x16x32_bf16 v[20:23], v[48:51], v[204:207], v[20:23]
	v_mfma_f32_16x16x32_bf16 v[68:71], v[192:195], v[196:199], v[68:71]
	v_mfma_f32_16x16x32_bf16 v[144:147], v[48:51], v[196:199], v[0:3]
	v_mfma_f32_16x16x32_bf16 v[180:183], v[164:167], v[196:199], v[32:35]
	v_mfma_f32_16x16x32_bf16 v[164:167], v[164:167], v[204:207], v[36:39]
	v_mfma_f32_16x16x32_bf16 v[188:191], v[184:187], v[196:199], v[44:47]
	v_mfma_f32_16x16x32_bf16 v[184:187], v[184:187], v[204:207], v[60:63]
	v_mfma_f32_16x16x32_bf16 v[192:195], v[192:195], v[204:207], v[96:99]
	s_barrier
	ds_read_b128 v[0:3], v225
	ds_read_b128 v[196:199], v225 offset:1024
	ds_read_b128 v[200:203], v225 offset:2048
	ds_read_b128 v[204:207], v225 offset:3072
	ds_read_b128 v[36:39], v228 offset:32768
	ds_read_b128 v[100:103], v228 offset:33792
	ds_read_b128 v[108:111], v229 offset:34816
	ds_read_b128 v[208:211], v229 offset:35840
	ds_read_b128 v[116:119], v229 offset:36864
	ds_read_b128 v[212:215], v229 offset:37888
	ds_read_b128 v[124:127], v229 offset:38912
	ds_read_b128 v[216:219], v229 offset:39936
	s_waitcnt vmcnt(2)
	s_barrier
; #define LDA(dst, b, h) for (int m = 0; m < 4; ++m) for (int k = 0; k < 2; ++k) \
;     dst[m][k] = *reinterpret_cast<const bf16x8*>((char*)SA(b, h) + lds_byte(wr * 64 + m * 16 + fr, k * 32 + fq * 8))
; #define LDB(dst, b, h) for (int n = 0; n < 2; ++n) for (int k = 0; k < 2; ++k) \
;     dst[n][k] = *reinterpret_cast<const bf16x8*>((char*)SB(b, h) + lds_byte(wc * 32 + n * 16 + fr, k * 32 + fq * 8))
; #define MMA(ai, bj, At_, Bt_) do { __builtin_amdgcn_s_setprio(1); \
;     for (int k = 0; k < 2; ++k) for (int m = 0; m < 4; ++m) for (int n = 0; n < 2; ++n) \
;       acc[ai][bj][m][n] = __builtin_amdgcn_mfma_f32_16x16x32_bf16(At_[m][k], Bt_[n][k], acc[ai][bj][m][n], 0, 0, 0); \
;     __builtin_amdgcn_s_setprio(0); } while (0)
; #define WAIT_V(n) asm volatile("s_waitcnt vmcnt(" #n ")" ::: "memory")
; #define WAIT_L(n) asm volatile("s_waitcnt lgkmcnt(" #n ")" ::: "memory")
; #define BAR __builtin_amdgcn_s_barrier()
; template <int EPI, int lda, int ldb, int N, int K>
; __device__ __forceinline__ void gemm_phase(const u16* __restrict__ A, const u16* __restrict__ Bt, const GemmEpi ep, int wv) {
;     ...
;     { LDB(B0, 1, 0); LDA(At, 1, 0); WAIT_V(2); BAR; WAIT_L(0); MMA(0, 0, At, B0); BAR;
;       LDB(B1, 1, 1); WAIT_V(0); BAR; WAIT_L(0); MMA(0, 1, At, B1); BAR;
;       LDA(At, 1, 1); BAR; WAIT_L(0); MMA(1, 0, At, B0); MMA(1, 1, At, B1); BAR; }
;     if (wr == 0) BAR;
	s_waitcnt lgkmcnt(0)
	v_mfma_f32_16x16x32_bf16 v[4:7], v[36:39], v[0:3], v[4:7]
	v_mfma_f32_16x16x32_bf16 v[16:19], v[36:39], v[200:203], v[16:19]
	v_mfma_f32_16x16x32_bf16 v[32:35], v[108:111], v[0:3], v[72:75]
	v_mfma_f32_16x16x32_bf16 v[44:47], v[108:111], v[200:203], v[76:79]
	v_mfma_f32_16x16x32_bf16 v[72:75], v[116:119], v[0:3], v[80:83]
	v_mfma_f32_16x16x32_bf16 v[76:79], v[116:119], v[200:203], v[84:87]
	v_mfma_f32_16x16x32_bf16 v[80:83], v[124:127], v[0:3], v[88:91]
	v_mfma_f32_16x16x32_bf16 v[84:87], v[124:127], v[200:203], v[92:95]
	v_mfma_f32_16x16x32_bf16 v[120:123], v[100:103], v[196:199], v[4:7]
	v_mfma_f32_16x16x32_bf16 v[60:63], v[100:103], v[204:207], v[16:19]
	v_mfma_f32_16x16x32_bf16 v[112:115], v[208:211], v[196:199], v[32:35]
	v_mfma_f32_16x16x32_bf16 v[48:51], v[208:211], v[204:207], v[44:47]
	v_mfma_f32_16x16x32_bf16 v[104:107], v[212:215], v[196:199], v[72:75]
	v_mfma_f32_16x16x32_bf16 v[44:47], v[212:215], v[204:207], v[76:79]
	v_mfma_f32_16x16x32_bf16 v[96:99], v[216:219], v[196:199], v[80:83]
	v_mfma_f32_16x16x32_bf16 v[32:35], v[216:219], v[204:207], v[84:87]
	s_barrier
	ds_read_b128 v[4:7], v226
	ds_read_b128 v[220:223], v226 offset:1024
	ds_read_b128 v[76:79], v226 offset:2048
	ds_read_b128 v[224:227], v226 offset:3072
	s_waitcnt vmcnt(0)
	s_barrier
	s_waitcnt lgkmcnt(0)
	v_mfma_f32_16x16x32_bf16 v[12:15], v[36:39], v[4:7], v[12:15]
	v_mfma_f32_16x16x32_bf16 v[16:19], v[36:39], v[76:79], v[40:43]
	v_mfma_f32_16x16x32_bf16 v[36:39], v[108:111], v[4:7], v[152:155]
	v_mfma_f32_16x16x32_bf16 v[40:43], v[108:111], v[76:79], v[156:159]
	v_mfma_f32_16x16x32_bf16 v[72:75], v[116:119], v[4:7], v[52:55]
	v_mfma_f32_16x16x32_bf16 v[80:83], v[116:119], v[76:79], v[56:59]
	v_mfma_f32_16x16x32_bf16 v[84:87], v[124:127], v[4:7], v[160:163]
	v_mfma_f32_16x16x32_bf16 v[64:67], v[124:127], v[76:79], v[64:67]
	v_mfma_f32_16x16x32_bf16 v[124:127], v[100:103], v[220:223], v[12:15]
	v_mfma_f32_16x16x32_bf16 v[56:59], v[100:103], v[224:227], v[16:19]
	v_mfma_f32_16x16x32_bf16 v[116:119], v[208:211], v[220:223], v[36:39]
	v_mfma_f32_16x16x32_bf16 v[52:55], v[208:211], v[224:227], v[40:43]
	v_mfma_f32_16x16x32_bf16 v[108:111], v[212:215], v[220:223], v[72:75]
	v_mfma_f32_16x16x32_bf16 v[40:43], v[212:215], v[224:227], v[80:83]
	v_mfma_f32_16x16x32_bf16 v[100:103], v[216:219], v[220:223], v[84:87]
	v_mfma_f32_16x16x32_bf16 v[36:39], v[216:219], v[224:227], v[64:67]
	s_barrier
	ds_read_b128 v[84:87], v228 offset:49152
	ds_read_b128 v[152:155], v228 offset:50176
	ds_read_b128 v[92:95], v229 offset:51200
	ds_read_b128 v[156:159], v229 offset:52224
	ds_read_b128 v[160:163], v229 offset:53248
	ds_read_b128 v[208:211], v229 offset:54272
	ds_read_b128 v[212:215], v229 offset:55296
	ds_read_b128 v[216:219], v229 offset:56320
	s_barrier
	s_waitcnt lgkmcnt(0)
	v_mfma_f32_16x16x32_bf16 v[8:11], v[84:87], v[0:3], v[8:11]
	v_mfma_f32_16x16x32_bf16 v[12:15], v[84:87], v[200:203], v[134:137]
	v_mfma_f32_16x16x32_bf16 v[16:19], v[92:95], v[0:3], v[148:151]
	v_mfma_f32_16x16x32_bf16 v[64:67], v[92:95], v[200:203], v[168:171]
	v_mfma_f32_16x16x32_bf16 v[72:75], v[160:163], v[0:3], v[172:175]
	v_mfma_f32_16x16x32_bf16 v[134:137], v[160:163], v[200:203], v[176:179]
	v_mfma_f32_16x16x32_bf16 v[0:3], v[212:215], v[0:3], v[24:27]
	v_mfma_f32_16x16x32_bf16 v[24:27], v[212:215], v[200:203], v[28:31]
	v_mfma_f32_16x16x32_bf16 v[88:91], v[152:155], v[196:199], v[8:11]
	v_mfma_f32_16x16x32_bf16 v[28:31], v[152:155], v[204:207], v[12:15]
	v_mfma_f32_16x16x32_bf16 v[80:83], v[156:159], v[196:199], v[16:19]
	v_mfma_f32_16x16x32_bf16 v[16:19], v[156:159], v[204:207], v[64:67]
	v_mfma_f32_16x16x32_bf16 v[72:75], v[208:211], v[196:199], v[72:75]
	v_mfma_f32_16x16x32_bf16 v[12:15], v[208:211], v[204:207], v[134:137]
	v_mfma_f32_16x16x32_bf16 v[64:67], v[216:219], v[196:199], v[0:3]
	v_mfma_f32_16x16x32_bf16 v[0:3], v[216:219], v[204:207], v[24:27]
	v_mfma_f32_16x16x32_bf16 v[8:11], v[84:87], v[4:7], v[144:147]
	v_mfma_f32_16x16x32_bf16 v[20:23], v[84:87], v[76:79], v[20:23]
	v_mfma_f32_16x16x32_bf16 v[84:87], v[92:95], v[4:7], v[180:183]
	v_mfma_f32_16x16x32_bf16 v[134:137], v[92:95], v[76:79], v[164:167]
	v_mfma_f32_16x16x32_bf16 v[144:147], v[160:163], v[4:7], v[188:191]
	v_mfma_f32_16x16x32_bf16 v[148:151], v[160:163], v[76:79], v[184:187]
	v_mfma_f32_16x16x32_bf16 v[4:7], v[212:215], v[4:7], v[68:71]
	v_mfma_f32_16x16x32_bf16 v[160:163], v[212:215], v[76:79], v[192:195]
	v_mfma_f32_16x16x32_bf16 v[92:95], v[152:155], v[220:223], v[8:11]
	v_mfma_f32_16x16x32_bf16 v[24:27], v[152:155], v[224:227], v[20:23]
	v_mfma_f32_16x16x32_bf16 v[84:87], v[156:159], v[220:223], v[84:87]
	v_mfma_f32_16x16x32_bf16 v[20:23], v[156:159], v[224:227], v[134:137]
	v_mfma_f32_16x16x32_bf16 v[76:79], v[208:211], v[220:223], v[144:147]
	v_mfma_f32_16x16x32_bf16 v[8:11], v[208:211], v[224:227], v[148:151]
	v_mfma_f32_16x16x32_bf16 v[68:71], v[216:219], v[220:223], v[4:7]
	v_mfma_f32_16x16x32_bf16 v[4:7], v[216:219], v[224:227], v[160:163]
	v_cmp_gt_u32_e32 vcc, s62, v130
	s_barrier
	s_and_saveexec_b64 s[46:47], vcc
	s_cbranch_execz .LBB0_1245
	s_barrier
	s_branch .LBB0_1245

; #define STAGE(P, BASE, LD, br, kt) do { const char* _g = (const char*)((BASE) + (size_t)(br) * (LD) + (size_t)(kt) * 64); \
;     for (int _i = 0; _i < 2; ++_i) { int _b = tidx * 16 + _i * 8192; int _r, _c; stage_rc(_b, _r, _c); \
;       __builtin_amdgcn_global_load_lds((const unsigned*)(_g + (unsigned)((_r * (LD) + _c) * 2)), (unsigned*)((char*)(P) + _b), 16, 0, 0); } } while (0)
; #define LDA(dst, b, h) for (int m = 0; m < 4; ++m) for (int k = 0; k < 2; ++k) \
;     dst[m][k] = *reinterpret_cast<const bf16x8*>((char*)SA(b, h) + lds_byte(wr * 64 + m * 16 + fr, k * 32 + fq * 8))
; #define LDB(dst, b, h) for (int n = 0; n < 2; ++n) for (int k = 0; k < 2; ++k) \
;     dst[n][k] = *reinterpret_cast<const bf16x8*>((char*)SB(b, h) + lds_byte(wc * 32 + n * 16 + fr, k * 32 + fq * 8))
; #define MMA(ai, bj, At_, Bt_) do { __builtin_amdgcn_s_setprio(1); \
;     for (int k = 0; k < 2; ++k) for (int m = 0; m < 4; ++m) for (int n = 0; n < 2; ++n) \
;       acc[ai][bj][m][n] = __builtin_amdgcn_mfma_f32_16x16x32_bf16(At_[m][k], Bt_[n][k], acc[ai][bj][m][n], 0, 0, 0); \
;     __builtin_amdgcn_s_setprio(0); } while (0)
; #define WAIT_V(n) asm volatile("s_waitcnt vmcnt(" #n ")" ::: "memory")
; #define WAIT_L(n) asm volatile("s_waitcnt lgkmcnt(" #n ")" ::: "memory")
; #define BAR __builtin_amdgcn_s_barrier()
; #define SCHED __builtin_amdgcn_sched_barrier(0)
; template <int EPI, int lda, int ldb, int N, int K>
; __device__ __forceinline__ void gemm_phase(const u16* __restrict__ A, const u16* __restrict__ Bt, const GemmEpi ep, int wv) {
;     ...
;     if (wr == 1) BAR;
;     WAIT_V(4); BAR;
;     STAGE(SB(1, 0), Bt, ldb, bcol, 1); STAGE(SA(1, 0), Ab, lda, brow, 1); STAGE(SB(1, 1), Bt, ldb, bcol + HALF, 1);
;     WAIT_V(6); BAR;
;     for (int t = 0; t < nt - 2; t += 2) {
;       LDB(B0, 0, 0); SCHED; LDA(At, 0, 0); STAGE(SA(1, 1), Ab, lda, brow + HALF, t + 1);
;       WAIT_L(8); BAR; WAIT_L(0); MMA(0, 0, At, B0); BAR; SCHED;
;       LDB(B1, 0, 1); STAGE(SB(0, 0), Bt, ldb, bcol, t + 2);
;       BAR; WAIT_L(0); MMA(0, 1, At, B1); BAR;
;       LDA(At, 0, 1); STAGE(SA(0, 0), Ab, lda, brow, t + 2);
;       BAR; WAIT_L(0); MMA(1, 0, At, B0); BAR; SCHED;
.LBB0_1349:
	s_or_b64 exec, exec, s[54:55]
	v_mov_b32_e32 v1, v129
	v_add_u32_e32 v7, s58, v6
	v_lshl_add_u64 v[12:13], s[46:47], 0, v[128:129]
	v_lshl_add_u64 v[14:15], s[46:47], 0, v[0:1]
	v_lshl_add_u64 v[2:3], s[52:53], 0, v[128:129]
	v_lshl_add_u64 v[0:1], s[52:53], 0, v[0:1]
	v_readfirstlane_b32 s53, v7
	v_add_u32_e32 v7, 0x2000, v7
	v_mov_b32_e32 v5, v129
	v_mov_b32_e32 v17, v129
	v_lshl_add_u64 v[26:27], v[12:13], 0, s[36:37]
	s_mov_b32 m0, s53
	v_readfirstlane_b32 s52, v7
	v_add_u32_e32 v7, 0x8000, v23
	v_lshl_add_u64 v[8:9], s[50:51], 0, v[4:5]
	v_lshl_add_u64 v[10:11], s[50:51], 0, v[16:17]
	s_waitcnt vmcnt(4)
	s_barrier
	global_load_lds_dwordx4 v[26:27], off
	v_lshl_add_u64 v[26:27], v[14:15], 0, s[36:37]
	s_mov_b32 m0, s52
	v_readfirstlane_b32 s51, v7
	v_add_u32_e32 v7, 0xa000, v23
	global_load_lds_dwordx4 v[26:27], off
	v_lshl_add_u64 v[26:27], v[8:9], 0, s[36:37]
	s_mov_b32 m0, s51
	v_readfirstlane_b32 s50, v7
	v_add_u32_e32 v25, s59, v6
	global_load_lds_dwordx4 v[26:27], off
	v_lshl_add_u64 v[26:27], v[10:11], 0, s[36:37]
	s_mov_b32 m0, s50
	v_readfirstlane_b32 s11, v25
	v_add_u32_e32 v25, 0x2000, v25
	global_load_lds_dwordx4 v[26:27], off
	v_lshl_add_u64 v[26:27], v[2:3], 0, s[36:37]
	s_mov_b32 m0, s11
	v_readfirstlane_b32 s5, v25
	global_load_lds_dwordx4 v[26:27], off
	v_lshl_add_u64 v[6:7], v[0:1], 0, s[36:37]
	s_mov_b32 m0, s5
	v_and_b32_e32 v132, 15, v20
	global_load_lds_dwordx4 v[6:7], off
	v_bfe_u32 v128, v20, 4, 2
	v_lshlrev_b32_e32 v7, 2, v20
	v_bfe_u32 v131, v130, 6, 2
	v_lshlrev_b32_e32 v25, 4, v128
	v_lshlrev_b32_e32 v6, 6, v132
	v_and_b32_e32 v50, 32, v7
	v_lshlrev_b32_e32 v126, 12, v131
	v_bitop3_b32 v127, v25, v50, v6 bitop3:0x36
	v_add3_u32 v133, s56, v127, v126
	s_waitcnt vmcnt(6)
	s_barrier
	ds_read_b128 v[26:29], v133
	ds_read_b128 v[30:33], v133 offset:1024
	ds_read_b128 v[34:37], v133 offset:2048
	ds_read_b128 v[38:41], v133 offset:3072
	v_lshl_add_u64 v[6:7], s[48:49], 0, v[4:5]
	v_lshl_add_u64 v[4:5], s[48:49], 0, v[16:17]
	v_lshlrev_b32_e32 v17, 6, v20
	v_and_b32_e32 v17, 0x3c0, v17
	v_add_u32_e32 v20, 0xc000, v23
	v_lshlrev_b32_e32 v16, 13, v139
	v_bitop3_b32 v17, v17, v50, v25 bitop3:0x36
	v_readfirstlane_b32 s47, v20
	v_add_u32_e32 v20, 0xe000, v23
	v_add3_u32 v228, 0, v127, v16
	v_add3_u32 v229, 0, v17, v16
	v_lshl_add_u64 v[16:17], v[6:7], 0, s[36:37]
	s_mov_b32 m0, s47
	v_readfirstlane_b32 s46, v20
	ds_read_b128 v[42:45], v228
	ds_read_b128 v[46:49], v228 offset:1024
	ds_read_b128 v[50:53], v229 offset:2048
	ds_read_b128 v[54:57], v229 offset:3072
	ds_read_b128 v[58:61], v229 offset:4096
	ds_read_b128 v[62:65], v229 offset:5120
	ds_read_b128 v[66:69], v229 offset:6144
	ds_read_b128 v[70:73], v229 offset:7168
	global_load_lds_dwordx4 v[16:17], off
	v_lshl_add_u64 v[16:17], v[4:5], 0, s[36:37]
	s_mov_b32 m0, s46
	s_nop 0
	global_load_lds_dwordx4 v[16:17], off
	s_waitcnt lgkmcnt(8)
	s_barrier
	s_waitcnt lgkmcnt(0)
	v_mfma_f32_16x16x32_bf16 v[74:77], v[42:45], v[26:29], 0
	v_mfma_f32_16x16x32_bf16 v[78:81], v[42:45], v[34:37], 0
	v_mfma_f32_16x16x32_bf16 v[82:85], v[50:53], v[26:29], 0
	v_mfma_f32_16x16x32_bf16 v[86:89], v[50:53], v[34:37], 0
	v_mfma_f32_16x16x32_bf16 v[90:93], v[58:61], v[26:29], 0
	v_mfma_f32_16x16x32_bf16 v[94:97], v[58:61], v[34:37], 0
	v_mfma_f32_16x16x32_bf16 v[98:101], v[66:69], v[26:29], 0
	v_mfma_f32_16x16x32_bf16 v[102:105], v[66:69], v[34:37], 0
	v_mfma_f32_16x16x32_bf16 v[74:77], v[46:49], v[30:33], v[74:77]
	v_mfma_f32_16x16x32_bf16 v[78:81], v[46:49], v[38:41], v[78:81]
	v_mfma_f32_16x16x32_bf16 v[82:85], v[54:57], v[30:33], v[82:85]
	v_mfma_f32_16x16x32_bf16 v[86:89], v[54:57], v[38:41], v[86:89]
	v_mfma_f32_16x16x32_bf16 v[90:93], v[62:65], v[30:33], v[90:93]
	v_mfma_f32_16x16x32_bf16 v[94:97], v[62:65], v[38:41], v[94:97]
	v_mfma_f32_16x16x32_bf16 v[98:101], v[70:73], v[30:33], v[98:101]
	v_mfma_f32_16x16x32_bf16 v[102:105], v[70:73], v[38:41], v[102:105]
	s_barrier
	v_readfirstlane_b32 s48, v21
	v_add_u32_e32 v20, 0x2000, v21
	v_add3_u32 v224, s57, v127, v126
	v_lshl_add_u64 v[16:17], v[12:13], 0, s[38:39]
	s_mov_b32 m0, s48
	v_readfirstlane_b32 s48, v20
	ds_read_b128 v[106:109], v224
	ds_read_b128 v[110:113], v224 offset:1024
	ds_read_b128 v[114:117], v224 offset:2048
	ds_read_b128 v[118:121], v224 offset:3072
	global_load_lds_dwordx4 v[16:17], off
	v_lshl_add_u64 v[16:17], v[14:15], 0, s[38:39]
	s_mov_b32 m0, s48
	s_nop 0
	global_load_lds_dwordx4 v[16:17], off
	s_barrier
	s_waitcnt lgkmcnt(0)
	v_mfma_f32_16x16x32_bf16 v[122:125], v[42:45], v[106:109], 0
	v_mfma_f32_16x16x32_bf16 v[42:45], v[42:45], v[114:117], 0
	v_mfma_f32_16x16x32_bf16 v[140:143], v[50:53], v[106:109], 0
	v_mfma_f32_16x16x32_bf16 v[50:53], v[50:53], v[114:117], 0
	v_mfma_f32_16x16x32_bf16 v[144:147], v[58:61], v[106:109], 0
	v_mfma_f32_16x16x32_bf16 v[58:61], v[58:61], v[114:117], 0
	v_mfma_f32_16x16x32_bf16 v[148:151], v[66:69], v[106:109], 0
	v_mfma_f32_16x16x32_bf16 v[66:69], v[66:69], v[114:117], 0
	v_mfma_f32_16x16x32_bf16 v[122:125], v[46:49], v[110:113], v[122:125]
	v_mfma_f32_16x16x32_bf16 v[42:45], v[46:49], v[118:121], v[42:45]
	v_mfma_f32_16x16x32_bf16 v[46:49], v[54:57], v[110:113], v[140:143]
	v_mfma_f32_16x16x32_bf16 v[50:53], v[54:57], v[118:121], v[50:53]
	v_mfma_f32_16x16x32_bf16 v[54:57], v[62:65], v[110:113], v[144:147]
	v_mfma_f32_16x16x32_bf16 v[58:61], v[62:65], v[118:121], v[58:61]
	v_mfma_f32_16x16x32_bf16 v[62:65], v[70:73], v[110:113], v[148:151]
	v_mfma_f32_16x16x32_bf16 v[66:69], v[70:73], v[118:121], v[66:69]
	s_barrier
; #define STAGE(P, BASE, LD, br, kt) do { const char* _g = (const char*)((BASE) + (size_t)(br) * (LD) + (size_t)(kt) * 64); \
;     for (int _i = 0; _i < 2; ++_i) { int _b = tidx * 16 + _i * 8192; int _r, _c; stage_rc(_b, _r, _c); \
;       __builtin_amdgcn_global_load_lds((const unsigned*)(_g + (unsigned)((_r * (LD) + _c) * 2)), (unsigned*)((char*)(P) + _b), 16, 0, 0); } } while (0)
; #define LDA(dst, b, h) for (int m = 0; m < 4; ++m) for (int k = 0; k < 2; ++k) \
;     dst[m][k] = *reinterpret_cast<const bf16x8*>((char*)SA(b, h) + lds_byte(wr * 64 + m * 16 + fr, k * 32 + fq * 8))
; #define LDB(dst, b, h) for (int n = 0; n < 2; ++n) for (int k = 0; k < 2; ++k) \
;     dst[n][k] = *reinterpret_cast<const bf16x8*>((char*)SB(b, h) + lds_byte(wc * 32 + n * 16 + fr, k * 32 + fq * 8))
; #define MMA(ai, bj, At_, Bt_) do { __builtin_amdgcn_s_setprio(1); \
;     for (int k = 0; k < 2; ++k) for (int m = 0; m < 4; ++m) for (int n = 0; n < 2; ++n) \
;       acc[ai][bj][m][n] = __builtin_amdgcn_mfma_f32_16x16x32_bf16(At_[m][k], Bt_[n][k], acc[ai][bj][m][n], 0, 0, 0); \
;     __builtin_amdgcn_s_setprio(0); } while (0)
; #define WAIT_V(n) asm volatile("s_waitcnt vmcnt(" #n ")" ::: "memory")
; #define WAIT_L(n) asm volatile("s_waitcnt lgkmcnt(" #n ")" ::: "memory")
; #define BAR __builtin_amdgcn_s_barrier()
; #define SCHED __builtin_amdgcn_sched_barrier(0)
; template <int EPI, int lda, int ldb, int N, int K>
; __device__ __forceinline__ void gemm_phase(const u16* __restrict__ A, const u16* __restrict__ Bt, const GemmEpi ep, int wv) {
;     ...
;       LDA(At, 0, 1); STAGE(SA(0, 0), Ab, lda, brow, t + 2);
;       BAR; WAIT_L(0); MMA(1, 0, At, B0); BAR; SCHED;
;       STAGE(SB(0, 1), Bt, ldb, bcol + HALF, t + 2);
;       WAIT_V(6); BAR; MMA(1, 1, At, B1); BAR;
;       LDB(B0, 1, 0); SCHED; LDA(At, 1, 0); STAGE(SA(0, 1), Ab, lda, brow + HALF, t + 2);
;       WAIT_L(8); BAR; WAIT_L(0); MMA(0, 0, At, B0); BAR; SCHED;
;       LDB(B1, 1, 1); STAGE(SB(1, 0), Bt, ldb, bcol, t + 3);
	v_readfirstlane_b32 s48, v23
	v_lshl_add_u64 v[16:17], v[8:9], 0, s[38:39]
	s_mov_b32 m0, s48
	v_readfirstlane_b32 s48, v24
	ds_read_b128 v[70:73], v228 offset:16384
	ds_read_b128 v[140:143], v228 offset:17408
	ds_read_b128 v[144:147], v229 offset:18432
	ds_read_b128 v[148:151], v229 offset:19456
	ds_read_b128 v[152:155], v229 offset:20480
	ds_read_b128 v[156:159], v229 offset:21504
	ds_read_b128 v[160:163], v229 offset:22528
	ds_read_b128 v[164:167], v229 offset:23552
	global_load_lds_dwordx4 v[16:17], off
	v_lshl_add_u64 v[16:17], v[10:11], 0, s[38:39]
	s_mov_b32 m0, s48
	s_nop 0
	global_load_lds_dwordx4 v[16:17], off
	s_barrier
	s_waitcnt lgkmcnt(0)
	v_mfma_f32_16x16x32_bf16 v[168:171], v[70:73], v[26:29], 0
	v_mfma_f32_16x16x32_bf16 v[172:175], v[70:73], v[34:37], 0
	v_mfma_f32_16x16x32_bf16 v[176:179], v[144:147], v[26:29], 0
	v_mfma_f32_16x16x32_bf16 v[180:183], v[144:147], v[34:37], 0
	v_mfma_f32_16x16x32_bf16 v[184:187], v[152:155], v[26:29], 0
	v_mfma_f32_16x16x32_bf16 v[188:191], v[152:155], v[34:37], 0
	v_mfma_f32_16x16x32_bf16 v[24:27], v[160:163], v[26:29], 0
	v_mfma_f32_16x16x32_bf16 v[34:37], v[160:163], v[34:37], 0
	v_mfma_f32_16x16x32_bf16 v[168:171], v[140:143], v[30:33], v[168:171]
	v_mfma_f32_16x16x32_bf16 v[176:179], v[148:151], v[30:33], v[176:179]
	v_mfma_f32_16x16x32_bf16 v[184:187], v[156:159], v[30:33], v[184:187]
	v_mfma_f32_16x16x32_bf16 v[24:27], v[164:167], v[30:33], v[24:27]
	v_mfma_f32_16x16x32_bf16 v[28:31], v[164:167], v[38:41], v[34:37]
	v_mfma_f32_16x16x32_bf16 v[172:175], v[140:143], v[38:41], v[172:175]
	v_mfma_f32_16x16x32_bf16 v[180:183], v[148:151], v[38:41], v[180:183]
	v_mfma_f32_16x16x32_bf16 v[188:191], v[156:159], v[38:41], v[188:191]
	s_barrier
	v_readfirstlane_b32 s48, v22
	v_add_u32_e32 v20, 0x2000, v22
	v_lshl_add_u64 v[16:17], v[2:3], 0, s[38:39]
	s_mov_b32 m0, s48
	v_readfirstlane_b32 s48, v20
	global_load_lds_dwordx4 v[16:17], off
	v_lshl_add_u64 v[16:17], v[0:1], 0, s[38:39]
	s_mov_b32 m0, s48
	s_nop 0
	global_load_lds_dwordx4 v[16:17], off
	s_waitcnt vmcnt(6)
	s_barrier
	v_mfma_f32_16x16x32_bf16 v[20:23], v[70:73], v[106:109], 0
	v_mfma_f32_16x16x32_bf16 v[32:35], v[70:73], v[114:117], 0
	v_mfma_f32_16x16x32_bf16 v[36:39], v[144:147], v[106:109], 0
	v_mfma_f32_16x16x32_bf16 v[70:73], v[144:147], v[114:117], 0
	v_mfma_f32_16x16x32_bf16 v[144:147], v[152:155], v[106:109], 0
	v_mfma_f32_16x16x32_bf16 v[152:155], v[152:155], v[114:117], 0
	v_mfma_f32_16x16x32_bf16 v[106:109], v[160:163], v[106:109], 0
	v_mfma_f32_16x16x32_bf16 v[114:117], v[160:163], v[114:117], 0
	v_mfma_f32_16x16x32_bf16 v[20:23], v[140:143], v[110:113], v[20:23]
	v_mfma_f32_16x16x32_bf16 v[32:35], v[140:143], v[118:121], v[32:35]
	v_mfma_f32_16x16x32_bf16 v[36:39], v[148:151], v[110:113], v[36:39]
	v_mfma_f32_16x16x32_bf16 v[70:73], v[148:151], v[118:121], v[70:73]
	v_mfma_f32_16x16x32_bf16 v[140:143], v[156:159], v[110:113], v[144:147]
	v_mfma_f32_16x16x32_bf16 v[106:109], v[164:167], v[110:113], v[106:109]
	v_mfma_f32_16x16x32_bf16 v[110:113], v[164:167], v[118:121], v[114:117]
	v_mfma_f32_16x16x32_bf16 v[144:147], v[156:159], v[118:121], v[152:155]
	s_barrier
	v_add3_u32 v225, s58, v127, v126
	ds_read_b128 v[114:117], v225
	ds_read_b128 v[118:121], v225 offset:1024
	ds_read_b128 v[148:151], v225 offset:2048
	ds_read_b128 v[152:155], v225 offset:3072
	v_readfirstlane_b32 s48, v18
	v_lshl_add_u64 v[16:17], v[6:7], 0, s[38:39]
	s_mov_b32 m0, s48
	v_readfirstlane_b32 s48, v19
	ds_read_b128 v[156:159], v228 offset:32768
	ds_read_b128 v[160:163], v228 offset:33792
	ds_read_b128 v[164:167], v229 offset:34816
	ds_read_b128 v[192:195], v229 offset:35840
	ds_read_b128 v[196:199], v229 offset:36864
	ds_read_b128 v[200:203], v229 offset:37888
	ds_read_b128 v[204:207], v229 offset:38912
	ds_read_b128 v[208:211], v229 offset:39936
	global_load_lds_dwordx4 v[16:17], off
	v_lshl_add_u64 v[16:17], v[4:5], 0, s[38:39]
	s_mov_b32 m0, s48
	s_nop 0
	global_load_lds_dwordx4 v[16:17], off
	s_waitcnt lgkmcnt(8)
	s_barrier
	s_waitcnt lgkmcnt(0)
	v_mfma_f32_16x16x32_bf16 v[16:19], v[156:159], v[114:117], v[74:77]
	v_mfma_f32_16x16x32_bf16 v[74:77], v[156:159], v[148:151], v[78:81]
	v_mfma_f32_16x16x32_bf16 v[78:81], v[164:167], v[114:117], v[82:85]
	v_mfma_f32_16x16x32_bf16 v[82:85], v[164:167], v[148:151], v[86:89]
	v_mfma_f32_16x16x32_bf16 v[86:89], v[196:199], v[114:117], v[90:93]
	v_mfma_f32_16x16x32_bf16 v[90:93], v[196:199], v[148:151], v[94:97]
	v_mfma_f32_16x16x32_bf16 v[94:97], v[204:207], v[114:117], v[98:101]
	v_mfma_f32_16x16x32_bf16 v[98:101], v[204:207], v[148:151], v[102:105]
	v_mfma_f32_16x16x32_bf16 v[16:19], v[160:163], v[118:121], v[16:19]
	v_mfma_f32_16x16x32_bf16 v[74:77], v[160:163], v[152:155], v[74:77]
	v_mfma_f32_16x16x32_bf16 v[78:81], v[192:195], v[118:121], v[78:81]
	v_mfma_f32_16x16x32_bf16 v[82:85], v[192:195], v[152:155], v[82:85]
	v_mfma_f32_16x16x32_bf16 v[86:89], v[200:203], v[118:121], v[86:89]
	v_mfma_f32_16x16x32_bf16 v[90:93], v[200:203], v[152:155], v[90:93]
	v_mfma_f32_16x16x32_bf16 v[94:97], v[208:211], v[118:121], v[94:97]
	v_mfma_f32_16x16x32_bf16 v[98:101], v[208:211], v[152:155], v[98:101]
	s_barrier
	s_mov_b32 m0, s53
	v_add3_u32 v226, s59, v127, v126
	v_lshl_add_u64 v[12:13], v[12:13], 0, s[40:41]
	ds_read_b128 v[102:105], v226
	ds_read_b128 v[212:215], v226 offset:1024
	ds_read_b128 v[216:219], v226 offset:2048
	ds_read_b128 v[220:223], v226 offset:3072
	global_load_lds_dwordx4 v[12:13], off
	v_lshl_add_u64 v[12:13], v[14:15], 0, s[40:41]
	s_mov_b32 m0, s52
	s_nop 0
	global_load_lds_dwordx4 v[12:13], off
	s_barrier
; #define STAGE(P, BASE, LD, br, kt) do { const char* _g = (const char*)((BASE) + (size_t)(br) * (LD) + (size_t)(kt) * 64); \
;     for (int _i = 0; _i < 2; ++_i) { int _b = tidx * 16 + _i * 8192; int _r, _c; stage_rc(_b, _r, _c); \
;       __builtin_amdgcn_global_load_lds((const unsigned*)(_g + (unsigned)((_r * (LD) + _c) * 2)), (unsigned*)((char*)(P) + _b), 16, 0, 0); } } while (0)
; #define LDA(dst, b, h) for (int m = 0; m < 4; ++m) for (int k = 0; k < 2; ++k) \
;     dst[m][k] = *reinterpret_cast<const bf16x8*>((char*)SA(b, h) + lds_byte(wr * 64 + m * 16 + fr, k * 32 + fq * 8))
; #define LDB(dst, b, h) for (int n = 0; n < 2; ++n) for (int k = 0; k < 2; ++k) \
;     dst[n][k] = *reinterpret_cast<const bf16x8*>((char*)SB(b, h) + lds_byte(wc * 32 + n * 16 + fr, k * 32 + fq * 8))
; #define MMA(ai, bj, At_, Bt_) do { __builtin_amdgcn_s_setprio(1); \
;     for (int k = 0; k < 2; ++k) for (int m = 0; m < 4; ++m) for (int n = 0; n < 2; ++n) \
;       acc[ai][bj][m][n] = __builtin_amdgcn_mfma_f32_16x16x32_bf16(At_[m][k], Bt_[n][k], acc[ai][bj][m][n], 0, 0, 0); \
;     __builtin_amdgcn_s_setprio(0); } while (0)
; #define WAIT_V(n) asm volatile("s_waitcnt vmcnt(" #n ")" ::: "memory")
; #define WAIT_L(n) asm volatile("s_waitcnt lgkmcnt(" #n ")" ::: "memory")
; #define BAR __builtin_amdgcn_s_barrier()
; #define SCHED __builtin_amdgcn_sched_barrier(0)
; template <int EPI, int lda, int ldb, int N, int K>
; __device__ __forceinline__ void gemm_phase(const u16* __restrict__ A, const u16* __restrict__ Bt, const GemmEpi ep, int wv) {
;     ...
;       BAR; WAIT_L(0); MMA(0, 1, At, B1); BAR;
;       LDA(At, 1, 1); STAGE(SA(1, 0), Ab, lda, brow, t + 3);
;       BAR; WAIT_L(0); MMA(1, 0, At, B0); BAR; SCHED;
;       STAGE(SB(1, 1), Bt, ldb, bcol + HALF, t + 3);
;       WAIT_V(6); BAR; MMA(1, 1, At, B1); BAR;
;     }
;     { LDB(B0, 0, 0); LDA(At, 0, 0); STAGE(SA(1, 1), Ab, lda, brow + HALF, nt - 1);
;       BAR; WAIT_L(0); MMA(0, 0, At, B0); BAR;
	s_waitcnt lgkmcnt(0)
	v_mfma_f32_16x16x32_bf16 v[12:15], v[156:159], v[102:105], v[122:125]
	v_mfma_f32_16x16x32_bf16 v[40:43], v[156:159], v[216:219], v[42:45]
	v_mfma_f32_16x16x32_bf16 v[44:47], v[164:167], v[102:105], v[46:49]
	v_mfma_f32_16x16x32_bf16 v[48:51], v[164:167], v[216:219], v[50:53]
	v_mfma_f32_16x16x32_bf16 v[52:55], v[196:199], v[102:105], v[54:57]
	v_mfma_f32_16x16x32_bf16 v[56:59], v[196:199], v[216:219], v[58:61]
	v_mfma_f32_16x16x32_bf16 v[60:63], v[204:207], v[102:105], v[62:65]
	v_mfma_f32_16x16x32_bf16 v[64:67], v[204:207], v[216:219], v[66:69]
	v_mfma_f32_16x16x32_bf16 v[12:15], v[160:163], v[212:215], v[12:15]
	v_mfma_f32_16x16x32_bf16 v[40:43], v[160:163], v[220:223], v[40:43]
	v_mfma_f32_16x16x32_bf16 v[44:47], v[192:195], v[212:215], v[44:47]
	v_mfma_f32_16x16x32_bf16 v[48:51], v[192:195], v[220:223], v[48:51]
	v_mfma_f32_16x16x32_bf16 v[52:55], v[200:203], v[212:215], v[52:55]
	v_mfma_f32_16x16x32_bf16 v[56:59], v[200:203], v[220:223], v[56:59]
	v_mfma_f32_16x16x32_bf16 v[60:63], v[208:211], v[212:215], v[60:63]
	v_mfma_f32_16x16x32_bf16 v[64:67], v[208:211], v[220:223], v[64:67]
	s_barrier
	s_mov_b32 m0, s51
	v_lshl_add_u64 v[8:9], v[8:9], 0, s[40:41]
	ds_read_b128 v[122:125], v228 offset:49152
	ds_read_b128 v[156:159], v228 offset:50176
	ds_read_b128 v[160:163], v229 offset:51200
	ds_read_b128 v[164:167], v229 offset:52224
	ds_read_b128 v[192:195], v229 offset:53248
	ds_read_b128 v[196:199], v229 offset:54272
	ds_read_b128 v[200:203], v229 offset:55296
	ds_read_b128 v[204:207], v229 offset:56320
	global_load_lds_dwordx4 v[8:9], off
	v_lshl_add_u64 v[8:9], v[10:11], 0, s[40:41]
	s_mov_b32 m0, s50
	s_nop 0
	global_load_lds_dwordx4 v[8:9], off
	s_barrier
	s_waitcnt lgkmcnt(0)
	v_mfma_f32_16x16x32_bf16 v[8:11], v[122:125], v[114:117], v[168:171]
	v_mfma_f32_16x16x32_bf16 v[168:171], v[122:125], v[148:151], v[172:175]
	v_mfma_f32_16x16x32_bf16 v[24:27], v[200:203], v[114:117], v[24:27]
	v_mfma_f32_16x16x32_bf16 v[28:31], v[200:203], v[148:151], v[28:31]
	v_mfma_f32_16x16x32_bf16 v[172:175], v[160:163], v[114:117], v[176:179]
	v_mfma_f32_16x16x32_bf16 v[176:179], v[160:163], v[148:151], v[180:183]
	v_mfma_f32_16x16x32_bf16 v[180:183], v[192:195], v[114:117], v[184:187]
	v_mfma_f32_16x16x32_bf16 v[184:187], v[192:195], v[148:151], v[188:191]
	v_mfma_f32_16x16x32_bf16 v[8:11], v[156:159], v[118:121], v[8:11]
	v_mfma_f32_16x16x32_bf16 v[114:117], v[156:159], v[152:155], v[168:171]
	v_mfma_f32_16x16x32_bf16 v[24:27], v[204:207], v[118:121], v[24:27]
	v_mfma_f32_16x16x32_bf16 v[28:31], v[204:207], v[152:155], v[28:31]
	v_mfma_f32_16x16x32_bf16 v[148:151], v[164:167], v[118:121], v[172:175]
	v_mfma_f32_16x16x32_bf16 v[168:171], v[164:167], v[152:155], v[176:179]
	v_mfma_f32_16x16x32_bf16 v[172:175], v[196:199], v[118:121], v[180:183]
	v_mfma_f32_16x16x32_bf16 v[176:179], v[196:199], v[152:155], v[184:187]
	s_barrier
	s_mov_b32 m0, s11
	v_lshl_add_u64 v[2:3], v[2:3], 0, s[40:41]
	global_load_lds_dwordx4 v[2:3], off
	v_lshl_add_u64 v[0:1], v[0:1], 0, s[40:41]
	s_mov_b32 m0, s5
	s_nop 0
	global_load_lds_dwordx4 v[0:1], off
	s_waitcnt vmcnt(6)
	s_barrier
	v_mfma_f32_16x16x32_bf16 v[0:3], v[122:125], v[102:105], v[20:23]
	v_mfma_f32_16x16x32_bf16 v[20:23], v[122:125], v[216:219], v[32:35]
	v_mfma_f32_16x16x32_bf16 v[32:35], v[160:163], v[102:105], v[36:39]
	v_mfma_f32_16x16x32_bf16 v[36:39], v[160:163], v[216:219], v[70:73]
	v_mfma_f32_16x16x32_bf16 v[68:71], v[192:195], v[102:105], v[140:143]
	v_mfma_f32_16x16x32_bf16 v[118:121], v[192:195], v[216:219], v[144:147]
	v_mfma_f32_16x16x32_bf16 v[102:105], v[200:203], v[102:105], v[106:109]
	v_mfma_f32_16x16x32_bf16 v[106:109], v[200:203], v[216:219], v[110:113]
	v_mfma_f32_16x16x32_bf16 v[0:3], v[156:159], v[212:215], v[0:3]
	v_mfma_f32_16x16x32_bf16 v[20:23], v[156:159], v[220:223], v[20:23]
	v_mfma_f32_16x16x32_bf16 v[32:35], v[164:167], v[212:215], v[32:35]
	v_mfma_f32_16x16x32_bf16 v[36:39], v[164:167], v[220:223], v[36:39]
	v_mfma_f32_16x16x32_bf16 v[68:71], v[196:199], v[212:215], v[68:71]
	v_mfma_f32_16x16x32_bf16 v[110:113], v[196:199], v[220:223], v[118:121]
	v_mfma_f32_16x16x32_bf16 v[102:105], v[204:207], v[212:215], v[102:105]
	v_mfma_f32_16x16x32_bf16 v[106:109], v[204:207], v[220:223], v[106:109]
	s_barrier
	s_mov_b32 m0, s47
	v_lshl_add_u64 v[6:7], v[6:7], 0, s[40:41]
	ds_read_b128 v[118:121], v133
	ds_read_b128 v[122:125], v133 offset:1024
	ds_read_b128 v[140:143], v133 offset:2048
	ds_read_b128 v[144:147], v133 offset:3072
	ds_read_b128 v[152:155], v228
	ds_read_b128 v[156:159], v228 offset:1024
	ds_read_b128 v[160:163], v229 offset:2048
	ds_read_b128 v[164:167], v229 offset:3072
	ds_read_b128 v[180:183], v229 offset:4096
	ds_read_b128 v[184:187], v229 offset:5120
	ds_read_b128 v[188:191], v229 offset:6144
	ds_read_b128 v[192:195], v229 offset:7168
	global_load_lds_dwordx4 v[6:7], off
	v_lshl_add_u64 v[4:5], v[4:5], 0, s[40:41]
	s_mov_b32 m0, s46
	s_nop 0
	global_load_lds_dwordx4 v[4:5], off
	s_barrier
	s_waitcnt lgkmcnt(0)
	v_mfma_f32_16x16x32_bf16 v[4:7], v[152:155], v[118:121], v[16:19]
	v_mfma_f32_16x16x32_bf16 v[16:19], v[152:155], v[140:143], v[74:77]
	v_mfma_f32_16x16x32_bf16 v[72:75], v[160:163], v[118:121], v[78:81]
	v_mfma_f32_16x16x32_bf16 v[76:79], v[160:163], v[140:143], v[82:85]
	v_mfma_f32_16x16x32_bf16 v[80:83], v[180:183], v[118:121], v[86:89]
	v_mfma_f32_16x16x32_bf16 v[84:87], v[180:183], v[140:143], v[90:93]
	v_mfma_f32_16x16x32_bf16 v[88:91], v[188:191], v[118:121], v[94:97]
	v_mfma_f32_16x16x32_bf16 v[92:95], v[188:191], v[140:143], v[98:101]
	v_mfma_f32_16x16x32_bf16 v[4:7], v[156:159], v[122:125], v[4:7]
	v_mfma_f32_16x16x32_bf16 v[16:19], v[156:159], v[144:147], v[16:19]
	v_mfma_f32_16x16x32_bf16 v[72:75], v[164:167], v[122:125], v[72:75]
	v_mfma_f32_16x16x32_bf16 v[76:79], v[164:167], v[144:147], v[76:79]
	v_mfma_f32_16x16x32_bf16 v[80:83], v[184:187], v[122:125], v[80:83]
	v_mfma_f32_16x16x32_bf16 v[84:87], v[184:187], v[144:147], v[84:87]
	v_mfma_f32_16x16x32_bf16 v[88:91], v[192:195], v[122:125], v[88:91]
	v_mfma_f32_16x16x32_bf16 v[92:95], v[192:195], v[144:147], v[92:95]
	s_barrier
; #define LDA(dst, b, h) for (int m = 0; m < 4; ++m) for (int k = 0; k < 2; ++k) \
;     dst[m][k] = *reinterpret_cast<const bf16x8*>((char*)SA(b, h) + lds_byte(wr * 64 + m * 16 + fr, k * 32 + fq * 8))
; #define LDB(dst, b, h) for (int n = 0; n < 2; ++n) for (int k = 0; k < 2; ++k) \
;     dst[n][k] = *reinterpret_cast<const bf16x8*>((char*)SB(b, h) + lds_byte(wc * 32 + n * 16 + fr, k * 32 + fq * 8))
; #define MMA(ai, bj, At_, Bt_) do { __builtin_amdgcn_s_setprio(1); \
;     for (int k = 0; k < 2; ++k) for (int m = 0; m < 4; ++m) for (int n = 0; n < 2; ++n) \
;       acc[ai][bj][m][n] = __builtin_amdgcn_mfma_f32_16x16x32_bf16(At_[m][k], Bt_[n][k], acc[ai][bj][m][n], 0, 0, 0); \
;     __builtin_amdgcn_s_setprio(0); } while (0)
; #define WAIT_V(n) asm volatile("s_waitcnt vmcnt(" #n ")" ::: "memory")
; #define WAIT_L(n) asm volatile("s_waitcnt lgkmcnt(" #n ")" ::: "memory")
; #define BAR __builtin_amdgcn_s_barrier()
; template <int EPI, int lda, int ldb, int N, int K>
; __device__ __forceinline__ void gemm_phase(const u16* __restrict__ A, const u16* __restrict__ Bt, const GemmEpi ep, int wv) {
;     ...
;       LDB(B1, 0, 1); BAR; WAIT_L(0); MMA(0, 1, At, B1); BAR;
;       LDA(At, 0, 1); WAIT_V(4); BAR; WAIT_L(0); MMA(1, 0, At, B0); MMA(1, 1, At, B1); BAR; }
;     { LDB(B0, 1, 0); LDA(At, 1, 0); WAIT_V(2); BAR; WAIT_L(0); MMA(0, 0, At, B0); BAR;
	ds_read_b128 v[96:99], v224
	ds_read_b128 v[196:199], v224 offset:1024
	ds_read_b128 v[200:203], v224 offset:2048
	ds_read_b128 v[204:207], v224 offset:3072
	s_barrier
	s_waitcnt lgkmcnt(0)
	v_mfma_f32_16x16x32_bf16 v[12:15], v[152:155], v[96:99], v[12:15]
	v_mfma_f32_16x16x32_bf16 v[40:43], v[152:155], v[200:203], v[40:43]
	v_mfma_f32_16x16x32_bf16 v[52:55], v[180:183], v[96:99], v[52:55]
	v_mfma_f32_16x16x32_bf16 v[56:59], v[180:183], v[200:203], v[56:59]
	v_mfma_f32_16x16x32_bf16 v[64:67], v[188:191], v[200:203], v[64:67]
	v_mfma_f32_16x16x32_bf16 v[44:47], v[160:163], v[96:99], v[44:47]
	v_mfma_f32_16x16x32_bf16 v[48:51], v[160:163], v[200:203], v[48:51]
	v_mfma_f32_16x16x32_bf16 v[60:63], v[188:191], v[96:99], v[60:63]
	v_mfma_f32_16x16x32_bf16 v[12:15], v[156:159], v[196:199], v[12:15]
	v_mfma_f32_16x16x32_bf16 v[40:43], v[156:159], v[204:207], v[40:43]
	v_mfma_f32_16x16x32_bf16 v[52:55], v[184:187], v[196:199], v[52:55]
	v_mfma_f32_16x16x32_bf16 v[56:59], v[184:187], v[204:207], v[56:59]
	v_mfma_f32_16x16x32_bf16 v[64:67], v[192:195], v[204:207], v[64:67]
	v_mfma_f32_16x16x32_bf16 v[152:155], v[164:167], v[196:199], v[44:47]
	v_mfma_f32_16x16x32_bf16 v[156:159], v[164:167], v[204:207], v[48:51]
	v_mfma_f32_16x16x32_bf16 v[160:163], v[192:195], v[196:199], v[60:63]
	s_barrier
	ds_read_b128 v[44:47], v228 offset:16384
	ds_read_b128 v[48:51], v228 offset:17408
	ds_read_b128 v[60:63], v229 offset:18432
	ds_read_b128 v[164:167], v229 offset:19456
	ds_read_b128 v[180:183], v229 offset:20480
	ds_read_b128 v[184:187], v229 offset:21504
	ds_read_b128 v[188:191], v229 offset:22528
	ds_read_b128 v[192:195], v229 offset:23552
	s_waitcnt vmcnt(4)
	s_barrier
	s_waitcnt lgkmcnt(0)
	v_mfma_f32_16x16x32_bf16 v[8:11], v[44:47], v[118:121], v[8:11]
	v_mfma_f32_16x16x32_bf16 v[24:27], v[188:191], v[118:121], v[24:27]
	v_mfma_f32_16x16x32_bf16 v[28:31], v[188:191], v[140:143], v[28:31]
	v_mfma_f32_16x16x32_bf16 v[114:117], v[44:47], v[140:143], v[114:117]
	v_mfma_f32_16x16x32_bf16 v[148:151], v[60:63], v[118:121], v[148:151]
	v_mfma_f32_16x16x32_bf16 v[168:171], v[60:63], v[140:143], v[168:171]
	v_mfma_f32_16x16x32_bf16 v[172:175], v[180:183], v[118:121], v[172:175]
	v_mfma_f32_16x16x32_bf16 v[176:179], v[180:183], v[140:143], v[176:179]
	v_mfma_f32_16x16x32_bf16 v[8:11], v[48:51], v[122:125], v[8:11]
	v_mfma_f32_16x16x32_bf16 v[24:27], v[192:195], v[122:125], v[24:27]
	v_mfma_f32_16x16x32_bf16 v[28:31], v[192:195], v[144:147], v[28:31]
	v_mfma_f32_16x16x32_bf16 v[140:143], v[48:51], v[144:147], v[114:117]
	v_mfma_f32_16x16x32_bf16 v[148:151], v[164:167], v[122:125], v[148:151]
	v_mfma_f32_16x16x32_bf16 v[168:171], v[164:167], v[144:147], v[168:171]
	v_mfma_f32_16x16x32_bf16 v[172:175], v[184:187], v[122:125], v[172:175]
	v_mfma_f32_16x16x32_bf16 v[176:179], v[184:187], v[144:147], v[176:179]
	v_mfma_f32_16x16x32_bf16 v[0:3], v[44:47], v[96:99], v[0:3]
	v_mfma_f32_16x16x32_bf16 v[20:23], v[44:47], v[200:203], v[20:23]
	v_mfma_f32_16x16x32_bf16 v[44:47], v[180:183], v[96:99], v[68:71]
	v_mfma_f32_16x16x32_bf16 v[68:71], v[188:191], v[96:99], v[102:105]
	v_mfma_f32_16x16x32_bf16 v[32:35], v[60:63], v[96:99], v[32:35]
	v_mfma_f32_16x16x32_bf16 v[36:39], v[60:63], v[200:203], v[36:39]
	v_mfma_f32_16x16x32_bf16 v[60:63], v[180:183], v[200:203], v[110:113]
	v_mfma_f32_16x16x32_bf16 v[96:99], v[188:191], v[200:203], v[106:109]
	v_mfma_f32_16x16x32_bf16 v[20:23], v[48:51], v[204:207], v[20:23]
	v_mfma_f32_16x16x32_bf16 v[68:71], v[192:195], v[196:199], v[68:71]
	v_mfma_f32_16x16x32_bf16 v[144:147], v[48:51], v[196:199], v[0:3]
	v_mfma_f32_16x16x32_bf16 v[180:183], v[164:167], v[196:199], v[32:35]
	v_mfma_f32_16x16x32_bf16 v[164:167], v[164:167], v[204:207], v[36:39]
	v_mfma_f32_16x16x32_bf16 v[188:191], v[184:187], v[196:199], v[44:47]
	v_mfma_f32_16x16x32_bf16 v[184:187], v[184:187], v[204:207], v[60:63]
	v_mfma_f32_16x16x32_bf16 v[192:195], v[192:195], v[204:207], v[96:99]
	s_barrier
	ds_read_b128 v[0:3], v225
	ds_read_b128 v[196:199], v225 offset:1024
	ds_read_b128 v[200:203], v225 offset:2048
	ds_read_b128 v[204:207], v225 offset:3072
	ds_read_b128 v[36:39], v228 offset:32768
	ds_read_b128 v[100:103], v228 offset:33792
	ds_read_b128 v[108:111], v229 offset:34816
	ds_read_b128 v[208:211], v229 offset:35840
	ds_read_b128 v[116:119], v229 offset:36864
	ds_read_b128 v[212:215], v229 offset:37888
	ds_read_b128 v[124:127], v229 offset:38912
	ds_read_b128 v[216:219], v229 offset:39936
	s_waitcnt vmcnt(2)
	s_barrier
; #define LDA(dst, b, h) for (int m = 0; m < 4; ++m) for (int k = 0; k < 2; ++k) \
;     dst[m][k] = *reinterpret_cast<const bf16x8*>((char*)SA(b, h) + lds_byte(wr * 64 + m * 16 + fr, k * 32 + fq * 8))
; #define LDB(dst, b, h) for (int n = 0; n < 2; ++n) for (int k = 0; k < 2; ++k) \
;     dst[n][k] = *reinterpret_cast<const bf16x8*>((char*)SB(b, h) + lds_byte(wc * 32 + n * 16 + fr, k * 32 + fq * 8))
; #define MMA(ai, bj, At_, Bt_) do { __builtin_amdgcn_s_setprio(1); \
;     for (int k = 0; k < 2; ++k) for (int m = 0; m < 4; ++m) for (int n = 0; n < 2; ++n) \
;       acc[ai][bj][m][n] = __builtin_amdgcn_mfma_f32_16x16x32_bf16(At_[m][k], Bt_[n][k], acc[ai][bj][m][n], 0, 0, 0); \
;     __builtin_amdgcn_s_setprio(0); } while (0)
; #define WAIT_V(n) asm volatile("s_waitcnt vmcnt(" #n ")" ::: "memory")
; #define WAIT_L(n) asm volatile("s_waitcnt lgkmcnt(" #n ")" ::: "memory")
; #define BAR __builtin_amdgcn_s_barrier()
; template <int EPI, int lda, int ldb, int N, int K>
; __device__ __forceinline__ void gemm_phase(const u16* __restrict__ A, const u16* __restrict__ Bt, const GemmEpi ep, int wv) {
;     ...
;     { LDB(B0, 1, 0); LDA(At, 1, 0); WAIT_V(2); BAR; WAIT_L(0); MMA(0, 0, At, B0); BAR;
;       LDB(B1, 1, 1); WAIT_V(0); BAR; WAIT_L(0); MMA(0, 1, At, B1); BAR;
;       LDA(At, 1, 1); BAR; WAIT_L(0); MMA(1, 0, At, B0); MMA(1, 1, At, B1); BAR; }
;     if (wr == 0) BAR;
	s_waitcnt lgkmcnt(0)
	v_mfma_f32_16x16x32_bf16 v[4:7], v[36:39], v[0:3], v[4:7]
	v_mfma_f32_16x16x32_bf16 v[16:19], v[36:39], v[200:203], v[16:19]
	v_mfma_f32_16x16x32_bf16 v[32:35], v[108:111], v[0:3], v[72:75]
	v_mfma_f32_16x16x32_bf16 v[44:47], v[108:111], v[200:203], v[76:79]
	v_mfma_f32_16x16x32_bf16 v[72:75], v[116:119], v[0:3], v[80:83]
	v_mfma_f32_16x16x32_bf16 v[76:79], v[116:119], v[200:203], v[84:87]
	v_mfma_f32_16x16x32_bf16 v[80:83], v[124:127], v[0:3], v[88:91]
	v_mfma_f32_16x16x32_bf16 v[84:87], v[124:127], v[200:203], v[92:95]
	v_mfma_f32_16x16x32_bf16 v[120:123], v[100:103], v[196:199], v[4:7]
	v_mfma_f32_16x16x32_bf16 v[60:63], v[100:103], v[204:207], v[16:19]
	v_mfma_f32_16x16x32_bf16 v[112:115], v[208:211], v[196:199], v[32:35]
	v_mfma_f32_16x16x32_bf16 v[48:51], v[208:211], v[204:207], v[44:47]
	v_mfma_f32_16x16x32_bf16 v[104:107], v[212:215], v[196:199], v[72:75]
	v_mfma_f32_16x16x32_bf16 v[44:47], v[212:215], v[204:207], v[76:79]
	v_mfma_f32_16x16x32_bf16 v[96:99], v[216:219], v[196:199], v[80:83]
	v_mfma_f32_16x16x32_bf16 v[32:35], v[216:219], v[204:207], v[84:87]
	s_barrier
	ds_read_b128 v[4:7], v226
	ds_read_b128 v[220:223], v226 offset:1024
	ds_read_b128 v[76:79], v226 offset:2048
	ds_read_b128 v[224:227], v226 offset:3072
	s_waitcnt vmcnt(0)
	s_barrier
	s_waitcnt lgkmcnt(0)
	v_mfma_f32_16x16x32_bf16 v[12:15], v[36:39], v[4:7], v[12:15]
	v_mfma_f32_16x16x32_bf16 v[16:19], v[36:39], v[76:79], v[40:43]
	v_mfma_f32_16x16x32_bf16 v[36:39], v[108:111], v[4:7], v[152:155]
	v_mfma_f32_16x16x32_bf16 v[40:43], v[108:111], v[76:79], v[156:159]
	v_mfma_f32_16x16x32_bf16 v[72:75], v[116:119], v[4:7], v[52:55]
	v_mfma_f32_16x16x32_bf16 v[80:83], v[116:119], v[76:79], v[56:59]
	v_mfma_f32_16x16x32_bf16 v[84:87], v[124:127], v[4:7], v[160:163]
	v_mfma_f32_16x16x32_bf16 v[64:67], v[124:127], v[76:79], v[64:67]
	v_mfma_f32_16x16x32_bf16 v[124:127], v[100:103], v[220:223], v[12:15]
	v_mfma_f32_16x16x32_bf16 v[56:59], v[100:103], v[224:227], v[16:19]
	v_mfma_f32_16x16x32_bf16 v[116:119], v[208:211], v[220:223], v[36:39]
	v_mfma_f32_16x16x32_bf16 v[52:55], v[208:211], v[224:227], v[40:43]
	v_mfma_f32_16x16x32_bf16 v[108:111], v[212:215], v[220:223], v[72:75]
	v_mfma_f32_16x16x32_bf16 v[40:43], v[212:215], v[224:227], v[80:83]
	v_mfma_f32_16x16x32_bf16 v[100:103], v[216:219], v[220:223], v[84:87]
	v_mfma_f32_16x16x32_bf16 v[36:39], v[216:219], v[224:227], v[64:67]
	s_barrier
	ds_read_b128 v[84:87], v228 offset:49152
	ds_read_b128 v[152:155], v228 offset:50176
	ds_read_b128 v[92:95], v229 offset:51200
	ds_read_b128 v[156:159], v229 offset:52224
	ds_read_b128 v[160:163], v229 offset:53248
	ds_read_b128 v[208:211], v229 offset:54272
	ds_read_b128 v[212:215], v229 offset:55296
	ds_read_b128 v[216:219], v229 offset:56320
	s_barrier
	s_waitcnt lgkmcnt(0)
	v_mfma_f32_16x16x32_bf16 v[8:11], v[84:87], v[0:3], v[8:11]
	v_mfma_f32_16x16x32_bf16 v[12:15], v[84:87], v[200:203], v[140:143]
	v_mfma_f32_16x16x32_bf16 v[16:19], v[92:95], v[0:3], v[148:151]
	v_mfma_f32_16x16x32_bf16 v[64:67], v[92:95], v[200:203], v[168:171]
	v_mfma_f32_16x16x32_bf16 v[72:75], v[160:163], v[0:3], v[172:175]
	v_mfma_f32_16x16x32_bf16 v[140:143], v[160:163], v[200:203], v[176:179]
	v_mfma_f32_16x16x32_bf16 v[0:3], v[212:215], v[0:3], v[24:27]
	v_mfma_f32_16x16x32_bf16 v[24:27], v[212:215], v[200:203], v[28:31]
	v_mfma_f32_16x16x32_bf16 v[88:91], v[152:155], v[196:199], v[8:11]
	v_mfma_f32_16x16x32_bf16 v[28:31], v[152:155], v[204:207], v[12:15]
	v_mfma_f32_16x16x32_bf16 v[80:83], v[156:159], v[196:199], v[16:19]
	v_mfma_f32_16x16x32_bf16 v[16:19], v[156:159], v[204:207], v[64:67]
	v_mfma_f32_16x16x32_bf16 v[72:75], v[208:211], v[196:199], v[72:75]
	v_mfma_f32_16x16x32_bf16 v[12:15], v[208:211], v[204:207], v[140:143]
	v_mfma_f32_16x16x32_bf16 v[64:67], v[216:219], v[196:199], v[0:3]
	v_mfma_f32_16x16x32_bf16 v[0:3], v[216:219], v[204:207], v[24:27]
	v_mfma_f32_16x16x32_bf16 v[8:11], v[84:87], v[4:7], v[144:147]
	v_mfma_f32_16x16x32_bf16 v[20:23], v[84:87], v[76:79], v[20:23]
	v_mfma_f32_16x16x32_bf16 v[84:87], v[92:95], v[4:7], v[180:183]
	v_mfma_f32_16x16x32_bf16 v[140:143], v[92:95], v[76:79], v[164:167]
	v_mfma_f32_16x16x32_bf16 v[144:147], v[160:163], v[4:7], v[188:191]
	v_mfma_f32_16x16x32_bf16 v[148:151], v[160:163], v[76:79], v[184:187]
	v_mfma_f32_16x16x32_bf16 v[4:7], v[212:215], v[4:7], v[68:71]
	v_mfma_f32_16x16x32_bf16 v[160:163], v[212:215], v[76:79], v[192:195]
	v_mfma_f32_16x16x32_bf16 v[92:95], v[152:155], v[220:223], v[8:11]
	v_mfma_f32_16x16x32_bf16 v[24:27], v[152:155], v[224:227], v[20:23]
	v_mfma_f32_16x16x32_bf16 v[84:87], v[156:159], v[220:223], v[84:87]
	v_mfma_f32_16x16x32_bf16 v[20:23], v[156:159], v[224:227], v[140:143]
	v_mfma_f32_16x16x32_bf16 v[76:79], v[208:211], v[220:223], v[144:147]
	v_mfma_f32_16x16x32_bf16 v[8:11], v[208:211], v[224:227], v[148:151]
	v_mfma_f32_16x16x32_bf16 v[68:71], v[216:219], v[220:223], v[4:7]
	v_mfma_f32_16x16x32_bf16 v[4:7], v[216:219], v[224:227], v[160:163]
	v_cmp_gt_u32_e32 vcc, s60, v130
	s_barrier
	s_and_saveexec_b64 s[46:47], vcc
	s_cbranch_execz .LBB0_1346
	s_barrier
	s_branch .LBB0_1346

; #define STAGE(P, BASE, LD, br, kt) do { const char* _g = (const char*)((BASE) + (size_t)(br) * (LD) + (size_t)(kt) * 64); \
;     for (int _i = 0; _i < 2; ++_i) { int _b = tidx * 16 + _i * 8192; int _r, _c; stage_rc(_b, _r, _c); \
;       __builtin_amdgcn_global_load_lds((const unsigned*)(_g + (unsigned)((_r * (LD) + _c) * 2)), (unsigned*)((char*)(P) + _b), 16, 0, 0); } } while (0)
; #define LDA(dst, b, h) for (int m = 0; m < 4; ++m) for (int k = 0; k < 2; ++k) \
;     dst[m][k] = *reinterpret_cast<const bf16x8*>((char*)SA(b, h) + lds_byte(wr * 64 + m * 16 + fr, k * 32 + fq * 8))
; #define LDB(dst, b, h) for (int n = 0; n < 2; ++n) for (int k = 0; k < 2; ++k) \
;     dst[n][k] = *reinterpret_cast<const bf16x8*>((char*)SB(b, h) + lds_byte(wc * 32 + n * 16 + fr, k * 32 + fq * 8))
; #define MMA(ai, bj, At_, Bt_) do { __builtin_amdgcn_s_setprio(1); \
;     for (int k = 0; k < 2; ++k) for (int m = 0; m < 4; ++m) for (int n = 0; n < 2; ++n) \
;       acc[ai][bj][m][n] = __builtin_amdgcn_mfma_f32_16x16x32_bf16(At_[m][k], Bt_[n][k], acc[ai][bj][m][n], 0, 0, 0); \
;     __builtin_amdgcn_s_setprio(0); } while (0)
; #define WAIT_L(n) asm volatile("s_waitcnt lgkmcnt(" #n ")" ::: "memory")
; #define BAR __builtin_amdgcn_s_barrier()
; #define SCHED __builtin_amdgcn_sched_barrier(0)
; template <int EPI, int lda, int ldb, int N, int K>
; __device__ __forceinline__ void gemm_phase(const u16* __restrict__ A, const u16* __restrict__ Bt, const GemmEpi ep, int wv) {
;     ...
;       LDB(B0, 0, 0); SCHED; LDA(At, 0, 0); STAGE(SA(1, 1), Ab, lda, brow + HALF, t + 1);
;       WAIT_L(8); BAR; WAIT_L(0); MMA(0, 0, At, B0); BAR; SCHED;
;       LDB(B1, 0, 1); STAGE(SB(0, 0), Bt, ldb, bcol, t + 2);
;       BAR; WAIT_L(0); MMA(0, 1, At, B1); BAR;
;       LDA(At, 0, 1); STAGE(SA(0, 0), Ab, lda, brow, t + 2);
;       BAR; WAIT_L(0); MMA(1, 0, At, B0); BAR; SCHED;
.LBB0_1448:
	ds_read_b128 v[164:167], v160
	ds_read_b128 v[170:173], v160 offset:1024
	ds_read_b128 v[174:177], v160 offset:2048
	ds_read_b128 v[178:181], v160 offset:3072
	v_add_u32_e32 v168, 0xc000, v143
	v_lshl_add_u64 v[234:235], v[138:139], 0, s[44:45]
	v_readfirstlane_b32 s47, v168
	v_add_u32_e32 v169, 0xe000, v143
	v_lshl_add_u64 v[162:163], v[234:235], 0, s[20:21]
	s_mov_b32 m0, s47
	v_lshl_add_u64 v[236:237], v[140:141], 0, s[44:45]
	v_readfirstlane_b32 s47, v169
	ds_read_b128 v[182:185], v151
	ds_read_b128 v[186:189], v151 offset:1024
	ds_read_b128 v[190:193], v150
	ds_read_b128 v[194:197], v150 offset:1024
	ds_read_b128 v[198:201], v149
	ds_read_b128 v[202:205], v149 offset:1024
	ds_read_b128 v[206:209], v148
	ds_read_b128 v[210:213], v148 offset:1024
	global_load_lds_dwordx4 v[162:163], off
	v_lshl_add_u64 v[162:163], v[236:237], 0, s[20:21]
	s_mov_b32 m0, s47
	s_nop 0
	global_load_lds_dwordx4 v[162:163], off
	s_waitcnt lgkmcnt(8)
	s_barrier
	s_waitcnt lgkmcnt(0)
	v_mfma_f32_16x16x32_bf16 v[124:127], v[164:167], v[182:185], v[124:127]
	v_mfma_f32_16x16x32_bf16 v[120:123], v[174:177], v[182:185], v[120:123]
	v_mfma_f32_16x16x32_bf16 v[116:119], v[164:167], v[190:193], v[116:119]
	v_mfma_f32_16x16x32_bf16 v[112:115], v[174:177], v[190:193], v[112:115]
	v_mfma_f32_16x16x32_bf16 v[108:111], v[164:167], v[198:201], v[108:111]
	v_mfma_f32_16x16x32_bf16 v[104:107], v[174:177], v[198:201], v[104:107]
	v_mfma_f32_16x16x32_bf16 v[100:103], v[164:167], v[206:209], v[100:103]
	v_mfma_f32_16x16x32_bf16 v[96:99], v[174:177], v[206:209], v[96:99]
	v_mfma_f32_16x16x32_bf16 v[124:127], v[170:173], v[186:189], v[124:127]
	v_mfma_f32_16x16x32_bf16 v[120:123], v[178:181], v[186:189], v[120:123]
	v_mfma_f32_16x16x32_bf16 v[116:119], v[170:173], v[194:197], v[116:119]
	v_mfma_f32_16x16x32_bf16 v[112:115], v[178:181], v[194:197], v[112:115]
	v_mfma_f32_16x16x32_bf16 v[108:111], v[170:173], v[202:205], v[108:111]
	v_mfma_f32_16x16x32_bf16 v[104:107], v[178:181], v[202:205], v[104:107]
	v_mfma_f32_16x16x32_bf16 v[100:103], v[170:173], v[210:213], v[100:103]
	v_mfma_f32_16x16x32_bf16 v[96:99], v[178:181], v[210:213], v[96:99]
	s_barrier
	v_add_u32_e32 v161, s55, v153
	v_lshl_add_u64 v[238:239], v[134:135], 0, s[44:45]
	v_readfirstlane_b32 s47, v161
	v_lshl_add_u64 v[162:163], v[238:239], 0, s[22:23]
	s_mov_b32 m0, s47
	ds_read_b128 v[214:217], v159
	ds_read_b128 v[218:221], v159 offset:1024
	ds_read_b128 v[222:225], v159 offset:2048
	ds_read_b128 v[226:229], v159 offset:3072
	global_load_lds_dwordx4 v[162:163], off
	v_add_u32_e32 v162, 0x2000, v161
	v_lshl_add_u64 v[240:241], v[136:137], 0, s[44:45]
	v_readfirstlane_b32 s47, v162
	v_lshl_add_u64 v[230:231], v[240:241], 0, s[22:23]
	s_mov_b32 m0, s47
	s_nop 0
	global_load_lds_dwordx4 v[230:231], off
	s_barrier
	s_waitcnt lgkmcnt(0)
	v_mfma_f32_16x16x32_bf16 v[92:95], v[214:217], v[182:185], v[92:95]
	v_mfma_f32_16x16x32_bf16 v[88:91], v[222:225], v[182:185], v[88:91]
	v_mfma_f32_16x16x32_bf16 v[84:87], v[214:217], v[190:193], v[84:87]
	v_mfma_f32_16x16x32_bf16 v[80:83], v[222:225], v[190:193], v[80:83]
	v_mfma_f32_16x16x32_bf16 v[76:79], v[214:217], v[198:201], v[76:79]
	v_mfma_f32_16x16x32_bf16 v[72:75], v[222:225], v[198:201], v[72:75]
	v_mfma_f32_16x16x32_bf16 v[68:71], v[214:217], v[206:209], v[68:71]
	v_mfma_f32_16x16x32_bf16 v[64:67], v[222:225], v[206:209], v[64:67]
	v_mfma_f32_16x16x32_bf16 v[92:95], v[218:221], v[186:189], v[92:95]
	v_mfma_f32_16x16x32_bf16 v[88:91], v[226:229], v[186:189], v[88:91]
	v_mfma_f32_16x16x32_bf16 v[84:87], v[218:221], v[194:197], v[84:87]
	v_mfma_f32_16x16x32_bf16 v[80:83], v[226:229], v[194:197], v[80:83]
	v_mfma_f32_16x16x32_bf16 v[76:79], v[218:221], v[202:205], v[76:79]
	v_mfma_f32_16x16x32_bf16 v[72:75], v[226:229], v[202:205], v[72:75]
	v_mfma_f32_16x16x32_bf16 v[68:71], v[218:221], v[210:213], v[68:71]
	v_mfma_f32_16x16x32_bf16 v[64:67], v[226:229], v[210:213], v[64:67]
	s_barrier
	v_readfirstlane_b32 s47, v143
	v_add_u32_e32 v163, 0x2000, v143
	v_lshl_add_u64 v[230:231], v[234:235], 0, s[24:25]
	s_mov_b32 m0, s47
	v_readfirstlane_b32 s47, v163
	ds_read_b128 v[182:185], v151 offset:16384
	ds_read_b128 v[186:189], v151 offset:17408
	ds_read_b128 v[190:193], v150 offset:16384
	ds_read_b128 v[194:197], v150 offset:17408
	ds_read_b128 v[198:201], v149 offset:16384
	ds_read_b128 v[202:205], v149 offset:17408
	ds_read_b128 v[206:209], v148 offset:16384
	ds_read_b128 v[210:213], v148 offset:17408
	global_load_lds_dwordx4 v[230:231], off
	v_lshl_add_u64 v[230:231], v[236:237], 0, s[24:25]
	s_mov_b32 m0, s47
	s_nop 0
	global_load_lds_dwordx4 v[230:231], off
	s_barrier
	s_waitcnt lgkmcnt(0)
	v_mfma_f32_16x16x32_bf16 v[60:63], v[164:167], v[182:185], v[60:63]
	v_mfma_f32_16x16x32_bf16 v[56:59], v[174:177], v[182:185], v[56:59]
	v_mfma_f32_16x16x32_bf16 v[52:55], v[164:167], v[190:193], v[52:55]
	v_mfma_f32_16x16x32_bf16 v[48:51], v[174:177], v[190:193], v[48:51]
	v_mfma_f32_16x16x32_bf16 v[44:47], v[164:167], v[198:201], v[44:47]
	v_mfma_f32_16x16x32_bf16 v[40:43], v[174:177], v[198:201], v[40:43]
	v_mfma_f32_16x16x32_bf16 v[36:39], v[164:167], v[206:209], v[36:39]
	v_mfma_f32_16x16x32_bf16 v[32:35], v[174:177], v[206:209], v[32:35]
	v_mfma_f32_16x16x32_bf16 v[60:63], v[170:173], v[186:189], v[60:63]
	v_mfma_f32_16x16x32_bf16 v[56:59], v[178:181], v[186:189], v[56:59]
	v_mfma_f32_16x16x32_bf16 v[52:55], v[170:173], v[194:197], v[52:55]
	v_mfma_f32_16x16x32_bf16 v[48:51], v[178:181], v[194:197], v[48:51]
	v_mfma_f32_16x16x32_bf16 v[44:47], v[170:173], v[202:205], v[44:47]
	v_mfma_f32_16x16x32_bf16 v[40:43], v[178:181], v[202:205], v[40:43]
	v_mfma_f32_16x16x32_bf16 v[36:39], v[170:173], v[210:213], v[36:39]
	v_mfma_f32_16x16x32_bf16 v[32:35], v[178:181], v[210:213], v[32:35]
	s_barrier
; #define STAGE(P, BASE, LD, br, kt) do { const char* _g = (const char*)((BASE) + (size_t)(br) * (LD) + (size_t)(kt) * 64); \
;     for (int _i = 0; _i < 2; ++_i) { int _b = tidx * 16 + _i * 8192; int _r, _c; stage_rc(_b, _r, _c); \
;       __builtin_amdgcn_global_load_lds((const unsigned*)(_g + (unsigned)((_r * (LD) + _c) * 2)), (unsigned*)((char*)(P) + _b), 16, 0, 0); } } while (0)
; #define LDA(dst, b, h) for (int m = 0; m < 4; ++m) for (int k = 0; k < 2; ++k) \
;     dst[m][k] = *reinterpret_cast<const bf16x8*>((char*)SA(b, h) + lds_byte(wr * 64 + m * 16 + fr, k * 32 + fq * 8))
; #define LDB(dst, b, h) for (int n = 0; n < 2; ++n) for (int k = 0; k < 2; ++k) \
;     dst[n][k] = *reinterpret_cast<const bf16x8*>((char*)SB(b, h) + lds_byte(wc * 32 + n * 16 + fr, k * 32 + fq * 8))
; #define MMA(ai, bj, At_, Bt_) do { __builtin_amdgcn_s_setprio(1); \
;     for (int k = 0; k < 2; ++k) for (int m = 0; m < 4; ++m) for (int n = 0; n < 2; ++n) \
;       acc[ai][bj][m][n] = __builtin_amdgcn_mfma_f32_16x16x32_bf16(At_[m][k], Bt_[n][k], acc[ai][bj][m][n], 0, 0, 0); \
;     __builtin_amdgcn_s_setprio(0); } while (0)
; #define WAIT_V(n) asm volatile("s_waitcnt vmcnt(" #n ")" ::: "memory")
; #define WAIT_L(n) asm volatile("s_waitcnt lgkmcnt(" #n ")" ::: "memory")
; #define BAR __builtin_amdgcn_s_barrier()
; #define SCHED __builtin_amdgcn_sched_barrier(0)
; template <int EPI, int lda, int ldb, int N, int K>
; __device__ __forceinline__ void gemm_phase(const u16* __restrict__ A, const u16* __restrict__ Bt, const GemmEpi ep, int wv) {
;     ...
;       STAGE(SB(0, 1), Bt, ldb, bcol + HALF, t + 2);
;       WAIT_V(6); BAR; MMA(1, 1, At, B1); BAR;
;       LDB(B0, 1, 0); SCHED; LDA(At, 1, 0); STAGE(SA(0, 1), Ab, lda, brow + HALF, t + 2);
;       WAIT_L(8); BAR; WAIT_L(0); MMA(0, 0, At, B0); BAR; SCHED;
;       LDB(B1, 1, 1); STAGE(SB(1, 0), Bt, ldb, bcol, t + 3);
;       BAR; WAIT_L(0); MMA(0, 1, At, B1); BAR;
	v_add_u32_e32 v164, s56, v153
	v_add_u32_e32 v165, 0x2000, v164
	v_readfirstlane_b32 s47, v164
	v_lshl_add_u64 v[166:167], v[238:239], 0, s[26:27]
	s_mov_b32 m0, s47
	v_readfirstlane_b32 s47, v165
	global_load_lds_dwordx4 v[166:167], off
	v_lshl_add_u64 v[166:167], v[240:241], 0, s[26:27]
	s_mov_b32 m0, s47
	s_nop 0
	global_load_lds_dwordx4 v[166:167], off
	s_waitcnt vmcnt(6)
	s_barrier
	v_mfma_f32_16x16x32_bf16 v[28:31], v[214:217], v[182:185], v[28:31]
	v_mfma_f32_16x16x32_bf16 v[24:27], v[222:225], v[182:185], v[24:27]
	v_mfma_f32_16x16x32_bf16 v[20:23], v[214:217], v[190:193], v[20:23]
	v_mfma_f32_16x16x32_bf16 v[16:19], v[222:225], v[190:193], v[16:19]
	v_mfma_f32_16x16x32_bf16 v[12:15], v[214:217], v[198:201], v[12:15]
	v_mfma_f32_16x16x32_bf16 v[8:11], v[222:225], v[198:201], v[8:11]
	v_mfma_f32_16x16x32_bf16 v[4:7], v[214:217], v[206:209], v[4:7]
	v_mfma_f32_16x16x32_bf16 v[0:3], v[222:225], v[206:209], v[0:3]
	v_mfma_f32_16x16x32_bf16 v[28:31], v[218:221], v[186:189], v[28:31]
	v_mfma_f32_16x16x32_bf16 v[24:27], v[226:229], v[186:189], v[24:27]
	v_mfma_f32_16x16x32_bf16 v[20:23], v[218:221], v[194:197], v[20:23]
	v_mfma_f32_16x16x32_bf16 v[16:19], v[226:229], v[194:197], v[16:19]
	v_mfma_f32_16x16x32_bf16 v[12:15], v[218:221], v[202:205], v[12:15]
	v_mfma_f32_16x16x32_bf16 v[8:11], v[226:229], v[202:205], v[8:11]
	v_mfma_f32_16x16x32_bf16 v[4:7], v[218:221], v[210:213], v[4:7]
	v_mfma_f32_16x16x32_bf16 v[0:3], v[226:229], v[210:213], v[0:3]
	s_barrier
	ds_read_b128 v[170:173], v154
	ds_read_b128 v[174:177], v154 offset:1024
	ds_read_b128 v[178:181], v154 offset:2048
	ds_read_b128 v[182:185], v154 offset:3072
	v_add_u32_e32 v166, 0x4000, v143
	v_add_u32_e32 v167, 0x6000, v143
	v_readfirstlane_b32 s47, v166
	v_lshl_add_u64 v[218:219], v[234:235], 0, s[34:35]
	s_mov_b32 m0, s47
	v_readfirstlane_b32 s47, v167
	ds_read_b128 v[186:189], v151 offset:32768
	ds_read_b128 v[190:193], v151 offset:33792
	ds_read_b128 v[194:197], v150 offset:32768
	ds_read_b128 v[198:201], v150 offset:33792
	ds_read_b128 v[202:205], v149 offset:32768
	ds_read_b128 v[206:209], v149 offset:33792
	ds_read_b128 v[210:213], v148 offset:32768
	ds_read_b128 v[214:217], v148 offset:33792
	global_load_lds_dwordx4 v[218:219], off
	v_lshl_add_u64 v[218:219], v[236:237], 0, s[34:35]
	s_mov_b32 m0, s47
	s_nop 0
	global_load_lds_dwordx4 v[218:219], off
	s_waitcnt lgkmcnt(8)
	s_barrier
	s_waitcnt lgkmcnt(0)
	v_mfma_f32_16x16x32_bf16 v[124:127], v[170:173], v[186:189], v[124:127]
	v_mfma_f32_16x16x32_bf16 v[120:123], v[178:181], v[186:189], v[120:123]
	v_mfma_f32_16x16x32_bf16 v[116:119], v[170:173], v[194:197], v[116:119]
	v_mfma_f32_16x16x32_bf16 v[112:115], v[178:181], v[194:197], v[112:115]
	v_mfma_f32_16x16x32_bf16 v[108:111], v[170:173], v[202:205], v[108:111]
	v_mfma_f32_16x16x32_bf16 v[104:107], v[178:181], v[202:205], v[104:107]
	v_mfma_f32_16x16x32_bf16 v[100:103], v[170:173], v[210:213], v[100:103]
	v_mfma_f32_16x16x32_bf16 v[96:99], v[178:181], v[210:213], v[96:99]
	v_mfma_f32_16x16x32_bf16 v[124:127], v[174:177], v[190:193], v[124:127]
	v_mfma_f32_16x16x32_bf16 v[120:123], v[182:185], v[190:193], v[120:123]
	v_mfma_f32_16x16x32_bf16 v[116:119], v[174:177], v[198:201], v[116:119]
	v_mfma_f32_16x16x32_bf16 v[112:115], v[182:185], v[198:201], v[112:115]
	v_mfma_f32_16x16x32_bf16 v[108:111], v[174:177], v[206:209], v[108:111]
	v_mfma_f32_16x16x32_bf16 v[104:107], v[182:185], v[206:209], v[104:107]
	v_mfma_f32_16x16x32_bf16 v[100:103], v[174:177], v[214:217], v[100:103]
	v_mfma_f32_16x16x32_bf16 v[96:99], v[182:185], v[214:217], v[96:99]
	s_barrier
	v_readfirstlane_b32 s47, v155
	v_add_u32_e32 v244, 0x2000, v155
	v_lshl_add_u64 v[242:243], v[238:239], 0, s[36:37]
	s_mov_b32 m0, s47
	v_readfirstlane_b32 s47, v244
	ds_read_b128 v[218:221], v152
	ds_read_b128 v[222:225], v152 offset:1024
	ds_read_b128 v[226:229], v152 offset:2048
	ds_read_b128 v[230:233], v152 offset:3072
	global_load_lds_dwordx4 v[242:243], off
	v_lshl_add_u64 v[242:243], v[240:241], 0, s[36:37]
	s_mov_b32 m0, s47
	s_nop 0
	global_load_lds_dwordx4 v[242:243], off
	s_barrier
	s_waitcnt lgkmcnt(0)
	v_mfma_f32_16x16x32_bf16 v[92:95], v[218:221], v[186:189], v[92:95]
	v_mfma_f32_16x16x32_bf16 v[88:91], v[226:229], v[186:189], v[88:91]
	v_mfma_f32_16x16x32_bf16 v[84:87], v[218:221], v[194:197], v[84:87]
	v_mfma_f32_16x16x32_bf16 v[80:83], v[226:229], v[194:197], v[80:83]
	v_mfma_f32_16x16x32_bf16 v[76:79], v[218:221], v[202:205], v[76:79]
	v_mfma_f32_16x16x32_bf16 v[72:75], v[226:229], v[202:205], v[72:75]
	v_mfma_f32_16x16x32_bf16 v[68:71], v[218:221], v[210:213], v[68:71]
	v_mfma_f32_16x16x32_bf16 v[64:67], v[226:229], v[210:213], v[64:67]
	v_mfma_f32_16x16x32_bf16 v[92:95], v[222:225], v[190:193], v[92:95]
	v_mfma_f32_16x16x32_bf16 v[88:91], v[230:233], v[190:193], v[88:91]
	v_mfma_f32_16x16x32_bf16 v[84:87], v[222:225], v[198:201], v[84:87]
	v_mfma_f32_16x16x32_bf16 v[80:83], v[230:233], v[198:201], v[80:83]
	v_mfma_f32_16x16x32_bf16 v[76:79], v[222:225], v[206:209], v[76:79]
	v_mfma_f32_16x16x32_bf16 v[72:75], v[230:233], v[206:209], v[72:75]
	v_mfma_f32_16x16x32_bf16 v[68:71], v[222:225], v[214:217], v[68:71]
	v_mfma_f32_16x16x32_bf16 v[64:67], v[230:233], v[214:217], v[64:67]
	s_barrier
	v_readfirstlane_b32 s47, v156
	v_lshl_add_u64 v[234:235], v[234:235], 0, s[38:39]
	s_mov_b32 m0, s47
	v_readfirstlane_b32 s47, v157
	ds_read_b128 v[186:189], v151 offset:49152
	ds_read_b128 v[190:193], v151 offset:50176
	ds_read_b128 v[194:197], v150 offset:49152
	ds_read_b128 v[198:201], v150 offset:50176
	ds_read_b128 v[202:205], v149 offset:49152
	ds_read_b128 v[206:209], v149 offset:50176
	ds_read_b128 v[210:213], v148 offset:49152
	ds_read_b128 v[214:217], v148 offset:50176
	global_load_lds_dwordx4 v[234:235], off
	v_lshl_add_u64 v[234:235], v[236:237], 0, s[38:39]
	s_mov_b32 m0, s47
	s_nop 0
	global_load_lds_dwordx4 v[234:235], off
	s_barrier
; #define STAGE(P, BASE, LD, br, kt) do { const char* _g = (const char*)((BASE) + (size_t)(br) * (LD) + (size_t)(kt) * 64); \
;     for (int _i = 0; _i < 2; ++_i) { int _b = tidx * 16 + _i * 8192; int _r, _c; stage_rc(_b, _r, _c); \
;       __builtin_amdgcn_global_load_lds((const unsigned*)(_g + (unsigned)((_r * (LD) + _c) * 2)), (unsigned*)((char*)(P) + _b), 16, 0, 0); } } while (0)
; #define LDA(dst, b, h) for (int m = 0; m < 4; ++m) for (int k = 0; k < 2; ++k) \
;     dst[m][k] = *reinterpret_cast<const bf16x8*>((char*)SA(b, h) + lds_byte(wr * 64 + m * 16 + fr, k * 32 + fq * 8))
; #define LDB(dst, b, h) for (int n = 0; n < 2; ++n) for (int k = 0; k < 2; ++k) \
;     dst[n][k] = *reinterpret_cast<const bf16x8*>((char*)SB(b, h) + lds_byte(wc * 32 + n * 16 + fr, k * 32 + fq * 8))
; #define MMA(ai, bj, At_, Bt_) do { __builtin_amdgcn_s_setprio(1); \
;     for (int k = 0; k < 2; ++k) for (int m = 0; m < 4; ++m) for (int n = 0; n < 2; ++n) \
;       acc[ai][bj][m][n] = __builtin_amdgcn_mfma_f32_16x16x32_bf16(At_[m][k], Bt_[n][k], acc[ai][bj][m][n], 0, 0, 0); \
;     __builtin_amdgcn_s_setprio(0); } while (0)
; #define WAIT_V(n) asm volatile("s_waitcnt vmcnt(" #n ")" ::: "memory")
; #define WAIT_L(n) asm volatile("s_waitcnt lgkmcnt(" #n ")" ::: "memory")
; #define BAR __builtin_amdgcn_s_barrier()
; #define SCHED __builtin_amdgcn_sched_barrier(0)
; template <int EPI, int lda, int ldb, int N, int K>
; __device__ __forceinline__ void gemm_phase(const u16* __restrict__ A, const u16* __restrict__ Bt, const GemmEpi ep, int wv) {
;     ...
;       LDA(At, 1, 1); STAGE(SA(1, 0), Ab, lda, brow, t + 3);
;       BAR; WAIT_L(0); MMA(1, 0, At, B0); BAR; SCHED;
;       STAGE(SB(1, 1), Bt, ldb, bcol + HALF, t + 3);
;       WAIT_V(6); BAR; MMA(1, 1, At, B1); BAR;
;     }
;     { LDB(B0, 0, 0); LDA(At, 0, 0); STAGE(SA(1, 1), Ab, lda, brow + HALF, nt - 1);
;       BAR; WAIT_L(0); MMA(0, 0, At, B0); BAR;
;       LDB(B1, 0, 1); BAR; WAIT_L(0); MMA(0, 1, At, B1); BAR;
	s_waitcnt lgkmcnt(0)
	v_mfma_f32_16x16x32_bf16 v[60:63], v[170:173], v[186:189], v[60:63]
	v_mfma_f32_16x16x32_bf16 v[56:59], v[178:181], v[186:189], v[56:59]
	v_mfma_f32_16x16x32_bf16 v[52:55], v[170:173], v[194:197], v[52:55]
	v_mfma_f32_16x16x32_bf16 v[48:51], v[178:181], v[194:197], v[48:51]
	v_mfma_f32_16x16x32_bf16 v[44:47], v[170:173], v[202:205], v[44:47]
	v_mfma_f32_16x16x32_bf16 v[40:43], v[178:181], v[202:205], v[40:43]
	v_mfma_f32_16x16x32_bf16 v[36:39], v[170:173], v[210:213], v[36:39]
	v_mfma_f32_16x16x32_bf16 v[32:35], v[178:181], v[210:213], v[32:35]
	v_mfma_f32_16x16x32_bf16 v[60:63], v[174:177], v[190:193], v[60:63]
	v_mfma_f32_16x16x32_bf16 v[56:59], v[182:185], v[190:193], v[56:59]
	v_mfma_f32_16x16x32_bf16 v[52:55], v[174:177], v[198:201], v[52:55]
	v_mfma_f32_16x16x32_bf16 v[48:51], v[182:185], v[198:201], v[48:51]
	v_mfma_f32_16x16x32_bf16 v[44:47], v[174:177], v[206:209], v[44:47]
	v_mfma_f32_16x16x32_bf16 v[40:43], v[182:185], v[206:209], v[40:43]
	v_mfma_f32_16x16x32_bf16 v[36:39], v[174:177], v[214:217], v[36:39]
	v_mfma_f32_16x16x32_bf16 v[32:35], v[182:185], v[214:217], v[32:35]
	s_barrier
	v_readfirstlane_b32 s47, v158
	v_add_u32_e32 v172, 0x2000, v158
	v_lshl_add_u64 v[170:171], v[238:239], 0, s[40:41]
	s_mov_b32 m0, s47
	v_readfirstlane_b32 s47, v172
	global_load_lds_dwordx4 v[170:171], off
	v_lshl_add_u64 v[170:171], v[240:241], 0, s[40:41]
	s_mov_b32 m0, s47
	s_nop 0
	global_load_lds_dwordx4 v[170:171], off
	s_add_i32 s46, s46, 2
	s_add_u32 s44, s44, 0x100
	s_addc_u32 s45, s45, 0
	s_cmp_gt_u32 s46, 27
	s_waitcnt vmcnt(6)
	s_barrier
	v_mfma_f32_16x16x32_bf16 v[28:31], v[218:221], v[186:189], v[28:31]
	v_mfma_f32_16x16x32_bf16 v[24:27], v[226:229], v[186:189], v[24:27]
	v_mfma_f32_16x16x32_bf16 v[20:23], v[218:221], v[194:197], v[20:23]
	v_mfma_f32_16x16x32_bf16 v[16:19], v[226:229], v[194:197], v[16:19]
	v_mfma_f32_16x16x32_bf16 v[12:15], v[218:221], v[202:205], v[12:15]
	v_mfma_f32_16x16x32_bf16 v[8:11], v[226:229], v[202:205], v[8:11]
	v_mfma_f32_16x16x32_bf16 v[4:7], v[218:221], v[210:213], v[4:7]
	v_mfma_f32_16x16x32_bf16 v[0:3], v[226:229], v[210:213], v[0:3]
	v_mfma_f32_16x16x32_bf16 v[28:31], v[222:225], v[190:193], v[28:31]
	v_mfma_f32_16x16x32_bf16 v[24:27], v[230:233], v[190:193], v[24:27]
	v_mfma_f32_16x16x32_bf16 v[20:23], v[222:225], v[198:201], v[20:23]
	v_mfma_f32_16x16x32_bf16 v[16:19], v[230:233], v[198:201], v[16:19]
	v_mfma_f32_16x16x32_bf16 v[12:15], v[222:225], v[206:209], v[12:15]
	v_mfma_f32_16x16x32_bf16 v[8:11], v[230:233], v[206:209], v[8:11]
	v_mfma_f32_16x16x32_bf16 v[4:7], v[222:225], v[214:217], v[4:7]
	v_mfma_f32_16x16x32_bf16 v[0:3], v[230:233], v[214:217], v[0:3]
	s_barrier
	s_cbranch_scc0 .LBB0_1448
	s_lshl_b64 s[44:45], s[16:17], 12
	s_add_u32 s44, s14, s44
	s_addc_u32 s45, s15, s45
	s_add_u32 s44, s44, 0x80000
	s_addc_u32 s45, s45, 0
	v_lshl_add_u64 v[156:157], s[44:45], 0, v[128:129]
	v_readfirstlane_b32 s46, v168
	v_lshl_add_u64 v[156:157], v[156:157], 0, s[42:43]
	s_mov_b32 m0, s46
	ds_read_b128 v[134:137], v160
	ds_read_b128 v[138:141], v160 offset:1024
	ds_read_b128 v[170:173], v160 offset:2048
	ds_read_b128 v[174:177], v160 offset:3072
	ds_read_b128 v[178:181], v151
	ds_read_b128 v[182:185], v151 offset:1024
	ds_read_b128 v[186:189], v150
	ds_read_b128 v[190:193], v150 offset:1024
	ds_read_b128 v[194:197], v149
	ds_read_b128 v[198:201], v149 offset:1024
	ds_read_b128 v[202:205], v148
	ds_read_b128 v[206:209], v148 offset:1024
	global_load_lds_dwordx4 v[156:157], off
	v_lshl_add_u64 v[156:157], s[44:45], 0, v[132:133]
	v_readfirstlane_b32 s44, v169
	v_lshl_add_u64 v[156:157], v[156:157], 0, s[42:43]
	s_mov_b32 m0, s44
	s_nop 0
	global_load_lds_dwordx4 v[156:157], off
	s_barrier
	s_waitcnt lgkmcnt(0)
	v_mfma_f32_16x16x32_bf16 v[124:127], v[134:137], v[178:181], v[124:127]
	v_mfma_f32_16x16x32_bf16 v[120:123], v[170:173], v[178:181], v[120:123]
	v_mfma_f32_16x16x32_bf16 v[116:119], v[134:137], v[186:189], v[116:119]
	v_mfma_f32_16x16x32_bf16 v[112:115], v[170:173], v[186:189], v[112:115]
	v_mfma_f32_16x16x32_bf16 v[108:111], v[134:137], v[194:197], v[108:111]
	v_mfma_f32_16x16x32_bf16 v[104:107], v[170:173], v[194:197], v[104:107]
	v_mfma_f32_16x16x32_bf16 v[100:103], v[134:137], v[202:205], v[100:103]
	v_mfma_f32_16x16x32_bf16 v[96:99], v[170:173], v[202:205], v[96:99]
	v_mfma_f32_16x16x32_bf16 v[124:127], v[138:141], v[182:185], v[124:127]
	v_mfma_f32_16x16x32_bf16 v[120:123], v[174:177], v[182:185], v[120:123]
	v_mfma_f32_16x16x32_bf16 v[116:119], v[138:141], v[190:193], v[116:119]
	v_mfma_f32_16x16x32_bf16 v[112:115], v[174:177], v[190:193], v[112:115]
	v_mfma_f32_16x16x32_bf16 v[108:111], v[138:141], v[198:201], v[108:111]
	v_mfma_f32_16x16x32_bf16 v[104:107], v[174:177], v[198:201], v[104:107]
	v_mfma_f32_16x16x32_bf16 v[100:103], v[138:141], v[206:209], v[100:103]
	v_mfma_f32_16x16x32_bf16 v[96:99], v[174:177], v[206:209], v[96:99]
	s_barrier
	ds_read_b128 v[210:213], v159
	ds_read_b128 v[214:217], v159 offset:1024
	ds_read_b128 v[218:221], v159 offset:2048
	ds_read_b128 v[156:159], v159 offset:3072
	s_barrier
; #define LDA(dst, b, h) for (int m = 0; m < 4; ++m) for (int k = 0; k < 2; ++k) \
;     dst[m][k] = *reinterpret_cast<const bf16x8*>((char*)SA(b, h) + lds_byte(wr * 64 + m * 16 + fr, k * 32 + fq * 8))
; #define LDB(dst, b, h) for (int n = 0; n < 2; ++n) for (int k = 0; k < 2; ++k) \
;     dst[n][k] = *reinterpret_cast<const bf16x8*>((char*)SB(b, h) + lds_byte(wc * 32 + n * 16 + fr, k * 32 + fq * 8))
; #define MMA(ai, bj, At_, Bt_) do { __builtin_amdgcn_s_setprio(1); \
;     for (int k = 0; k < 2; ++k) for (int m = 0; m < 4; ++m) for (int n = 0; n < 2; ++n) \
;       acc[ai][bj][m][n] = __builtin_amdgcn_mfma_f32_16x16x32_bf16(At_[m][k], Bt_[n][k], acc[ai][bj][m][n], 0, 0, 0); \
;     __builtin_amdgcn_s_setprio(0); } while (0)
; #define WAIT_V(n) asm volatile("s_waitcnt vmcnt(" #n ")" ::: "memory")
; #define WAIT_L(n) asm volatile("s_waitcnt lgkmcnt(" #n ")" ::: "memory")
; #define BAR __builtin_amdgcn_s_barrier()
; template <int EPI, int lda, int ldb, int N, int K>
; __device__ __forceinline__ void gemm_phase(const u16* __restrict__ A, const u16* __restrict__ Bt, const GemmEpi ep, int wv) {
;     ...
;       LDB(B1, 0, 1); BAR; WAIT_L(0); MMA(0, 1, At, B1); BAR;
;       LDA(At, 0, 1); WAIT_V(4); BAR; WAIT_L(0); MMA(1, 0, At, B0); MMA(1, 1, At, B1); BAR; }
;     { LDB(B0, 1, 0); LDA(At, 1, 0); WAIT_V(2); BAR; WAIT_L(0); MMA(0, 0, At, B0); BAR;
	s_waitcnt lgkmcnt(0)
	v_mfma_f32_16x16x32_bf16 v[92:95], v[210:213], v[178:181], v[92:95]
	v_mfma_f32_16x16x32_bf16 v[88:91], v[218:221], v[178:181], v[88:91]
	v_mfma_f32_16x16x32_bf16 v[76:79], v[210:213], v[194:197], v[76:79]
	v_mfma_f32_16x16x32_bf16 v[72:75], v[218:221], v[194:197], v[72:75]
	v_mfma_f32_16x16x32_bf16 v[84:87], v[210:213], v[186:189], v[84:87]
	v_mfma_f32_16x16x32_bf16 v[80:83], v[218:221], v[186:189], v[80:83]
	v_mfma_f32_16x16x32_bf16 v[68:71], v[210:213], v[202:205], v[68:71]
	v_mfma_f32_16x16x32_bf16 v[64:67], v[218:221], v[202:205], v[64:67]
	v_mfma_f32_16x16x32_bf16 v[92:95], v[214:217], v[182:185], v[92:95]
	v_mfma_f32_16x16x32_bf16 v[88:91], v[156:159], v[182:185], v[88:91]
	v_mfma_f32_16x16x32_bf16 v[76:79], v[214:217], v[198:201], v[76:79]
	v_mfma_f32_16x16x32_bf16 v[72:75], v[156:159], v[198:201], v[72:75]
	v_mfma_f32_16x16x32_bf16 v[178:181], v[214:217], v[190:193], v[84:87]
	v_mfma_f32_16x16x32_bf16 v[182:185], v[156:159], v[190:193], v[80:83]
	v_mfma_f32_16x16x32_bf16 v[186:189], v[214:217], v[206:209], v[68:71]
	v_mfma_f32_16x16x32_bf16 v[190:193], v[156:159], v[206:209], v[64:67]
	s_barrier
	s_nop 0
	ds_read_b128 v[64:67], v151 offset:16384
	ds_read_b128 v[68:71], v151 offset:17408
	ds_read_b128 v[80:83], v150 offset:16384
	ds_read_b128 v[84:87], v150 offset:17408
	ds_read_b128 v[194:197], v149 offset:16384
	ds_read_b128 v[198:201], v149 offset:17408
	ds_read_b128 v[202:205], v148 offset:16384
	ds_read_b128 v[206:209], v148 offset:17408
	s_waitcnt vmcnt(4)
	s_barrier
	s_waitcnt lgkmcnt(0)
	v_mfma_f32_16x16x32_bf16 v[60:63], v[134:137], v[64:67], v[60:63]
	v_mfma_f32_16x16x32_bf16 v[56:59], v[170:173], v[64:67], v[56:59]
	v_mfma_f32_16x16x32_bf16 v[52:55], v[134:137], v[80:83], v[52:55]
	v_mfma_f32_16x16x32_bf16 v[48:51], v[170:173], v[80:83], v[48:51]
	v_mfma_f32_16x16x32_bf16 v[44:47], v[134:137], v[194:197], v[44:47]
	v_mfma_f32_16x16x32_bf16 v[40:43], v[170:173], v[194:197], v[40:43]
	v_mfma_f32_16x16x32_bf16 v[36:39], v[134:137], v[202:205], v[36:39]
	v_mfma_f32_16x16x32_bf16 v[32:35], v[170:173], v[202:205], v[32:35]
	v_mfma_f32_16x16x32_bf16 v[60:63], v[138:141], v[68:71], v[60:63]
	v_mfma_f32_16x16x32_bf16 v[56:59], v[174:177], v[68:71], v[56:59]
	v_mfma_f32_16x16x32_bf16 v[52:55], v[138:141], v[84:87], v[52:55]
	v_mfma_f32_16x16x32_bf16 v[48:51], v[174:177], v[84:87], v[48:51]
	v_mfma_f32_16x16x32_bf16 v[44:47], v[138:141], v[198:201], v[44:47]
	v_mfma_f32_16x16x32_bf16 v[40:43], v[174:177], v[198:201], v[40:43]
	v_mfma_f32_16x16x32_bf16 v[36:39], v[138:141], v[206:209], v[36:39]
	v_mfma_f32_16x16x32_bf16 v[32:35], v[174:177], v[206:209], v[32:35]
	v_mfma_f32_16x16x32_bf16 v[28:31], v[210:213], v[64:67], v[28:31]
	v_mfma_f32_16x16x32_bf16 v[20:23], v[210:213], v[80:83], v[20:23]
	v_mfma_f32_16x16x32_bf16 v[12:15], v[210:213], v[194:197], v[12:15]
	v_mfma_f32_16x16x32_bf16 v[4:7], v[210:213], v[202:205], v[4:7]
	v_mfma_f32_16x16x32_bf16 v[24:27], v[218:221], v[64:67], v[24:27]
	v_mfma_f32_16x16x32_bf16 v[16:19], v[218:221], v[80:83], v[16:19]
	v_mfma_f32_16x16x32_bf16 v[8:11], v[218:221], v[194:197], v[8:11]
	v_mfma_f32_16x16x32_bf16 v[0:3], v[218:221], v[202:205], v[0:3]
	v_mfma_f32_16x16x32_bf16 v[28:31], v[214:217], v[68:71], v[28:31]
	v_mfma_f32_16x16x32_bf16 v[20:23], v[214:217], v[84:87], v[20:23]
	v_mfma_f32_16x16x32_bf16 v[12:15], v[214:217], v[198:201], v[12:15]
	v_mfma_f32_16x16x32_bf16 v[4:7], v[214:217], v[206:209], v[4:7]
	v_mfma_f32_16x16x32_bf16 v[134:137], v[156:159], v[68:71], v[24:27]
	v_mfma_f32_16x16x32_bf16 v[138:141], v[156:159], v[84:87], v[16:19]
	v_mfma_f32_16x16x32_bf16 v[168:171], v[156:159], v[198:201], v[8:11]
	v_mfma_f32_16x16x32_bf16 v[156:159], v[156:159], v[206:209], v[0:3]
	s_barrier
	s_nop 0
	ds_read_b128 v[0:3], v154
	ds_read_b128 v[8:11], v154 offset:1024
	ds_read_b128 v[16:19], v154 offset:2048
	ds_read_b128 v[172:175], v154 offset:3072
	ds_read_b128 v[24:27], v151 offset:32768
	ds_read_b128 v[194:197], v151 offset:33792
	ds_read_b128 v[198:201], v150 offset:32768
	ds_read_b128 v[202:205], v150 offset:33792
	ds_read_b128 v[206:209], v149 offset:32768
	ds_read_b128 v[210:213], v149 offset:33792
	ds_read_b128 v[214:217], v148 offset:32768
	ds_read_b128 v[218:221], v148 offset:33792
	s_waitcnt vmcnt(2)
	s_barrier
; #define LDA(dst, b, h) for (int m = 0; m < 4; ++m) for (int k = 0; k < 2; ++k) \
;     dst[m][k] = *reinterpret_cast<const bf16x8*>((char*)SA(b, h) + lds_byte(wr * 64 + m * 16 + fr, k * 32 + fq * 8))
; #define LDB(dst, b, h) for (int n = 0; n < 2; ++n) for (int k = 0; k < 2; ++k) \
;     dst[n][k] = *reinterpret_cast<const bf16x8*>((char*)SB(b, h) + lds_byte(wc * 32 + n * 16 + fr, k * 32 + fq * 8))
; #define MMA(ai, bj, At_, Bt_) do { __builtin_amdgcn_s_setprio(1); \
;     for (int k = 0; k < 2; ++k) for (int m = 0; m < 4; ++m) for (int n = 0; n < 2; ++n) \
;       acc[ai][bj][m][n] = __builtin_amdgcn_mfma_f32_16x16x32_bf16(At_[m][k], Bt_[n][k], acc[ai][bj][m][n], 0, 0, 0); \
;     __builtin_amdgcn_s_setprio(0); } while (0)
; #define WAIT_V(n) asm volatile("s_waitcnt vmcnt(" #n ")" ::: "memory")
; #define WAIT_L(n) asm volatile("s_waitcnt lgkmcnt(" #n ")" ::: "memory")
; #define BAR __builtin_amdgcn_s_barrier()
; template <int EPI, int lda, int ldb, int N, int K>
; __device__ __forceinline__ void gemm_phase(const u16* __restrict__ A, const u16* __restrict__ Bt, const GemmEpi ep, int wv) {
;     ...
;     { LDB(B0, 1, 0); LDA(At, 1, 0); WAIT_V(2); BAR; WAIT_L(0); MMA(0, 0, At, B0); BAR;
;       LDB(B1, 1, 1); WAIT_V(0); BAR; WAIT_L(0); MMA(0, 1, At, B1); BAR;
;       LDA(At, 1, 1); BAR; WAIT_L(0); MMA(1, 0, At, B0); MMA(1, 1, At, B1); BAR; }
;     if (wr == 0) BAR;
	s_waitcnt lgkmcnt(0)
	v_mfma_f32_16x16x32_bf16 v[64:67], v[0:3], v[24:27], v[124:127]
	v_mfma_f32_16x16x32_bf16 v[68:71], v[16:19], v[24:27], v[120:123]
	v_mfma_f32_16x16x32_bf16 v[80:83], v[0:3], v[198:201], v[116:119]
	v_mfma_f32_16x16x32_bf16 v[84:87], v[16:19], v[198:201], v[112:115]
	v_mfma_f32_16x16x32_bf16 v[108:111], v[0:3], v[206:209], v[108:111]
	v_mfma_f32_16x16x32_bf16 v[104:107], v[16:19], v[206:209], v[104:107]
	v_mfma_f32_16x16x32_bf16 v[120:123], v[0:3], v[214:217], v[100:103]
	v_mfma_f32_16x16x32_bf16 v[124:127], v[16:19], v[214:217], v[96:99]
	v_mfma_f32_16x16x32_bf16 v[116:119], v[8:11], v[194:197], v[64:67]
	v_mfma_f32_16x16x32_bf16 v[112:115], v[172:175], v[194:197], v[68:71]
	v_mfma_f32_16x16x32_bf16 v[100:103], v[8:11], v[202:205], v[80:83]
	v_mfma_f32_16x16x32_bf16 v[96:99], v[172:175], v[202:205], v[84:87]
	v_mfma_f32_16x16x32_bf16 v[84:87], v[8:11], v[210:213], v[108:111]
	v_mfma_f32_16x16x32_bf16 v[80:83], v[172:175], v[210:213], v[104:107]
	v_mfma_f32_16x16x32_bf16 v[68:71], v[8:11], v[218:221], v[120:123]
	v_mfma_f32_16x16x32_bf16 v[64:67], v[172:175], v[218:221], v[124:127]
	s_barrier
	ds_read_b128 v[222:225], v152
	ds_read_b128 v[226:229], v152 offset:1024
	ds_read_b128 v[230:233], v152 offset:2048
	ds_read_b128 v[152:155], v152 offset:3072
	s_waitcnt vmcnt(0)
	s_barrier
	s_waitcnt lgkmcnt(0)
	v_mfma_f32_16x16x32_bf16 v[92:95], v[222:225], v[24:27], v[92:95]
	v_mfma_f32_16x16x32_bf16 v[24:27], v[230:233], v[24:27], v[88:91]
	v_mfma_f32_16x16x32_bf16 v[88:91], v[222:225], v[198:201], v[178:181]
	v_mfma_f32_16x16x32_bf16 v[104:107], v[230:233], v[198:201], v[182:185]
	v_mfma_f32_16x16x32_bf16 v[76:79], v[222:225], v[206:209], v[76:79]
	v_mfma_f32_16x16x32_bf16 v[72:75], v[230:233], v[206:209], v[72:75]
	v_mfma_f32_16x16x32_bf16 v[176:179], v[222:225], v[214:217], v[186:189]
	v_mfma_f32_16x16x32_bf16 v[180:183], v[230:233], v[214:217], v[190:193]
	v_mfma_f32_16x16x32_bf16 v[124:127], v[226:229], v[194:197], v[92:95]
	v_mfma_f32_16x16x32_bf16 v[120:123], v[152:155], v[194:197], v[24:27]
	v_mfma_f32_16x16x32_bf16 v[108:111], v[226:229], v[202:205], v[88:91]
	v_mfma_f32_16x16x32_bf16 v[104:107], v[152:155], v[202:205], v[104:107]
	v_mfma_f32_16x16x32_bf16 v[92:95], v[226:229], v[210:213], v[76:79]
	v_mfma_f32_16x16x32_bf16 v[88:91], v[152:155], v[210:213], v[72:75]
	v_mfma_f32_16x16x32_bf16 v[76:79], v[226:229], v[218:221], v[176:179]
	v_mfma_f32_16x16x32_bf16 v[72:75], v[152:155], v[218:221], v[180:183]
	s_barrier
	ds_read_b128 v[176:179], v151 offset:49152
	ds_read_b128 v[180:183], v151 offset:50176
	ds_read_b128 v[184:187], v150 offset:49152
	ds_read_b128 v[188:191], v150 offset:50176
	ds_read_b128 v[192:195], v149 offset:49152
	ds_read_b128 v[196:199], v149 offset:50176
	ds_read_b128 v[200:203], v148 offset:49152
	ds_read_b128 v[148:151], v148 offset:50176
	s_barrier
	s_waitcnt lgkmcnt(0)
	v_mfma_f32_16x16x32_bf16 v[24:27], v[0:3], v[176:179], v[60:63]
	v_mfma_f32_16x16x32_bf16 v[60:63], v[16:19], v[176:179], v[56:59]
	v_mfma_f32_16x16x32_bf16 v[52:55], v[0:3], v[184:187], v[52:55]
	v_mfma_f32_16x16x32_bf16 v[204:207], v[16:19], v[184:187], v[48:51]
	v_mfma_f32_16x16x32_bf16 v[44:47], v[0:3], v[192:195], v[44:47]
	v_mfma_f32_16x16x32_bf16 v[208:211], v[16:19], v[192:195], v[40:43]
	v_mfma_f32_16x16x32_bf16 v[0:3], v[0:3], v[200:203], v[36:39]
	v_mfma_f32_16x16x32_bf16 v[36:39], v[16:19], v[200:203], v[32:35]
	v_mfma_f32_16x16x32_bf16 v[56:59], v[8:11], v[180:183], v[24:27]
	v_mfma_f32_16x16x32_bf16 v[48:51], v[172:175], v[180:183], v[60:63]
	v_mfma_f32_16x16x32_bf16 v[40:43], v[8:11], v[188:191], v[52:55]
	v_mfma_f32_16x16x32_bf16 v[32:35], v[172:175], v[188:191], v[204:207]
	v_mfma_f32_16x16x32_bf16 v[24:27], v[8:11], v[196:199], v[44:47]
	v_mfma_f32_16x16x32_bf16 v[16:19], v[172:175], v[196:199], v[208:211]
	v_mfma_f32_16x16x32_bf16 v[8:11], v[8:11], v[148:151], v[0:3]
	v_mfma_f32_16x16x32_bf16 v[0:3], v[172:175], v[148:151], v[36:39]
	v_mfma_f32_16x16x32_bf16 v[28:31], v[222:225], v[176:179], v[28:31]
	v_mfma_f32_16x16x32_bf16 v[36:39], v[230:233], v[176:179], v[134:137]
	v_mfma_f32_16x16x32_bf16 v[20:23], v[222:225], v[184:187], v[20:23]
	v_mfma_f32_16x16x32_bf16 v[134:137], v[230:233], v[184:187], v[138:141]
	v_mfma_f32_16x16x32_bf16 v[12:15], v[222:225], v[192:195], v[12:15]
	v_mfma_f32_16x16x32_bf16 v[138:141], v[230:233], v[192:195], v[168:171]
	v_mfma_f32_16x16x32_bf16 v[4:7], v[222:225], v[200:203], v[4:7]
	v_mfma_f32_16x16x32_bf16 v[156:159], v[230:233], v[200:203], v[156:159]
	v_mfma_f32_16x16x32_bf16 v[60:63], v[226:229], v[180:183], v[28:31]
	v_mfma_f32_16x16x32_bf16 v[52:55], v[152:155], v[180:183], v[36:39]
	v_mfma_f32_16x16x32_bf16 v[44:47], v[226:229], v[188:191], v[20:23]
	v_mfma_f32_16x16x32_bf16 v[36:39], v[152:155], v[188:191], v[134:137]
	v_mfma_f32_16x16x32_bf16 v[28:31], v[226:229], v[196:199], v[12:15]
	v_mfma_f32_16x16x32_bf16 v[20:23], v[152:155], v[196:199], v[138:141]
	v_mfma_f32_16x16x32_bf16 v[12:15], v[226:229], v[148:151], v[4:7]
	v_mfma_f32_16x16x32_bf16 v[4:7], v[152:155], v[148:151], v[156:159]
	v_cmp_gt_u32_e32 vcc, s60, v130
	s_barrier
	s_and_saveexec_b64 s[44:45], vcc
	s_cbranch_execz .LBB0_1451
	s_barrier

; #define STAGE(P, BASE, LD, br, kt) do { const char* _g = (const char*)((BASE) + (size_t)(br) * (LD) + (size_t)(kt) * 64); \
;     for (int _i = 0; _i < 2; ++_i) { int _b = tidx * 16 + _i * 8192; int _r, _c; stage_rc(_b, _r, _c); \
;       __builtin_amdgcn_global_load_lds((const unsigned*)(_g + (unsigned)((_r * (LD) + _c) * 2)), (unsigned*)((char*)(P) + _b), 16, 0, 0); } } while (0)
; #define LDA(dst, b, h) for (int m = 0; m < 4; ++m) for (int k = 0; k < 2; ++k) \
;     dst[m][k] = *reinterpret_cast<const bf16x8*>((char*)SA(b, h) + lds_byte(wr * 64 + m * 16 + fr, k * 32 + fq * 8))
; #define LDB(dst, b, h) for (int n = 0; n < 2; ++n) for (int k = 0; k < 2; ++k) \
;     dst[n][k] = *reinterpret_cast<const bf16x8*>((char*)SB(b, h) + lds_byte(wc * 32 + n * 16 + fr, k * 32 + fq * 8))
; #define MMA(ai, bj, At_, Bt_) do { __builtin_amdgcn_s_setprio(1); \
;     for (int k = 0; k < 2; ++k) for (int m = 0; m < 4; ++m) for (int n = 0; n < 2; ++n) \
;       acc[ai][bj][m][n] = __builtin_amdgcn_mfma_f32_16x16x32_bf16(At_[m][k], Bt_[n][k], acc[ai][bj][m][n], 0, 0, 0); \
;     __builtin_amdgcn_s_setprio(0); } while (0)
; #define WAIT_L(n) asm volatile("s_waitcnt lgkmcnt(" #n ")" ::: "memory")
; #define BAR __builtin_amdgcn_s_barrier()
; #define SCHED __builtin_amdgcn_sched_barrier(0)
; template <int EPI, int lda, int ldb, int N, int K>
; __device__ __forceinline__ void gemm_phase(const u16* __restrict__ A, const u16* __restrict__ Bt, const GemmEpi ep, int wv) {
;     ...
;       LDB(B0, 0, 0); SCHED; LDA(At, 0, 0); STAGE(SA(1, 1), Ab, lda, brow + HALF, t + 1);
;       WAIT_L(8); BAR; WAIT_L(0); MMA(0, 0, At, B0); BAR; SCHED;
;       LDB(B1, 0, 1); STAGE(SB(0, 0), Bt, ldb, bcol, t + 2);
;       BAR; WAIT_L(0); MMA(0, 1, At, B1); BAR;
;       LDA(At, 0, 1); STAGE(SA(0, 0), Ab, lda, brow, t + 2);
;       BAR; WAIT_L(0); MMA(1, 0, At, B0); BAR; SCHED;
.LBB0_1564:
	ds_read_b128 v[172:175], v161
	ds_read_b128 v[176:179], v161 offset:1024
	ds_read_b128 v[180:183], v161 offset:2048
	ds_read_b128 v[184:187], v161 offset:3072
	v_add_u32_e32 v169, 0xc000, v148
	v_lshl_add_u64 v[236:237], v[136:137], 0, s[40:41]
	v_readfirstlane_b32 s43, v169
	v_add_u32_e32 v170, 0xe000, v148
	v_lshl_add_u64 v[162:163], v[236:237], 0, s[14:15]
	s_mov_b32 m0, s43
	v_lshl_add_u64 v[238:239], v[134:135], 0, s[40:41]
	v_readfirstlane_b32 s43, v170
	ds_read_b128 v[164:167], v152
	ds_read_b128 v[188:191], v152 offset:1024
	ds_read_b128 v[192:195], v151
	ds_read_b128 v[196:199], v151 offset:1024
	ds_read_b128 v[200:203], v150
	ds_read_b128 v[204:207], v150 offset:1024
	ds_read_b128 v[208:211], v149
	ds_read_b128 v[212:215], v149 offset:1024
	global_load_lds_dwordx4 v[162:163], off
	v_lshl_add_u64 v[162:163], v[238:239], 0, s[14:15]
	s_mov_b32 m0, s43
	s_nop 0
	global_load_lds_dwordx4 v[162:163], off
	s_waitcnt lgkmcnt(8)
	s_barrier
	s_waitcnt lgkmcnt(0)
	v_mfma_f32_16x16x32_bf16 v[124:127], v[172:175], v[164:167], v[124:127]
	v_mfma_f32_16x16x32_bf16 v[120:123], v[180:183], v[164:167], v[120:123]
	v_mfma_f32_16x16x32_bf16 v[116:119], v[172:175], v[192:195], v[116:119]
	v_mfma_f32_16x16x32_bf16 v[112:115], v[180:183], v[192:195], v[112:115]
	v_mfma_f32_16x16x32_bf16 v[108:111], v[172:175], v[200:203], v[108:111]
	v_mfma_f32_16x16x32_bf16 v[104:107], v[180:183], v[200:203], v[104:107]
	v_mfma_f32_16x16x32_bf16 v[100:103], v[172:175], v[208:211], v[100:103]
	v_mfma_f32_16x16x32_bf16 v[96:99], v[180:183], v[208:211], v[96:99]
	v_mfma_f32_16x16x32_bf16 v[124:127], v[176:179], v[188:191], v[124:127]
	v_mfma_f32_16x16x32_bf16 v[120:123], v[184:187], v[188:191], v[120:123]
	v_mfma_f32_16x16x32_bf16 v[116:119], v[176:179], v[196:199], v[116:119]
	v_mfma_f32_16x16x32_bf16 v[112:115], v[184:187], v[196:199], v[112:115]
	v_mfma_f32_16x16x32_bf16 v[108:111], v[176:179], v[204:207], v[108:111]
	v_mfma_f32_16x16x32_bf16 v[104:107], v[184:187], v[204:207], v[104:107]
	v_mfma_f32_16x16x32_bf16 v[100:103], v[176:179], v[212:215], v[100:103]
	v_mfma_f32_16x16x32_bf16 v[96:99], v[184:187], v[212:215], v[96:99]
	s_barrier
	v_add_u32_e32 v162, s52, v153
	v_lshl_add_u64 v[240:241], v[140:141], 0, s[40:41]
	v_readfirstlane_b32 s43, v162
	v_add_u32_e32 v163, 0x2000, v162
	v_lshl_add_u64 v[232:233], v[240:241], 0, s[16:17]
	s_mov_b32 m0, s43
	v_lshl_add_u64 v[242:243], v[138:139], 0, s[40:41]
	v_readfirstlane_b32 s43, v163
	ds_read_b128 v[216:219], v160
	ds_read_b128 v[220:223], v160 offset:1024
	ds_read_b128 v[224:227], v160 offset:2048
	ds_read_b128 v[228:231], v160 offset:3072
	global_load_lds_dwordx4 v[232:233], off
	v_lshl_add_u64 v[232:233], v[242:243], 0, s[16:17]
	s_mov_b32 m0, s43
	s_nop 0
	global_load_lds_dwordx4 v[232:233], off
	s_barrier
	s_waitcnt lgkmcnt(0)
	v_mfma_f32_16x16x32_bf16 v[92:95], v[216:219], v[164:167], v[92:95]
	v_mfma_f32_16x16x32_bf16 v[88:91], v[224:227], v[164:167], v[88:91]
	v_mfma_f32_16x16x32_bf16 v[84:87], v[216:219], v[192:195], v[84:87]
	v_mfma_f32_16x16x32_bf16 v[80:83], v[224:227], v[192:195], v[80:83]
	v_mfma_f32_16x16x32_bf16 v[76:79], v[216:219], v[200:203], v[76:79]
	v_mfma_f32_16x16x32_bf16 v[72:75], v[224:227], v[200:203], v[72:75]
	v_mfma_f32_16x16x32_bf16 v[68:71], v[216:219], v[208:211], v[68:71]
	v_mfma_f32_16x16x32_bf16 v[64:67], v[224:227], v[208:211], v[64:67]
	v_mfma_f32_16x16x32_bf16 v[92:95], v[220:223], v[188:191], v[92:95]
	v_mfma_f32_16x16x32_bf16 v[88:91], v[228:231], v[188:191], v[88:91]
	v_mfma_f32_16x16x32_bf16 v[84:87], v[220:223], v[196:199], v[84:87]
	v_mfma_f32_16x16x32_bf16 v[80:83], v[228:231], v[196:199], v[80:83]
	v_mfma_f32_16x16x32_bf16 v[76:79], v[220:223], v[204:207], v[76:79]
	v_mfma_f32_16x16x32_bf16 v[72:75], v[228:231], v[204:207], v[72:75]
	v_mfma_f32_16x16x32_bf16 v[68:71], v[220:223], v[212:215], v[68:71]
	v_mfma_f32_16x16x32_bf16 v[64:67], v[228:231], v[212:215], v[64:67]
	s_barrier
	v_readfirstlane_b32 s43, v148
	v_lshl_add_u64 v[164:165], v[236:237], 0, s[18:19]
	s_mov_b32 m0, s43
	ds_read_b128 v[188:191], v152 offset:16384
	ds_read_b128 v[192:195], v152 offset:17408
	ds_read_b128 v[196:199], v151 offset:16384
	ds_read_b128 v[200:203], v151 offset:17408
	ds_read_b128 v[204:207], v150 offset:16384
	ds_read_b128 v[208:211], v150 offset:17408
	ds_read_b128 v[212:215], v149 offset:16384
	ds_read_b128 v[232:235], v149 offset:17408
	global_load_lds_dwordx4 v[164:165], off
	v_add_u32_e32 v164, 0x2000, v148
	v_lshl_add_u64 v[166:167], v[238:239], 0, s[18:19]
	v_readfirstlane_b32 s43, v164
	s_mov_b32 m0, s43
	s_nop 0
	global_load_lds_dwordx4 v[166:167], off
	s_barrier
	s_waitcnt lgkmcnt(0)
	v_mfma_f32_16x16x32_bf16 v[60:63], v[172:175], v[188:191], v[60:63]
	v_mfma_f32_16x16x32_bf16 v[56:59], v[180:183], v[188:191], v[56:59]
	v_mfma_f32_16x16x32_bf16 v[52:55], v[172:175], v[196:199], v[52:55]
	v_mfma_f32_16x16x32_bf16 v[48:51], v[180:183], v[196:199], v[48:51]
	v_mfma_f32_16x16x32_bf16 v[44:47], v[172:175], v[204:207], v[44:47]
	v_mfma_f32_16x16x32_bf16 v[40:43], v[180:183], v[204:207], v[40:43]
	v_mfma_f32_16x16x32_bf16 v[36:39], v[172:175], v[212:215], v[36:39]
	v_mfma_f32_16x16x32_bf16 v[32:35], v[180:183], v[212:215], v[32:35]
	v_mfma_f32_16x16x32_bf16 v[60:63], v[176:179], v[192:195], v[60:63]
	v_mfma_f32_16x16x32_bf16 v[56:59], v[184:187], v[192:195], v[56:59]
	v_mfma_f32_16x16x32_bf16 v[52:55], v[176:179], v[200:203], v[52:55]
	v_mfma_f32_16x16x32_bf16 v[48:51], v[184:187], v[200:203], v[48:51]
	v_mfma_f32_16x16x32_bf16 v[44:47], v[176:179], v[208:211], v[44:47]
	v_mfma_f32_16x16x32_bf16 v[40:43], v[184:187], v[208:211], v[40:43]
	v_mfma_f32_16x16x32_bf16 v[36:39], v[176:179], v[232:235], v[36:39]
	v_mfma_f32_16x16x32_bf16 v[32:35], v[184:187], v[232:235], v[32:35]
	s_barrier
; #define STAGE(P, BASE, LD, br, kt) do { const char* _g = (const char*)((BASE) + (size_t)(br) * (LD) + (size_t)(kt) * 64); \
;     for (int _i = 0; _i < 2; ++_i) { int _b = tidx * 16 + _i * 8192; int _r, _c; stage_rc(_b, _r, _c); \
;       __builtin_amdgcn_global_load_lds((const unsigned*)(_g + (unsigned)((_r * (LD) + _c) * 2)), (unsigned*)((char*)(P) + _b), 16, 0, 0); } } while (0)
; #define LDA(dst, b, h) for (int m = 0; m < 4; ++m) for (int k = 0; k < 2; ++k) \
;     dst[m][k] = *reinterpret_cast<const bf16x8*>((char*)SA(b, h) + lds_byte(wr * 64 + m * 16 + fr, k * 32 + fq * 8))
; #define LDB(dst, b, h) for (int n = 0; n < 2; ++n) for (int k = 0; k < 2; ++k) \
;     dst[n][k] = *reinterpret_cast<const bf16x8*>((char*)SB(b, h) + lds_byte(wc * 32 + n * 16 + fr, k * 32 + fq * 8))
; #define MMA(ai, bj, At_, Bt_) do { __builtin_amdgcn_s_setprio(1); \
;     for (int k = 0; k < 2; ++k) for (int m = 0; m < 4; ++m) for (int n = 0; n < 2; ++n) \
;       acc[ai][bj][m][n] = __builtin_amdgcn_mfma_f32_16x16x32_bf16(At_[m][k], Bt_[n][k], acc[ai][bj][m][n], 0, 0, 0); \
;     __builtin_amdgcn_s_setprio(0); } while (0)
; #define WAIT_V(n) asm volatile("s_waitcnt vmcnt(" #n ")" ::: "memory")
; #define WAIT_L(n) asm volatile("s_waitcnt lgkmcnt(" #n ")" ::: "memory")
; #define BAR __builtin_amdgcn_s_barrier()
; #define SCHED __builtin_amdgcn_sched_barrier(0)
; template <int EPI, int lda, int ldb, int N, int K>
; __device__ __forceinline__ void gemm_phase(const u16* __restrict__ A, const u16* __restrict__ Bt, const GemmEpi ep, int wv) {
;     ...
;       STAGE(SB(0, 1), Bt, ldb, bcol + HALF, t + 2);
;       WAIT_V(6); BAR; MMA(1, 1, At, B1); BAR;
;       LDB(B0, 1, 0); SCHED; LDA(At, 1, 0); STAGE(SA(0, 1), Ab, lda, brow + HALF, t + 2);
;       WAIT_L(8); BAR; WAIT_L(0); MMA(0, 0, At, B0); BAR; SCHED;
;       LDB(B1, 1, 1); STAGE(SB(1, 0), Bt, ldb, bcol, t + 3);
;       BAR; WAIT_L(0); MMA(0, 1, At, B1); BAR;
	v_add_u32_e32 v165, s53, v153
	v_lshl_add_u64 v[166:167], v[240:241], 0, s[20:21]
	v_readfirstlane_b32 s43, v165
	s_mov_b32 m0, s43
	v_lshl_add_u64 v[172:173], v[242:243], 0, s[20:21]
	global_load_lds_dwordx4 v[166:167], off
	v_add_u32_e32 v166, 0x2000, v165
	s_nop 0
	v_readfirstlane_b32 s43, v166
	s_mov_b32 m0, s43
	s_nop 0
	global_load_lds_dwordx4 v[172:173], off
	s_waitcnt vmcnt(6)
	s_barrier
	v_mfma_f32_16x16x32_bf16 v[28:31], v[216:219], v[188:191], v[28:31]
	v_mfma_f32_16x16x32_bf16 v[24:27], v[224:227], v[188:191], v[24:27]
	v_mfma_f32_16x16x32_bf16 v[20:23], v[216:219], v[196:199], v[20:23]
	v_mfma_f32_16x16x32_bf16 v[16:19], v[224:227], v[196:199], v[16:19]
	v_mfma_f32_16x16x32_bf16 v[12:15], v[216:219], v[204:207], v[12:15]
	v_mfma_f32_16x16x32_bf16 v[8:11], v[224:227], v[204:207], v[8:11]
	v_mfma_f32_16x16x32_bf16 v[4:7], v[216:219], v[212:215], v[4:7]
	v_mfma_f32_16x16x32_bf16 v[0:3], v[224:227], v[212:215], v[0:3]
	v_mfma_f32_16x16x32_bf16 v[28:31], v[220:223], v[192:195], v[28:31]
	v_mfma_f32_16x16x32_bf16 v[24:27], v[228:231], v[192:195], v[24:27]
	v_mfma_f32_16x16x32_bf16 v[20:23], v[220:223], v[200:203], v[20:23]
	v_mfma_f32_16x16x32_bf16 v[16:19], v[228:231], v[200:203], v[16:19]
	v_mfma_f32_16x16x32_bf16 v[12:15], v[220:223], v[208:211], v[12:15]
	v_mfma_f32_16x16x32_bf16 v[8:11], v[228:231], v[208:211], v[8:11]
	v_mfma_f32_16x16x32_bf16 v[4:7], v[220:223], v[232:235], v[4:7]
	v_mfma_f32_16x16x32_bf16 v[0:3], v[228:231], v[232:235], v[0:3]
	s_barrier
	ds_read_b128 v[172:175], v156
	ds_read_b128 v[176:179], v156 offset:1024
	ds_read_b128 v[180:183], v156 offset:2048
	ds_read_b128 v[184:187], v156 offset:3072
	v_add_u32_e32 v167, 0x4000, v148
	v_add_u32_e32 v168, 0x6000, v148
	v_readfirstlane_b32 s43, v167
	v_lshl_add_u64 v[220:221], v[236:237], 0, s[22:23]
	s_mov_b32 m0, s43
	v_readfirstlane_b32 s43, v168
	ds_read_b128 v[188:191], v152 offset:32768
	ds_read_b128 v[192:195], v152 offset:33792
	ds_read_b128 v[196:199], v151 offset:32768
	ds_read_b128 v[200:203], v151 offset:33792
	ds_read_b128 v[204:207], v150 offset:32768
	ds_read_b128 v[208:211], v150 offset:33792
	ds_read_b128 v[212:215], v149 offset:32768
	ds_read_b128 v[216:219], v149 offset:33792
	global_load_lds_dwordx4 v[220:221], off
	v_lshl_add_u64 v[220:221], v[238:239], 0, s[22:23]
	s_mov_b32 m0, s43
	s_nop 0
	global_load_lds_dwordx4 v[220:221], off
	s_waitcnt lgkmcnt(8)
	s_barrier
	s_waitcnt lgkmcnt(0)
	v_mfma_f32_16x16x32_bf16 v[124:127], v[172:175], v[188:191], v[124:127]
	v_mfma_f32_16x16x32_bf16 v[120:123], v[180:183], v[188:191], v[120:123]
	v_mfma_f32_16x16x32_bf16 v[116:119], v[172:175], v[196:199], v[116:119]
	v_mfma_f32_16x16x32_bf16 v[112:115], v[180:183], v[196:199], v[112:115]
	v_mfma_f32_16x16x32_bf16 v[108:111], v[172:175], v[204:207], v[108:111]
	v_mfma_f32_16x16x32_bf16 v[104:107], v[180:183], v[204:207], v[104:107]
	v_mfma_f32_16x16x32_bf16 v[100:103], v[172:175], v[212:215], v[100:103]
	v_mfma_f32_16x16x32_bf16 v[96:99], v[180:183], v[212:215], v[96:99]
	v_mfma_f32_16x16x32_bf16 v[124:127], v[176:179], v[192:195], v[124:127]
	v_mfma_f32_16x16x32_bf16 v[120:123], v[184:187], v[192:195], v[120:123]
	v_mfma_f32_16x16x32_bf16 v[116:119], v[176:179], v[200:203], v[116:119]
	v_mfma_f32_16x16x32_bf16 v[112:115], v[184:187], v[200:203], v[112:115]
	v_mfma_f32_16x16x32_bf16 v[108:111], v[176:179], v[208:211], v[108:111]
	v_mfma_f32_16x16x32_bf16 v[104:107], v[184:187], v[208:211], v[104:107]
	v_mfma_f32_16x16x32_bf16 v[100:103], v[176:179], v[216:219], v[100:103]
	v_mfma_f32_16x16x32_bf16 v[96:99], v[184:187], v[216:219], v[96:99]
	s_barrier
	v_readfirstlane_b32 s43, v155
	v_add_u32_e32 v171, 0x2000, v155
	v_lshl_add_u64 v[244:245], v[240:241], 0, s[24:25]
	s_mov_b32 m0, s43
	v_readfirstlane_b32 s43, v171
	ds_read_b128 v[220:223], v154
	ds_read_b128 v[224:227], v154 offset:1024
	ds_read_b128 v[228:231], v154 offset:2048
	ds_read_b128 v[232:235], v154 offset:3072
	global_load_lds_dwordx4 v[244:245], off
	v_lshl_add_u64 v[244:245], v[242:243], 0, s[24:25]
	s_mov_b32 m0, s43
	s_nop 0
	global_load_lds_dwordx4 v[244:245], off
	s_barrier
	s_waitcnt lgkmcnt(0)
	v_mfma_f32_16x16x32_bf16 v[92:95], v[220:223], v[188:191], v[92:95]
	v_mfma_f32_16x16x32_bf16 v[88:91], v[228:231], v[188:191], v[88:91]
	v_mfma_f32_16x16x32_bf16 v[84:87], v[220:223], v[196:199], v[84:87]
	v_mfma_f32_16x16x32_bf16 v[80:83], v[228:231], v[196:199], v[80:83]
	v_mfma_f32_16x16x32_bf16 v[76:79], v[220:223], v[204:207], v[76:79]
	v_mfma_f32_16x16x32_bf16 v[72:75], v[228:231], v[204:207], v[72:75]
	v_mfma_f32_16x16x32_bf16 v[68:71], v[220:223], v[212:215], v[68:71]
	v_mfma_f32_16x16x32_bf16 v[64:67], v[228:231], v[212:215], v[64:67]
	v_mfma_f32_16x16x32_bf16 v[92:95], v[224:227], v[192:195], v[92:95]
	v_mfma_f32_16x16x32_bf16 v[88:91], v[232:235], v[192:195], v[88:91]
	v_mfma_f32_16x16x32_bf16 v[84:87], v[224:227], v[200:203], v[84:87]
	v_mfma_f32_16x16x32_bf16 v[80:83], v[232:235], v[200:203], v[80:83]
	v_mfma_f32_16x16x32_bf16 v[76:79], v[224:227], v[208:211], v[76:79]
	v_mfma_f32_16x16x32_bf16 v[72:75], v[232:235], v[208:211], v[72:75]
	v_mfma_f32_16x16x32_bf16 v[68:71], v[224:227], v[216:219], v[68:71]
	v_mfma_f32_16x16x32_bf16 v[64:67], v[232:235], v[216:219], v[64:67]
	s_barrier
	v_readfirstlane_b32 s43, v157
	v_lshl_add_u64 v[236:237], v[236:237], 0, s[26:27]
	s_mov_b32 m0, s43
	v_readfirstlane_b32 s43, v158
	ds_read_b128 v[188:191], v152 offset:49152
	ds_read_b128 v[192:195], v152 offset:50176
	ds_read_b128 v[196:199], v151 offset:49152
	ds_read_b128 v[200:203], v151 offset:50176
	ds_read_b128 v[204:207], v150 offset:49152
	ds_read_b128 v[208:211], v150 offset:50176
	ds_read_b128 v[212:215], v149 offset:49152
	ds_read_b128 v[216:219], v149 offset:50176
	global_load_lds_dwordx4 v[236:237], off
	v_lshl_add_u64 v[236:237], v[238:239], 0, s[26:27]
	s_mov_b32 m0, s43
	s_nop 0
	global_load_lds_dwordx4 v[236:237], off
	s_barrier
; #define STAGE(P, BASE, LD, br, kt) do { const char* _g = (const char*)((BASE) + (size_t)(br) * (LD) + (size_t)(kt) * 64); \
;     for (int _i = 0; _i < 2; ++_i) { int _b = tidx * 16 + _i * 8192; int _r, _c; stage_rc(_b, _r, _c); \
;       __builtin_amdgcn_global_load_lds((const unsigned*)(_g + (unsigned)((_r * (LD) + _c) * 2)), (unsigned*)((char*)(P) + _b), 16, 0, 0); } } while (0)
; #define LDA(dst, b, h) for (int m = 0; m < 4; ++m) for (int k = 0; k < 2; ++k) \
;     dst[m][k] = *reinterpret_cast<const bf16x8*>((char*)SA(b, h) + lds_byte(wr * 64 + m * 16 + fr, k * 32 + fq * 8))
; #define LDB(dst, b, h) for (int n = 0; n < 2; ++n) for (int k = 0; k < 2; ++k) \
;     dst[n][k] = *reinterpret_cast<const bf16x8*>((char*)SB(b, h) + lds_byte(wc * 32 + n * 16 + fr, k * 32 + fq * 8))
; #define MMA(ai, bj, At_, Bt_) do { __builtin_amdgcn_s_setprio(1); \
;     for (int k = 0; k < 2; ++k) for (int m = 0; m < 4; ++m) for (int n = 0; n < 2; ++n) \
;       acc[ai][bj][m][n] = __builtin_amdgcn_mfma_f32_16x16x32_bf16(At_[m][k], Bt_[n][k], acc[ai][bj][m][n], 0, 0, 0); \
;     __builtin_amdgcn_s_setprio(0); } while (0)
; #define WAIT_V(n) asm volatile("s_waitcnt vmcnt(" #n ")" ::: "memory")
; #define WAIT_L(n) asm volatile("s_waitcnt lgkmcnt(" #n ")" ::: "memory")
; #define BAR __builtin_amdgcn_s_barrier()
; #define SCHED __builtin_amdgcn_sched_barrier(0)
; template <int EPI, int lda, int ldb, int N, int K>
; __device__ __forceinline__ void gemm_phase(const u16* __restrict__ A, const u16* __restrict__ Bt, const GemmEpi ep, int wv) {
;     ...
;       LDA(At, 1, 1); STAGE(SA(1, 0), Ab, lda, brow, t + 3);
;       BAR; WAIT_L(0); MMA(1, 0, At, B0); BAR; SCHED;
;       STAGE(SB(1, 1), Bt, ldb, bcol + HALF, t + 3);
;       WAIT_V(6); BAR; MMA(1, 1, At, B1); BAR;
;     }
;     { LDB(B0, 0, 0); LDA(At, 0, 0); STAGE(SA(1, 1), Ab, lda, brow + HALF, nt - 1);
;       BAR; WAIT_L(0); MMA(0, 0, At, B0); BAR;
;       LDB(B1, 0, 1); BAR; WAIT_L(0); MMA(0, 1, At, B1); BAR;
	s_waitcnt lgkmcnt(0)
	v_mfma_f32_16x16x32_bf16 v[60:63], v[172:175], v[188:191], v[60:63]
	v_mfma_f32_16x16x32_bf16 v[56:59], v[180:183], v[188:191], v[56:59]
	v_mfma_f32_16x16x32_bf16 v[52:55], v[172:175], v[196:199], v[52:55]
	v_mfma_f32_16x16x32_bf16 v[48:51], v[180:183], v[196:199], v[48:51]
	v_mfma_f32_16x16x32_bf16 v[44:47], v[172:175], v[204:207], v[44:47]
	v_mfma_f32_16x16x32_bf16 v[40:43], v[180:183], v[204:207], v[40:43]
	v_mfma_f32_16x16x32_bf16 v[36:39], v[172:175], v[212:215], v[36:39]
	v_mfma_f32_16x16x32_bf16 v[32:35], v[180:183], v[212:215], v[32:35]
	v_mfma_f32_16x16x32_bf16 v[60:63], v[176:179], v[192:195], v[60:63]
	v_mfma_f32_16x16x32_bf16 v[56:59], v[184:187], v[192:195], v[56:59]
	v_mfma_f32_16x16x32_bf16 v[52:55], v[176:179], v[200:203], v[52:55]
	v_mfma_f32_16x16x32_bf16 v[48:51], v[184:187], v[200:203], v[48:51]
	v_mfma_f32_16x16x32_bf16 v[44:47], v[176:179], v[208:211], v[44:47]
	v_mfma_f32_16x16x32_bf16 v[40:43], v[184:187], v[208:211], v[40:43]
	v_mfma_f32_16x16x32_bf16 v[36:39], v[176:179], v[216:219], v[36:39]
	v_mfma_f32_16x16x32_bf16 v[32:35], v[184:187], v[216:219], v[32:35]
	s_barrier
	v_readfirstlane_b32 s43, v159
	v_add_u32_e32 v171, 0x2000, v159
	v_lshl_add_u64 v[172:173], v[240:241], 0, s[34:35]
	s_mov_b32 m0, s43
	v_readfirstlane_b32 s43, v171
	global_load_lds_dwordx4 v[172:173], off
	v_lshl_add_u64 v[172:173], v[242:243], 0, s[34:35]
	s_mov_b32 m0, s43
	s_nop 0
	global_load_lds_dwordx4 v[172:173], off
	s_add_i32 s42, s42, 2
	s_add_u32 s40, s40, 0x100
	s_addc_u32 s41, s41, 0
	s_cmp_gt_u32 s42, 27
	s_waitcnt vmcnt(6)
	s_barrier
	v_mfma_f32_16x16x32_bf16 v[28:31], v[220:223], v[188:191], v[28:31]
	v_mfma_f32_16x16x32_bf16 v[24:27], v[228:231], v[188:191], v[24:27]
	v_mfma_f32_16x16x32_bf16 v[20:23], v[220:223], v[196:199], v[20:23]
	v_mfma_f32_16x16x32_bf16 v[16:19], v[228:231], v[196:199], v[16:19]
	v_mfma_f32_16x16x32_bf16 v[12:15], v[220:223], v[204:207], v[12:15]
	v_mfma_f32_16x16x32_bf16 v[8:11], v[228:231], v[204:207], v[8:11]
	v_mfma_f32_16x16x32_bf16 v[4:7], v[220:223], v[212:215], v[4:7]
	v_mfma_f32_16x16x32_bf16 v[0:3], v[228:231], v[212:215], v[0:3]
	v_mfma_f32_16x16x32_bf16 v[28:31], v[224:227], v[192:195], v[28:31]
	v_mfma_f32_16x16x32_bf16 v[24:27], v[232:235], v[192:195], v[24:27]
	v_mfma_f32_16x16x32_bf16 v[20:23], v[224:227], v[200:203], v[20:23]
	v_mfma_f32_16x16x32_bf16 v[16:19], v[232:235], v[200:203], v[16:19]
	v_mfma_f32_16x16x32_bf16 v[12:15], v[224:227], v[208:211], v[12:15]
	v_mfma_f32_16x16x32_bf16 v[8:11], v[232:235], v[208:211], v[8:11]
	v_mfma_f32_16x16x32_bf16 v[4:7], v[224:227], v[216:219], v[4:7]
	v_mfma_f32_16x16x32_bf16 v[0:3], v[232:235], v[216:219], v[0:3]
	s_barrier
	s_cbranch_scc0 .LBB0_1564
	s_add_i32 s40, s38, 0x80
	s_mul_hi_i32 s41, s40, 0x1080
	s_mulk_i32 s40, 0x1080
	s_add_u32 s40, s49, s40
	s_addc_u32 s41, s50, s41
	v_lshl_add_u64 v[158:159], s[40:41], 0, v[128:129]
	v_readfirstlane_b32 s42, v169
	v_lshl_add_u64 v[158:159], v[158:159], 0, s[36:37]
	s_mov_b32 m0, s42
	ds_read_b128 v[134:137], v161
	ds_read_b128 v[138:141], v161 offset:1024
	ds_read_b128 v[172:175], v161 offset:2048
	ds_read_b128 v[176:179], v161 offset:3072
	ds_read_b128 v[180:183], v152
	ds_read_b128 v[184:187], v152 offset:1024
	ds_read_b128 v[188:191], v151
	ds_read_b128 v[192:195], v151 offset:1024
	ds_read_b128 v[196:199], v150
	ds_read_b128 v[200:203], v150 offset:1024
	ds_read_b128 v[204:207], v149
	ds_read_b128 v[208:211], v149 offset:1024
	global_load_lds_dwordx4 v[158:159], off
	v_lshl_add_u64 v[158:159], s[40:41], 0, v[132:133]
	v_readfirstlane_b32 s40, v170
	v_lshl_add_u64 v[158:159], v[158:159], 0, s[36:37]
	s_mov_b32 m0, s40
	s_nop 0
	global_load_lds_dwordx4 v[158:159], off
	s_barrier
	s_waitcnt lgkmcnt(0)
	v_mfma_f32_16x16x32_bf16 v[124:127], v[134:137], v[180:183], v[124:127]
	v_mfma_f32_16x16x32_bf16 v[120:123], v[172:175], v[180:183], v[120:123]
	v_mfma_f32_16x16x32_bf16 v[116:119], v[134:137], v[188:191], v[116:119]
	v_mfma_f32_16x16x32_bf16 v[112:115], v[172:175], v[188:191], v[112:115]
	v_mfma_f32_16x16x32_bf16 v[108:111], v[134:137], v[196:199], v[108:111]
	v_mfma_f32_16x16x32_bf16 v[104:107], v[172:175], v[196:199], v[104:107]
	v_mfma_f32_16x16x32_bf16 v[100:103], v[134:137], v[204:207], v[100:103]
	v_mfma_f32_16x16x32_bf16 v[96:99], v[172:175], v[204:207], v[96:99]
	v_mfma_f32_16x16x32_bf16 v[124:127], v[138:141], v[184:187], v[124:127]
	v_mfma_f32_16x16x32_bf16 v[120:123], v[176:179], v[184:187], v[120:123]
	v_mfma_f32_16x16x32_bf16 v[116:119], v[138:141], v[192:195], v[116:119]
	v_mfma_f32_16x16x32_bf16 v[112:115], v[176:179], v[192:195], v[112:115]
	v_mfma_f32_16x16x32_bf16 v[108:111], v[138:141], v[200:203], v[108:111]
	v_mfma_f32_16x16x32_bf16 v[104:107], v[176:179], v[200:203], v[104:107]
	v_mfma_f32_16x16x32_bf16 v[100:103], v[138:141], v[208:211], v[100:103]
	v_mfma_f32_16x16x32_bf16 v[96:99], v[176:179], v[208:211], v[96:99]
	s_barrier
	ds_read_b128 v[212:215], v160
	ds_read_b128 v[216:219], v160 offset:1024
	ds_read_b128 v[220:223], v160 offset:2048
	ds_read_b128 v[158:161], v160 offset:3072
	s_barrier
; #define LDA(dst, b, h) for (int m = 0; m < 4; ++m) for (int k = 0; k < 2; ++k) \
;     dst[m][k] = *reinterpret_cast<const bf16x8*>((char*)SA(b, h) + lds_byte(wr * 64 + m * 16 + fr, k * 32 + fq * 8))
; #define LDB(dst, b, h) for (int n = 0; n < 2; ++n) for (int k = 0; k < 2; ++k) \
;     dst[n][k] = *reinterpret_cast<const bf16x8*>((char*)SB(b, h) + lds_byte(wc * 32 + n * 16 + fr, k * 32 + fq * 8))
; #define MMA(ai, bj, At_, Bt_) do { __builtin_amdgcn_s_setprio(1); \
;     for (int k = 0; k < 2; ++k) for (int m = 0; m < 4; ++m) for (int n = 0; n < 2; ++n) \
;       acc[ai][bj][m][n] = __builtin_amdgcn_mfma_f32_16x16x32_bf16(At_[m][k], Bt_[n][k], acc[ai][bj][m][n], 0, 0, 0); \
;     __builtin_amdgcn_s_setprio(0); } while (0)
; #define WAIT_V(n) asm volatile("s_waitcnt vmcnt(" #n ")" ::: "memory")
; #define WAIT_L(n) asm volatile("s_waitcnt lgkmcnt(" #n ")" ::: "memory")
; #define BAR __builtin_amdgcn_s_barrier()
; template <int EPI, int lda, int ldb, int N, int K>
; __device__ __forceinline__ void gemm_phase(const u16* __restrict__ A, const u16* __restrict__ Bt, const GemmEpi ep, int wv) {
;     ...
;       LDB(B1, 0, 1); BAR; WAIT_L(0); MMA(0, 1, At, B1); BAR;
;       LDA(At, 0, 1); WAIT_V(4); BAR; WAIT_L(0); MMA(1, 0, At, B0); MMA(1, 1, At, B1); BAR; }
;     { LDB(B0, 1, 0); LDA(At, 1, 0); WAIT_V(2); BAR; WAIT_L(0); MMA(0, 0, At, B0); BAR;
	s_waitcnt lgkmcnt(0)
	v_mfma_f32_16x16x32_bf16 v[92:95], v[212:215], v[180:183], v[92:95]
	v_mfma_f32_16x16x32_bf16 v[88:91], v[220:223], v[180:183], v[88:91]
	v_mfma_f32_16x16x32_bf16 v[76:79], v[212:215], v[196:199], v[76:79]
	v_mfma_f32_16x16x32_bf16 v[72:75], v[220:223], v[196:199], v[72:75]
	v_mfma_f32_16x16x32_bf16 v[84:87], v[212:215], v[188:191], v[84:87]
	v_mfma_f32_16x16x32_bf16 v[80:83], v[220:223], v[188:191], v[80:83]
	v_mfma_f32_16x16x32_bf16 v[68:71], v[212:215], v[204:207], v[68:71]
	v_mfma_f32_16x16x32_bf16 v[64:67], v[220:223], v[204:207], v[64:67]
	v_mfma_f32_16x16x32_bf16 v[92:95], v[216:219], v[184:187], v[92:95]
	v_mfma_f32_16x16x32_bf16 v[88:91], v[158:161], v[184:187], v[88:91]
	v_mfma_f32_16x16x32_bf16 v[76:79], v[216:219], v[200:203], v[76:79]
	v_mfma_f32_16x16x32_bf16 v[72:75], v[158:161], v[200:203], v[72:75]
	v_mfma_f32_16x16x32_bf16 v[180:183], v[216:219], v[192:195], v[84:87]
	v_mfma_f32_16x16x32_bf16 v[184:187], v[158:161], v[192:195], v[80:83]
	v_mfma_f32_16x16x32_bf16 v[188:191], v[216:219], v[208:211], v[68:71]
	v_mfma_f32_16x16x32_bf16 v[192:195], v[158:161], v[208:211], v[64:67]
	s_barrier
	s_nop 0
	ds_read_b128 v[64:67], v152 offset:16384
	ds_read_b128 v[68:71], v152 offset:17408
	ds_read_b128 v[80:83], v151 offset:16384
	ds_read_b128 v[84:87], v151 offset:17408
	ds_read_b128 v[196:199], v150 offset:16384
	ds_read_b128 v[200:203], v150 offset:17408
	ds_read_b128 v[204:207], v149 offset:16384
	ds_read_b128 v[208:211], v149 offset:17408
	s_waitcnt vmcnt(4)
	s_barrier
	s_waitcnt lgkmcnt(0)
	v_mfma_f32_16x16x32_bf16 v[60:63], v[134:137], v[64:67], v[60:63]
	v_mfma_f32_16x16x32_bf16 v[56:59], v[172:175], v[64:67], v[56:59]
	v_mfma_f32_16x16x32_bf16 v[52:55], v[134:137], v[80:83], v[52:55]
	v_mfma_f32_16x16x32_bf16 v[48:51], v[172:175], v[80:83], v[48:51]
	v_mfma_f32_16x16x32_bf16 v[44:47], v[134:137], v[196:199], v[44:47]
	v_mfma_f32_16x16x32_bf16 v[40:43], v[172:175], v[196:199], v[40:43]
	v_mfma_f32_16x16x32_bf16 v[36:39], v[134:137], v[204:207], v[36:39]
	v_mfma_f32_16x16x32_bf16 v[32:35], v[172:175], v[204:207], v[32:35]
	v_mfma_f32_16x16x32_bf16 v[60:63], v[138:141], v[68:71], v[60:63]
	v_mfma_f32_16x16x32_bf16 v[56:59], v[176:179], v[68:71], v[56:59]
	v_mfma_f32_16x16x32_bf16 v[52:55], v[138:141], v[84:87], v[52:55]
	v_mfma_f32_16x16x32_bf16 v[48:51], v[176:179], v[84:87], v[48:51]
	v_mfma_f32_16x16x32_bf16 v[44:47], v[138:141], v[200:203], v[44:47]
	v_mfma_f32_16x16x32_bf16 v[40:43], v[176:179], v[200:203], v[40:43]
	v_mfma_f32_16x16x32_bf16 v[36:39], v[138:141], v[208:211], v[36:39]
	v_mfma_f32_16x16x32_bf16 v[32:35], v[176:179], v[208:211], v[32:35]
	v_mfma_f32_16x16x32_bf16 v[28:31], v[212:215], v[64:67], v[28:31]
	v_mfma_f32_16x16x32_bf16 v[24:27], v[220:223], v[64:67], v[24:27]
	v_mfma_f32_16x16x32_bf16 v[12:15], v[212:215], v[196:199], v[12:15]
	v_mfma_f32_16x16x32_bf16 v[8:11], v[220:223], v[196:199], v[8:11]
	v_mfma_f32_16x16x32_bf16 v[20:23], v[212:215], v[80:83], v[20:23]
	v_mfma_f32_16x16x32_bf16 v[16:19], v[220:223], v[80:83], v[16:19]
	v_mfma_f32_16x16x32_bf16 v[4:7], v[212:215], v[204:207], v[4:7]
	v_mfma_f32_16x16x32_bf16 v[0:3], v[220:223], v[204:207], v[0:3]
	v_mfma_f32_16x16x32_bf16 v[28:31], v[216:219], v[68:71], v[28:31]
	v_mfma_f32_16x16x32_bf16 v[24:27], v[158:161], v[68:71], v[24:27]
	v_mfma_f32_16x16x32_bf16 v[12:15], v[216:219], v[200:203], v[12:15]
	v_mfma_f32_16x16x32_bf16 v[8:11], v[158:161], v[200:203], v[8:11]
	v_mfma_f32_16x16x32_bf16 v[134:137], v[216:219], v[84:87], v[20:23]
	v_mfma_f32_16x16x32_bf16 v[138:141], v[158:161], v[84:87], v[16:19]
	v_mfma_f32_16x16x32_bf16 v[170:173], v[216:219], v[208:211], v[4:7]
	v_mfma_f32_16x16x32_bf16 v[158:161], v[158:161], v[208:211], v[0:3]
	s_barrier
	s_nop 0
	ds_read_b128 v[0:3], v156
	ds_read_b128 v[4:7], v156 offset:1024
	ds_read_b128 v[16:19], v156 offset:2048
	ds_read_b128 v[174:177], v156 offset:3072
	ds_read_b128 v[20:23], v152 offset:32768
	ds_read_b128 v[196:199], v152 offset:33792
	ds_read_b128 v[200:203], v151 offset:32768
	ds_read_b128 v[204:207], v151 offset:33792
	ds_read_b128 v[208:211], v150 offset:32768
	ds_read_b128 v[212:215], v150 offset:33792
	ds_read_b128 v[216:219], v149 offset:32768
	ds_read_b128 v[220:223], v149 offset:33792
	s_waitcnt vmcnt(2)
	s_barrier
; #define LDA(dst, b, h) for (int m = 0; m < 4; ++m) for (int k = 0; k < 2; ++k) \
;     dst[m][k] = *reinterpret_cast<const bf16x8*>((char*)SA(b, h) + lds_byte(wr * 64 + m * 16 + fr, k * 32 + fq * 8))
; #define LDB(dst, b, h) for (int n = 0; n < 2; ++n) for (int k = 0; k < 2; ++k) \
;     dst[n][k] = *reinterpret_cast<const bf16x8*>((char*)SB(b, h) + lds_byte(wc * 32 + n * 16 + fr, k * 32 + fq * 8))
; #define MMA(ai, bj, At_, Bt_) do { __builtin_amdgcn_s_setprio(1); \
;     for (int k = 0; k < 2; ++k) for (int m = 0; m < 4; ++m) for (int n = 0; n < 2; ++n) \
;       acc[ai][bj][m][n] = __builtin_amdgcn_mfma_f32_16x16x32_bf16(At_[m][k], Bt_[n][k], acc[ai][bj][m][n], 0, 0, 0); \
;     __builtin_amdgcn_s_setprio(0); } while (0)
; #define WAIT_V(n) asm volatile("s_waitcnt vmcnt(" #n ")" ::: "memory")
; #define WAIT_L(n) asm volatile("s_waitcnt lgkmcnt(" #n ")" ::: "memory")
; #define BAR __builtin_amdgcn_s_barrier()
; template <int EPI, int lda, int ldb, int N, int K>
; __device__ __forceinline__ void gemm_phase(const u16* __restrict__ A, const u16* __restrict__ Bt, const GemmEpi ep, int wv) {
;     ...
;     { LDB(B0, 1, 0); LDA(At, 1, 0); WAIT_V(2); BAR; WAIT_L(0); MMA(0, 0, At, B0); BAR;
;       LDB(B1, 1, 1); WAIT_V(0); BAR; WAIT_L(0); MMA(0, 1, At, B1); BAR;
;       LDA(At, 1, 1); BAR; WAIT_L(0); MMA(1, 0, At, B0); MMA(1, 1, At, B1); BAR; }
;     if (wr == 0) BAR;
	s_waitcnt lgkmcnt(0)
	v_mfma_f32_16x16x32_bf16 v[64:67], v[0:3], v[20:23], v[124:127]
	v_mfma_f32_16x16x32_bf16 v[68:71], v[16:19], v[20:23], v[120:123]
	v_mfma_f32_16x16x32_bf16 v[80:83], v[0:3], v[200:203], v[116:119]
	v_mfma_f32_16x16x32_bf16 v[84:87], v[16:19], v[200:203], v[112:115]
	v_mfma_f32_16x16x32_bf16 v[108:111], v[0:3], v[208:211], v[108:111]
	v_mfma_f32_16x16x32_bf16 v[104:107], v[16:19], v[208:211], v[104:107]
	v_mfma_f32_16x16x32_bf16 v[120:123], v[0:3], v[216:219], v[100:103]
	v_mfma_f32_16x16x32_bf16 v[124:127], v[16:19], v[216:219], v[96:99]
	v_mfma_f32_16x16x32_bf16 v[116:119], v[4:7], v[196:199], v[64:67]
	v_mfma_f32_16x16x32_bf16 v[112:115], v[174:177], v[196:199], v[68:71]
	v_mfma_f32_16x16x32_bf16 v[100:103], v[4:7], v[204:207], v[80:83]
	v_mfma_f32_16x16x32_bf16 v[96:99], v[174:177], v[204:207], v[84:87]
	v_mfma_f32_16x16x32_bf16 v[84:87], v[4:7], v[212:215], v[108:111]
	v_mfma_f32_16x16x32_bf16 v[80:83], v[174:177], v[212:215], v[104:107]
	v_mfma_f32_16x16x32_bf16 v[68:71], v[4:7], v[220:223], v[120:123]
	v_mfma_f32_16x16x32_bf16 v[64:67], v[174:177], v[220:223], v[124:127]
	s_barrier
	ds_read_b128 v[224:227], v154
	ds_read_b128 v[228:231], v154 offset:1024
	ds_read_b128 v[232:235], v154 offset:2048
	ds_read_b128 v[154:157], v154 offset:3072
	s_waitcnt vmcnt(0)
	s_barrier
	s_waitcnt lgkmcnt(0)
	v_mfma_f32_16x16x32_bf16 v[92:95], v[224:227], v[20:23], v[92:95]
	v_mfma_f32_16x16x32_bf16 v[20:23], v[232:235], v[20:23], v[88:91]
	v_mfma_f32_16x16x32_bf16 v[88:91], v[224:227], v[200:203], v[180:183]
	v_mfma_f32_16x16x32_bf16 v[104:107], v[232:235], v[200:203], v[184:187]
	v_mfma_f32_16x16x32_bf16 v[76:79], v[224:227], v[208:211], v[76:79]
	v_mfma_f32_16x16x32_bf16 v[72:75], v[232:235], v[208:211], v[72:75]
	v_mfma_f32_16x16x32_bf16 v[178:181], v[224:227], v[216:219], v[188:191]
	v_mfma_f32_16x16x32_bf16 v[182:185], v[232:235], v[216:219], v[192:195]
	v_mfma_f32_16x16x32_bf16 v[124:127], v[228:231], v[196:199], v[92:95]
	v_mfma_f32_16x16x32_bf16 v[120:123], v[154:157], v[196:199], v[20:23]
	v_mfma_f32_16x16x32_bf16 v[108:111], v[228:231], v[204:207], v[88:91]
	v_mfma_f32_16x16x32_bf16 v[104:107], v[154:157], v[204:207], v[104:107]
	v_mfma_f32_16x16x32_bf16 v[92:95], v[228:231], v[212:215], v[76:79]
	v_mfma_f32_16x16x32_bf16 v[88:91], v[154:157], v[212:215], v[72:75]
	v_mfma_f32_16x16x32_bf16 v[76:79], v[228:231], v[220:223], v[178:181]
	v_mfma_f32_16x16x32_bf16 v[72:75], v[154:157], v[220:223], v[182:185]
	s_barrier
	ds_read_b128 v[178:181], v152 offset:49152
	ds_read_b128 v[182:185], v152 offset:50176
	ds_read_b128 v[186:189], v151 offset:49152
	ds_read_b128 v[190:193], v151 offset:50176
	ds_read_b128 v[194:197], v150 offset:49152
	ds_read_b128 v[150:153], v150 offset:50176
	ds_read_b128 v[198:201], v149 offset:49152
	ds_read_b128 v[202:205], v149 offset:50176
	s_barrier
	s_waitcnt lgkmcnt(0)
	v_mfma_f32_16x16x32_bf16 v[20:23], v[0:3], v[178:181], v[60:63]
	v_mfma_f32_16x16x32_bf16 v[56:59], v[16:19], v[178:181], v[56:59]
	v_mfma_f32_16x16x32_bf16 v[60:63], v[0:3], v[186:189], v[52:55]
	v_mfma_f32_16x16x32_bf16 v[206:209], v[16:19], v[186:189], v[48:51]
	v_mfma_f32_16x16x32_bf16 v[44:47], v[0:3], v[194:197], v[44:47]
	v_mfma_f32_16x16x32_bf16 v[40:43], v[16:19], v[194:197], v[40:43]
	v_mfma_f32_16x16x32_bf16 v[0:3], v[0:3], v[198:201], v[36:39]
	v_mfma_f32_16x16x32_bf16 v[210:213], v[16:19], v[198:201], v[32:35]
	v_mfma_f32_16x16x32_bf16 v[52:55], v[4:7], v[182:185], v[20:23]
	v_mfma_f32_16x16x32_bf16 v[48:51], v[174:177], v[182:185], v[56:59]
	v_mfma_f32_16x16x32_bf16 v[36:39], v[4:7], v[190:193], v[60:63]
	v_mfma_f32_16x16x32_bf16 v[32:35], v[174:177], v[190:193], v[206:209]
	v_mfma_f32_16x16x32_bf16 v[20:23], v[4:7], v[150:153], v[44:47]
	v_mfma_f32_16x16x32_bf16 v[16:19], v[174:177], v[150:153], v[40:43]
	v_mfma_f32_16x16x32_bf16 v[4:7], v[4:7], v[202:205], v[0:3]
	v_mfma_f32_16x16x32_bf16 v[0:3], v[174:177], v[202:205], v[210:213]
	v_mfma_f32_16x16x32_bf16 v[28:31], v[224:227], v[178:181], v[28:31]
	v_mfma_f32_16x16x32_bf16 v[24:27], v[232:235], v[178:181], v[24:27]
	v_mfma_f32_16x16x32_bf16 v[40:43], v[224:227], v[186:189], v[134:137]
	v_mfma_f32_16x16x32_bf16 v[134:137], v[232:235], v[186:189], v[138:141]
	v_mfma_f32_16x16x32_bf16 v[12:15], v[224:227], v[194:197], v[12:15]
	v_mfma_f32_16x16x32_bf16 v[8:11], v[232:235], v[194:197], v[8:11]
	v_mfma_f32_16x16x32_bf16 v[138:141], v[224:227], v[198:201], v[170:173]
	v_mfma_f32_16x16x32_bf16 v[158:161], v[232:235], v[198:201], v[158:161]
	v_mfma_f32_16x16x32_bf16 v[60:63], v[228:231], v[182:185], v[28:31]
	v_mfma_f32_16x16x32_bf16 v[56:59], v[154:157], v[182:185], v[24:27]
	v_mfma_f32_16x16x32_bf16 v[44:47], v[228:231], v[190:193], v[40:43]
	v_mfma_f32_16x16x32_bf16 v[40:43], v[154:157], v[190:193], v[134:137]
	v_mfma_f32_16x16x32_bf16 v[28:31], v[228:231], v[150:153], v[12:15]
	v_mfma_f32_16x16x32_bf16 v[24:27], v[154:157], v[150:153], v[8:11]
	v_mfma_f32_16x16x32_bf16 v[12:15], v[228:231], v[202:205], v[138:141]
	v_mfma_f32_16x16x32_bf16 v[8:11], v[154:157], v[202:205], v[158:161]
	v_cmp_gt_u32_e32 vcc, s54, v130
	s_barrier
	s_and_saveexec_b64 s[40:41], vcc
	s_cbranch_execz .LBB0_1567
	s_barrier

; #define STAGE(P, BASE, LD, br, kt) do { const char* _g = (const char*)((BASE) + (size_t)(br) * (LD) + (size_t)(kt) * 64); \
;     for (int _i = 0; _i < 2; ++_i) { int _b = tidx * 16 + _i * 8192; int _r, _c; stage_rc(_b, _r, _c); \
;       __builtin_amdgcn_global_load_lds((const unsigned*)(_g + (unsigned)((_r * (LD) + _c) * 2)), (unsigned*)((char*)(P) + _b), 16, 0, 0); } } while (0)
; #define LDA(dst, b, h) for (int m = 0; m < 4; ++m) for (int k = 0; k < 2; ++k) \
;     dst[m][k] = *reinterpret_cast<const bf16x8*>((char*)SA(b, h) + lds_byte(wr * 64 + m * 16 + fr, k * 32 + fq * 8))
; #define LDB(dst, b, h) for (int n = 0; n < 2; ++n) for (int k = 0; k < 2; ++k) \
;     dst[n][k] = *reinterpret_cast<const bf16x8*>((char*)SB(b, h) + lds_byte(wc * 32 + n * 16 + fr, k * 32 + fq * 8))
; #define MMA(ai, bj, At_, Bt_) do { __builtin_amdgcn_s_setprio(1); \
;     for (int k = 0; k < 2; ++k) for (int m = 0; m < 4; ++m) for (int n = 0; n < 2; ++n) \
;       acc[ai][bj][m][n] = __builtin_amdgcn_mfma_f32_16x16x32_bf16(At_[m][k], Bt_[n][k], acc[ai][bj][m][n], 0, 0, 0); \
;     __builtin_amdgcn_s_setprio(0); } while (0)
; #define WAIT_L(n) asm volatile("s_waitcnt lgkmcnt(" #n ")" ::: "memory")
; #define BAR __builtin_amdgcn_s_barrier()
; #define SCHED __builtin_amdgcn_sched_barrier(0)
; template <int EPI, int lda, int ldb, int N, int K>
; __device__ __forceinline__ void gemm_phase(const u16* __restrict__ A, const u16* __restrict__ Bt, const GemmEpi ep, int wv) {
;     ...
;       LDB(B0, 0, 0); SCHED; LDA(At, 0, 0); STAGE(SA(1, 1), Ab, lda, brow + HALF, t + 1);
;       WAIT_L(8); BAR; WAIT_L(0); MMA(0, 0, At, B0); BAR; SCHED;
;       LDB(B1, 0, 1); STAGE(SB(0, 0), Bt, ldb, bcol, t + 2);
;       BAR; WAIT_L(0); MMA(0, 1, At, B1); BAR;
;       LDA(At, 0, 1); STAGE(SA(0, 0), Ab, lda, brow, t + 2);
;       BAR; WAIT_L(0); MMA(1, 0, At, B0); BAR; SCHED;
.LBB0_1624:
	ds_read_b128 v[174:177], v163
	ds_read_b128 v[178:181], v163 offset:1024
	ds_read_b128 v[182:185], v163 offset:2048
	ds_read_b128 v[186:189], v163 offset:3072
	v_add_u32_e32 v171, 0xc000, v149
	v_lshl_add_u64 v[238:239], v[134:135], 0, s[28:29]
	v_readfirstlane_b32 s50, v171
	v_add_u32_e32 v172, 0xe000, v149
	v_lshl_add_u64 v[164:165], v[238:239], 0, s[10:11]
	s_mov_b32 m0, s50
	v_lshl_add_u64 v[240:241], v[132:133], 0, s[28:29]
	v_readfirstlane_b32 s50, v172
	ds_read_b128 v[166:169], v154
	ds_read_b128 v[190:193], v154 offset:1024
	ds_read_b128 v[194:197], v153
	ds_read_b128 v[198:201], v153 offset:1024
	ds_read_b128 v[202:205], v151
	ds_read_b128 v[206:209], v151 offset:1024
	ds_read_b128 v[210:213], v150
	ds_read_b128 v[214:217], v150 offset:1024
	global_load_lds_dwordx4 v[164:165], off
	v_lshl_add_u64 v[164:165], v[240:241], 0, s[10:11]
	s_mov_b32 m0, s50
	s_nop 0
	global_load_lds_dwordx4 v[164:165], off
	s_waitcnt lgkmcnt(8)
	s_barrier
	s_waitcnt lgkmcnt(0)
	v_mfma_f32_16x16x32_bf16 v[124:127], v[166:169], v[174:177], v[124:127]
	v_mfma_f32_16x16x32_bf16 v[120:123], v[166:169], v[182:185], v[120:123]
	v_mfma_f32_16x16x32_bf16 v[116:119], v[194:197], v[174:177], v[116:119]
	v_mfma_f32_16x16x32_bf16 v[112:115], v[194:197], v[182:185], v[112:115]
	v_mfma_f32_16x16x32_bf16 v[108:111], v[202:205], v[174:177], v[108:111]
	v_mfma_f32_16x16x32_bf16 v[104:107], v[202:205], v[182:185], v[104:107]
	v_mfma_f32_16x16x32_bf16 v[100:103], v[210:213], v[174:177], v[100:103]
	v_mfma_f32_16x16x32_bf16 v[96:99], v[210:213], v[182:185], v[96:99]
	v_mfma_f32_16x16x32_bf16 v[124:127], v[190:193], v[178:181], v[124:127]
	v_mfma_f32_16x16x32_bf16 v[120:123], v[190:193], v[186:189], v[120:123]
	v_mfma_f32_16x16x32_bf16 v[116:119], v[198:201], v[178:181], v[116:119]
	v_mfma_f32_16x16x32_bf16 v[112:115], v[198:201], v[186:189], v[112:115]
	v_mfma_f32_16x16x32_bf16 v[108:111], v[206:209], v[178:181], v[108:111]
	v_mfma_f32_16x16x32_bf16 v[104:107], v[206:209], v[186:189], v[104:107]
	v_mfma_f32_16x16x32_bf16 v[100:103], v[214:217], v[178:181], v[100:103]
	v_mfma_f32_16x16x32_bf16 v[96:99], v[214:217], v[186:189], v[96:99]
	s_barrier
	v_add_u32_e32 v164, s40, v155
	v_lshl_add_u64 v[242:243], v[142:143], 0, s[28:29]
	v_readfirstlane_b32 s50, v164
	v_add_u32_e32 v165, 0x2000, v164
	v_lshl_add_u64 v[234:235], v[242:243], 0, s[12:13]
	s_mov_b32 m0, s50
	v_lshl_add_u64 v[244:245], v[140:141], 0, s[28:29]
	v_readfirstlane_b32 s50, v165
	ds_read_b128 v[218:221], v162
	ds_read_b128 v[222:225], v162 offset:1024
	ds_read_b128 v[226:229], v162 offset:2048
	ds_read_b128 v[230:233], v162 offset:3072
	global_load_lds_dwordx4 v[234:235], off
	v_lshl_add_u64 v[234:235], v[244:245], 0, s[12:13]
	s_mov_b32 m0, s50
	s_nop 0
	global_load_lds_dwordx4 v[234:235], off
	s_barrier
	s_waitcnt lgkmcnt(0)
	v_mfma_f32_16x16x32_bf16 v[92:95], v[166:169], v[218:221], v[92:95]
	v_mfma_f32_16x16x32_bf16 v[88:91], v[166:169], v[226:229], v[88:91]
	v_mfma_f32_16x16x32_bf16 v[84:87], v[194:197], v[218:221], v[84:87]
	v_mfma_f32_16x16x32_bf16 v[80:83], v[194:197], v[226:229], v[80:83]
	v_mfma_f32_16x16x32_bf16 v[76:79], v[202:205], v[218:221], v[76:79]
	v_mfma_f32_16x16x32_bf16 v[72:75], v[202:205], v[226:229], v[72:75]
	v_mfma_f32_16x16x32_bf16 v[68:71], v[210:213], v[218:221], v[68:71]
	v_mfma_f32_16x16x32_bf16 v[64:67], v[210:213], v[226:229], v[64:67]
	v_mfma_f32_16x16x32_bf16 v[92:95], v[190:193], v[222:225], v[92:95]
	v_mfma_f32_16x16x32_bf16 v[88:91], v[190:193], v[230:233], v[88:91]
	v_mfma_f32_16x16x32_bf16 v[84:87], v[198:201], v[222:225], v[84:87]
	v_mfma_f32_16x16x32_bf16 v[80:83], v[198:201], v[230:233], v[80:83]
	v_mfma_f32_16x16x32_bf16 v[76:79], v[206:209], v[222:225], v[76:79]
	v_mfma_f32_16x16x32_bf16 v[72:75], v[206:209], v[230:233], v[72:75]
	v_mfma_f32_16x16x32_bf16 v[68:71], v[214:217], v[222:225], v[68:71]
	v_mfma_f32_16x16x32_bf16 v[64:67], v[214:217], v[230:233], v[64:67]
	s_barrier
	v_readfirstlane_b32 s50, v149
	v_lshl_add_u64 v[166:167], v[238:239], 0, s[14:15]
	s_mov_b32 m0, s50
	ds_read_b128 v[190:193], v154 offset:16384
	ds_read_b128 v[194:197], v154 offset:17408
	ds_read_b128 v[198:201], v153 offset:16384
	ds_read_b128 v[202:205], v153 offset:17408
	ds_read_b128 v[206:209], v151 offset:16384
	ds_read_b128 v[210:213], v151 offset:17408
	ds_read_b128 v[214:217], v150 offset:16384
	ds_read_b128 v[234:237], v150 offset:17408
	global_load_lds_dwordx4 v[166:167], off
	v_add_u32_e32 v166, 0x2000, v149
	v_lshl_add_u64 v[168:169], v[240:241], 0, s[14:15]
	v_readfirstlane_b32 s50, v166
	s_mov_b32 m0, s50
	s_nop 0
	global_load_lds_dwordx4 v[168:169], off
	s_barrier
	s_waitcnt lgkmcnt(0)
	v_mfma_f32_16x16x32_bf16 v[60:63], v[190:193], v[174:177], v[60:63]
	v_mfma_f32_16x16x32_bf16 v[56:59], v[190:193], v[182:185], v[56:59]
	v_mfma_f32_16x16x32_bf16 v[52:55], v[198:201], v[174:177], v[52:55]
	v_mfma_f32_16x16x32_bf16 v[48:51], v[198:201], v[182:185], v[48:51]
	v_mfma_f32_16x16x32_bf16 v[44:47], v[206:209], v[174:177], v[44:47]
	v_mfma_f32_16x16x32_bf16 v[40:43], v[206:209], v[182:185], v[40:43]
	v_mfma_f32_16x16x32_bf16 v[36:39], v[214:217], v[174:177], v[36:39]
	v_mfma_f32_16x16x32_bf16 v[32:35], v[214:217], v[182:185], v[32:35]
	v_mfma_f32_16x16x32_bf16 v[60:63], v[194:197], v[178:181], v[60:63]
	v_mfma_f32_16x16x32_bf16 v[56:59], v[194:197], v[186:189], v[56:59]
	v_mfma_f32_16x16x32_bf16 v[52:55], v[202:205], v[178:181], v[52:55]
	v_mfma_f32_16x16x32_bf16 v[48:51], v[202:205], v[186:189], v[48:51]
	v_mfma_f32_16x16x32_bf16 v[44:47], v[210:213], v[178:181], v[44:47]
	v_mfma_f32_16x16x32_bf16 v[40:43], v[210:213], v[186:189], v[40:43]
	v_mfma_f32_16x16x32_bf16 v[36:39], v[234:237], v[178:181], v[36:39]
	v_mfma_f32_16x16x32_bf16 v[32:35], v[234:237], v[186:189], v[32:35]
	s_barrier
; #define STAGE(P, BASE, LD, br, kt) do { const char* _g = (const char*)((BASE) + (size_t)(br) * (LD) + (size_t)(kt) * 64); \
;     for (int _i = 0; _i < 2; ++_i) { int _b = tidx * 16 + _i * 8192; int _r, _c; stage_rc(_b, _r, _c); \
;       __builtin_amdgcn_global_load_lds((const unsigned*)(_g + (unsigned)((_r * (LD) + _c) * 2)), (unsigned*)((char*)(P) + _b), 16, 0, 0); } } while (0)
; #define LDA(dst, b, h) for (int m = 0; m < 4; ++m) for (int k = 0; k < 2; ++k) \
;     dst[m][k] = *reinterpret_cast<const bf16x8*>((char*)SA(b, h) + lds_byte(wr * 64 + m * 16 + fr, k * 32 + fq * 8))
; #define LDB(dst, b, h) for (int n = 0; n < 2; ++n) for (int k = 0; k < 2; ++k) \
;     dst[n][k] = *reinterpret_cast<const bf16x8*>((char*)SB(b, h) + lds_byte(wc * 32 + n * 16 + fr, k * 32 + fq * 8))
; #define MMA(ai, bj, At_, Bt_) do { __builtin_amdgcn_s_setprio(1); \
;     for (int k = 0; k < 2; ++k) for (int m = 0; m < 4; ++m) for (int n = 0; n < 2; ++n) \
;       acc[ai][bj][m][n] = __builtin_amdgcn_mfma_f32_16x16x32_bf16(At_[m][k], Bt_[n][k], acc[ai][bj][m][n], 0, 0, 0); \
;     __builtin_amdgcn_s_setprio(0); } while (0)
; #define WAIT_V(n) asm volatile("s_waitcnt vmcnt(" #n ")" ::: "memory")
; #define WAIT_L(n) asm volatile("s_waitcnt lgkmcnt(" #n ")" ::: "memory")
; #define BAR __builtin_amdgcn_s_barrier()
; #define SCHED __builtin_amdgcn_sched_barrier(0)
; template <int EPI, int lda, int ldb, int N, int K>
; __device__ __forceinline__ void gemm_phase(const u16* __restrict__ A, const u16* __restrict__ Bt, const GemmEpi ep, int wv) {
;     ...
;       STAGE(SB(0, 1), Bt, ldb, bcol + HALF, t + 2);
;       WAIT_V(6); BAR; MMA(1, 1, At, B1); BAR;
;       LDB(B0, 1, 0); SCHED; LDA(At, 1, 0); STAGE(SA(0, 1), Ab, lda, brow + HALF, t + 2);
;       WAIT_L(8); BAR; WAIT_L(0); MMA(0, 0, At, B0); BAR; SCHED;
;       LDB(B1, 1, 1); STAGE(SB(1, 0), Bt, ldb, bcol, t + 3);
;       BAR; WAIT_L(0); MMA(0, 1, At, B1); BAR;
	v_add_u32_e32 v167, s41, v155
	v_lshl_add_u64 v[246:247], v[138:139], 0, s[28:29]
	v_readfirstlane_b32 s50, v167
	v_lshl_add_u64 v[168:169], v[246:247], 0, s[16:17]
	s_mov_b32 m0, s50
	v_lshl_add_u64 v[248:249], v[136:137], 0, s[28:29]
	global_load_lds_dwordx4 v[168:169], off
	v_add_u32_e32 v168, 0x2000, v167
	v_lshl_add_u64 v[174:175], v[248:249], 0, s[16:17]
	v_readfirstlane_b32 s50, v168
	s_mov_b32 m0, s50
	s_nop 0
	global_load_lds_dwordx4 v[174:175], off
	s_waitcnt vmcnt(6)
	s_barrier
	v_mfma_f32_16x16x32_bf16 v[28:31], v[190:193], v[218:221], v[28:31]
	v_mfma_f32_16x16x32_bf16 v[24:27], v[190:193], v[226:229], v[24:27]
	v_mfma_f32_16x16x32_bf16 v[20:23], v[198:201], v[218:221], v[20:23]
	v_mfma_f32_16x16x32_bf16 v[16:19], v[198:201], v[226:229], v[16:19]
	v_mfma_f32_16x16x32_bf16 v[12:15], v[206:209], v[218:221], v[12:15]
	v_mfma_f32_16x16x32_bf16 v[8:11], v[206:209], v[226:229], v[8:11]
	v_mfma_f32_16x16x32_bf16 v[4:7], v[214:217], v[218:221], v[4:7]
	v_mfma_f32_16x16x32_bf16 v[0:3], v[214:217], v[226:229], v[0:3]
	v_mfma_f32_16x16x32_bf16 v[28:31], v[194:197], v[222:225], v[28:31]
	v_mfma_f32_16x16x32_bf16 v[24:27], v[194:197], v[230:233], v[24:27]
	v_mfma_f32_16x16x32_bf16 v[20:23], v[202:205], v[222:225], v[20:23]
	v_mfma_f32_16x16x32_bf16 v[16:19], v[202:205], v[230:233], v[16:19]
	v_mfma_f32_16x16x32_bf16 v[12:15], v[210:213], v[222:225], v[12:15]
	v_mfma_f32_16x16x32_bf16 v[8:11], v[210:213], v[230:233], v[8:11]
	v_mfma_f32_16x16x32_bf16 v[4:7], v[234:237], v[222:225], v[4:7]
	v_mfma_f32_16x16x32_bf16 v[0:3], v[234:237], v[230:233], v[0:3]
	s_barrier
	ds_read_b128 v[174:177], v158
	ds_read_b128 v[178:181], v158 offset:1024
	ds_read_b128 v[182:185], v158 offset:2048
	ds_read_b128 v[186:189], v158 offset:3072
	v_add_u32_e32 v169, 0x4000, v149
	v_add_u32_e32 v170, 0x6000, v149
	v_readfirstlane_b32 s50, v169
	v_lshl_add_u64 v[222:223], v[238:239], 0, s[18:19]
	s_mov_b32 m0, s50
	v_readfirstlane_b32 s50, v170
	ds_read_b128 v[190:193], v154 offset:32768
	ds_read_b128 v[194:197], v154 offset:33792
	ds_read_b128 v[198:201], v153 offset:32768
	ds_read_b128 v[202:205], v153 offset:33792
	ds_read_b128 v[206:209], v151 offset:32768
	ds_read_b128 v[210:213], v151 offset:33792
	ds_read_b128 v[214:217], v150 offset:32768
	ds_read_b128 v[218:221], v150 offset:33792
	global_load_lds_dwordx4 v[222:223], off
	v_lshl_add_u64 v[222:223], v[240:241], 0, s[18:19]
	s_mov_b32 m0, s50
	s_nop 0
	global_load_lds_dwordx4 v[222:223], off
	s_waitcnt lgkmcnt(8)
	s_barrier
	s_waitcnt lgkmcnt(0)
	v_mfma_f32_16x16x32_bf16 v[124:127], v[190:193], v[174:177], v[124:127]
	v_mfma_f32_16x16x32_bf16 v[120:123], v[190:193], v[182:185], v[120:123]
	v_mfma_f32_16x16x32_bf16 v[116:119], v[198:201], v[174:177], v[116:119]
	v_mfma_f32_16x16x32_bf16 v[112:115], v[198:201], v[182:185], v[112:115]
	v_mfma_f32_16x16x32_bf16 v[108:111], v[206:209], v[174:177], v[108:111]
	v_mfma_f32_16x16x32_bf16 v[104:107], v[206:209], v[182:185], v[104:107]
	v_mfma_f32_16x16x32_bf16 v[100:103], v[214:217], v[174:177], v[100:103]
	v_mfma_f32_16x16x32_bf16 v[96:99], v[214:217], v[182:185], v[96:99]
	v_mfma_f32_16x16x32_bf16 v[124:127], v[194:197], v[178:181], v[124:127]
	v_mfma_f32_16x16x32_bf16 v[120:123], v[194:197], v[186:189], v[120:123]
	v_mfma_f32_16x16x32_bf16 v[116:119], v[202:205], v[178:181], v[116:119]
	v_mfma_f32_16x16x32_bf16 v[112:115], v[202:205], v[186:189], v[112:115]
	v_mfma_f32_16x16x32_bf16 v[108:111], v[210:213], v[178:181], v[108:111]
	v_mfma_f32_16x16x32_bf16 v[104:107], v[210:213], v[186:189], v[104:107]
	v_mfma_f32_16x16x32_bf16 v[100:103], v[218:221], v[178:181], v[100:103]
	v_mfma_f32_16x16x32_bf16 v[96:99], v[218:221], v[186:189], v[96:99]
	s_barrier
	v_readfirstlane_b32 s50, v157
	v_add_u32_e32 v173, 0x2000, v157
	v_lshl_add_u64 v[242:243], v[242:243], 0, s[20:21]
	s_mov_b32 m0, s50
	v_readfirstlane_b32 s50, v173
	ds_read_b128 v[222:225], v156
	ds_read_b128 v[226:229], v156 offset:1024
	ds_read_b128 v[230:233], v156 offset:2048
	ds_read_b128 v[234:237], v156 offset:3072
	global_load_lds_dwordx4 v[242:243], off
	v_lshl_add_u64 v[242:243], v[244:245], 0, s[20:21]
	s_mov_b32 m0, s50
	s_nop 0
	global_load_lds_dwordx4 v[242:243], off
	s_barrier
	s_waitcnt lgkmcnt(0)
	v_mfma_f32_16x16x32_bf16 v[92:95], v[190:193], v[222:225], v[92:95]
	v_mfma_f32_16x16x32_bf16 v[88:91], v[190:193], v[230:233], v[88:91]
	v_mfma_f32_16x16x32_bf16 v[84:87], v[198:201], v[222:225], v[84:87]
	v_mfma_f32_16x16x32_bf16 v[80:83], v[198:201], v[230:233], v[80:83]
	v_mfma_f32_16x16x32_bf16 v[76:79], v[206:209], v[222:225], v[76:79]
	v_mfma_f32_16x16x32_bf16 v[72:75], v[206:209], v[230:233], v[72:75]
	v_mfma_f32_16x16x32_bf16 v[68:71], v[214:217], v[222:225], v[68:71]
	v_mfma_f32_16x16x32_bf16 v[64:67], v[214:217], v[230:233], v[64:67]
	v_mfma_f32_16x16x32_bf16 v[92:95], v[194:197], v[226:229], v[92:95]
	v_mfma_f32_16x16x32_bf16 v[88:91], v[194:197], v[234:237], v[88:91]
	v_mfma_f32_16x16x32_bf16 v[84:87], v[202:205], v[226:229], v[84:87]
	v_mfma_f32_16x16x32_bf16 v[80:83], v[202:205], v[234:237], v[80:83]
	v_mfma_f32_16x16x32_bf16 v[76:79], v[210:213], v[226:229], v[76:79]
	v_mfma_f32_16x16x32_bf16 v[72:75], v[210:213], v[234:237], v[72:75]
	v_mfma_f32_16x16x32_bf16 v[68:71], v[218:221], v[226:229], v[68:71]
	v_mfma_f32_16x16x32_bf16 v[64:67], v[218:221], v[234:237], v[64:67]
	s_barrier
; #define STAGE(P, BASE, LD, br, kt) do { const char* _g = (const char*)((BASE) + (size_t)(br) * (LD) + (size_t)(kt) * 64); \
;     for (int _i = 0; _i < 2; ++_i) { int _b = tidx * 16 + _i * 8192; int _r, _c; stage_rc(_b, _r, _c); \
;       __builtin_amdgcn_global_load_lds((const unsigned*)(_g + (unsigned)((_r * (LD) + _c) * 2)), (unsigned*)((char*)(P) + _b), 16, 0, 0); } } while (0)
; #define LDA(dst, b, h) for (int m = 0; m < 4; ++m) for (int k = 0; k < 2; ++k) \
;     dst[m][k] = *reinterpret_cast<const bf16x8*>((char*)SA(b, h) + lds_byte(wr * 64 + m * 16 + fr, k * 32 + fq * 8))
; #define LDB(dst, b, h) for (int n = 0; n < 2; ++n) for (int k = 0; k < 2; ++k) \
;     dst[n][k] = *reinterpret_cast<const bf16x8*>((char*)SB(b, h) + lds_byte(wc * 32 + n * 16 + fr, k * 32 + fq * 8))
; #define MMA(ai, bj, At_, Bt_) do { __builtin_amdgcn_s_setprio(1); \
;     for (int k = 0; k < 2; ++k) for (int m = 0; m < 4; ++m) for (int n = 0; n < 2; ++n) \
;       acc[ai][bj][m][n] = __builtin_amdgcn_mfma_f32_16x16x32_bf16(At_[m][k], Bt_[n][k], acc[ai][bj][m][n], 0, 0, 0); \
;     __builtin_amdgcn_s_setprio(0); } while (0)
; #define WAIT_V(n) asm volatile("s_waitcnt vmcnt(" #n ")" ::: "memory")
; #define WAIT_L(n) asm volatile("s_waitcnt lgkmcnt(" #n ")" ::: "memory")
; #define BAR __builtin_amdgcn_s_barrier()
; #define SCHED __builtin_amdgcn_sched_barrier(0)
; template <int EPI, int lda, int ldb, int N, int K>
; __device__ __forceinline__ void gemm_phase(const u16* __restrict__ A, const u16* __restrict__ Bt, const GemmEpi ep, int wv) {
;     ...
;       LDA(At, 1, 1); STAGE(SA(1, 0), Ab, lda, brow, t + 3);
;       BAR; WAIT_L(0); MMA(1, 0, At, B0); BAR; SCHED;
;       STAGE(SB(1, 1), Bt, ldb, bcol + HALF, t + 3);
;       WAIT_V(6); BAR; MMA(1, 1, At, B1); BAR;
;     }
;     { LDB(B0, 0, 0); LDA(At, 0, 0); STAGE(SA(1, 1), Ab, lda, brow + HALF, nt - 1);
;       BAR; WAIT_L(0); MMA(0, 0, At, B0); BAR;
;       LDB(B1, 0, 1); BAR; WAIT_L(0); MMA(0, 1, At, B1); BAR;
	v_readfirstlane_b32 s50, v159
	v_lshl_add_u64 v[238:239], v[238:239], 0, s[22:23]
	s_mov_b32 m0, s50
	v_readfirstlane_b32 s50, v160
	ds_read_b128 v[190:193], v154 offset:49152
	ds_read_b128 v[194:197], v154 offset:50176
	ds_read_b128 v[198:201], v153 offset:49152
	ds_read_b128 v[202:205], v153 offset:50176
	ds_read_b128 v[206:209], v151 offset:49152
	ds_read_b128 v[210:213], v151 offset:50176
	ds_read_b128 v[214:217], v150 offset:49152
	ds_read_b128 v[218:221], v150 offset:50176
	global_load_lds_dwordx4 v[238:239], off
	v_lshl_add_u64 v[238:239], v[240:241], 0, s[22:23]
	s_mov_b32 m0, s50
	s_nop 0
	global_load_lds_dwordx4 v[238:239], off
	s_barrier
	s_waitcnt lgkmcnt(0)
	v_mfma_f32_16x16x32_bf16 v[60:63], v[190:193], v[174:177], v[60:63]
	v_mfma_f32_16x16x32_bf16 v[56:59], v[190:193], v[182:185], v[56:59]
	v_mfma_f32_16x16x32_bf16 v[52:55], v[198:201], v[174:177], v[52:55]
	v_mfma_f32_16x16x32_bf16 v[48:51], v[198:201], v[182:185], v[48:51]
	v_mfma_f32_16x16x32_bf16 v[44:47], v[206:209], v[174:177], v[44:47]
	v_mfma_f32_16x16x32_bf16 v[40:43], v[206:209], v[182:185], v[40:43]
	v_mfma_f32_16x16x32_bf16 v[36:39], v[214:217], v[174:177], v[36:39]
	v_mfma_f32_16x16x32_bf16 v[32:35], v[214:217], v[182:185], v[32:35]
	v_mfma_f32_16x16x32_bf16 v[60:63], v[194:197], v[178:181], v[60:63]
	v_mfma_f32_16x16x32_bf16 v[56:59], v[194:197], v[186:189], v[56:59]
	v_mfma_f32_16x16x32_bf16 v[52:55], v[202:205], v[178:181], v[52:55]
	v_mfma_f32_16x16x32_bf16 v[48:51], v[202:205], v[186:189], v[48:51]
	v_mfma_f32_16x16x32_bf16 v[44:47], v[210:213], v[178:181], v[44:47]
	v_mfma_f32_16x16x32_bf16 v[40:43], v[210:213], v[186:189], v[40:43]
	v_mfma_f32_16x16x32_bf16 v[36:39], v[218:221], v[178:181], v[36:39]
	v_mfma_f32_16x16x32_bf16 v[32:35], v[218:221], v[186:189], v[32:35]
	s_barrier
	v_readfirstlane_b32 s50, v161
	v_add_u32_e32 v173, 0x2000, v161
	v_lshl_add_u64 v[174:175], v[246:247], 0, s[24:25]
	s_mov_b32 m0, s50
	v_readfirstlane_b32 s50, v173
	global_load_lds_dwordx4 v[174:175], off
	v_lshl_add_u64 v[174:175], v[248:249], 0, s[24:25]
	s_mov_b32 m0, s50
	s_nop 0
	global_load_lds_dwordx4 v[174:175], off
	s_add_i32 s49, s49, 2
	s_add_u32 s28, s28, 0x100
	s_addc_u32 s29, s29, 0
	s_cmpk_gt_u32 s49, 0x51
	s_waitcnt vmcnt(6)
	s_barrier
	v_mfma_f32_16x16x32_bf16 v[28:31], v[190:193], v[222:225], v[28:31]
	v_mfma_f32_16x16x32_bf16 v[24:27], v[190:193], v[230:233], v[24:27]
	v_mfma_f32_16x16x32_bf16 v[20:23], v[198:201], v[222:225], v[20:23]
	v_mfma_f32_16x16x32_bf16 v[16:19], v[198:201], v[230:233], v[16:19]
	v_mfma_f32_16x16x32_bf16 v[12:15], v[206:209], v[222:225], v[12:15]
	v_mfma_f32_16x16x32_bf16 v[8:11], v[206:209], v[230:233], v[8:11]
	v_mfma_f32_16x16x32_bf16 v[4:7], v[214:217], v[222:225], v[4:7]
	v_mfma_f32_16x16x32_bf16 v[0:3], v[214:217], v[230:233], v[0:3]
	v_mfma_f32_16x16x32_bf16 v[28:31], v[194:197], v[226:229], v[28:31]
	v_mfma_f32_16x16x32_bf16 v[24:27], v[194:197], v[234:237], v[24:27]
	v_mfma_f32_16x16x32_bf16 v[20:23], v[202:205], v[226:229], v[20:23]
	v_mfma_f32_16x16x32_bf16 v[16:19], v[202:205], v[234:237], v[16:19]
	v_mfma_f32_16x16x32_bf16 v[12:15], v[210:213], v[226:229], v[12:15]
	v_mfma_f32_16x16x32_bf16 v[8:11], v[210:213], v[234:237], v[8:11]
	v_mfma_f32_16x16x32_bf16 v[4:7], v[218:221], v[226:229], v[4:7]
	v_mfma_f32_16x16x32_bf16 v[0:3], v[218:221], v[234:237], v[0:3]
	s_barrier
	s_cbranch_scc0 .LBB0_1624
	s_add_i32 s28, s48, 0x80
	s_mul_hi_i32 s29, s28, 0x2b00
	s_mulk_i32 s28, 0x2b00
	s_add_u32 s28, s34, s28
	s_addc_u32 s29, s35, s29
	s_add_u32 s28, s28, 0x2a80
	s_addc_u32 s29, s29, 0
	v_readfirstlane_b32 s49, v171
	v_lshl_add_u64 v[160:161], s[28:29], 0, v[128:129]
	s_mov_b32 m0, s49
	ds_read_b128 v[132:135], v163
	ds_read_b128 v[136:139], v163 offset:1024
	ds_read_b128 v[140:143], v163 offset:2048
	ds_read_b128 v[174:177], v163 offset:3072
	ds_read_b128 v[178:181], v154
	ds_read_b128 v[182:185], v154 offset:1024
	ds_read_b128 v[186:189], v153
	ds_read_b128 v[190:193], v153 offset:1024
	ds_read_b128 v[194:197], v151
	ds_read_b128 v[198:201], v151 offset:1024
	ds_read_b128 v[202:205], v150
	ds_read_b128 v[206:209], v150 offset:1024
	global_load_lds_dwordx4 v[160:161], off
	v_lshl_add_u64 v[160:161], s[28:29], 0, v[130:131]
	v_readfirstlane_b32 s28, v172
	s_mov_b32 m0, s28
	s_nop 0
	global_load_lds_dwordx4 v[160:161], off
	s_barrier
	s_waitcnt lgkmcnt(0)
	v_mfma_f32_16x16x32_bf16 v[124:127], v[178:181], v[132:135], v[124:127]
	v_mfma_f32_16x16x32_bf16 v[120:123], v[178:181], v[140:143], v[120:123]
	v_mfma_f32_16x16x32_bf16 v[116:119], v[186:189], v[132:135], v[116:119]
	v_mfma_f32_16x16x32_bf16 v[112:115], v[186:189], v[140:143], v[112:115]
	v_mfma_f32_16x16x32_bf16 v[108:111], v[194:197], v[132:135], v[108:111]
	v_mfma_f32_16x16x32_bf16 v[104:107], v[194:197], v[140:143], v[104:107]
	v_mfma_f32_16x16x32_bf16 v[100:103], v[202:205], v[132:135], v[100:103]
	v_mfma_f32_16x16x32_bf16 v[96:99], v[202:205], v[140:143], v[96:99]
	v_mfma_f32_16x16x32_bf16 v[124:127], v[182:185], v[136:139], v[124:127]
	v_mfma_f32_16x16x32_bf16 v[120:123], v[182:185], v[174:177], v[120:123]
	v_mfma_f32_16x16x32_bf16 v[116:119], v[190:193], v[136:139], v[116:119]
	v_mfma_f32_16x16x32_bf16 v[112:115], v[190:193], v[174:177], v[112:115]
	v_mfma_f32_16x16x32_bf16 v[108:111], v[198:201], v[136:139], v[108:111]
	v_mfma_f32_16x16x32_bf16 v[104:107], v[198:201], v[174:177], v[104:107]
	v_mfma_f32_16x16x32_bf16 v[100:103], v[206:209], v[136:139], v[100:103]
	v_mfma_f32_16x16x32_bf16 v[96:99], v[206:209], v[174:177], v[96:99]
	s_barrier
	ds_read_b128 v[210:213], v162
	ds_read_b128 v[214:217], v162 offset:1024
	ds_read_b128 v[218:221], v162 offset:2048
	ds_read_b128 v[160:163], v162 offset:3072
	s_barrier
; #define LDA(dst, b, h) for (int m = 0; m < 4; ++m) for (int k = 0; k < 2; ++k) \
;     dst[m][k] = *reinterpret_cast<const bf16x8*>((char*)SA(b, h) + lds_byte(wr * 64 + m * 16 + fr, k * 32 + fq * 8))
; #define LDB(dst, b, h) for (int n = 0; n < 2; ++n) for (int k = 0; k < 2; ++k) \
;     dst[n][k] = *reinterpret_cast<const bf16x8*>((char*)SB(b, h) + lds_byte(wc * 32 + n * 16 + fr, k * 32 + fq * 8))
; #define MMA(ai, bj, At_, Bt_) do { __builtin_amdgcn_s_setprio(1); \
;     for (int k = 0; k < 2; ++k) for (int m = 0; m < 4; ++m) for (int n = 0; n < 2; ++n) \
;       acc[ai][bj][m][n] = __builtin_amdgcn_mfma_f32_16x16x32_bf16(At_[m][k], Bt_[n][k], acc[ai][bj][m][n], 0, 0, 0); \
;     __builtin_amdgcn_s_setprio(0); } while (0)
; #define WAIT_V(n) asm volatile("s_waitcnt vmcnt(" #n ")" ::: "memory")
; #define WAIT_L(n) asm volatile("s_waitcnt lgkmcnt(" #n ")" ::: "memory")
; #define BAR __builtin_amdgcn_s_barrier()
; template <int EPI, int lda, int ldb, int N, int K>
; __device__ __forceinline__ void gemm_phase(const u16* __restrict__ A, const u16* __restrict__ Bt, const GemmEpi ep, int wv) {
;     ...
;       LDB(B1, 0, 1); BAR; WAIT_L(0); MMA(0, 1, At, B1); BAR;
;       LDA(At, 0, 1); WAIT_V(4); BAR; WAIT_L(0); MMA(1, 0, At, B0); MMA(1, 1, At, B1); BAR; }
;     { LDB(B0, 1, 0); LDA(At, 1, 0); WAIT_V(2); BAR; WAIT_L(0); MMA(0, 0, At, B0); BAR;
	s_waitcnt lgkmcnt(0)
	v_mfma_f32_16x16x32_bf16 v[92:95], v[178:181], v[210:213], v[92:95]
	v_mfma_f32_16x16x32_bf16 v[88:91], v[178:181], v[218:221], v[88:91]
	v_mfma_f32_16x16x32_bf16 v[72:75], v[194:197], v[218:221], v[72:75]
	v_mfma_f32_16x16x32_bf16 v[68:71], v[202:205], v[210:213], v[68:71]
	v_mfma_f32_16x16x32_bf16 v[84:87], v[186:189], v[210:213], v[84:87]
	v_mfma_f32_16x16x32_bf16 v[80:83], v[186:189], v[218:221], v[80:83]
	v_mfma_f32_16x16x32_bf16 v[76:79], v[194:197], v[210:213], v[76:79]
	v_mfma_f32_16x16x32_bf16 v[64:67], v[202:205], v[218:221], v[64:67]
	v_mfma_f32_16x16x32_bf16 v[92:95], v[182:185], v[214:217], v[92:95]
	v_mfma_f32_16x16x32_bf16 v[88:91], v[182:185], v[160:163], v[88:91]
	v_mfma_f32_16x16x32_bf16 v[72:75], v[198:201], v[160:163], v[72:75]
	v_mfma_f32_16x16x32_bf16 v[68:71], v[206:209], v[214:217], v[68:71]
	v_mfma_f32_16x16x32_bf16 v[178:181], v[190:193], v[214:217], v[84:87]
	v_mfma_f32_16x16x32_bf16 v[182:185], v[190:193], v[160:163], v[80:83]
	v_mfma_f32_16x16x32_bf16 v[186:189], v[198:201], v[214:217], v[76:79]
	v_mfma_f32_16x16x32_bf16 v[190:193], v[206:209], v[160:163], v[64:67]
	s_barrier
	s_nop 0
	ds_read_b128 v[64:67], v154 offset:16384
	ds_read_b128 v[76:79], v154 offset:17408
	ds_read_b128 v[80:83], v153 offset:16384
	ds_read_b128 v[84:87], v153 offset:17408
	ds_read_b128 v[194:197], v151 offset:16384
	ds_read_b128 v[198:201], v151 offset:17408
	ds_read_b128 v[202:205], v150 offset:16384
	ds_read_b128 v[206:209], v150 offset:17408
	s_waitcnt vmcnt(4)
	s_barrier
	s_waitcnt lgkmcnt(0)
	v_mfma_f32_16x16x32_bf16 v[60:63], v[64:67], v[132:135], v[60:63]
	v_mfma_f32_16x16x32_bf16 v[56:59], v[64:67], v[140:143], v[56:59]
	v_mfma_f32_16x16x32_bf16 v[52:55], v[80:83], v[132:135], v[52:55]
	v_mfma_f32_16x16x32_bf16 v[48:51], v[80:83], v[140:143], v[48:51]
	v_mfma_f32_16x16x32_bf16 v[44:47], v[194:197], v[132:135], v[44:47]
	v_mfma_f32_16x16x32_bf16 v[40:43], v[194:197], v[140:143], v[40:43]
	v_mfma_f32_16x16x32_bf16 v[36:39], v[202:205], v[132:135], v[36:39]
	v_mfma_f32_16x16x32_bf16 v[32:35], v[202:205], v[140:143], v[32:35]
	v_mfma_f32_16x16x32_bf16 v[60:63], v[76:79], v[136:139], v[60:63]
	v_mfma_f32_16x16x32_bf16 v[56:59], v[76:79], v[174:177], v[56:59]
	v_mfma_f32_16x16x32_bf16 v[52:55], v[84:87], v[136:139], v[52:55]
	v_mfma_f32_16x16x32_bf16 v[48:51], v[84:87], v[174:177], v[48:51]
	v_mfma_f32_16x16x32_bf16 v[44:47], v[198:201], v[136:139], v[44:47]
	v_mfma_f32_16x16x32_bf16 v[40:43], v[198:201], v[174:177], v[40:43]
	v_mfma_f32_16x16x32_bf16 v[36:39], v[206:209], v[136:139], v[36:39]
	v_mfma_f32_16x16x32_bf16 v[32:35], v[206:209], v[174:177], v[32:35]
	v_mfma_f32_16x16x32_bf16 v[28:31], v[64:67], v[210:213], v[28:31]
	v_mfma_f32_16x16x32_bf16 v[24:27], v[64:67], v[218:221], v[24:27]
	v_mfma_f32_16x16x32_bf16 v[12:15], v[194:197], v[210:213], v[12:15]
	v_mfma_f32_16x16x32_bf16 v[8:11], v[194:197], v[218:221], v[8:11]
	v_mfma_f32_16x16x32_bf16 v[20:23], v[80:83], v[210:213], v[20:23]
	v_mfma_f32_16x16x32_bf16 v[16:19], v[80:83], v[218:221], v[16:19]
	v_mfma_f32_16x16x32_bf16 v[4:7], v[202:205], v[210:213], v[4:7]
	v_mfma_f32_16x16x32_bf16 v[0:3], v[202:205], v[218:221], v[0:3]
	v_mfma_f32_16x16x32_bf16 v[28:31], v[76:79], v[214:217], v[28:31]
	v_mfma_f32_16x16x32_bf16 v[24:27], v[76:79], v[160:163], v[24:27]
	v_mfma_f32_16x16x32_bf16 v[12:15], v[198:201], v[214:217], v[12:15]
	v_mfma_f32_16x16x32_bf16 v[8:11], v[198:201], v[160:163], v[8:11]
	v_mfma_f32_16x16x32_bf16 v[132:135], v[84:87], v[214:217], v[20:23]
	v_mfma_f32_16x16x32_bf16 v[136:139], v[84:87], v[160:163], v[16:19]
	v_mfma_f32_16x16x32_bf16 v[140:143], v[206:209], v[214:217], v[4:7]
	v_mfma_f32_16x16x32_bf16 v[160:163], v[206:209], v[160:163], v[0:3]
	s_barrier
	s_nop 0
	ds_read_b128 v[0:3], v158
	ds_read_b128 v[4:7], v158 offset:1024
	ds_read_b128 v[16:19], v158 offset:2048
	ds_read_b128 v[172:175], v158 offset:3072
	ds_read_b128 v[20:23], v154 offset:32768
	ds_read_b128 v[194:197], v154 offset:33792
	ds_read_b128 v[198:201], v153 offset:32768
	ds_read_b128 v[202:205], v153 offset:33792
	ds_read_b128 v[206:209], v151 offset:32768
	ds_read_b128 v[210:213], v151 offset:33792
	ds_read_b128 v[214:217], v150 offset:32768
	ds_read_b128 v[218:221], v150 offset:33792
	s_waitcnt vmcnt(2)
	s_barrier
; #define LDA(dst, b, h) for (int m = 0; m < 4; ++m) for (int k = 0; k < 2; ++k) \
;     dst[m][k] = *reinterpret_cast<const bf16x8*>((char*)SA(b, h) + lds_byte(wr * 64 + m * 16 + fr, k * 32 + fq * 8))
; #define LDB(dst, b, h) for (int n = 0; n < 2; ++n) for (int k = 0; k < 2; ++k) \
;     dst[n][k] = *reinterpret_cast<const bf16x8*>((char*)SB(b, h) + lds_byte(wc * 32 + n * 16 + fr, k * 32 + fq * 8))
; #define MMA(ai, bj, At_, Bt_) do { __builtin_amdgcn_s_setprio(1); \
;     for (int k = 0; k < 2; ++k) for (int m = 0; m < 4; ++m) for (int n = 0; n < 2; ++n) \
;       acc[ai][bj][m][n] = __builtin_amdgcn_mfma_f32_16x16x32_bf16(At_[m][k], Bt_[n][k], acc[ai][bj][m][n], 0, 0, 0); \
;     __builtin_amdgcn_s_setprio(0); } while (0)
; #define WAIT_V(n) asm volatile("s_waitcnt vmcnt(" #n ")" ::: "memory")
; #define WAIT_L(n) asm volatile("s_waitcnt lgkmcnt(" #n ")" ::: "memory")
; #define BAR __builtin_amdgcn_s_barrier()
; template <int EPI, int lda, int ldb, int N, int K>
; __device__ __forceinline__ void gemm_phase(const u16* __restrict__ A, const u16* __restrict__ Bt, const GemmEpi ep, int wv) {
;     ...
;     { LDB(B0, 1, 0); LDA(At, 1, 0); WAIT_V(2); BAR; WAIT_L(0); MMA(0, 0, At, B0); BAR;
;       LDB(B1, 1, 1); WAIT_V(0); BAR; WAIT_L(0); MMA(0, 1, At, B1); BAR;
;       LDA(At, 1, 1); BAR; WAIT_L(0); MMA(1, 0, At, B0); MMA(1, 1, At, B1); BAR; }
;     if (wr == 0) BAR;
	s_waitcnt lgkmcnt(0)
	v_mfma_f32_16x16x32_bf16 v[64:67], v[20:23], v[0:3], v[124:127]
	v_mfma_f32_16x16x32_bf16 v[76:79], v[20:23], v[16:19], v[120:123]
	v_mfma_f32_16x16x32_bf16 v[80:83], v[198:201], v[0:3], v[116:119]
	v_mfma_f32_16x16x32_bf16 v[84:87], v[198:201], v[16:19], v[112:115]
	v_mfma_f32_16x16x32_bf16 v[108:111], v[206:209], v[0:3], v[108:111]
	v_mfma_f32_16x16x32_bf16 v[104:107], v[206:209], v[16:19], v[104:107]
	v_mfma_f32_16x16x32_bf16 v[120:123], v[214:217], v[0:3], v[100:103]
	v_mfma_f32_16x16x32_bf16 v[124:127], v[214:217], v[16:19], v[96:99]
	v_mfma_f32_16x16x32_bf16 v[116:119], v[194:197], v[4:7], v[64:67]
	v_mfma_f32_16x16x32_bf16 v[112:115], v[194:197], v[172:175], v[76:79]
	v_mfma_f32_16x16x32_bf16 v[100:103], v[202:205], v[4:7], v[80:83]
	v_mfma_f32_16x16x32_bf16 v[96:99], v[202:205], v[172:175], v[84:87]
	v_mfma_f32_16x16x32_bf16 v[84:87], v[210:213], v[4:7], v[108:111]
	v_mfma_f32_16x16x32_bf16 v[80:83], v[210:213], v[172:175], v[104:107]
	v_mfma_f32_16x16x32_bf16 v[76:79], v[218:221], v[4:7], v[120:123]
	v_mfma_f32_16x16x32_bf16 v[64:67], v[218:221], v[172:175], v[124:127]
	s_barrier
	ds_read_b128 v[222:225], v156
	ds_read_b128 v[226:229], v156 offset:1024
	ds_read_b128 v[230:233], v156 offset:2048
	ds_read_b128 v[156:159], v156 offset:3072
	s_waitcnt vmcnt(0)
	s_barrier
	s_waitcnt lgkmcnt(0)
	v_mfma_f32_16x16x32_bf16 v[92:95], v[20:23], v[222:225], v[92:95]
	v_mfma_f32_16x16x32_bf16 v[20:23], v[20:23], v[230:233], v[88:91]
	v_mfma_f32_16x16x32_bf16 v[88:91], v[198:201], v[222:225], v[178:181]
	v_mfma_f32_16x16x32_bf16 v[104:107], v[198:201], v[230:233], v[182:185]
	v_mfma_f32_16x16x32_bf16 v[176:179], v[206:209], v[222:225], v[186:189]
	v_mfma_f32_16x16x32_bf16 v[72:75], v[206:209], v[230:233], v[72:75]
	v_mfma_f32_16x16x32_bf16 v[68:71], v[214:217], v[222:225], v[68:71]
	v_mfma_f32_16x16x32_bf16 v[180:183], v[214:217], v[230:233], v[190:193]
	v_mfma_f32_16x16x32_bf16 v[124:127], v[194:197], v[226:229], v[92:95]
	v_mfma_f32_16x16x32_bf16 v[120:123], v[194:197], v[156:159], v[20:23]
	v_mfma_f32_16x16x32_bf16 v[108:111], v[202:205], v[226:229], v[88:91]
	v_mfma_f32_16x16x32_bf16 v[104:107], v[202:205], v[156:159], v[104:107]
	v_mfma_f32_16x16x32_bf16 v[92:95], v[210:213], v[226:229], v[176:179]
	v_mfma_f32_16x16x32_bf16 v[88:91], v[210:213], v[156:159], v[72:75]
	v_mfma_f32_16x16x32_bf16 v[72:75], v[218:221], v[226:229], v[68:71]
	v_mfma_f32_16x16x32_bf16 v[68:71], v[218:221], v[156:159], v[180:183]
	s_barrier
	ds_read_b128 v[176:179], v154 offset:49152
	ds_read_b128 v[180:183], v154 offset:50176
	ds_read_b128 v[184:187], v153 offset:49152
	ds_read_b128 v[188:191], v153 offset:50176
	ds_read_b128 v[192:195], v151 offset:49152
	ds_read_b128 v[196:199], v151 offset:50176
	ds_read_b128 v[200:203], v150 offset:49152
	ds_read_b128 v[204:207], v150 offset:50176
	s_barrier
	s_waitcnt lgkmcnt(0)
	v_mfma_f32_16x16x32_bf16 v[20:23], v[176:179], v[0:3], v[60:63]
	v_mfma_f32_16x16x32_bf16 v[56:59], v[176:179], v[16:19], v[56:59]
	v_mfma_f32_16x16x32_bf16 v[60:63], v[184:187], v[0:3], v[52:55]
	v_mfma_f32_16x16x32_bf16 v[208:211], v[184:187], v[16:19], v[48:51]
	v_mfma_f32_16x16x32_bf16 v[44:47], v[192:195], v[0:3], v[44:47]
	v_mfma_f32_16x16x32_bf16 v[40:43], v[192:195], v[16:19], v[40:43]
	v_mfma_f32_16x16x32_bf16 v[0:3], v[200:203], v[0:3], v[36:39]
	v_mfma_f32_16x16x32_bf16 v[212:215], v[200:203], v[16:19], v[32:35]
	v_mfma_f32_16x16x32_bf16 v[52:55], v[180:183], v[4:7], v[20:23]
	v_mfma_f32_16x16x32_bf16 v[48:51], v[180:183], v[172:175], v[56:59]
	v_mfma_f32_16x16x32_bf16 v[36:39], v[188:191], v[4:7], v[60:63]
	v_mfma_f32_16x16x32_bf16 v[32:35], v[188:191], v[172:175], v[208:211]
	v_mfma_f32_16x16x32_bf16 v[20:23], v[196:199], v[4:7], v[44:47]
	v_mfma_f32_16x16x32_bf16 v[16:19], v[196:199], v[172:175], v[40:43]
	v_mfma_f32_16x16x32_bf16 v[4:7], v[204:207], v[4:7], v[0:3]
	v_mfma_f32_16x16x32_bf16 v[0:3], v[204:207], v[172:175], v[212:215]
	v_mfma_f32_16x16x32_bf16 v[28:31], v[176:179], v[222:225], v[28:31]
	v_mfma_f32_16x16x32_bf16 v[24:27], v[176:179], v[230:233], v[24:27]
	v_mfma_f32_16x16x32_bf16 v[40:43], v[184:187], v[222:225], v[132:135]
	v_mfma_f32_16x16x32_bf16 v[132:135], v[184:187], v[230:233], v[136:139]
	v_mfma_f32_16x16x32_bf16 v[12:15], v[192:195], v[222:225], v[12:15]
	v_mfma_f32_16x16x32_bf16 v[8:11], v[192:195], v[230:233], v[8:11]
	v_mfma_f32_16x16x32_bf16 v[136:139], v[200:203], v[222:225], v[140:143]
	v_mfma_f32_16x16x32_bf16 v[140:143], v[200:203], v[230:233], v[160:163]
	v_mfma_f32_16x16x32_bf16 v[60:63], v[180:183], v[226:229], v[28:31]
	v_mfma_f32_16x16x32_bf16 v[56:59], v[180:183], v[156:159], v[24:27]
	v_mfma_f32_16x16x32_bf16 v[44:47], v[188:191], v[226:229], v[40:43]
	v_mfma_f32_16x16x32_bf16 v[40:43], v[188:191], v[156:159], v[132:135]
	v_mfma_f32_16x16x32_bf16 v[28:31], v[196:199], v[226:229], v[12:15]
	v_mfma_f32_16x16x32_bf16 v[24:27], v[196:199], v[156:159], v[8:11]
	v_mfma_f32_16x16x32_bf16 v[12:15], v[204:207], v[226:229], v[136:139]
	v_mfma_f32_16x16x32_bf16 v[8:11], v[204:207], v[156:159], v[140:143]
	v_cmp_gt_u32_e32 vcc, s46, v147
	s_barrier
	s_and_saveexec_b64 s[28:29], vcc
	s_cbranch_execz .LBB0_1627
	s_barrier
